# tool-driven LDS read hoisting also in RWKV stage H token sections and in the GLA chunk loops
# speedup vs baseline: 1.0007x; 1.0007x over previous
.LBB0_327:
	s_or_b64 exec, exec, s[0:1]
	s_nop 5
	v_cvt_f16_f32_e32 v2, v52
	v_cvt_f16_f32_e32 v52, v53
	v_cvt_f16_f32_e32 v53, v54
	v_cvt_f16_f32_e32 v54, v55
	v_cndmask_b32_e64 v2, v2, 0, s[18:19]
	v_cndmask_b32_e64 v52, 0, v52, s[20:21]
	v_cndmask_b32_e64 v53, v53, 0, s[22:23]
	v_cndmask_b32_e64 v54, v54, 0, s[24:25]
	v_pack_b32_f16 v53, v53, v54
	v_pack_b32_f16 v52, v2, v52
	ds_write_b64 v123, v[52:53]
	s_waitcnt lgkmcnt(0)
	s_barrier
	ds_read_b128 v[126:129], v124 offset:55360
	ds_read_b128 v[52:55], v125
	ds_read_b128 v[134:137], v125 offset:64
	ds_read_b128 v[138:141], v125 offset:2304
	ds_read_b128 v[142:145], v125 offset:2368
	ds_read_b128 v[146:149], v125 offset:4608
	ds_read_b128 v[178:181], v125 offset:4672
	ds_read_b128 v[68:71], v124 offset:55296
	s_nop 0
	s_nop 0
	ds_read_b128 v[182:185], v125 offset:6912
	s_nop 0
	s_waitcnt lgkmcnt(1)
	v_mfma_f32_16x16x32_f16 v[48:51], v[68:71], v[52:55], v[48:51]
	s_nop 0
	v_add_u32_e32 v2, 0x1e500, v96
	ds_read_b128 v[186:189], v125 offset:6976
	s_add_i32 s28, s28, 1
	s_nop 0
	v_mfma_f32_16x16x32_f16 v[52:55], v[126:129], v[134:137], v[48:51]
	ds_read_b128 v[134:137], v2
	s_nop 2
	s_nop 0
	s_nop 0
	v_mfma_f32_16x16x32_f16 v[48:51], v[68:71], v[138:141], v[56:59]
	s_nop 2
	s_nop 0
	ds_read_b128 v[138:141], v125 offset:46080
	v_cvt_pk_f16_f32 v55, v54, v55
	v_cvt_pk_f16_f32 v54, v52, v53
	s_nop 0
	v_mfma_f32_16x16x32_f16 v[56:59], v[126:129], v[142:145], v[48:51]
	ds_read_b128 v[142:145], v125 offset:46144
	s_nop 2
	s_nop 0
	s_nop 0
	ds_read_b128 v[190:193], v2 offset:64
	v_mfma_f32_16x16x32_f16 v[48:51], v[68:71], v[146:149], v[60:63]
	s_nop 2
	s_nop 0
	s_nop 0
	ds_read_b128 v[146:149], v125 offset:48384
	v_mfma_f32_16x16x32_f16 v[60:63], v[126:129], v[178:181], v[48:51]
	s_nop 2
	s_nop 0
	ds_read_b128 v[178:181], v125 offset:48448
	s_nop 0
	s_waitcnt lgkmcnt(7)
	v_mfma_f32_16x16x32_f16 v[48:51], v[68:71], v[182:185], v[64:67]
	s_nop 2
	ds_read_b128 v[182:185], v2 offset:128
	s_nop 0
	s_nop 0
	s_waitcnt lgkmcnt(7)
	v_mfma_f32_16x16x32_f16 v[48:51], v[126:129], v[186:189], v[48:51]
	s_nop 0
	ds_read_b128 v[186:189], v125 offset:50688
	s_nop 0
	s_waitcnt lgkmcnt(7)
	v_pk_mul_f32 v[44:45], v[44:45], v[134:135]
	v_pk_mul_f32 v[46:47], v[46:47], v[136:137]
	ds_read_b128 v[134:137], v125 offset:50752
	s_nop 0
	s_nop 2
	v_cvt_pk_f16_f32 v51, v50, v51
	s_nop 0
	s_waitcnt lgkmcnt(7)
	v_mfma_f32_16x16x32_f16 v[44:47], v[138:141], v[68:71], v[44:47]
	ds_read_b128 v[138:141], v2 offset:192
	s_nop 0
	v_cvt_pk_f16_f32 v50, v48, v49
	s_nop 0
	s_waitcnt lgkmcnt(7)
	v_mfma_f32_16x16x32_f16 v[44:47], v[142:145], v[126:129], v[44:47]
	ds_read_b128 v[142:145], v125 offset:52992
	s_nop 0
	s_nop 0
	s_waitcnt lgkmcnt(7)
	v_pk_mul_f32 v[32:33], v[32:33], v[190:191]
	v_pk_mul_f32 v[34:35], v[34:35], v[192:193]
	s_nop 0
	s_nop 0
	s_waitcnt lgkmcnt(6)
	v_mfma_f32_16x16x32_f16 v[32:35], v[146:149], v[68:71], v[32:35]
	s_nop 0
	s_nop 0
	s_waitcnt lgkmcnt(5)
	v_mfma_f32_16x16x32_f16 v[32:35], v[178:181], v[126:129], v[32:35]
	s_nop 0
	s_nop 0
	s_waitcnt lgkmcnt(4)
	v_pk_mul_f32 v[40:41], v[40:41], v[182:183]
	v_pk_mul_f32 v[42:43], v[42:43], v[184:185]
	s_nop 0
	s_nop 0
	s_waitcnt lgkmcnt(3)
	v_mfma_f32_16x16x32_f16 v[40:43], v[186:189], v[68:71], v[40:43]
	s_nop 0
	s_nop 0
	s_waitcnt lgkmcnt(2)
	v_mfma_f32_16x16x32_f16 v[40:43], v[134:137], v[126:129], v[40:43]
	s_nop 0
	v_add_u32_e32 v2, s26, v91
	s_add_i32 s26, s26, 64
	s_nop 0
	s_waitcnt lgkmcnt(1)
	v_pk_mul_f32 v[36:37], v[36:37], v[138:139]
	v_pk_mul_f32 v[38:39], v[38:39], v[140:141]
	s_nop 0
	s_nop 0
	s_waitcnt lgkmcnt(0)
	v_mfma_f32_16x16x32_f16 v[36:39], v[142:145], v[68:71], v[36:39]
	ds_read_b128 v[64:67], v125 offset:53056
	s_nop 0
	s_waitcnt lgkmcnt(0)
	v_mfma_f32_16x16x32_f16 v[36:39], v[64:67], v[126:129], v[36:39]
	v_add_u32_e32 v64, s27, v112
	v_add_u32_e32 v65, 0xff, v64
	v_cndmask_b32_e64 v65, v65, v2, s[2:3]
	v_add_u32_e32 v52, v65, v89
	v_mad_i64_i32 v[52:53], s[0:1], v52, s91, v[82:83]
	global_store_dwordx2 v[52:53], v[54:55], off
	v_add_u32_e32 v52, 16, v2
	v_add_u32_e32 v53, 0xef, v64
	v_cndmask_b32_e64 v54, v53, v52, s[2:3]
	v_add_u32_e32 v54, v54, v89
	v_cvt_pk_f16_f32 v53, v58, v59
	v_cvt_pk_f16_f32 v52, v56, v57
	v_mad_i64_i32 v[54:55], s[0:1], v54, s91, v[82:83]
	global_store_dwordx2 v[54:55], v[52:53], off
	v_add_u32_e32 v52, 32, v2
	v_add_u32_e32 v53, 0xdf, v64
	v_cndmask_b32_e64 v54, v53, v52, s[2:3]
	v_add_u32_e32 v54, v54, v89
	v_cvt_pk_f16_f32 v53, v62, v63
	v_cvt_pk_f16_f32 v52, v60, v61
	v_mad_i64_i32 v[54:55], s[0:1], v54, s91, v[82:83]
	global_store_dwordx2 v[54:55], v[52:53], off
	v_add_u32_e32 v2, 48, v2
	v_add_u32_e32 v52, 0xcf, v64
	v_cndmask_b32_e64 v2, v52, v2, s[2:3]
	v_add_u32_e32 v2, v2, v89
	s_sub_i32 s27, s27, 64
	v_mad_i64_i32 v[48:49], s[0:1], v2, s91, v[82:83]
	s_cmpk_lg_i32 s27, 0xff00
	global_store_dwordx2 v[48:49], v[50:51], off
	s_cbranch_scc0 .LBB0_485

.LBB0_336:
	v_add_u32_e32 v253, v93, v106
	ds_read_b128 v[48:51], v253
	ds_read_b128 v[52:55], v253 offset:64
	v_add_u32_e32 v2, v93, v106
	s_nop 0
	s_nop 0
	s_nop 0
	s_waitcnt lgkmcnt(1)
	v_mfma_f32_16x16x32_f16 v[48:51], v[48:51], v[24:27], 0
	s_nop 0
	s_waitcnt lgkmcnt(0)
	v_mfma_f32_16x16x32_f16 v[48:51], v[52:55], v[28:31], v[48:51]
	s_nop 7
	ds_write_b128 v107, v[48:51]
	s_and_saveexec_b64 s[0:1], s[76:77]
	s_cbranch_execz .LBB0_338
	v_mul_f32_e32 v2, 0x3fb8aa3b, v48
	v_exp_f32_e32 v48, v2
	v_mul_f32_e32 v2, 0x3fb8aa3b, v49
	v_exp_f32_e32 v49, v2
	v_mul_f32_e32 v2, 0x3fb8aa3b, v50
	v_exp_f32_e32 v50, v2
	v_mul_f32_e32 v2, 0x3fb8aa3b, v51
	v_exp_f32_e32 v51, v2
	ds_write_b128 v110, v[48:51]
.LBB0_338:
	s_or_b64 exec, exec, s[0:1]
	v_add_u32_e32 v253, v93, v108
	ds_read_b128 v[48:51], v253
	ds_read_b128 v[52:55], v253 offset:64
	v_add_u32_e32 v2, v93, v108
	s_nop 0
	s_nop 0
	s_nop 0
	s_waitcnt lgkmcnt(1)
	v_mfma_f32_16x16x32_f16 v[48:51], v[48:51], v[24:27], 0
	s_nop 0
	s_waitcnt lgkmcnt(0)
	v_mfma_f32_16x16x32_f16 v[48:51], v[52:55], v[28:31], v[48:51]
	s_nop 7
	ds_write_b128 v109, v[48:51]
	s_and_saveexec_b64 s[0:1], s[76:77]
	s_cbranch_execz .LBB0_340
	v_mul_f32_e32 v2, 0x3fb8aa3b, v48
	v_exp_f32_e32 v48, v2
	v_mul_f32_e32 v2, 0x3fb8aa3b, v49
	v_exp_f32_e32 v49, v2
	v_mul_f32_e32 v2, 0x3fb8aa3b, v50
	v_exp_f32_e32 v50, v2
	v_mul_f32_e32 v2, 0x3fb8aa3b, v51
	v_exp_f32_e32 v51, v2
	ds_write_b128 v111, v[48:51]
.LBB0_340:
	s_or_b64 exec, exec, s[0:1]
	s_waitcnt lgkmcnt(0)
	s_barrier
	ds_read_b128 v[52:55], v92 offset:9216
	ds_read_b128 v[60:63], v94
	ds_read_b128 v[48:51], v92
	s_nop 0
	s_nop 0
	ds_read_b128 v[68:71], v101
	ds_read_b128 v[56:59], v94 offset:16
	s_nop 0
	v_add_u32_e32 v81, v95, v103
	s_nop 0
	s_waitcnt lgkmcnt(4)
	v_cvt_f32_f16_sdwa v67, v52 dst_sel:DWORD dst_unused:UNUSED_PAD src0_sel:WORD_1
	s_nop 0
	s_waitcnt lgkmcnt(3)
	v_mul_f32_e32 v2, 0x3fb8aa3b, v60
	v_exp_f32_e32 v60, v2
	v_mul_f32_e32 v2, 0x3fb8aa3b, v61
	v_exp_f32_e32 v61, v2
	v_cvt_f32_f16_e32 v66, v52
	v_rcp_f32_e32 v64, v60
	v_add_u32_e32 v52, v78, v97
	v_rcp_f32_e32 v65, v61
	v_cvt_f32_f16_sdwa v127, v54 dst_sel:DWORD dst_unused:UNUSED_PAD src0_sel:WORD_1
	v_cvt_f32_f16_e32 v126, v54
	v_pk_mul_f32 v[66:67], v[64:65], v[66:67]
	s_waitcnt lgkmcnt(2)
	v_cvt_f32_f16_sdwa v65, v48 dst_sel:DWORD dst_unused:UNUSED_PAD src0_sel:WORD_1
	v_cvt_f32_f16_e32 v64, v48
	s_nop 0
	s_waitcnt lgkmcnt(1)
	v_fma_mixlo_f16 v2, v68, v66, 0
	ds_write_b16 v52, v2 offset:46080
	v_fma_mixlo_f16 v2, v69, v67, 0
	v_pk_mul_f32 v[64:65], v[64:65], s[68:69] op_sel_hi:[1,0]
	ds_write_b16 v121, v2 offset:46080
	v_mul_f32_e32 v2, 0x3fb8aa3b, v62
	v_pk_mul_f32 v[64:65], v[64:65], v[60:61]
	v_exp_f32_e32 v60, v2
	v_mul_f32_e32 v2, 0x3fb8aa3b, v63
	v_exp_f32_e32 v61, v2
	v_cvt_f32_f16_sdwa v69, v53 dst_sel:DWORD dst_unused:UNUSED_PAD src0_sel:WORD_1
	v_rcp_f32_e32 v62, v60
	v_cvt_f32_f16_e32 v68, v53
	v_rcp_f32_e32 v63, v61
	v_cvt_f32_f16_sdwa v53, v49 dst_sel:DWORD dst_unused:UNUSED_PAD src0_sel:WORD_1
	v_cvt_f32_f16_e32 v52, v49
	v_cvt_pk_f16_f32 v48, v64, v65
	v_pk_mul_f32 v[68:69], v[62:63], v[68:69]
	v_pk_mul_f32 v[52:53], v[52:53], s[68:69] op_sel_hi:[1,0]
	v_fma_mixlo_f16 v2, v70, v68, 0
	ds_write_b16 v121, v2 offset:46224
	v_fma_mixlo_f16 v2, v71, v69, 0
	ds_write_b16 v121, v2 offset:46368
	s_waitcnt lgkmcnt(4)
	v_mul_f32_e32 v2, 0x3fb8aa3b, v56
	v_exp_f32_e32 v56, v2
	v_mul_f32_e32 v2, 0x3fb8aa3b, v57
	v_exp_f32_e32 v57, v2
	v_pk_mul_f32 v[52:53], v[52:53], v[60:61]
	ds_read_b128 v[60:63], v102
	v_rcp_f32_e32 v70, v56
	s_nop 0
	v_rcp_f32_e32 v71, v57
	v_cvt_pk_f16_f32 v49, v52, v53
	v_pk_mul_f32 v[70:71], v[70:71], v[126:127]
	s_nop 0
	s_waitcnt lgkmcnt(0)
	v_fma_mixlo_f16 v2, v60, v70, 0
	ds_write_b16 v121, v2 offset:46512
	v_fma_mixlo_f16 v2, v61, v71, 0
	ds_write_b16 v121, v2 offset:46656
	v_mul_f32_e32 v2, 0x3fb8aa3b, v58
	v_cvt_f32_f16_sdwa v127, v50 dst_sel:DWORD dst_unused:UNUSED_PAD src0_sel:WORD_1
	v_cvt_f32_f16_e32 v126, v50
	v_exp_f32_e32 v58, v2
	v_mul_f32_e32 v2, 0x3fb8aa3b, v59
	v_exp_f32_e32 v59, v2
	v_pk_mul_f32 v[126:127], v[126:127], s[68:69] op_sel_hi:[1,0]
	v_cvt_f32_f16_sdwa v61, v55 dst_sel:DWORD dst_unused:UNUSED_PAD src0_sel:WORD_1
	v_pk_mul_f32 v[126:127], v[126:127], v[56:57]
	v_rcp_f32_e32 v56, v58
	v_rcp_f32_e32 v57, v59
	v_cvt_f32_f16_e32 v60, v55
	v_bfe_u32 v55, v71, 16, 1
	v_add3_u32 v55, v71, v55, s34
	v_cvt_pk_f16_f32 v50, v126, v127
	v_pk_mul_f32 v[128:129], v[56:57], v[60:61]
	v_bfe_u32 v56, v70, 16, 1
	v_fma_mixlo_f16 v2, v62, v128, 0
	ds_write_b16 v121, v2 offset:46800
	v_bfe_u32 v2, v129, 16, 1
	v_bfe_u32 v54, v128, 16, 1
	v_bfe_u32 v57, v69, 16, 1
	v_bfe_u32 v60, v68, 16, 1
	v_bfe_u32 v61, v67, 16, 1
	v_bfe_u32 v62, v66, 16, 1
	v_add3_u32 v62, v66, v62, s34
	v_add3_u32 v61, v67, v61, s34
	v_add3_u32 v60, v68, v60, s34
	v_add3_u32 v66, v69, v57, s34
	v_add3_u32 v56, v70, v56, s34
	v_add3_u32 v54, v128, v54, s34
	v_add3_u32 v2, v129, v2, s34
	v_perm_b32 v57, v2, v54, s82
	v_perm_b32 v56, v55, v56, s82
	v_perm_b32 v55, v66, v60, s82
	v_perm_b32 v54, v61, v62, s82
	v_cvt_f32_f16_sdwa v61, v51 dst_sel:DWORD dst_unused:UNUSED_PAD src0_sel:WORD_1
	v_cvt_f32_f16_e32 v60, v51
	v_bfe_u32 v62, v126, 16, 1
	v_bfe_u32 v66, v53, 16, 1
	v_bfe_u32 v67, v52, 16, 1
	v_pk_mul_f32 v[60:61], v[60:61], s[68:69] op_sel_hi:[1,0]
	v_bfe_u32 v68, v65, 16, 1
	v_pk_mul_f32 v[58:59], v[60:61], v[58:59]
	v_bfe_u32 v61, v127, 16, 1
	v_bfe_u32 v2, v59, 16, 1
	v_bfe_u32 v60, v58, 16, 1
	v_cvt_pk_f16_f32 v51, v58, v59
	v_bfe_u32 v69, v64, 16, 1
	v_add3_u32 v58, v58, v60, s34
	v_add3_u32 v2, v59, v2, s34
	v_add3_u32 v64, v64, v69, s34
	v_add3_u32 v65, v65, v68, s34
	v_add3_u32 v52, v52, v67, s34
	v_add3_u32 v53, v53, v66, s34
	v_add3_u32 v62, v126, v62, s34
	v_add3_u32 v66, v127, v61, s34
	v_perm_b32 v61, v2, v58, s82
	v_fma_mixlo_f16 v2, v63, v129, 0
	v_perm_b32 v60, v66, v62, s82
	v_perm_b32 v59, v53, v52, s82
	v_perm_b32 v58, v65, v64, s82
	ds_write_b16 v121, v2 offset:46944
	ds_write_b128 v92, v[58:61] offset:18432
	ds_write_b128 v92, v[54:57] offset:27648
	ds_write_b128 v92, v[48:51] offset:36864
	v_add_u32_e32 v2, v79, v72
	s_nop 0
	s_barrier
	ds_read_b128 v[52:55], v81 offset:36864
	ds_read_b128 v[56:59], v81 offset:39168
	ds_read_b128 v[60:63], v81 offset:41472
	ds_read_b128 v[64:67], v81 offset:43776
	ds_read_b128 v[68:71], v2 offset:64
	ds_read_b128 v[134:137], v81 offset:36928
	ds_read_b128 v[138:141], v81 offset:39232
	ds_read_b128 v[142:145], v81 offset:41536
	ds_read_b128 v[48:51], v2
	s_nop 0
	s_nop 0
	s_nop 0
	s_nop 0
	s_nop 0
	s_waitcnt lgkmcnt(0)
	v_mfma_f32_16x16x32_f16 v[52:55], v[48:51], v[52:55], 0
	s_nop 0
	v_mfma_f32_16x16x32_f16 v[56:59], v[48:51], v[56:59], 0
	s_nop 0
	v_mfma_f32_16x16x32_f16 v[60:63], v[48:51], v[60:63], 0
	s_nop 0
	v_mfma_f32_16x16x32_f16 v[64:67], v[48:51], v[64:67], 0
	s_nop 0
	s_nop 0
	v_add_u32_e32 v2, v100, v72
	s_nop 0
	v_mfma_f32_16x16x32_f16 v[48:51], v[68:71], v[134:137], v[52:55]
	s_nop 2
	s_nop 0
	s_nop 0
	v_mfma_f32_16x16x32_f16 v[56:59], v[68:71], v[138:141], v[56:59]
	s_nop 0
	s_nop 0
	v_mfma_f32_16x16x32_f16 v[60:63], v[68:71], v[142:145], v[60:63]
	ds_read_b128 v[52:55], v81 offset:43840
	s_nop 0
	s_waitcnt lgkmcnt(0)
	v_mfma_f32_16x16x32_f16 v[64:67], v[68:71], v[52:55], v[64:67]
	v_mov_b32_e32 v52, 0
	v_mov_b32_e32 v68, 0
	v_mov_b32_e32 v69, 0
	v_mov_b32_e32 v70, 0
	v_mov_b32_e32 v71, 0
	s_and_saveexec_b64 s[0:1], s[6:7]
	s_cbranch_execz .LBB0_342
	v_add_u32_e32 v253, v95, v106
	ds_read_b128 v[68:71], v2 offset:18432
	ds_read_b128 v[126:129], v253 offset:27648
	v_add_u32_e32 v53, v95, v106
	s_nop 0
	s_nop 0
	s_nop 0
	s_waitcnt lgkmcnt(0)
	v_mfma_f32_16x16x32_bf16 v[68:71], v[126:129], v[68:71], 0
	ds_read_b128 v[130:133], v53 offset:27712
	ds_read_b128 v[126:129], v2 offset:18496
	s_nop 0
	s_nop 0
	s_waitcnt lgkmcnt(0)
	v_mfma_f32_16x16x32_bf16 v[68:71], v[130:133], v[126:129], v[68:71]
.LBB0_342:
	s_or_b64 exec, exec, s[0:1]
	s_nop 6
	v_cvt_f16_f32_e32 v53, v68
	v_cvt_f16_f32_e32 v54, v69
	v_cvt_f16_f32_e32 v55, v70
	v_cvt_f16_f32_e32 v68, v71
	v_cndmask_b32_e64 v53, v53, 0, s[10:11]
	v_cndmask_b32_e64 v54, 0, v54, s[12:13]
	v_cndmask_b32_e64 v55, v55, 0, s[14:15]
	v_cndmask_b32_e64 v68, v68, 0, s[16:17]
	v_pack_b32_f16 v55, v55, v68
	v_pack_b32_f16 v54, v53, v54
	ds_write_b64 v122, v[54:55]
	v_mov_b32_e32 v53, 0
	v_mov_b32_e32 v54, 0
	v_mov_b32_e32 v55, 0
	s_and_saveexec_b64 s[0:1], s[8:9]
	s_cbranch_execz .LBB0_327
	v_add_u32_e32 v253, v95, v108
	ds_read_b128 v[52:55], v2 offset:18432
	ds_read_b128 v[68:71], v253 offset:27648
	v_add_u32_e32 v81, v95, v108
	s_nop 0
	s_nop 0
	s_nop 0
	s_waitcnt lgkmcnt(0)
	v_mfma_f32_16x16x32_bf16 v[52:55], v[68:71], v[52:55], 0
	ds_read_b128 v[126:129], v81 offset:27712
	ds_read_b128 v[68:71], v2 offset:18496
	s_nop 0
	s_nop 0
	s_waitcnt lgkmcnt(0)
	v_mfma_f32_16x16x32_bf16 v[52:55], v[126:129], v[68:71], v[52:55]
	s_branch .LBB0_327

.LBB0_356:
	s_and_b32 s27, s26, 1
	v_lshl_add_u32 v0, s27, 13, v232
	ds_read2_b64 v[36:39], v0 offset1:32
	v_mad_u32_u24 v2, s27, v165, v233
	s_waitcnt lgkmcnt(0)
	v_pk_mul_f32 v[66:67], v[36:37], v[38:39]
	ds_read2_b64 v[38:41], v0 offset0:64 offset1:96
	s_waitcnt lgkmcnt(0)
	v_pk_mul_f32 v[64:65], v[66:67], v[38:39]
	s_nop 0
	v_pk_mul_f32 v[60:61], v[64:65], v[40:41]
	ds_read2_b64 v[38:41], v0 offset0:128 offset1:160
	s_waitcnt lgkmcnt(0)
	v_pk_mul_f32 v[54:55], v[60:61], v[38:39]
	s_nop 0
	v_pk_mul_f32 v[48:49], v[54:55], v[40:41]
	ds_read2_b64 v[38:41], v0 offset0:192 offset1:224
	v_add_u32_e32 v0, 0x800, v0
	ds_read2_b64 v[68:71], v0 offset0:128 offset1:160
	s_waitcnt lgkmcnt(1)
	v_pk_mul_f32 v[44:45], v[48:49], v[38:39]
	s_nop 0
	v_pk_mul_f32 v[38:39], v[44:45], v[40:41]
	ds_read2_b64 v[40:43], v0 offset1:32
	s_waitcnt lgkmcnt(0)
	v_pk_mul_f32 v[58:59], v[38:39], v[40:41]
	s_nop 0
	v_pk_mul_f32 v[50:51], v[58:59], v[42:43]
	ds_read2_b64 v[40:43], v0 offset0:64 offset1:96
	s_waitcnt lgkmcnt(0)
	v_pk_mul_f32 v[46:47], v[50:51], v[40:41]
	s_nop 0
	v_pk_mul_f32 v[42:43], v[46:47], v[42:43]
	v_rcp_f32_e32 v40, v38
	v_pk_mul_f32 v[62:63], v[42:43], v[68:69]
	v_rcp_f32_e32 v41, v39
	v_pk_mul_f32 v[56:57], v[62:63], v[70:71]
	ds_read2_b64 v[68:71], v0 offset0:192 offset1:224
	s_waitcnt lgkmcnt(0)
	v_pk_mul_f32 v[52:53], v[56:57], v[68:69]
	s_nop 0
	v_pk_mul_f32 v[0:1], v[52:53], v[70:71]
	s_and_saveexec_b64 s[28:29], s[4:5]
	s_cbranch_execz .LBB0_358
	v_lshl_add_u32 v252, v177, 1, v2
	ds_read2st64_b32 v[72:73], v252 offset0:96 offset1:112
	ds_read2st64_b32 v[68:69], v252 offset0:64 offset1:80
	v_lshl_add_u32 v74, v177, 1, v2
	s_nop 0
	ds_read_b32 v84, v74 offset:32768
	s_nop 0
	v_rcp_f32_e32 v70, v36
	v_rcp_f32_e32 v71, v37
	s_nop 0
	s_nop 0
	s_waitcnt lgkmcnt(2)
	v_cvt_f32_f16_e32 v78, v73
	v_cvt_f32_f16_sdwa v79, v73 dst_sel:DWORD dst_unused:UNUSED_PAD src0_sel:WORD_1
	s_nop 0
	v_lshl_add_u32 v252, v184, 1, v2
	ds_read2st64_b32 v[148:149], v252 offset0:64 offset1:80
	s_waitcnt lgkmcnt(2)
	v_cvt_f32_f16_e32 v74, v68
	v_cvt_f32_f16_sdwa v75, v68 dst_sel:DWORD dst_unused:UNUSED_PAD src0_sel:WORD_1
	v_cvt_f32_f16_e32 v76, v72
	ds_read2st64_b32 v[240:241], v252 offset0:96 offset1:112
	v_cvt_f32_f16_sdwa v77, v72 dst_sel:DWORD dst_unused:UNUSED_PAD src0_sel:WORD_1
	v_cvt_f32_f16_e32 v72, v69
	v_cvt_f32_f16_sdwa v73, v69 dst_sel:DWORD dst_unused:UNUSED_PAD src0_sel:WORD_1
	v_pk_mul_f32 v[78:79], v[36:37], v[78:79]
	v_pk_mul_f32 v[76:77], v[70:71], v[76:77]
	v_pk_mul_f32 v[70:71], v[70:71], v[74:75]
	v_pk_mul_f32 v[72:73], v[40:41], v[72:73]
	v_pk_mul_f32 v[74:75], v[40:41], v[78:79]
	v_cvt_pk_f16_f32 v68, v78, v79
	v_pk_mul_f32 v[80:81], v[38:39], v[76:77]
	v_pk_mul_f32 v[82:83], v[38:39], v[70:71]
	ds_write2st64_b32 v183, v69, v68 offset1:18
	v_cvt_pk_f16_f32 v68, v72, v73
	v_cvt_pk_f16_f32 v69, v74, v75
	v_pk_mul_f32 v[76:77], v[0:1], v[76:77]
	ds_write2st64_b32 v183, v68, v69 offset0:36 offset1:54
	v_cvt_pk_f16_f32 v68, v80, v81
	v_cvt_pk_f16_f32 v69, v82, v83
	ds_write2st64_b32 v183, v68, v69 offset0:72 offset1:90
	v_cvt_f16_f32_e32 v68, v76
	v_pk_mul_f32 v[70:71], v[0:1], v[70:71]
	v_cvt_f16_f32_e32 v69, v77
	v_cvt_f16_f32_e32 v70, v70
	v_cvt_f16_f32_e32 v71, v71
	ds_write_b16 v178, v68
	ds_write_b16 v178, v69 offset:40
	ds_write_b16 v178, v70 offset:5120
	ds_write_b16 v178, v71 offset:5160
	s_nop 0
	s_waitcnt lgkmcnt(9)
	ds_write_b16 v178, v84 offset:10240
	v_lshl_add_u32 v74, v184, 1, v2
	s_nop 0
	s_nop 0
	ds_read_b32 v82, v74 offset:32768
	v_rcp_f32_e32 v70, v66
	v_rcp_f32_e32 v71, v67
	s_nop 0
	s_waitcnt lgkmcnt(10)
	v_cvt_f32_f16_e32 v76, v149
	v_cvt_f32_f16_sdwa v77, v149 dst_sel:DWORD dst_unused:UNUSED_PAD src0_sel:WORD_1
	s_nop 0
	s_waitcnt lgkmcnt(9)
	v_cvt_f32_f16_e32 v80, v241
	v_cvt_f32_f16_sdwa v81, v241 dst_sel:DWORD dst_unused:UNUSED_PAD src0_sel:WORD_1
	v_lshl_add_u32 v252, v186, 1, v2
	ds_read2st64_b32 v[242:243], v252 offset0:64 offset1:80
	v_cvt_f32_f16_e32 v74, v148
	v_cvt_f32_f16_e32 v78, v240
	v_cvt_f32_f16_sdwa v79, v240 dst_sel:DWORD dst_unused:UNUSED_PAD src0_sel:WORD_1
	ds_read2st64_b32 v[240:241], v252 offset0:96 offset1:112
	v_cvt_f32_f16_sdwa v75, v148 dst_sel:DWORD dst_unused:UNUSED_PAD src0_sel:WORD_1
	v_pk_mul_f32 v[36:37], v[36:37], v[76:77]
	v_pk_mul_f32 v[68:69], v[66:67], v[80:81]
	v_pk_mul_f32 v[72:73], v[70:71], v[78:79]
	v_pk_mul_f32 v[70:71], v[70:71], v[74:75]
	v_pk_mul_f32 v[74:75], v[40:41], v[36:37]
	v_pk_mul_f32 v[76:77], v[40:41], v[68:69]
	v_cvt_pk_f16_f32 v36, v36, v37
	v_cvt_pk_f16_f32 v37, v68, v69
	v_pk_mul_f32 v[78:79], v[38:39], v[72:73]
	v_pk_mul_f32 v[80:81], v[38:39], v[70:71]
	ds_write2st64_b32 v185, v36, v37 offset1:18
	v_cvt_pk_f16_f32 v36, v74, v75
	v_cvt_pk_f16_f32 v37, v76, v77
	v_pk_mul_f32 v[72:73], v[0:1], v[72:73]
	ds_write2st64_b32 v185, v36, v37 offset0:36 offset1:54
	v_cvt_pk_f16_f32 v36, v78, v79
	v_cvt_pk_f16_f32 v37, v80, v81
	ds_write2st64_b32 v185, v36, v37 offset0:72 offset1:90
	v_cvt_f16_f32_e32 v36, v72
	v_pk_mul_f32 v[70:71], v[0:1], v[70:71]
	v_cvt_f16_f32_e32 v37, v73
	v_cvt_f16_f32_e32 v68, v70
	v_cvt_f16_f32_e32 v69, v71
	ds_write_b16 v178, v36 offset:2
	s_waitcnt lgkmcnt(14)
	ds_write_b16 v178, v37 offset:42
	s_waitcnt lgkmcnt(14)
	ds_write_b16 v178, v68 offset:5122
	s_waitcnt lgkmcnt(14)
	ds_write_b16 v178, v69 offset:5162
	s_nop 0
	s_waitcnt lgkmcnt(9)
	ds_write_b16 v178, v82 offset:10242
	v_lshl_add_u32 v72, v186, 1, v2
	s_nop 0
	s_nop 0
	ds_read_b32 v80, v72 offset:32768
	v_rcp_f32_e32 v68, v64
	v_rcp_f32_e32 v69, v65
	s_nop 0
	s_waitcnt lgkmcnt(10)
	v_cvt_f32_f16_e32 v74, v243
	v_cvt_f32_f16_sdwa v75, v243 dst_sel:DWORD dst_unused:UNUSED_PAD src0_sel:WORD_1
	s_nop 0
	s_waitcnt lgkmcnt(9)
	v_cvt_f32_f16_e32 v78, v241
	v_cvt_f32_f16_sdwa v79, v241 dst_sel:DWORD dst_unused:UNUSED_PAD src0_sel:WORD_1
	v_lshl_add_u32 v252, v188, 1, v2
	ds_read2st64_b32 v[148:149], v252 offset0:64 offset1:80
	v_cvt_f32_f16_e32 v72, v242
	v_cvt_f32_f16_e32 v76, v240
	v_cvt_f32_f16_sdwa v77, v240 dst_sel:DWORD dst_unused:UNUSED_PAD src0_sel:WORD_1
	ds_read2st64_b32 v[240:241], v252 offset0:96 offset1:112
	v_cvt_f32_f16_sdwa v73, v242 dst_sel:DWORD dst_unused:UNUSED_PAD src0_sel:WORD_1
	v_pk_mul_f32 v[36:37], v[66:67], v[74:75]
	v_pk_mul_f32 v[66:67], v[64:65], v[78:79]
	v_pk_mul_f32 v[70:71], v[68:69], v[76:77]
	v_pk_mul_f32 v[68:69], v[68:69], v[72:73]
	v_pk_mul_f32 v[72:73], v[40:41], v[36:37]
	v_pk_mul_f32 v[74:75], v[40:41], v[66:67]
	v_cvt_pk_f16_f32 v36, v36, v37
	v_cvt_pk_f16_f32 v37, v66, v67
	v_pk_mul_f32 v[76:77], v[38:39], v[70:71]
	v_pk_mul_f32 v[78:79], v[38:39], v[68:69]
	ds_write2st64_b32 v187, v36, v37 offset1:18
	v_cvt_pk_f16_f32 v36, v72, v73
	v_cvt_pk_f16_f32 v37, v74, v75
	v_pk_mul_f32 v[70:71], v[0:1], v[70:71]
	ds_write2st64_b32 v187, v36, v37 offset0:36 offset1:54
	v_cvt_pk_f16_f32 v36, v76, v77
	v_cvt_pk_f16_f32 v37, v78, v79
	ds_write2st64_b32 v187, v36, v37 offset0:72 offset1:90
	v_cvt_f16_f32_e32 v36, v70
	v_pk_mul_f32 v[68:69], v[0:1], v[68:69]
	v_cvt_f16_f32_e32 v37, v71
	v_cvt_f16_f32_e32 v66, v68
	v_cvt_f16_f32_e32 v67, v69
	ds_write_b16 v178, v36 offset:4
	s_waitcnt lgkmcnt(14)
	ds_write_b16 v178, v37 offset:44
	s_waitcnt lgkmcnt(14)
	ds_write_b16 v178, v66 offset:5124
	s_waitcnt lgkmcnt(14)
	ds_write_b16 v178, v67 offset:5164
	s_nop 0
	s_waitcnt lgkmcnt(9)
	ds_write_b16 v178, v80 offset:10244
	v_lshl_add_u32 v70, v188, 1, v2
	s_nop 0
	s_nop 0
	ds_read_b32 v78, v70 offset:32768
	v_rcp_f32_e32 v66, v60
	v_rcp_f32_e32 v67, v61
	s_nop 0
	s_waitcnt lgkmcnt(10)
	v_cvt_f32_f16_e32 v72, v149
	v_cvt_f32_f16_sdwa v73, v149 dst_sel:DWORD dst_unused:UNUSED_PAD src0_sel:WORD_1
	s_nop 0
	s_waitcnt lgkmcnt(9)
	v_cvt_f32_f16_e32 v76, v241
	v_cvt_f32_f16_sdwa v77, v241 dst_sel:DWORD dst_unused:UNUSED_PAD src0_sel:WORD_1
	v_cvt_f32_f16_e32 v70, v148
	v_cvt_f32_f16_e32 v74, v240
	v_cvt_f32_f16_sdwa v75, v240 dst_sel:DWORD dst_unused:UNUSED_PAD src0_sel:WORD_1
	v_cvt_f32_f16_sdwa v71, v148 dst_sel:DWORD dst_unused:UNUSED_PAD src0_sel:WORD_1
	v_pk_mul_f32 v[36:37], v[64:65], v[72:73]
	v_pk_mul_f32 v[64:65], v[60:61], v[76:77]
	v_pk_mul_f32 v[68:69], v[66:67], v[74:75]
	v_pk_mul_f32 v[66:67], v[66:67], v[70:71]
	v_pk_mul_f32 v[70:71], v[40:41], v[36:37]
	v_pk_mul_f32 v[72:73], v[40:41], v[64:65]
	v_cvt_pk_f16_f32 v36, v36, v37
	v_cvt_pk_f16_f32 v37, v64, v65
	v_pk_mul_f32 v[74:75], v[38:39], v[68:69]
	v_pk_mul_f32 v[76:77], v[38:39], v[66:67]
	ds_write2st64_b32 v189, v36, v37 offset1:18
	v_cvt_pk_f16_f32 v36, v70, v71
	v_cvt_pk_f16_f32 v37, v72, v73
	v_pk_mul_f32 v[68:69], v[0:1], v[68:69]
	ds_write2st64_b32 v189, v36, v37 offset0:36 offset1:54
	v_cvt_pk_f16_f32 v36, v74, v75
	v_cvt_pk_f16_f32 v37, v76, v77
	ds_write2st64_b32 v189, v36, v37 offset0:72 offset1:90
	v_cvt_f16_f32_e32 v36, v68
	v_pk_mul_f32 v[66:67], v[0:1], v[66:67]
	v_cvt_f16_f32_e32 v37, v69
	v_cvt_f16_f32_e32 v64, v66
	v_cvt_f16_f32_e32 v65, v67
	ds_write_b16 v178, v36 offset:6
	ds_write_b16 v178, v37 offset:46
	ds_write_b16 v178, v64 offset:5126
	s_waitcnt lgkmcnt(14)
	ds_write_b16 v178, v65 offset:5166
	s_nop 0
	s_waitcnt lgkmcnt(7)
	ds_write_b16 v178, v78 offset:10246
	v_perm_b32 v36, v82, v84, s82
	v_perm_b32 v37, v78, v80, s82
	ds_write_b64 v178, v[36:37] offset:10280

.LBB0_362:
	s_or_b64 exec, exec, s[28:29]
	s_waitcnt lgkmcnt(0)
	s_barrier
	ds_read_b128 v[40:43], v214 offset:9216
	ds_read_b128 v[48:51], v214 offset:18496
	ds_read_b128 v[56:59], v214 offset:9280
	ds_read_b128 v[60:63], v214 offset:23040
	ds_read_b128 v[36:39], v214 offset:18432
	s_nop 0
	s_nop 0
	s_nop 0
	ds_read_b128 v[64:67], v214 offset:13824
	s_waitcnt lgkmcnt(1)
	v_mfma_f32_16x16x32_f16 v[52:55], v[40:43], v[36:39], 0
	s_nop 0
	s_nop 0
	s_nop 0
	ds_read_b128 v[68:71], v214 offset:13888
	ds_read_b128 v[72:75], v214 offset:23104
	v_add_u32_e32 v80, 0x1000, v220
	s_nop 0
	v_mfma_f32_16x16x32_f16 v[52:55], v[56:59], v[48:51], v[52:55]
	v_mov_b32_e32 v82, v3
	v_mov_b32_e32 v83, v3
	v_mov_b32_e32 v86, v3
	v_mfma_f32_16x16x32_f16 v[44:47], v[36:39], v[40:43], 0
	s_nop 3
	v_cvt_f16_f32_e32 v0, v52
	v_cvt_f16_f32_e32 v1, v54
	v_cvt_f16_f32_e32 v2, v55
	v_mfma_f32_16x16x32_f16 v[44:47], v[48:51], v[56:59], v[44:47]
	v_cndmask_b32_e64 v79, 0, v0, s[12:13]
	v_cvt_f16_f32_e32 v0, v53
	v_cndmask_b32_e64 v54, 0, v1, s[18:19]
	s_nop 0
	v_mfma_f32_16x16x32_f16 v[40:43], v[60:63], v[40:43], 0
	v_cndmask_b32_e64 v55, 0, v2, s[22:23]
	s_nop 1
	v_cndmask_b32_e64 v76, 0, v44, s[10:11]
	v_cndmask_b32_e64 v77, 0, v45, s[14:15]
	s_nop 0
	s_waitcnt lgkmcnt(2)
	v_mfma_f32_16x16x32_f16 v[36:39], v[36:39], v[64:67], 0
	v_cndmask_b32_e64 v52, 0, v46, s[16:17]
	v_cndmask_b32_e64 v78, 0, v47, s[20:21]
	v_cndmask_b32_e64 v53, v0, 0, s[10:11]
	v_mfma_f32_16x16x32_f16 v[44:47], v[60:63], v[64:67], 0
	v_cvt_pk_f16_f32 v1, v52, v78
	v_cvt_pk_f16_f32 v0, v76, v77
	v_mov_b32_e32 v2, v3
	s_nop 0
	s_waitcnt lgkmcnt(0)
	v_mfma_f32_16x16x32_f16 v[60:63], v[72:75], v[56:59], v[40:43]
	v_add_f32_e32 v56, v215, v76
	v_add_f32_e32 v57, v217, v77
	v_add_f32_e32 v58, v218, v52
	v_mfma_f32_16x16x32_f16 v[40:43], v[48:51], v[68:71], v[36:39]
	v_add_f32_e32 v59, v219, v78
	v_cvt_pk_f16_f32 v67, v26, v27
	v_cvt_pk_f16_f32 v66, v24, v25
	v_pack_b32_f16 v37, v54, v55
	v_pack_b32_f16 v36, v79, v53
	v_mov_b32_e32 v38, v3
	v_mov_b32_e32 v39, v3
	v_mfma_f32_16x16x32_f16 v[52:55], v[72:75], v[68:71], v[44:47]
	ds_read2_b64 v[68:71], v220 offset0:8 offset1:12
	v_cvt_pk_f16_f32 v65, v30, v31
	v_cvt_pk_f16_f32 v64, v28, v29
	v_mfma_f32_16x16x32_f16 v[48:51], v[0:3], v[36:39], 0
	v_cvt_pk_f16_f32 v45, v58, v59
	v_cvt_pk_f16_f32 v44, v56, v57
	v_mov_b32_e32 v46, v3
	v_mfma_f32_16x16x32_f16 v[36:39], v[36:39], v[0:3], 0
	v_mov_b32_e32 v47, v3
	s_nop 2
	v_cvt_pk_f16_f32 v1, v50, v51
	v_cvt_pk_f16_f32 v0, v48, v49
	v_mov_b32_e32 v50, v3
	v_mov_b32_e32 v51, v3
	v_cvt_pk_f16_f32 v49, v38, v39
	v_cvt_pk_f16_f32 v48, v36, v37
	v_mfma_f32_16x16x32_f16 v[44:47], v[0:3], v[44:47], v[56:59]
	v_mov_b32_e32 v87, v3
	v_mov_b32_e32 v90, v3
	v_mov_b32_e32 v91, v3
	v_mfma_f32_16x16x32_f16 v[36:39], v[48:51], v[0:3], 0
	ds_read2_b64 v[128:131], v220 offset1:4
	v_cvt_pk_f16_f32 v59, v34, v35
	v_cvt_pk_f16_f32 v58, v32, v33
	v_cvt_pk_f16_f32 v57, v22, v23
	v_mfma_f32_16x16x32_f16 v[48:51], v[0:3], v[48:51], 0
	v_cvt_pk_f16_f32 v56, v20, v21
	s_nop 2
	v_cvt_pk_f16_f32 v1, v38, v39
	v_cvt_pk_f16_f32 v0, v36, v37
	v_cvt_pk_f16_f32 v37, v46, v47
	v_cvt_pk_f16_f32 v36, v44, v45
	v_mov_b32_e32 v38, v3
	v_mov_b32_e32 v39, v3
	v_cvt_f16_f32_e32 v52, v52
	s_add_i32 s27, s26, 1
	v_mfma_f32_16x16x32_f16 v[44:47], v[0:3], v[36:39], v[44:47]
	v_cvt_pk_f16_f32 v37, v50, v51
	v_cvt_pk_f16_f32 v36, v48, v49
	v_mov_b32_e32 v50, v3
	v_mov_b32_e32 v51, v3
	v_mfma_f32_16x16x32_f16 v[36:39], v[36:39], v[0:3], 0
	s_nop 2
	v_cvt_pk_f16_f32 v1, v46, v47
	v_cvt_pk_f16_f32 v0, v44, v45
	s_nop 2
	v_cvt_pk_f16_f32 v49, v38, v39
	v_cvt_pk_f16_f32 v48, v36, v37
	s_nop 0
	s_nop 0
	s_waitcnt lgkmcnt(0)
	v_mfma_f32_16x16x32_f16 v[36:39], v[128:131], v[56:59], 0
	v_mfma_f32_16x16x32_f16 v[44:47], v[48:51], v[0:3], v[44:47]
	v_cvt_f16_f32_e32 v0, v60
	v_cvt_f16_f32_e32 v1, v61
	v_cvt_f16_f32_e32 v2, v62
	v_cvt_f16_f32_e32 v48, v63
	v_mfma_f32_16x16x32_f16 v[76:79], v[68:71], v[64:67], v[36:39]
	ds_read2_b64 v[72:75], v80 offset0:64 offset1:68
	ds_read2st64_b64 v[132:135], v221 offset0:20 offset1:25
	ds_read2_b64 v[68:71], v80 offset0:72 offset1:76
	s_nop 0
	s_nop 0
	v_cndmask_b32_e64 v0, 0, v0, s[10:11]
	v_cndmask_b32_e64 v49, 0, v1, s[14:15]
	v_cndmask_b32_e64 v1, 0, v2, s[16:17]
	v_cndmask_b32_e64 v2, 0, v48, s[20:21]
	v_pack_b32_f16 v1, v1, v2
	v_pack_b32_f16 v0, v0, v49
	v_mov_b32_e32 v2, v3
	s_nop 0
	s_waitcnt lgkmcnt(1)
	v_mov_b32_e32 v60, v132
	v_mov_b32_e32 v61, v133
	ds_read2_b64 v[128:131], v236 offset1:80
	v_mov_b32_e32 v62, v3
	v_mov_b32_e32 v63, v3
	v_cvt_f16_f32_e32 v36, v40
	ds_read_b128 v[136:139], v180
	v_cvt_f16_f32_e32 v40, v42
	v_mfma_f32_16x16x32_f16 v[48:51], v[0:3], v[60:63], v[76:79]
	v_cvt_pk_f16_f32 v1, v46, v47
	v_cvt_pk_f16_f32 v0, v44, v45
	v_cvt_f16_f32_e32 v37, v41
	v_mov_b32_e32 v78, v3
	v_mov_b32_e32 v79, v3
	s_nop 2
	v_cvt_pk_f16_f32 v77, v50, v51
	v_cvt_pk_f16_f32 v76, v48, v49
	v_cndmask_b32_e64 v88, v40, 0, s[18:19]
	v_mfma_f32_16x16x32_f16 v[56:59], v[72:75], v[56:59], 0
	v_cndmask_b32_e64 v36, v36, 0, s[12:13]
	v_cndmask_b32_e64 v37, 0, v37, s[10:11]
	v_mov_b32_e32 v74, v3
	v_mfma_f32_16x16x32_f16 v[44:47], v[0:3], v[76:79], 0
	ds_read_b64 v[76:77], v222 offset:5120
	ds_read_b128 v[140:143], v180 offset:64
	v_mov_b32_e32 v75, v3
	s_waitcnt lgkmcnt(4)
	v_mfma_f32_16x16x32_f16 v[56:59], v[68:71], v[64:67], v[56:59]
	s_nop 5
	v_cvt_pk_f16_f32 v1, v46, v47
	v_cvt_pk_f16_f32 v0, v44, v45
	s_nop 0
	s_nop 0
	s_nop 0
	s_nop 0
	s_waitcnt lgkmcnt(3)
	v_mov_b32_e32 v80, v128
	v_mov_b32_e32 v81, v129
	ds_read_b64 v[44:45], v223 offset:5120
	ds_read2_b64 v[144:147], v236 offset0:160 offset1:240
	s_nop 0
	s_waitcnt lgkmcnt(4)
	v_pk_mul_f32 v[50:51], v[22:23], v[138:139]
	v_pk_mul_f32 v[48:49], v[20:21], v[136:137]
	ds_read_b128 v[136:139], v180 offset:128
	s_nop 1
	v_mfma_f32_16x16x32_f16 v[48:51], v[80:83], v[0:3], v[48:51]
	v_cvt_f16_f32_e32 v80, v43
	v_cndmask_b32_e64 v89, v80, 0, s[22:23]
	s_nop 0
	s_waitcnt lgkmcnt(4)
	v_mfma_f32_16x16x32_f16 v[40:43], v[76:79], v[60:63], v[48:51]
	s_nop 3
	s_nop 0
	s_nop 0
	ds_read_b64 v[80:81], v224 offset:5120
	v_mov_b32_e32 v76, v130
	v_mov_b32_e32 v77, v131
	v_mov_b32_e32 v46, v3
	s_nop 0
	s_waitcnt lgkmcnt(4)
	v_pk_mul_f32 v[50:51], v[34:35], v[142:143]
	v_pk_mul_f32 v[48:49], v[32:33], v[140:141]
	v_mov_b32_e32 v47, v3
	ds_read_b128 v[128:131], v180 offset:192
	s_nop 0
	v_mfma_f32_16x16x32_f16 v[48:51], v[76:79], v[0:3], v[48:51]
	s_nop 0
	s_nop 0
	s_waitcnt lgkmcnt(3)
	v_mov_b32_e32 v84, v144
	v_mfma_f32_16x16x32_f16 v[48:51], v[44:47], v[60:63], v[48:51]
	s_nop 0
	s_nop 0
	v_mov_b32_e32 v85, v145
	v_pack_b32_f16 v77, v88, v89
	v_mov_b32_e32 v88, v146
	s_nop 0
	s_waitcnt lgkmcnt(2)
	v_pk_mul_f32 v[46:47], v[30:31], v[138:139]
	v_pk_mul_f32 v[44:45], v[28:29], v[136:137]
	v_mov_b32_e32 v89, v147
	v_pack_b32_f16 v76, v36, v37
	v_mfma_f32_16x16x32_f16 v[44:47], v[84:87], v[0:3], v[44:47]
	ds_read_b64 v[84:85], v225 offset:5120
	v_cndmask_b32_e64 v36, v52, 0, s[12:13]
	v_cvt_f16_f32_e32 v37, v53
	v_cndmask_b32_e64 v37, 0, v37, s[10:11]
	s_nop 0
	s_waitcnt lgkmcnt(2)
	v_mfma_f32_16x16x32_f16 v[44:47], v[80:83], v[60:63], v[44:47]
	s_nop 0
	s_nop 0
	v_pack_b32_f16 v72, v36, v37
	ds_read_b128 v[68:71], v226 offset:9216
	ds_read_b128 v[94:97], v226 offset:9280
	s_nop 0
	s_waitcnt lgkmcnt(3)
	v_pk_mul_f32 v[82:83], v[26:27], v[130:131]
	ds_read_b128 v[64:67], v226 offset:18432
	v_pk_mul_f32 v[80:81], v[24:25], v[128:129]
	s_nop 0
	ds_read_b128 v[98:101], v226 offset:23104
	v_mfma_f32_16x16x32_f16 v[78:81], v[88:91], v[0:3], v[80:83]
	ds_read_b128 v[90:93], v226 offset:18496
	s_nop 1
	v_cvt_f16_f32_e32 v82, v54
	v_cvt_f16_f32_e32 v83, v55
	s_nop 0
	s_waitcnt lgkmcnt(5)
	v_mfma_f32_16x16x32_f16 v[52:55], v[84:87], v[60:63], v[78:81]
	ds_read_b128 v[86:89], v226 offset:13824
	s_nop 1
	v_cndmask_b32_e64 v78, v82, 0, s[18:19]
	v_cndmask_b32_e64 v79, v83, 0, s[22:23]
	v_pack_b32_f16 v73, v78, v79
	v_mov_b32_e32 v78, v3
	v_mov_b32_e32 v79, v3
	v_add_u32_e32 v80, s77, v122
	v_add_u32_e32 v81, s76, v235
	v_mfma_f32_16x16x32_f16 v[56:59], v[76:79], v[0:3], v[56:59]
	ds_read_b128 v[76:79], v226 offset:23040
	v_subrev_u32_e32 v102, 64, v80
	v_add_u32_e32 v0, 0xff, v81
	v_mfma_f32_16x16x32_f16 v[58:61], v[72:75], v[60:63], v[56:59]
	v_cndmask_b32_e64 v0, v0, v102, s[2:3]
	v_add_u32_e32 v0, v0, v173
	v_mad_i64_i32 v[0:1], s[28:29], v0, s91, v[126:127]
	s_nop 0
	s_waitcnt lgkmcnt(4)
	v_mfma_f32_16x16x32_f16 v[82:85], v[68:71], v[64:67], 0
	s_nop 2
	v_cvt_f16_f32_e32 v2, v58
	v_cvt_f16_f32_e32 v60, v60
	ds_read_b128 v[128:131], v226 offset:13888
	global_store_short v[0:1], v2, off
	v_subrev_u32_e32 v0, 63, v80
	v_xad_u32 v1, v102, -2, v166
	v_cvt_f16_f32_e32 v2, v59
	s_nop 0
	v_mfma_f32_16x16x32_f16 v[72:75], v[64:67], v[68:71], 0
	v_cndmask_b32_e64 v0, v1, v0, s[2:3]
	v_add_u32_e32 v0, v0, v173
	v_mad_i64_i32 v[0:1], s[28:29], v0, s91, v[126:127]
	s_nop 0
	s_waitcnt lgkmcnt(2)
	v_mfma_f32_16x16x32_f16 v[62:65], v[64:67], v[86:89], 0
	global_store_short v[0:1], v2, off
	v_subrev_u32_e32 v0, 62, v80
	v_xad_u32 v1, v102, -3, v166
	v_mfma_f32_16x16x32_f16 v[82:85], v[94:97], v[90:93], v[82:85]
	v_cndmask_b32_e64 v36, v1, v0, s[2:3]
	v_add_u32_e32 v36, v36, v173
	s_nop 0
	s_waitcnt lgkmcnt(1)
	v_mfma_f32_16x16x32_f16 v[68:71], v[76:79], v[68:71], 0
	v_mfma_f32_16x16x32_f16 v[86:89], v[76:79], v[86:89], 0
	s_nop 2
	v_cvt_f16_f32_e32 v1, v82
	v_cvt_f16_f32_e32 v2, v83
	v_cvt_f16_f32_e32 v66, v85
	v_mfma_f32_16x16x32_f16 v[72:75], v[90:93], v[94:97], v[72:75]
	v_mov_b32_e32 v85, v3
	v_cndmask_b32_e64 v66, 0, v66, s[22:23]
	s_nop 0
	s_waitcnt lgkmcnt(0)
	v_mfma_f32_16x16x32_f16 v[76:79], v[90:93], v[128:131], v[62:65]
	v_mov_b32_e32 v92, v3
	s_nop 2
	v_cndmask_b32_e64 v0, 0, v72, s[10:11]
	v_cndmask_b32_e64 v37, 0, v73, s[14:15]
	v_cvt_f16_f32_e32 v63, v84
	v_mfma_f32_16x16x32_f16 v[94:97], v[98:101], v[94:97], v[68:71]
	v_cndmask_b32_e64 v64, 0, v74, s[16:17]
	v_cndmask_b32_e64 v65, 0, v75, s[20:21]
	v_cndmask_b32_e64 v63, 0, v63, s[18:19]
	v_cndmask_b32_e64 v68, 0, v1, s[12:13]
	v_cndmask_b32_e64 v69, v2, 0, s[10:11]
	v_add_f32_e32 v62, v215, v0
	v_cvt_pk_f16_f32 v1, v64, v65
	v_cvt_pk_f16_f32 v0, v0, v37
	v_mov_b32_e32 v2, v3
	v_pack_b32_f16 v67, v63, v66
	v_pack_b32_f16 v66, v68, v69
	v_mov_b32_e32 v68, v3
	v_mov_b32_e32 v69, v3
	v_add_f32_e32 v63, v217, v37
	v_add_f32_e32 v64, v218, v64
	v_mfma_f32_16x16x32_f16 v[70:73], v[0:3], v[66:69], 0
	v_add_f32_e32 v65, v219, v65
	v_cvt_pk_f16_f32 v83, v64, v65
	v_cvt_pk_f16_f32 v82, v62, v63
	v_mfma_f32_16x16x32_f16 v[66:69], v[66:69], v[0:3], 0
	v_mov_b32_e32 v84, v3
	s_nop 2
	v_cvt_pk_f16_f32 v0, v70, v71
	v_mov_b32_e32 v70, v3
	v_mov_b32_e32 v71, v3
	v_cvt_pk_f16_f32 v1, v72, v73
	v_cvt_pk_f16_f32 v69, v68, v69
	v_cvt_pk_f16_f32 v68, v66, v67
	v_mfma_f32_16x16x32_f16 v[62:65], v[0:3], v[82:85], v[62:65]
	v_mad_i64_i32 v[36:37], s[28:29], v36, s91, v[126:127]
	global_store_short v[36:37], v60, off
	v_mfma_f32_16x16x32_f16 v[72:75], v[68:71], v[0:3], 0
	v_cvt_f16_f32_e32 v82, v61
	v_subrev_u32_e32 v36, 61, v80
	v_xad_u32 v37, v102, -4, v166
	v_mfma_f32_16x16x32_f16 v[66:69], v[0:3], v[68:71], 0
	s_nop 0
	v_cvt_pk_f16_f32 v71, v64, v65
	s_nop 1
	v_cvt_pk_f16_f32 v1, v74, v75
	v_cvt_pk_f16_f32 v0, v72, v73
	ds_read2_b64 v[136:139], v227 offset1:4
	v_mfma_f32_16x16x32_f16 v[56:59], v[98:101], v[128:131], v[86:89]
	v_cvt_pk_f16_f32 v70, v62, v63
	v_mov_b32_e32 v72, v3
	v_mov_b32_e32 v73, v3
	v_cvt_pk_f16_f32 v85, v68, v69
	ds_read2_b64 v[128:131], v227 offset0:8 offset1:12
	v_cvt_pk_f16_f32 v84, v66, v67
	v_mov_b32_e32 v86, v3
	v_mov_b32_e32 v87, v3
	v_mfma_f32_16x16x32_f16 v[88:91], v[0:3], v[70:73], v[62:65]
	s_nop 0
	s_nop 0
	v_cndmask_b32_e64 v36, v37, v36, s[2:3]
	v_mfma_f32_16x16x32_f16 v[60:63], v[84:87], v[0:3], 0
	v_add_u32_e32 v83, v36, v173
	s_nop 2
	v_cvt_pk_f16_f32 v1, v90, v91
	v_cvt_pk_f16_f32 v0, v88, v89
	v_cvt_pk_f16_f32 v67, v54, v55
	v_cvt_pk_f16_f32 v66, v52, v53
	v_cvt_pk_f16_f32 v85, v62, v63
	v_cvt_pk_f16_f32 v84, v60, v61
	v_cvt_pk_f16_f32 v63, v50, v51
	v_cvt_pk_f16_f32 v62, v48, v49
	v_cvt_pk_f16_f32 v61, v42, v43
	v_cvt_pk_f16_f32 v60, v40, v41
	v_cvt_pk_f16_f32 v65, v46, v47
	v_cvt_pk_f16_f32 v64, v44, v45
	s_nop 0
	s_waitcnt lgkmcnt(1)
	v_mfma_f32_16x16x32_f16 v[68:71], v[136:139], v[60:63], 0
	v_add_u32_e32 v36, 0x1000, v227
	v_mov_b32_e32 v93, v3
	v_cvt_f16_f32_e32 v76, v76
	s_nop 0
	s_waitcnt lgkmcnt(0)
	v_mfma_f32_16x16x32_f16 v[98:101], v[128:131], v[64:67], v[68:71]
	ds_read2_b64 v[72:75], v36 offset0:64 offset1:68
	s_nop 1
	ds_read2_b64 v[68:71], v36 offset0:72 offset1:76
	v_cvt_f16_f32_e32 v36, v97
	v_cvt_f16_f32_e32 v97, v77
	v_mfma_f32_16x16x32_f16 v[84:87], v[84:87], v[0:3], v[88:91]
	v_cvt_f16_f32_e32 v0, v94
	v_cvt_f16_f32_e32 v1, v95
	v_cvt_f16_f32_e32 v2, v96
	v_cndmask_b32_e64 v96, v76, 0, s[12:13]
	v_cndmask_b32_e64 v0, 0, v0, s[10:11]
	v_cndmask_b32_e64 v37, 0, v1, s[14:15]
	v_cndmask_b32_e64 v1, 0, v2, s[16:17]
	v_cndmask_b32_e64 v2, 0, v36, s[20:21]
	v_pack_b32_f16 v1, v1, v2
	v_pack_b32_f16 v0, v0, v37
	v_mov_b32_e32 v2, v3
	v_mov_b32_e32 v36, v134
	v_mov_b32_e32 v37, v135
	v_add_u32_e32 v253, 0x800, v236
	ds_read2_b64 v[128:131], v253 offset0:64 offset1:144
	v_mov_b32_e32 v38, v3
	v_mov_b32_e32 v39, v3
	v_mov_b32_e32 v94, v3
	ds_read_b128 v[132:135], v180 offset:256
	v_mov_b32_e32 v95, v3
	v_mfma_f32_16x16x32_f16 v[88:91], v[0:3], v[36:39], v[98:101]
	v_cvt_pk_f16_f32 v1, v86, v87
	v_cvt_pk_f16_f32 v0, v84, v85
	v_cvt_f16_f32_e32 v56, v56
	v_cvt_f16_f32_e32 v98, v78
	v_cvt_f16_f32_e32 v99, v79
	s_nop 2
	v_cvt_pk_f16_f32 v91, v90, v91
	v_cvt_pk_f16_f32 v90, v88, v89
	v_cndmask_b32_e64 v97, 0, v97, s[10:11]
	v_cndmask_b32_e64 v98, v98, 0, s[18:19]
	v_mfma_f32_16x16x32_f16 v[84:87], v[0:3], v[90:93], 0
	v_add_u32_e32 v2, 0x800, v236
	v_mov_b32_e32 v90, v3
	v_mov_b32_e32 v91, v3
	v_cndmask_b32_e64 v99, v99, 0, s[22:23]
	ds_read_b64 v[88:89], v228 offset:5120
	ds_read_b128 v[136:139], v180 offset:320
	s_nop 3
	v_cvt_pk_f16_f32 v1, v86, v87
	v_cvt_pk_f16_f32 v0, v84, v85
	s_nop 0
	s_nop 0
	s_nop 0
	v_mov_b32_e32 v2, v3
	s_nop 0
	s_waitcnt lgkmcnt(3)
	v_mov_b32_e32 v92, v128
	v_mov_b32_e32 v93, v129
	v_add_u32_e32 v253, 0xc00, v236
	ds_read_b64 v[84:85], v229 offset:5120
	ds_read2_b64 v[140:143], v253 offset0:96 offset1:176
	ds_read_b128 v[144:147], v180 offset:384
	s_nop 0
	s_waitcnt lgkmcnt(5)
	v_pk_mul_f32 v[42:43], v[42:43], v[134:135]
	v_pk_mul_f32 v[40:41], v[40:41], v[132:133]
	s_nop 0
	s_nop 0
	v_mfma_f32_16x16x32_f16 v[40:43], v[92:95], v[0:3], v[40:43]
	s_nop 0
	s_waitcnt lgkmcnt(3)
	v_pk_mul_f32 v[48:49], v[48:49], v[136:137]
	v_add_u32_e32 v76, 0xc00, v236
	v_mfma_f32_16x16x32_f16 v[40:43], v[88:91], v[36:39], v[40:43]
	v_mov_b32_e32 v88, v130
	v_mov_b32_e32 v89, v131
	v_pk_mul_f32 v[50:51], v[50:51], v[138:139]
	v_mov_b32_e32 v86, v3
	v_mov_b32_e32 v87, v3
	s_nop 0
	v_mfma_f32_16x16x32_f16 v[48:51], v[88:91], v[0:3], v[48:51]
	ds_read_b64 v[88:89], v230 offset:5120
	s_nop 0
	s_waitcnt lgkmcnt(2)
	v_mov_b32_e32 v92, v140
	v_mfma_f32_16x16x32_f16 v[48:51], v[84:87], v[36:39], v[48:51]
	s_nop 0
	s_nop 0
	v_mov_b32_e32 v93, v141
	v_pack_b32_f16 v76, v96, v97
	v_cndmask_b32_e64 v96, v56, 0, s[12:13]
	s_nop 0
	s_waitcnt lgkmcnt(1)
	v_pk_mul_f32 v[46:47], v[46:47], v[146:147]
	v_pk_mul_f32 v[44:45], v[44:45], v[144:145]
	ds_read_b128 v[84:87], v180 offset:448
	v_cvt_f16_f32_e32 v56, v57
	v_cvt_f16_f32_e32 v57, v58
	v_mfma_f32_16x16x32_f16 v[44:47], v[92:95], v[0:3], v[44:47]
	v_cvt_f16_f32_e32 v58, v59
	v_mov_b32_e32 v92, v142
	v_mov_b32_e32 v93, v143
	s_nop 0
	s_waitcnt lgkmcnt(1)
	v_mfma_f32_16x16x32_f16 v[44:47], v[88:91], v[36:39], v[44:47]
	ds_read_b64 v[88:89], v231 offset:5120
	s_nop 0
	s_nop 0
	v_cndmask_b32_e64 v78, v57, 0, s[18:19]
	v_cndmask_b32_e64 v79, v58, 0, s[22:23]
	v_pack_b32_f16 v77, v98, v99
	s_nop 0
	s_waitcnt lgkmcnt(1)
	v_pk_mul_f32 v[52:53], v[52:53], v[84:85]
	v_cndmask_b32_e64 v84, 0, v56, s[10:11]
	v_mfma_f32_16x16x32_f16 v[56:59], v[72:75], v[60:63], 0
	v_pack_b32_f16 v61, v78, v79
	v_mov_b32_e32 v78, v3
	v_mov_b32_e32 v79, v3
	v_mfma_f32_16x16x32_f16 v[56:59], v[68:71], v[64:67], v[56:59]
	v_mul_f32_e64 v54, v54, v86
	v_mul_f32_e64 v55, v55, v87
	v_pack_b32_f16 v60, v96, v84
	v_mov_b32_e32 v62, v3
	v_mov_b32_e32 v63, v3
	v_mfma_f32_16x16x32_f16 v[52:55], v[92:95], v[0:3], v[52:55]
	v_mfma_f32_16x16x32_f16 v[56:59], v[76:79], v[0:3], v[56:59]
	v_mad_i64_i32 v[0:1], s[28:29], v83, s91, v[126:127]
	global_store_short v[0:1], v82, off
	s_nop 0
	s_waitcnt lgkmcnt(0)
	v_mfma_f32_16x16x32_f16 v[52:55], v[88:91], v[36:39], v[52:55]
	v_subrev_u32_e32 v0, 48, v80
	v_add_u32_e32 v1, 0xef, v81
	v_cndmask_b32_e64 v0, v1, v0, s[2:3]
	v_mfma_f32_16x16x32_f16 v[36:39], v[60:63], v[36:39], v[56:59]
	v_add_u32_e32 v0, v0, v173
	v_mad_i64_i32 v[0:1], s[28:29], v0, s91, v[126:127]
	s_nop 5
	v_cvt_f16_f32_e32 v2, v36
	global_store_short v[0:1], v2, off
	v_subrev_u32_e32 v0, 47, v80
	v_add_u32_e32 v1, 0xee, v81
	v_cvt_f16_f32_e32 v2, v37
	v_cndmask_b32_e64 v0, v1, v0, s[2:3]
	v_add_u32_e32 v0, v0, v173
	v_mad_i64_i32 v[0:1], s[28:29], v0, s91, v[126:127]
	global_store_short v[0:1], v2, off
	v_subrev_u32_e32 v0, 46, v80
	v_add_u32_e32 v1, 0xed, v81
	v_cvt_f16_f32_e32 v2, v38
	v_cndmask_b32_e64 v0, v1, v0, s[2:3]
	v_add_u32_e32 v0, v0, v173
	v_mad_i64_i32 v[0:1], s[28:29], v0, s91, v[126:127]
	global_store_short v[0:1], v2, off
	v_subrev_u32_e32 v0, 45, v80
	v_add_u32_e32 v1, 0xec, v81
	v_cndmask_b32_e64 v0, v1, v0, s[2:3]
	v_cvt_f16_f32_e32 v2, v39
	v_add_u32_e32 v0, v0, v173
	v_mad_i64_i32 v[0:1], s[28:29], v0, s91, v[126:127]
	s_mov_b64 s[28:29], 0
	global_store_short v[0:1], v2, off

.LBB0_369:
	v_cmp_lt_i32_e32 vcc, 2, v176
	s_and_saveexec_b64 s[30:31], vcc
	s_xor_b64 s[70:71], exec, s[30:31]
	s_cbranch_execz .LBB0_371
	v_lshl_add_u32 v252, v206, 1, v2
	ds_read2st64_b32 v[36:37], v252 offset0:64 offset1:80
	ds_read2st64_b32 v[46:47], v252 offset0:96 offset1:112
	v_lshl_add_u32 v48, v206, 1, v2
	s_nop 0
	s_nop 0
	ds_read_b32 v60, v48 offset:32768
	v_rcp_f32_e32 v44, v62
	v_rcp_f32_e32 v45, v63
	s_nop 0
	s_waitcnt lgkmcnt(1)
	v_cvt_f32_f16_e32 v58, v47
	v_cvt_f32_f16_e32 v50, v37
	v_cvt_f32_f16_sdwa v51, v37 dst_sel:DWORD dst_unused:UNUSED_PAD src0_sel:WORD_1
	v_cvt_f32_f16_sdwa v59, v47 dst_sel:DWORD dst_unused:UNUSED_PAD src0_sel:WORD_1
	v_lshl_add_u32 v252, v208, 1, v2
	ds_read2st64_b32 v[148:149], v252 offset0:64 offset1:80
	v_cvt_f32_f16_e32 v48, v36
	v_cvt_f32_f16_e32 v54, v46
	v_cvt_f32_f16_sdwa v55, v46 dst_sel:DWORD dst_unused:UNUSED_PAD src0_sel:WORD_1
	ds_read2st64_b32 v[240:241], v252 offset0:96 offset1:112
	v_cvt_f32_f16_sdwa v49, v36 dst_sel:DWORD dst_unused:UNUSED_PAD src0_sel:WORD_1
	v_pk_mul_f32 v[36:37], v[42:43], v[50:51]
	v_pk_mul_f32 v[42:43], v[62:63], v[58:59]
	v_pk_mul_f32 v[46:47], v[44:45], v[54:55]
	v_pk_mul_f32 v[44:45], v[44:45], v[48:49]
	v_pk_mul_f32 v[48:49], v[40:41], v[36:37]
	v_pk_mul_f32 v[50:51], v[40:41], v[42:43]
	v_cvt_pk_f16_f32 v36, v36, v37
	v_cvt_pk_f16_f32 v37, v42, v43
	v_pk_mul_f32 v[54:55], v[38:39], v[46:47]
	v_pk_mul_f32 v[58:59], v[38:39], v[44:45]
	ds_write2st64_b32 v207, v36, v37 offset1:18
	v_cvt_pk_f16_f32 v36, v48, v49
	v_cvt_pk_f16_f32 v37, v50, v51
	v_pk_mul_f32 v[46:47], v[0:1], v[46:47]
	ds_write2st64_b32 v207, v36, v37 offset0:36 offset1:54
	v_cvt_pk_f16_f32 v36, v54, v55
	v_cvt_pk_f16_f32 v37, v58, v59
	ds_write2st64_b32 v207, v36, v37 offset0:72 offset1:90
	v_cvt_f16_f32_e32 v36, v46
	v_pk_mul_f32 v[44:45], v[0:1], v[44:45]
	v_cvt_f16_f32_e32 v37, v47
	v_cvt_f16_f32_e32 v42, v44
	v_cvt_f16_f32_e32 v43, v45
	ds_write_b16 v178, v36 offset:24
	ds_write_b16 v178, v37 offset:64
	ds_write_b16 v178, v42 offset:5144
	ds_write_b16 v178, v43 offset:5184
	s_nop 0
	s_waitcnt lgkmcnt(9)
	ds_write_b16 v178, v60 offset:10264
	v_lshl_add_u32 v46, v208, 1, v2
	s_nop 0
	s_nop 0
	ds_read_b32 v61, v46 offset:32768
	v_rcp_f32_e32 v42, v56
	v_rcp_f32_e32 v43, v57
	s_nop 0
	s_waitcnt lgkmcnt(10)
	v_cvt_f32_f16_e32 v48, v149
	v_cvt_f32_f16_sdwa v49, v149 dst_sel:DWORD dst_unused:UNUSED_PAD src0_sel:WORD_1
	s_nop 0
	s_waitcnt lgkmcnt(9)
	v_cvt_f32_f16_e32 v54, v241
	v_cvt_f32_f16_sdwa v55, v241 dst_sel:DWORD dst_unused:UNUSED_PAD src0_sel:WORD_1
	v_cvt_f32_f16_e32 v46, v148
	v_lshl_add_u32 v252, v210, 1, v2
	ds_read2st64_b32 v[242:243], v252 offset0:64 offset1:80
	v_cvt_f32_f16_e32 v50, v240
	v_cvt_f32_f16_sdwa v51, v240 dst_sel:DWORD dst_unused:UNUSED_PAD src0_sel:WORD_1
	v_cvt_f32_f16_sdwa v47, v148 dst_sel:DWORD dst_unused:UNUSED_PAD src0_sel:WORD_1
	ds_read2st64_b32 v[148:149], v252 offset0:96 offset1:112
	v_pk_mul_f32 v[36:37], v[62:63], v[48:49]
	v_pk_mul_f32 v[44:45], v[56:57], v[54:55]
	v_pk_mul_f32 v[48:49], v[42:43], v[50:51]
	v_pk_mul_f32 v[42:43], v[42:43], v[46:47]
	v_pk_mul_f32 v[46:47], v[40:41], v[36:37]
	v_pk_mul_f32 v[50:51], v[40:41], v[44:45]
	v_cvt_pk_f16_f32 v36, v36, v37
	v_cvt_pk_f16_f32 v37, v44, v45
	v_pk_mul_f32 v[54:55], v[38:39], v[48:49]
	v_pk_mul_f32 v[58:59], v[38:39], v[42:43]
	ds_write2st64_b32 v209, v36, v37 offset1:18
	v_cvt_pk_f16_f32 v36, v46, v47
	v_cvt_pk_f16_f32 v37, v50, v51
	v_pk_mul_f32 v[48:49], v[0:1], v[48:49]
	ds_write2st64_b32 v209, v36, v37 offset0:36 offset1:54
	v_cvt_pk_f16_f32 v36, v54, v55
	v_cvt_pk_f16_f32 v37, v58, v59
	ds_write2st64_b32 v209, v36, v37 offset0:72 offset1:90
	v_cvt_f16_f32_e32 v36, v48
	v_pk_mul_f32 v[42:43], v[0:1], v[42:43]
	v_cvt_f16_f32_e32 v37, v49
	v_cvt_f16_f32_e32 v42, v42
	v_cvt_f16_f32_e32 v43, v43
	ds_write_b16 v178, v36 offset:26
	s_waitcnt lgkmcnt(14)
	ds_write_b16 v178, v37 offset:66
	s_waitcnt lgkmcnt(14)
	ds_write_b16 v178, v42 offset:5146
	s_waitcnt lgkmcnt(14)
	ds_write_b16 v178, v43 offset:5186
	s_nop 0
	s_waitcnt lgkmcnt(9)
	ds_write_b16 v178, v61 offset:10266
	v_lshl_add_u32 v46, v210, 1, v2
	s_nop 0
	s_nop 0
	ds_read_b32 v58, v46 offset:32768
	v_rcp_f32_e32 v42, v52
	v_rcp_f32_e32 v43, v53
	v_lshl_add_u32 v2, v212, 1, v2
	s_nop 0
	s_waitcnt lgkmcnt(10)
	v_cvt_f32_f16_e32 v48, v243
	v_cvt_f32_f16_sdwa v49, v243 dst_sel:DWORD dst_unused:UNUSED_PAD src0_sel:WORD_1
	s_nop 0
	s_waitcnt lgkmcnt(9)
	v_cvt_f32_f16_e32 v54, v149
	ds_read2st64_b32 v[240:241], v2 offset0:64 offset1:80
	v_cvt_f32_f16_sdwa v55, v149 dst_sel:DWORD dst_unused:UNUSED_PAD src0_sel:WORD_1
	v_cvt_f32_f16_e32 v46, v242
	v_cvt_f32_f16_e32 v50, v148
	ds_read2st64_b32 v[244:245], v2 offset0:96 offset1:112
	v_cvt_f32_f16_sdwa v51, v148 dst_sel:DWORD dst_unused:UNUSED_PAD src0_sel:WORD_1
	v_cvt_f32_f16_sdwa v47, v242 dst_sel:DWORD dst_unused:UNUSED_PAD src0_sel:WORD_1
	v_pk_mul_f32 v[36:37], v[56:57], v[48:49]
	v_pk_mul_f32 v[44:45], v[52:53], v[54:55]
	v_pk_mul_f32 v[48:49], v[42:43], v[50:51]
	v_pk_mul_f32 v[42:43], v[42:43], v[46:47]
	v_pk_mul_f32 v[46:47], v[40:41], v[36:37]
	v_pk_mul_f32 v[50:51], v[40:41], v[44:45]
	v_cvt_pk_f16_f32 v36, v36, v37
	v_cvt_pk_f16_f32 v37, v44, v45
	v_pk_mul_f32 v[54:55], v[38:39], v[48:49]
	v_pk_mul_f32 v[56:57], v[38:39], v[42:43]
	ds_write2st64_b32 v211, v36, v37 offset1:18
	v_cvt_pk_f16_f32 v36, v46, v47
	v_cvt_pk_f16_f32 v37, v50, v51
	v_pk_mul_f32 v[48:49], v[0:1], v[48:49]
	ds_write2st64_b32 v211, v36, v37 offset0:36 offset1:54
	v_cvt_pk_f16_f32 v36, v54, v55
	v_cvt_pk_f16_f32 v37, v56, v57
	ds_write2st64_b32 v211, v36, v37 offset0:72 offset1:90
	v_cvt_f16_f32_e32 v36, v48
	v_pk_mul_f32 v[42:43], v[0:1], v[42:43]
	v_cvt_f16_f32_e32 v37, v49
	v_cvt_f16_f32_e32 v42, v42
	v_cvt_f16_f32_e32 v43, v43
	ds_write_b16 v178, v36 offset:28
	s_waitcnt lgkmcnt(14)
	ds_write_b16 v178, v37 offset:68
	s_waitcnt lgkmcnt(14)
	ds_write_b16 v178, v42 offset:5148
	s_waitcnt lgkmcnt(14)
	ds_write_b16 v178, v43 offset:5188
	s_nop 0
	s_waitcnt lgkmcnt(9)
	ds_write_b16 v178, v58 offset:10268
	s_nop 0
	s_nop 0
	ds_read_b32 v2, v2 offset:32768
	v_rcp_f32_e32 v42, v0
	v_rcp_f32_e32 v43, v1
	s_nop 0
	s_waitcnt lgkmcnt(10)
	v_cvt_f32_f16_e32 v48, v241
	v_cvt_f32_f16_sdwa v49, v241 dst_sel:DWORD dst_unused:UNUSED_PAD src0_sel:WORD_1
	s_nop 0
	s_waitcnt lgkmcnt(9)
	v_cvt_f32_f16_e32 v54, v245
	v_cvt_f32_f16_sdwa v55, v245 dst_sel:DWORD dst_unused:UNUSED_PAD src0_sel:WORD_1
	v_cvt_f32_f16_e32 v46, v240
	v_cvt_f32_f16_e32 v50, v244
	v_cvt_f32_f16_sdwa v51, v244 dst_sel:DWORD dst_unused:UNUSED_PAD src0_sel:WORD_1
	v_cvt_f32_f16_sdwa v47, v240 dst_sel:DWORD dst_unused:UNUSED_PAD src0_sel:WORD_1
	v_pk_mul_f32 v[36:37], v[52:53], v[48:49]
	v_pk_mul_f32 v[44:45], v[0:1], v[54:55]
	v_pk_mul_f32 v[48:49], v[42:43], v[50:51]
	v_pk_mul_f32 v[42:43], v[42:43], v[46:47]
	v_pk_mul_f32 v[46:47], v[40:41], v[36:37]
	v_pk_mul_f32 v[40:41], v[40:41], v[44:45]
	v_cvt_pk_f16_f32 v36, v36, v37
	v_cvt_pk_f16_f32 v37, v44, v45
	v_pk_mul_f32 v[50:51], v[38:39], v[48:49]
	v_pk_mul_f32 v[38:39], v[38:39], v[42:43]
	ds_write2st64_b32 v213, v36, v37 offset1:18
	v_cvt_pk_f16_f32 v36, v46, v47
	v_cvt_pk_f16_f32 v37, v40, v41
	v_pk_mul_f32 v[48:49], v[0:1], v[48:49]
	ds_write2st64_b32 v213, v36, v37 offset0:36 offset1:54
	v_cvt_pk_f16_f32 v36, v50, v51
	v_cvt_pk_f16_f32 v37, v38, v39
	ds_write2st64_b32 v213, v36, v37 offset0:72 offset1:90
	v_cvt_f16_f32_e32 v36, v48
	v_pk_mul_f32 v[42:43], v[0:1], v[42:43]
	v_cvt_f16_f32_e32 v37, v49
	v_cvt_f16_f32_e32 v38, v42
	v_cvt_f16_f32_e32 v39, v43
	ds_write_b16 v178, v36 offset:30
	ds_write_b16 v178, v37 offset:70
	ds_write_b16 v178, v38 offset:5150
	s_waitcnt lgkmcnt(14)
	ds_write_b16 v178, v39 offset:5190
	s_nop 0
	s_waitcnt lgkmcnt(7)
	ds_write_b16 v178, v2 offset:10270
	v_perm_b32 v36, v61, v60, s82
	v_perm_b32 v37, v2, v58, s82
	ds_write_b64 v178, v[36:37] offset:10304
.LBB0_371:
	s_andn2_saveexec_b64 s[70:71], s[70:71]
	s_cbranch_execz .LBB0_373
	v_lshl_add_u32 v252, v198, 1, v2
	ds_read2st64_b32 v[36:37], v252 offset0:64 offset1:80
	ds_read2st64_b32 v[48:49], v252 offset0:96 offset1:112
	v_lshl_add_u32 v52, v198, 1, v2
	s_nop 0
	s_nop 0
	ds_read_b32 v64, v52 offset:32768
	v_rcp_f32_e32 v44, v58
	v_rcp_f32_e32 v45, v59
	s_nop 0
	s_waitcnt lgkmcnt(1)
	v_cvt_f32_f16_e32 v60, v49
	v_cvt_f32_f16_e32 v54, v37
	v_cvt_f32_f16_sdwa v55, v37 dst_sel:DWORD dst_unused:UNUSED_PAD src0_sel:WORD_1
	v_cvt_f32_f16_sdwa v61, v49 dst_sel:DWORD dst_unused:UNUSED_PAD src0_sel:WORD_1
	v_lshl_add_u32 v252, v200, 1, v2
	ds_read2st64_b32 v[148:149], v252 offset0:64 offset1:80
	v_cvt_f32_f16_e32 v52, v36
	v_cvt_f32_f16_e32 v56, v48
	v_cvt_f32_f16_sdwa v57, v48 dst_sel:DWORD dst_unused:UNUSED_PAD src0_sel:WORD_1
	ds_read2st64_b32 v[240:241], v252 offset0:96 offset1:112
	v_cvt_f32_f16_sdwa v53, v36 dst_sel:DWORD dst_unused:UNUSED_PAD src0_sel:WORD_1
	v_pk_mul_f32 v[36:37], v[38:39], v[54:55]
	v_pk_mul_f32 v[48:49], v[58:59], v[60:61]
	v_pk_mul_f32 v[54:55], v[44:45], v[56:57]
	v_pk_mul_f32 v[44:45], v[44:45], v[52:53]
	v_pk_mul_f32 v[52:53], v[40:41], v[36:37]
	v_pk_mul_f32 v[56:57], v[40:41], v[48:49]
	v_cvt_pk_f16_f32 v36, v36, v37
	v_cvt_pk_f16_f32 v37, v48, v49
	v_pk_mul_f32 v[60:61], v[38:39], v[54:55]
	v_pk_mul_f32 v[62:63], v[38:39], v[44:45]
	ds_write2st64_b32 v199, v36, v37 offset1:18
	v_cvt_pk_f16_f32 v36, v52, v53
	v_cvt_pk_f16_f32 v37, v56, v57
	v_pk_mul_f32 v[54:55], v[0:1], v[54:55]
	ds_write2st64_b32 v199, v36, v37 offset0:36 offset1:54
	v_cvt_pk_f16_f32 v36, v60, v61
	v_cvt_pk_f16_f32 v37, v62, v63
	ds_write2st64_b32 v199, v36, v37 offset0:72 offset1:90
	v_cvt_f16_f32_e32 v36, v54
	v_pk_mul_f32 v[44:45], v[0:1], v[44:45]
	v_cvt_f16_f32_e32 v37, v55
	v_cvt_f16_f32_e32 v44, v44
	v_cvt_f16_f32_e32 v45, v45
	ds_write_b16 v178, v36 offset:16
	ds_write_b16 v178, v37 offset:56
	ds_write_b16 v178, v44 offset:5136
	ds_write_b16 v178, v45 offset:5176
	s_nop 0
	s_waitcnt lgkmcnt(9)
	ds_write_b16 v178, v64 offset:10256
	v_lshl_add_u32 v52, v200, 1, v2
	s_nop 0
	s_nop 0
	ds_read_b32 v62, v52 offset:32768
	v_rcp_f32_e32 v44, v50
	v_rcp_f32_e32 v45, v51
	s_nop 0
	s_waitcnt lgkmcnt(10)
	v_cvt_f32_f16_e32 v54, v149
	v_cvt_f32_f16_sdwa v55, v149 dst_sel:DWORD dst_unused:UNUSED_PAD src0_sel:WORD_1
	s_nop 0
	s_waitcnt lgkmcnt(9)
	v_cvt_f32_f16_e32 v60, v241
	v_cvt_f32_f16_sdwa v61, v241 dst_sel:DWORD dst_unused:UNUSED_PAD src0_sel:WORD_1
	v_cvt_f32_f16_e32 v52, v148
	v_lshl_add_u32 v252, v202, 1, v2
	ds_read2st64_b32 v[242:243], v252 offset0:64 offset1:80
	v_cvt_f32_f16_e32 v56, v240
	v_cvt_f32_f16_sdwa v57, v240 dst_sel:DWORD dst_unused:UNUSED_PAD src0_sel:WORD_1
	v_cvt_f32_f16_sdwa v53, v148 dst_sel:DWORD dst_unused:UNUSED_PAD src0_sel:WORD_1
	ds_read2st64_b32 v[148:149], v252 offset0:96 offset1:112
	v_pk_mul_f32 v[36:37], v[58:59], v[54:55]
	v_pk_mul_f32 v[48:49], v[50:51], v[60:61]
	v_pk_mul_f32 v[54:55], v[44:45], v[56:57]
	v_pk_mul_f32 v[44:45], v[44:45], v[52:53]
	v_pk_mul_f32 v[52:53], v[40:41], v[36:37]
	v_pk_mul_f32 v[56:57], v[40:41], v[48:49]
	v_cvt_pk_f16_f32 v36, v36, v37
	v_cvt_pk_f16_f32 v37, v48, v49
	v_pk_mul_f32 v[58:59], v[38:39], v[54:55]
	v_pk_mul_f32 v[60:61], v[38:39], v[44:45]
	ds_write2st64_b32 v201, v36, v37 offset1:18
	v_cvt_pk_f16_f32 v36, v52, v53
	v_cvt_pk_f16_f32 v37, v56, v57
	v_pk_mul_f32 v[54:55], v[0:1], v[54:55]
	ds_write2st64_b32 v201, v36, v37 offset0:36 offset1:54
	v_cvt_pk_f16_f32 v36, v58, v59
	v_cvt_pk_f16_f32 v37, v60, v61
	ds_write2st64_b32 v201, v36, v37 offset0:72 offset1:90
	v_cvt_f16_f32_e32 v36, v54
	v_pk_mul_f32 v[44:45], v[0:1], v[44:45]
	v_cvt_f16_f32_e32 v37, v55
	v_cvt_f16_f32_e32 v44, v44
	v_cvt_f16_f32_e32 v45, v45
	ds_write_b16 v178, v36 offset:18
	s_waitcnt lgkmcnt(14)
	ds_write_b16 v178, v37 offset:58
	s_waitcnt lgkmcnt(14)
	ds_write_b16 v178, v44 offset:5138
	s_waitcnt lgkmcnt(14)
	ds_write_b16 v178, v45 offset:5178
	s_nop 0
	s_waitcnt lgkmcnt(9)
	ds_write_b16 v178, v62 offset:10258
	v_lshl_add_u32 v52, v202, 1, v2
	s_nop 0
	s_nop 0
	ds_read_b32 v60, v52 offset:32768
	v_rcp_f32_e32 v44, v46
	v_rcp_f32_e32 v45, v47
	v_lshl_add_u32 v2, v204, 1, v2
	s_nop 0
	s_waitcnt lgkmcnt(10)
	v_cvt_f32_f16_e32 v54, v243
	v_cvt_f32_f16_sdwa v55, v243 dst_sel:DWORD dst_unused:UNUSED_PAD src0_sel:WORD_1
	s_nop 0
	s_waitcnt lgkmcnt(9)
	v_cvt_f32_f16_e32 v58, v149
	ds_read2st64_b32 v[240:241], v2 offset0:64 offset1:80
	v_cvt_f32_f16_sdwa v59, v149 dst_sel:DWORD dst_unused:UNUSED_PAD src0_sel:WORD_1
	v_cvt_f32_f16_e32 v52, v242
	v_cvt_f32_f16_e32 v56, v148
	ds_read2st64_b32 v[244:245], v2 offset0:96 offset1:112
	v_cvt_f32_f16_sdwa v57, v148 dst_sel:DWORD dst_unused:UNUSED_PAD src0_sel:WORD_1
	v_cvt_f32_f16_sdwa v53, v242 dst_sel:DWORD dst_unused:UNUSED_PAD src0_sel:WORD_1
	v_pk_mul_f32 v[36:37], v[50:51], v[54:55]
	v_pk_mul_f32 v[48:49], v[46:47], v[58:59]
	v_pk_mul_f32 v[50:51], v[44:45], v[56:57]
	v_pk_mul_f32 v[44:45], v[44:45], v[52:53]
	v_pk_mul_f32 v[52:53], v[40:41], v[36:37]
	v_pk_mul_f32 v[54:55], v[40:41], v[48:49]
	v_cvt_pk_f16_f32 v36, v36, v37
	v_cvt_pk_f16_f32 v37, v48, v49
	v_pk_mul_f32 v[56:57], v[38:39], v[50:51]
	v_pk_mul_f32 v[58:59], v[38:39], v[44:45]
	ds_write2st64_b32 v203, v36, v37 offset1:18
	v_cvt_pk_f16_f32 v36, v52, v53
	v_cvt_pk_f16_f32 v37, v54, v55
	v_pk_mul_f32 v[50:51], v[0:1], v[50:51]
	ds_write2st64_b32 v203, v36, v37 offset0:36 offset1:54
	v_cvt_pk_f16_f32 v36, v56, v57
	v_cvt_pk_f16_f32 v37, v58, v59
	ds_write2st64_b32 v203, v36, v37 offset0:72 offset1:90
	v_cvt_f16_f32_e32 v36, v50
	v_pk_mul_f32 v[44:45], v[0:1], v[44:45]
	v_cvt_f16_f32_e32 v37, v51
	v_cvt_f16_f32_e32 v44, v44
	v_cvt_f16_f32_e32 v45, v45
	ds_write_b16 v178, v36 offset:20
	s_waitcnt lgkmcnt(14)
	ds_write_b16 v178, v37 offset:60
	s_waitcnt lgkmcnt(14)
	ds_write_b16 v178, v44 offset:5140
	s_waitcnt lgkmcnt(14)
	ds_write_b16 v178, v45 offset:5180
	s_nop 0
	s_waitcnt lgkmcnt(9)
	ds_write_b16 v178, v60 offset:10260
	s_nop 0
	s_nop 0
	ds_read_b32 v2, v2 offset:32768
	v_rcp_f32_e32 v44, v42
	v_rcp_f32_e32 v45, v43
	s_nop 0
	s_waitcnt lgkmcnt(10)
	v_cvt_f32_f16_e32 v52, v241
	v_cvt_f32_f16_sdwa v53, v241 dst_sel:DWORD dst_unused:UNUSED_PAD src0_sel:WORD_1
	s_nop 0
	s_waitcnt lgkmcnt(9)
	v_cvt_f32_f16_e32 v56, v245
	v_cvt_f32_f16_sdwa v57, v245 dst_sel:DWORD dst_unused:UNUSED_PAD src0_sel:WORD_1
	v_cvt_f32_f16_e32 v50, v240
	v_cvt_f32_f16_e32 v54, v244
	v_cvt_f32_f16_sdwa v55, v244 dst_sel:DWORD dst_unused:UNUSED_PAD src0_sel:WORD_1
	v_cvt_f32_f16_sdwa v51, v240 dst_sel:DWORD dst_unused:UNUSED_PAD src0_sel:WORD_1
	v_pk_mul_f32 v[36:37], v[46:47], v[52:53]
	v_pk_mul_f32 v[42:43], v[42:43], v[56:57]
	v_pk_mul_f32 v[46:47], v[44:45], v[54:55]
	v_pk_mul_f32 v[44:45], v[44:45], v[50:51]
	v_pk_mul_f32 v[48:49], v[40:41], v[36:37]
	v_pk_mul_f32 v[40:41], v[40:41], v[42:43]
	v_cvt_pk_f16_f32 v36, v36, v37
	v_cvt_pk_f16_f32 v37, v42, v43
	v_pk_mul_f32 v[50:51], v[38:39], v[46:47]
	v_pk_mul_f32 v[38:39], v[38:39], v[44:45]
	ds_write2st64_b32 v205, v36, v37 offset1:18
	v_cvt_pk_f16_f32 v36, v48, v49
	v_cvt_pk_f16_f32 v37, v40, v41
	v_pk_mul_f32 v[46:47], v[0:1], v[46:47]
	ds_write2st64_b32 v205, v36, v37 offset0:36 offset1:54
	v_cvt_pk_f16_f32 v36, v50, v51
	v_cvt_pk_f16_f32 v37, v38, v39
	ds_write2st64_b32 v205, v36, v37 offset0:72 offset1:90
	v_cvt_f16_f32_e32 v36, v46
	v_pk_mul_f32 v[44:45], v[0:1], v[44:45]
	v_cvt_f16_f32_e32 v37, v47
	v_cvt_f16_f32_e32 v38, v44
	v_cvt_f16_f32_e32 v39, v45
	ds_write_b16 v178, v36 offset:22
	ds_write_b16 v178, v37 offset:62
	ds_write_b16 v178, v38 offset:5142
	s_waitcnt lgkmcnt(14)
	ds_write_b16 v178, v39 offset:5182
	s_nop 0
	s_waitcnt lgkmcnt(7)
	ds_write_b16 v178, v2 offset:10262
	v_perm_b32 v36, v62, v64, s82
	v_perm_b32 v37, v2, v60, s82
	ds_write_b64 v178, v[36:37] offset:10296

.LBB0_374:
	v_cmp_eq_u32_e32 vcc, 1, v176
	s_and_saveexec_b64 s[70:71], vcc
	s_cbranch_execz .LBB0_376
	v_lshl_add_u32 v252, v190, 1, v2
	ds_read2st64_b32 v[36:37], v252 offset0:64 offset1:80
	ds_read2st64_b32 v[46:47], v252 offset0:96 offset1:112
	v_lshl_add_u32 v50, v190, 1, v2
	s_nop 0
	s_nop 0
	ds_read_b32 v62, v50 offset:32768
	v_rcp_f32_e32 v42, v54
	v_rcp_f32_e32 v43, v55
	s_nop 0
	s_waitcnt lgkmcnt(1)
	v_cvt_f32_f16_e32 v58, v47
	v_cvt_f32_f16_e32 v52, v37
	v_cvt_f32_f16_sdwa v53, v37 dst_sel:DWORD dst_unused:UNUSED_PAD src0_sel:WORD_1
	v_cvt_f32_f16_sdwa v59, v47 dst_sel:DWORD dst_unused:UNUSED_PAD src0_sel:WORD_1
	v_lshl_add_u32 v252, v192, 1, v2
	ds_read2st64_b32 v[148:149], v252 offset0:64 offset1:80
	v_cvt_f32_f16_e32 v50, v36
	v_cvt_f32_f16_e32 v56, v46
	v_cvt_f32_f16_sdwa v57, v46 dst_sel:DWORD dst_unused:UNUSED_PAD src0_sel:WORD_1
	ds_read2st64_b32 v[240:241], v252 offset0:96 offset1:112
	v_cvt_f32_f16_sdwa v51, v36 dst_sel:DWORD dst_unused:UNUSED_PAD src0_sel:WORD_1
	v_pk_mul_f32 v[36:37], v[60:61], v[52:53]
	v_pk_mul_f32 v[46:47], v[54:55], v[58:59]
	v_pk_mul_f32 v[52:53], v[42:43], v[56:57]
	v_pk_mul_f32 v[42:43], v[42:43], v[50:51]
	v_pk_mul_f32 v[50:51], v[40:41], v[36:37]
	v_pk_mul_f32 v[56:57], v[40:41], v[46:47]
	v_cvt_pk_f16_f32 v36, v36, v37
	v_cvt_pk_f16_f32 v37, v46, v47
	v_pk_mul_f32 v[58:59], v[38:39], v[52:53]
	v_pk_mul_f32 v[60:61], v[38:39], v[42:43]
	ds_write2st64_b32 v191, v36, v37 offset1:18
	v_cvt_pk_f16_f32 v36, v50, v51
	v_cvt_pk_f16_f32 v37, v56, v57
	v_pk_mul_f32 v[52:53], v[0:1], v[52:53]
	ds_write2st64_b32 v191, v36, v37 offset0:36 offset1:54
	v_cvt_pk_f16_f32 v36, v58, v59
	v_cvt_pk_f16_f32 v37, v60, v61
	ds_write2st64_b32 v191, v36, v37 offset0:72 offset1:90
	v_cvt_f16_f32_e32 v36, v52
	v_pk_mul_f32 v[42:43], v[0:1], v[42:43]
	v_cvt_f16_f32_e32 v37, v53
	v_cvt_f16_f32_e32 v42, v42
	v_cvt_f16_f32_e32 v43, v43
	ds_write_b16 v178, v36 offset:8
	ds_write_b16 v178, v37 offset:48
	ds_write_b16 v178, v42 offset:5128
	ds_write_b16 v178, v43 offset:5168
	s_nop 0
	s_waitcnt lgkmcnt(9)
	ds_write_b16 v178, v62 offset:10248
	v_lshl_add_u32 v50, v192, 1, v2
	s_nop 0
	s_nop 0
	ds_read_b32 v60, v50 offset:32768
	v_rcp_f32_e32 v42, v48
	v_rcp_f32_e32 v43, v49
	s_nop 0
	s_waitcnt lgkmcnt(10)
	v_cvt_f32_f16_e32 v52, v149
	v_cvt_f32_f16_sdwa v53, v149 dst_sel:DWORD dst_unused:UNUSED_PAD src0_sel:WORD_1
	s_nop 0
	s_waitcnt lgkmcnt(9)
	v_cvt_f32_f16_e32 v58, v241
	v_cvt_f32_f16_sdwa v59, v241 dst_sel:DWORD dst_unused:UNUSED_PAD src0_sel:WORD_1
	v_cvt_f32_f16_e32 v50, v148
	v_lshl_add_u32 v252, v194, 1, v2
	ds_read2st64_b32 v[242:243], v252 offset0:64 offset1:80
	v_cvt_f32_f16_e32 v56, v240
	v_cvt_f32_f16_sdwa v57, v240 dst_sel:DWORD dst_unused:UNUSED_PAD src0_sel:WORD_1
	v_cvt_f32_f16_sdwa v51, v148 dst_sel:DWORD dst_unused:UNUSED_PAD src0_sel:WORD_1
	ds_read2st64_b32 v[148:149], v252 offset0:96 offset1:112
	v_pk_mul_f32 v[36:37], v[54:55], v[52:53]
	v_pk_mul_f32 v[46:47], v[48:49], v[58:59]
	v_pk_mul_f32 v[52:53], v[42:43], v[56:57]
	v_pk_mul_f32 v[42:43], v[42:43], v[50:51]
	v_pk_mul_f32 v[50:51], v[40:41], v[36:37]
	v_pk_mul_f32 v[54:55], v[40:41], v[46:47]
	v_cvt_pk_f16_f32 v36, v36, v37
	v_cvt_pk_f16_f32 v37, v46, v47
	v_pk_mul_f32 v[56:57], v[38:39], v[52:53]
	v_pk_mul_f32 v[58:59], v[38:39], v[42:43]
	ds_write2st64_b32 v193, v36, v37 offset1:18
	v_cvt_pk_f16_f32 v36, v50, v51
	v_cvt_pk_f16_f32 v37, v54, v55
	v_pk_mul_f32 v[52:53], v[0:1], v[52:53]
	ds_write2st64_b32 v193, v36, v37 offset0:36 offset1:54
	v_cvt_pk_f16_f32 v36, v56, v57
	v_cvt_pk_f16_f32 v37, v58, v59
	ds_write2st64_b32 v193, v36, v37 offset0:72 offset1:90
	v_cvt_f16_f32_e32 v36, v52
	v_pk_mul_f32 v[42:43], v[0:1], v[42:43]
	v_cvt_f16_f32_e32 v37, v53
	v_cvt_f16_f32_e32 v42, v42
	v_cvt_f16_f32_e32 v43, v43
	ds_write_b16 v178, v36 offset:10
	s_waitcnt lgkmcnt(14)
	ds_write_b16 v178, v37 offset:50
	s_waitcnt lgkmcnt(14)
	ds_write_b16 v178, v42 offset:5130
	s_waitcnt lgkmcnt(14)
	ds_write_b16 v178, v43 offset:5170
	s_nop 0
	s_waitcnt lgkmcnt(9)
	ds_write_b16 v178, v60 offset:10250
	v_lshl_add_u32 v50, v194, 1, v2
	s_nop 0
	s_nop 0
	ds_read_b32 v58, v50 offset:32768
	v_rcp_f32_e32 v42, v44
	v_rcp_f32_e32 v43, v45
	v_lshl_add_u32 v2, v196, 1, v2
	s_nop 0
	s_waitcnt lgkmcnt(10)
	v_cvt_f32_f16_e32 v52, v243
	v_cvt_f32_f16_sdwa v53, v243 dst_sel:DWORD dst_unused:UNUSED_PAD src0_sel:WORD_1
	ds_read2st64_b32 v[240:241], v2 offset0:64 offset1:80
	s_nop 0
	s_waitcnt lgkmcnt(10)
	v_cvt_f32_f16_e32 v56, v149
	v_cvt_f32_f16_sdwa v57, v149 dst_sel:DWORD dst_unused:UNUSED_PAD src0_sel:WORD_1
	ds_read2st64_b32 v[244:245], v2 offset0:96 offset1:112
	v_cvt_f32_f16_e32 v50, v242
	v_cvt_f32_f16_e32 v54, v148
	v_cvt_f32_f16_sdwa v55, v148 dst_sel:DWORD dst_unused:UNUSED_PAD src0_sel:WORD_1
	v_cvt_f32_f16_sdwa v51, v242 dst_sel:DWORD dst_unused:UNUSED_PAD src0_sel:WORD_1
	v_pk_mul_f32 v[36:37], v[48:49], v[52:53]
	v_pk_mul_f32 v[46:47], v[44:45], v[56:57]
	v_pk_mul_f32 v[48:49], v[42:43], v[54:55]
	v_pk_mul_f32 v[42:43], v[42:43], v[50:51]
	v_pk_mul_f32 v[50:51], v[40:41], v[36:37]
	v_pk_mul_f32 v[52:53], v[40:41], v[46:47]
	v_cvt_pk_f16_f32 v36, v36, v37
	v_cvt_pk_f16_f32 v37, v46, v47
	v_pk_mul_f32 v[54:55], v[38:39], v[48:49]
	v_pk_mul_f32 v[56:57], v[38:39], v[42:43]
	ds_write2st64_b32 v195, v36, v37 offset1:18
	v_cvt_pk_f16_f32 v36, v50, v51
	v_cvt_pk_f16_f32 v37, v52, v53
	v_pk_mul_f32 v[48:49], v[0:1], v[48:49]
	ds_write2st64_b32 v195, v36, v37 offset0:36 offset1:54
	v_cvt_pk_f16_f32 v36, v54, v55
	v_cvt_pk_f16_f32 v37, v56, v57
	ds_write2st64_b32 v195, v36, v37 offset0:72 offset1:90
	v_cvt_f16_f32_e32 v36, v48
	v_pk_mul_f32 v[42:43], v[0:1], v[42:43]
	v_cvt_f16_f32_e32 v37, v49
	v_cvt_f16_f32_e32 v42, v42
	v_cvt_f16_f32_e32 v43, v43
	ds_write_b16 v178, v36 offset:12
	s_waitcnt lgkmcnt(14)
	ds_write_b16 v178, v37 offset:52
	s_waitcnt lgkmcnt(14)
	ds_write_b16 v178, v42 offset:5132
	s_waitcnt lgkmcnt(14)
	ds_write_b16 v178, v43 offset:5172
	s_nop 0
	s_waitcnt lgkmcnt(9)
	ds_write_b16 v178, v58 offset:10252
	s_nop 0
	s_nop 0
	ds_read_b32 v2, v2 offset:32768
	s_nop 0
	s_waitcnt lgkmcnt(10)
	v_cvt_f32_f16_e32 v48, v241
	v_cvt_f32_f16_sdwa v49, v241 dst_sel:DWORD dst_unused:UNUSED_PAD src0_sel:WORD_1
	s_nop 0
	s_waitcnt lgkmcnt(9)
	v_cvt_f32_f16_e32 v52, v245
	v_cvt_f32_f16_sdwa v53, v245 dst_sel:DWORD dst_unused:UNUSED_PAD src0_sel:WORD_1
	v_cvt_f32_f16_e32 v46, v240
	v_cvt_f32_f16_e32 v50, v244
	v_cvt_f32_f16_sdwa v51, v244 dst_sel:DWORD dst_unused:UNUSED_PAD src0_sel:WORD_1
	v_cvt_f32_f16_sdwa v47, v240 dst_sel:DWORD dst_unused:UNUSED_PAD src0_sel:WORD_1
	v_pk_mul_f32 v[36:37], v[44:45], v[48:49]
	v_pk_mul_f32 v[42:43], v[38:39], v[52:53]
	v_pk_mul_f32 v[44:45], v[40:41], v[50:51]
	v_pk_mul_f32 v[46:47], v[40:41], v[46:47]
	v_pk_mul_f32 v[48:49], v[40:41], v[36:37]
	v_pk_mul_f32 v[40:41], v[40:41], v[42:43]
	v_cvt_pk_f16_f32 v36, v36, v37
	v_cvt_pk_f16_f32 v37, v42, v43
	v_pk_mul_f32 v[50:51], v[38:39], v[44:45]
	v_pk_mul_f32 v[38:39], v[38:39], v[46:47]
	ds_write2st64_b32 v197, v36, v37 offset1:18
	v_cvt_pk_f16_f32 v36, v48, v49
	v_cvt_pk_f16_f32 v37, v40, v41
	v_pk_mul_f32 v[44:45], v[0:1], v[44:45]
	ds_write2st64_b32 v197, v36, v37 offset0:36 offset1:54
	v_cvt_pk_f16_f32 v36, v50, v51
	v_cvt_pk_f16_f32 v37, v38, v39
	ds_write2st64_b32 v197, v36, v37 offset0:72 offset1:90
	v_cvt_f16_f32_e32 v36, v44
	v_pk_mul_f32 v[46:47], v[0:1], v[46:47]
	v_cvt_f16_f32_e32 v37, v45
	v_cvt_f16_f32_e32 v38, v46
	v_cvt_f16_f32_e32 v39, v47
	ds_write_b16 v178, v36 offset:14
	ds_write_b16 v178, v37 offset:54
	ds_write_b16 v178, v38 offset:5134
	s_waitcnt lgkmcnt(14)
	ds_write_b16 v178, v39 offset:5174
	s_nop 0
	s_waitcnt lgkmcnt(7)
	ds_write_b16 v178, v2 offset:10254
	v_perm_b32 v36, v60, v62, s82
	v_perm_b32 v37, v2, v58, s82
	ds_write_b64 v178, v[36:37] offset:10288

.LBB0_421:
	s_or_b64 exec, exec, s[0:1]
	s_nop 5
	v_cvt_f16_f32_e32 v65, v65
	v_cvt_f16_f32_e32 v64, v64
	s_add_i32 s30, s30, 1
	v_cndmask_b32_e64 v68, 0, v65, s[24:25]
	v_cvt_f16_f32_e32 v65, v66
	v_cvt_f16_f32_e32 v66, v67
	v_cndmask_b32_e64 v64, v64, 0, s[22:23]
	v_pack_b32_f16 v64, v64, v68
	v_cndmask_b32_e64 v65, v65, 0, s[26:27]
	v_cndmask_b32_e64 v66, v66, 0, s[28:29]
	v_pack_b32_f16 v65, v65, v66
	ds_write_b64 v115, v[64:65]
	s_waitcnt lgkmcnt(0)
	s_barrier
	ds_read_b128 v[118:121], v116 offset:55360
	ds_read_b128 v[122:125], v117
	ds_read_b128 v[142:145], v117 offset:64
	ds_read_b128 v[146:149], v117 offset:2304
	ds_read_b128 v[178:181], v117 offset:2368
	ds_read_b128 v[182:185], v117 offset:4608
	ds_read_b128 v[186:189], v117 offset:4672
	ds_read_b128 v[190:193], v117 offset:6912
	ds_read_b128 v[64:67], v116 offset:55296
	ds_read_b128 v[194:197], v117 offset:6976
	s_nop 0
	s_nop 0
	s_nop 0
	v_add_u32_e32 v253, 0x1e500, v87
	s_waitcnt lgkmcnt(1)
	v_mfma_f32_16x16x32_f16 v[52:55], v[64:67], v[122:125], v[52:55]
	ds_read_b128 v[198:201], v253
	s_nop 0
	v_add_u32_e32 v68, 0x1e500, v87
	s_nop 0
	v_mfma_f32_16x16x32_f16 v[52:55], v[118:121], v[142:145], v[52:55]
	s_nop 0
	ds_read_b128 v[142:145], v117 offset:46080
	s_nop 0
	v_mfma_f32_16x16x32_f16 v[56:59], v[64:67], v[146:149], v[56:59]
	s_nop 0
	s_nop 3
	ds_read_b128 v[146:149], v117 offset:46144
	v_cvt_pk_f16_f32 v55, v54, v55
	v_cvt_pk_f16_f32 v54, v52, v53
	s_nop 0
	ds_read_b128 v[202:205], v68 offset:64
	v_mfma_f32_16x16x32_f16 v[56:59], v[118:121], v[178:181], v[56:59]
	s_nop 0
	s_nop 0
	v_mfma_f32_16x16x32_f16 v[60:63], v[64:67], v[182:185], v[60:63]
	ds_read_b128 v[178:181], v117 offset:48384
	s_nop 0
	s_nop 0
	v_mfma_f32_16x16x32_f16 v[60:63], v[118:121], v[186:189], v[60:63]
	ds_read_b128 v[182:185], v117 offset:48448
	s_nop 0
	s_nop 0
	v_mfma_f32_16x16x32_f16 v[48:51], v[64:67], v[190:193], v[48:51]
	ds_read_b128 v[186:189], v68 offset:128
	s_nop 0
	s_nop 0
	s_waitcnt lgkmcnt(7)
	v_mfma_f32_16x16x32_f16 v[48:51], v[118:121], v[194:197], v[48:51]
	s_nop 0
	ds_read_b128 v[190:193], v117 offset:50688
	s_nop 0
	s_waitcnt lgkmcnt(7)
	v_pk_mul_f32 v[8:9], v[8:9], v[198:199]
	v_pk_mul_f32 v[10:11], v[10:11], v[200:201]
	ds_read_b128 v[194:197], v117 offset:50752
	s_nop 0
	s_nop 2
	v_cvt_pk_f16_f32 v51, v50, v51
	ds_read_b128 v[198:201], v68 offset:192
	s_nop 0
	s_waitcnt lgkmcnt(8)
	v_mfma_f32_16x16x32_f16 v[8:11], v[142:145], v[64:67], v[8:11]
	s_nop 0
	v_cvt_pk_f16_f32 v50, v48, v49
	s_nop 0
	s_waitcnt lgkmcnt(7)
	v_mfma_f32_16x16x32_f16 v[8:11], v[146:149], v[118:121], v[8:11]
	s_nop 0
	s_nop 0
	s_waitcnt lgkmcnt(6)
	v_pk_mul_f32 v[4:5], v[4:5], v[202:203]
	v_pk_mul_f32 v[6:7], v[6:7], v[204:205]
	s_nop 0
	s_nop 0
	s_waitcnt lgkmcnt(5)
	v_mfma_f32_16x16x32_f16 v[4:7], v[178:181], v[64:67], v[4:7]
	s_nop 0
	s_nop 0
	s_waitcnt lgkmcnt(4)
	v_mfma_f32_16x16x32_f16 v[4:7], v[182:185], v[118:121], v[4:7]
	s_nop 0
	s_nop 0
	s_waitcnt lgkmcnt(3)
	v_pk_mul_f32 v[16:17], v[16:17], v[186:187]
	v_pk_mul_f32 v[18:19], v[18:19], v[188:189]
	s_nop 0
	s_nop 0
	s_waitcnt lgkmcnt(2)
	v_mfma_f32_16x16x32_f16 v[16:19], v[190:193], v[64:67], v[16:19]
	s_nop 0
	s_nop 0
	s_waitcnt lgkmcnt(1)
	v_mfma_f32_16x16x32_f16 v[16:19], v[194:197], v[118:121], v[16:19]
	s_nop 0
	s_nop 0
	s_waitcnt lgkmcnt(0)
	v_pk_mul_f32 v[12:13], v[12:13], v[198:199]
	v_pk_mul_f32 v[14:15], v[14:15], v[200:201]
	ds_read_b128 v[122:125], v117 offset:52992
	s_nop 0
	s_waitcnt lgkmcnt(0)
	v_mfma_f32_16x16x32_f16 v[12:15], v[122:125], v[64:67], v[12:15]
	ds_read_b128 v[64:67], v117 offset:53056
	s_nop 0
	s_waitcnt lgkmcnt(0)
	v_mfma_f32_16x16x32_f16 v[12:15], v[64:67], v[118:121], v[12:15]
	v_add_u32_e32 v65, s79, v104
	v_add_u32_e32 v64, s78, v80
	v_add_u32_e32 v66, 0x7ff, v65
	v_cndmask_b32_e64 v66, v66, v64, s[2:3]
	v_add_u32_e32 v52, v66, v81
	v_mad_i64_i32 v[52:53], s[0:1], v52, s91, v[76:77]
	global_store_dwordx2 v[52:53], v[54:55], off
	v_add_u32_e32 v52, 16, v64
	v_add_u32_e32 v53, 0x7ef, v65
	v_cndmask_b32_e64 v54, v53, v52, s[2:3]
	v_add_u32_e32 v54, v54, v81
	v_cvt_pk_f16_f32 v53, v58, v59
	v_cvt_pk_f16_f32 v52, v56, v57
	v_mad_i64_i32 v[54:55], s[0:1], v54, s91, v[76:77]
	global_store_dwordx2 v[54:55], v[52:53], off
	v_add_u32_e32 v52, 32, v64
	v_add_u32_e32 v53, 0x7df, v65
	v_cndmask_b32_e64 v54, v53, v52, s[2:3]
	v_add_u32_e32 v54, v54, v81
	v_cvt_pk_f16_f32 v53, v62, v63
	v_cvt_pk_f16_f32 v52, v60, v61
	v_mad_i64_i32 v[54:55], s[0:1], v54, s91, v[76:77]
	global_store_dwordx2 v[54:55], v[52:53], off
	v_add_u32_e32 v52, 48, v64
	v_add_u32_e32 v53, 0x7cf, v65
	v_cndmask_b32_e64 v52, v53, v52, s[2:3]
	v_add_u32_e32 v48, v52, v81
	s_sub_i32 s79, s79, 64
	s_add_i32 s78, s78, 64
	v_mad_i64_i32 v[48:49], s[0:1], v48, s91, v[76:77]
	s_cmpk_lg_i32 s79, 0xf800
	global_store_dwordx2 v[48:49], v[50:51], off
	s_cbranch_scc0 .LBB0_438

.LBB0_430:
	v_add_u32_e32 v253, v84, v98
	ds_read_b128 v[48:51], v253
	v_add_u32_e32 v52, v84, v98
	s_nop 0
	ds_read_b128 v[52:55], v253 offset:64
	s_nop 0
	s_waitcnt lgkmcnt(1)
	v_mfma_f32_16x16x32_f16 v[48:51], v[48:51], v[40:43], 0
	s_nop 0
	s_waitcnt lgkmcnt(0)
	v_mfma_f32_16x16x32_f16 v[48:51], v[52:55], v[44:47], v[48:51]
	s_nop 7
	ds_write_b128 v99, v[48:51]
	s_and_saveexec_b64 s[0:1], s[76:77]
	s_cbranch_execz .LBB0_432
	v_mul_f32_e32 v48, 0x3fb8aa3b, v48
	v_mul_f32_e32 v49, 0x3fb8aa3b, v49
	v_mul_f32_e32 v50, 0x3fb8aa3b, v50
	v_mul_f32_e32 v51, 0x3fb8aa3b, v51
	v_exp_f32_e32 v48, v48
	v_exp_f32_e32 v49, v49
	v_exp_f32_e32 v50, v50
	v_exp_f32_e32 v51, v51
	ds_write_b128 v102, v[48:51]
.LBB0_432:
	s_or_b64 exec, exec, s[0:1]
	v_add_u32_e32 v253, v84, v100
	ds_read_b128 v[48:51], v253
	v_add_u32_e32 v52, v84, v100
	s_nop 0
	ds_read_b128 v[52:55], v253 offset:64
	s_nop 0
	s_waitcnt lgkmcnt(1)
	v_mfma_f32_16x16x32_f16 v[48:51], v[48:51], v[40:43], 0
	s_nop 0
	s_waitcnt lgkmcnt(0)
	v_mfma_f32_16x16x32_f16 v[48:51], v[52:55], v[44:47], v[48:51]
	s_nop 7
	ds_write_b128 v101, v[48:51]
	s_and_saveexec_b64 s[0:1], s[76:77]
	s_cbranch_execz .LBB0_434
	v_mul_f32_e32 v48, 0x3fb8aa3b, v48
	v_mul_f32_e32 v49, 0x3fb8aa3b, v49
	v_mul_f32_e32 v50, 0x3fb8aa3b, v50
	v_mul_f32_e32 v51, 0x3fb8aa3b, v51
	v_exp_f32_e32 v48, v48
	v_exp_f32_e32 v49, v49
	v_exp_f32_e32 v50, v50
	v_exp_f32_e32 v51, v51
	ds_write_b128 v103, v[48:51]
.LBB0_434:
	s_or_b64 exec, exec, s[0:1]
	v_add_u32_e32 v57, s78, v82
	v_add_u32_e32 v56, 0x7ff, v56
	v_cndmask_b32_e64 v56, v56, v57, s[2:3]
	s_waitcnt lgkmcnt(0)
	s_barrier
	ds_read_b128 v[58:61], v83
	ds_read_b128 v[62:65], v88
	ds_read_b128 v[48:51], v83 offset:9216
	s_nop 0
	ds_read_b128 v[66:69], v85
	ds_read_b128 v[52:55], v88 offset:9216
	v_lshrrev_b32_e32 v57, 6, v56
	v_and_b32_e32 v56, 63, v56
	v_cndmask_b32_e64 v56, v56, v57, s[6:7]
	v_lshl_or_b32 v57, v56, 6, v112
	s_nop 0
	v_add_u32_e32 v253, s83, v57
	ds_read_b128 v[122:125], v253
	ds_read_b128 v[118:121], v85 offset:16
	v_add_u32_e32 v75, s83, v57
	s_add_i32 s0, 0, 0x1f600
	v_add_u32_e32 v252, s0, v57
	ds_read_b128 v[126:129], v252
	v_add_u32_e32 v79, s0, v57
	s_nop 0
	s_nop 0
	s_nop 0
	s_waitcnt lgkmcnt(6)
	v_cvt_f32_f16_sdwa v137, v62 dst_sel:DWORD dst_unused:UNUSED_PAD src0_sel:WORD_1
	v_cvt_f32_f16_e32 v136, v62
	v_or_b32_e32 v57, 16, v57
	v_cvt_f32_f16_sdwa v135, v58 dst_sel:DWORD dst_unused:UNUSED_PAD src0_sel:WORD_1
	v_cvt_f32_f16_e32 v134, v58
	s_nop 0
	s_waitcnt lgkmcnt(4)
	v_mul_f32_e32 v56, 0x3fb8aa3b, v66
	v_add_u32_e32 v140, s83, v57
	ds_read_b128 v[130:133], v93
	v_add_u32_e32 v141, s0, v57
	v_mul_f32_e32 v57, 0x3fb8aa3b, v67
	v_exp_f32_e32 v56, v56
	v_exp_f32_e32 v57, v57
	v_pk_mul_f32 v[136:137], v[136:137], s[68:69] op_sel_hi:[1,0]
	v_pk_mul_f32 v[134:135], v[134:135], s[68:69] op_sel_hi:[1,0]
	s_nop 0
	s_waitcnt lgkmcnt(1)
	v_pk_mul_f32 v[136:137], v[136:137], v[126:127]
	v_rcp_f32_e32 v66, v56
	v_cndmask_b32_e64 v137, v137, -v137, s[8:9]
	v_cndmask_b32_e64 v136, v136, -v136, s[8:9]
	v_pk_fma_f32 v[134:135], v[134:135], v[122:123], v[136:137]
	v_cvt_f32_f16_sdwa v137, v48 dst_sel:DWORD dst_unused:UNUSED_PAD src0_sel:WORD_1
	v_pk_mul_f32 v[138:139], v[134:135], v[56:57]
	v_cvt_f32_f16_sdwa v135, v52 dst_sel:DWORD dst_unused:UNUSED_PAD src0_sel:WORD_1
	v_cvt_f32_f16_e32 v134, v52
	v_cvt_f32_f16_e32 v136, v48
	s_nop 0
	v_rcp_f32_e32 v67, v57
	v_pk_mul_f32 v[126:127], v[126:127], v[134:135]
	v_add_u32_e32 v52, v72, v89
	v_cndmask_b32_e64 v127, v127, -v127, s[8:9]
	v_cndmask_b32_e64 v126, v126, -v126, s[8:9]
	v_pk_fma_f32 v[122:123], v[122:123], v[136:137], v[126:127]
	ds_read_b128 v[134:137], v94
	v_pk_mul_f32 v[126:127], v[122:123], v[66:67]
	v_cvt_f32_f16_e32 v58, v63
	s_nop 0
	s_waitcnt lgkmcnt(1)
	v_fma_mixlo_f16 v48, v130, v126, 0
	ds_write_b16 v52, v48 offset:46080
	v_fma_mixlo_f16 v48, v131, v127, 0
	ds_write_b16 v113, v48 offset:46080
	v_mul_f32_e32 v48, 0x3fb8aa3b, v68
	v_exp_f32_e32 v66, v48
	v_mul_f32_e32 v48, 0x3fb8aa3b, v69
	v_cvt_f32_f16_sdwa v69, v59 dst_sel:DWORD dst_unused:UNUSED_PAD src0_sel:WORD_1
	v_cvt_f32_f16_e32 v68, v59
	v_cvt_f32_f16_sdwa v59, v63 dst_sel:DWORD dst_unused:UNUSED_PAD src0_sel:WORD_1
	v_exp_f32_e32 v67, v48
	v_cvt_f32_f16_e32 v52, v49
	v_pk_mul_f32 v[68:69], v[68:69], s[68:69] op_sel_hi:[1,0]
	v_pk_mul_f32 v[58:59], v[58:59], s[68:69] op_sel_hi:[1,0]
	v_rcp_f32_e32 v62, v66
	v_pk_mul_f32 v[58:59], v[58:59], v[128:129]
	v_rcp_f32_e32 v63, v67
	v_cndmask_b32_e64 v59, v59, -v59, s[8:9]
	v_cndmask_b32_e64 v58, v58, -v58, s[8:9]
	v_pk_fma_f32 v[58:59], v[68:69], v[124:125], v[58:59]
	v_cvt_pk_f16_f32 v56, v138, v139
	v_pk_mul_f32 v[130:131], v[58:59], v[66:67]
	v_cvt_f32_f16_sdwa v59, v53 dst_sel:DWORD dst_unused:UNUSED_PAD src0_sel:WORD_1
	v_cvt_f32_f16_e32 v58, v53
	v_cvt_f32_f16_sdwa v53, v49 dst_sel:DWORD dst_unused:UNUSED_PAD src0_sel:WORD_1
	v_cvt_pk_f16_f32 v57, v130, v131
	v_pk_mul_f32 v[48:49], v[128:129], v[58:59]
	s_nop 0
	v_cndmask_b32_e64 v49, v49, -v49, s[8:9]
	v_cndmask_b32_e64 v48, v48, -v48, s[8:9]
	v_pk_fma_f32 v[48:49], v[124:125], v[52:53], v[48:49]
	v_cvt_f32_f16_sdwa v59, v60 dst_sel:DWORD dst_unused:UNUSED_PAD src0_sel:WORD_1
	v_pk_mul_f32 v[48:49], v[48:49], v[62:63]
	v_cvt_f32_f16_sdwa v63, v64 dst_sel:DWORD dst_unused:UNUSED_PAD src0_sel:WORD_1
	v_fma_mixlo_f16 v52, v132, v48, 0
	ds_write_b16 v113, v52 offset:46224
	v_fma_mixlo_f16 v52, v133, v49, 0
	ds_write_b16 v113, v52 offset:46368
	ds_read_b128 v[122:125], v141
	ds_read_b128 v[66:69], v140
	s_nop 0
	v_cvt_f32_f16_e32 v62, v64
	v_cvt_f32_f16_e32 v58, v60
	v_mul_f32_e32 v52, 0x3fb8aa3b, v118
	v_mul_f32_e32 v53, 0x3fb8aa3b, v119
	v_pk_mul_f32 v[62:63], v[62:63], s[68:69] op_sel_hi:[1,0]
	v_exp_f32_e32 v52, v52
	s_nop 0
	s_waitcnt lgkmcnt(1)
	v_pk_mul_f32 v[62:63], v[62:63], v[122:123]
	v_exp_f32_e32 v53, v53
	v_pk_mul_f32 v[58:59], v[58:59], s[68:69] op_sel_hi:[1,0]
	v_cndmask_b32_e64 v63, v63, -v63, s[8:9]
	v_cndmask_b32_e64 v62, v62, -v62, s[8:9]
	s_waitcnt lgkmcnt(0)
	v_pk_fma_f32 v[58:59], v[58:59], v[66:67], v[62:63]
	v_cvt_f32_f16_sdwa v63, v54 dst_sel:DWORD dst_unused:UNUSED_PAD src0_sel:WORD_1
	v_cvt_f32_f16_e32 v62, v54
	v_cvt_f32_f16_sdwa v129, v50 dst_sel:DWORD dst_unused:UNUSED_PAD src0_sel:WORD_1
	v_cvt_f32_f16_e32 v128, v50
	v_rcp_f32_e32 v118, v52
	v_rcp_f32_e32 v119, v53
	v_pk_mul_f32 v[62:63], v[122:123], v[62:63]
	v_cvt_f32_f16_e32 v60, v65
	v_cndmask_b32_e64 v63, v63, -v63, s[8:9]
	v_cndmask_b32_e64 v62, v62, -v62, s[8:9]
	v_pk_fma_f32 v[62:63], v[66:67], v[128:129], v[62:63]
	v_pk_mul_f32 v[52:53], v[58:59], v[52:53]
	v_pk_mul_f32 v[66:67], v[62:63], v[118:119]
	v_cvt_f32_f16_sdwa v119, v61 dst_sel:DWORD dst_unused:UNUSED_PAD src0_sel:WORD_1
	v_fma_mixlo_f16 v50, v134, v66, 0
	v_cvt_f32_f16_e32 v118, v61
	v_cvt_f32_f16_sdwa v61, v65 dst_sel:DWORD dst_unused:UNUSED_PAD src0_sel:WORD_1
	ds_write_b16 v113, v50 offset:46512
	v_fma_mixlo_f16 v50, v135, v67, 0
	ds_write_b16 v113, v50 offset:46656
	v_mul_f32_e32 v50, 0x3fb8aa3b, v120
	v_exp_f32_e32 v62, v50
	v_mul_f32_e32 v50, 0x3fb8aa3b, v121
	v_exp_f32_e32 v63, v50
	v_pk_mul_f32 v[60:61], v[60:61], s[68:69] op_sel_hi:[1,0]
	v_pk_mul_f32 v[118:119], v[118:119], s[68:69] op_sel_hi:[1,0]
	v_pk_mul_f32 v[60:61], v[60:61], v[124:125]
	v_rcp_f32_e32 v64, v62
	v_cndmask_b32_e64 v61, v61, -v61, s[8:9]
	v_cndmask_b32_e64 v60, v60, -v60, s[8:9]
	v_pk_fma_f32 v[60:61], v[118:119], v[68:69], v[60:61]
	v_rcp_f32_e32 v65, v63
	v_pk_mul_f32 v[60:61], v[60:61], v[62:63]
	v_bfe_u32 v62, v131, 16, 1
	v_bfe_u32 v63, v130, 16, 1
	v_bfe_u32 v75, v53, 16, 1
	v_bfe_u32 v79, v52, 16, 1
	v_cvt_pk_f16_f32 v58, v52, v53
	v_bfe_u32 v50, v61, 16, 1
	v_add3_u32 v120, v130, v63, s34
	v_add3_u32 v62, v131, v62, s34
	v_add3_u32 v52, v52, v79, s34
	v_add3_u32 v53, v53, v75, s34
	v_cvt_pk_f16_f32 v59, v60, v61
	v_bfe_u32 v54, v60, 16, 1
	v_add3_u32 v50, v61, v50, s34
	v_perm_b32 v61, v62, v120, s82
	v_perm_b32 v62, v53, v52, s82
	v_cvt_f32_f16_sdwa v53, v55 dst_sel:DWORD dst_unused:UNUSED_PAD src0_sel:WORD_1
	v_cvt_f32_f16_e32 v52, v55
	v_add3_u32 v54, v60, v54, s34
	v_perm_b32 v63, v50, v54, s82
	v_cvt_f32_f16_sdwa v55, v51 dst_sel:DWORD dst_unused:UNUSED_PAD src0_sel:WORD_1
	v_cvt_f32_f16_e32 v54, v51
	v_pk_mul_f32 v[50:51], v[124:125], v[52:53]
	v_bfe_u32 v118, v139, 16, 1
	v_cndmask_b32_e64 v51, v51, -v51, s[8:9]
	v_cndmask_b32_e64 v50, v50, -v50, s[8:9]
	v_pk_fma_f32 v[50:51], v[68:69], v[54:55], v[50:51]
	v_bfe_u32 v119, v138, 16, 1
	v_pk_mul_f32 v[52:53], v[50:51], v[64:65]
	v_bfe_u32 v51, v48, 16, 1
	v_fma_mixlo_f16 v50, v136, v52, 0
	v_bfe_u32 v54, v53, 16, 1
	v_bfe_u32 v55, v52, 16, 1
	ds_write_b16 v113, v50 offset:46800
	v_bfe_u32 v50, v49, 16, 1
	v_bfe_u32 v64, v67, 16, 1
	v_bfe_u32 v65, v66, 16, 1
	v_bfe_u32 v68, v127, 16, 1
	v_bfe_u32 v69, v126, 16, 1
	v_add3_u32 v52, v52, v55, s34
	v_add3_u32 v54, v53, v54, s34
	v_add3_u32 v60, v138, v119, s34
	v_add3_u32 v118, v139, v118, s34
	v_add3_u32 v48, v48, v51, s34
	v_add3_u32 v49, v49, v50, s34
	v_add3_u32 v55, v126, v69, s34
	v_add3_u32 v68, v127, v68, s34
	v_add3_u32 v50, v66, v65, s34
	v_add3_u32 v64, v67, v64, s34
	v_perm_b32 v51, v54, v52, s82
	v_fma_mixlo_f16 v52, v137, v53, 0
	v_perm_b32 v60, v118, v60, s82
	v_perm_b32 v49, v49, v48, s82
	v_perm_b32 v50, v64, v50, s82
	v_perm_b32 v48, v68, v55, s82
	ds_write_b16 v113, v52 offset:46944
	ds_write_b128 v83, v[60:63] offset:18432
	ds_write_b128 v83, v[48:51] offset:27648
	ds_write_b128 v83, v[56:59] offset:36864
	v_add_u32_e32 v56, v73, v0
	s_nop 0
	s_barrier
	v_add_u32_e32 v253, v86, v95
	ds_read_b128 v[52:55], v253 offset:36864
	ds_read_b128 v[64:67], v56 offset:64
	ds_read_b128 v[142:145], v253 offset:36928
	ds_read_b128 v[60:63], v253 offset:39168
	ds_read_b128 v[118:121], v253 offset:39232
	ds_read_b128 v[122:125], v253 offset:41472
	ds_read_b128 v[126:129], v253 offset:41536
	ds_read_b128 v[130:133], v253 offset:43776
	ds_read_b128 v[134:137], v253 offset:43840
	ds_read_b128 v[48:51], v56
	v_add_u32_e32 v68, v86, v95
	s_nop 0
	s_nop 0
	s_nop 0
	s_nop 0
	s_nop 0
	s_nop 0
	s_nop 0
	s_nop 0
	s_nop 0
	s_nop 0
	s_waitcnt lgkmcnt(0)
	v_mfma_f32_16x16x32_f16 v[52:55], v[48:51], v[52:55], 0
	v_add_u32_e32 v75, v92, v0
	v_mov_b32_e32 v68, 0
	v_mov_b32_e32 v69, 0
	s_nop 0
	v_mfma_f32_16x16x32_f16 v[60:63], v[48:51], v[60:63], 0
	s_nop 0
	v_mfma_f32_16x16x32_f16 v[122:125], v[48:51], v[122:125], 0
	s_nop 0
	v_mfma_f32_16x16x32_f16 v[48:51], v[48:51], v[130:133], 0
	v_mfma_f32_16x16x32_f16 v[52:55], v[64:67], v[142:145], v[52:55]
	v_mfma_f32_16x16x32_f16 v[56:59], v[64:67], v[118:121], v[60:63]
	v_mfma_f32_16x16x32_f16 v[60:63], v[64:67], v[126:129], v[122:125]
	s_nop 0
	v_mfma_f32_16x16x32_f16 v[48:51], v[64:67], v[134:137], v[48:51]
	v_mov_b32_e32 v64, 0
	v_mov_b32_e32 v66, 0
	v_mov_b32_e32 v67, 0
	s_and_saveexec_b64 s[0:1], s[10:11]
	s_cbranch_execz .LBB0_436
	v_add_u32_e32 v253, v86, v98
	ds_read_b128 v[66:69], v75 offset:18432
	ds_read_b128 v[118:121], v253 offset:27648
	v_add_u32_e32 v65, v86, v98
	s_nop 0
	s_nop 0
	s_nop 0
	s_waitcnt lgkmcnt(0)
	v_mfma_f32_16x16x32_bf16 v[66:69], v[118:121], v[66:69], 0
	ds_read_b128 v[122:125], v65 offset:27712
	ds_read_b128 v[118:121], v75 offset:18496
	s_nop 0
	s_nop 0
	s_waitcnt lgkmcnt(0)
	v_mfma_f32_16x16x32_bf16 v[66:69], v[122:125], v[118:121], v[66:69]
.LBB0_436:
	s_or_b64 exec, exec, s[0:1]
	s_nop 6
	v_cvt_f16_f32_e32 v65, v66
	v_cvt_f16_f32_e32 v66, v67
	v_cvt_f16_f32_e32 v67, v68
	v_cvt_f16_f32_e32 v68, v69
	v_cndmask_b32_e64 v65, v65, 0, s[14:15]
	v_cndmask_b32_e64 v66, 0, v66, s[16:17]
	v_cndmask_b32_e64 v67, v67, 0, s[18:19]
	v_cndmask_b32_e64 v68, v68, 0, s[20:21]
	v_pack_b32_f16 v67, v67, v68
	v_pack_b32_f16 v66, v65, v66
	ds_write_b64 v114, v[66:67]
	v_mov_b32_e32 v65, 0
	v_mov_b32_e32 v66, 0
	v_mov_b32_e32 v67, 0
	s_and_saveexec_b64 s[0:1], s[12:13]
	s_cbranch_execz .LBB0_421
	v_add_u32_e32 v253, v86, v100
	ds_read_b128 v[64:67], v75 offset:18432
	ds_read_b128 v[118:121], v253 offset:27648
	v_add_u32_e32 v68, v86, v100
	s_nop 0
	s_nop 0
	s_nop 0
	s_waitcnt lgkmcnt(0)
	v_mfma_f32_16x16x32_bf16 v[64:67], v[118:121], v[64:67], 0
	ds_read_b128 v[122:125], v68 offset:27712
	ds_read_b128 v[118:121], v75 offset:18496
	s_nop 0
	s_nop 0
	s_waitcnt lgkmcnt(0)
	v_mfma_f32_16x16x32_bf16 v[64:67], v[122:125], v[118:121], v[64:67]
	s_branch .LBB0_421

.LBB0_455:
	s_andn2_b64 vcc, exec, s[24:25]
	s_mov_b64 s[26:27], -1
	s_cbranch_vccnz .LBB0_463
	s_and_b32 s26, s76, 1
	v_lshl_add_u32 v0, s26, 13, v227
	ds_read2_b64 v[36:39], v0 offset1:32
	v_mad_u32_u24 v2, s26, v165, v228
	s_waitcnt lgkmcnt(0)
	v_pk_mul_f32 v[66:67], v[36:37], v[38:39]
	ds_read2_b64 v[38:41], v0 offset0:64 offset1:96
	s_waitcnt lgkmcnt(0)
	v_pk_mul_f32 v[64:65], v[66:67], v[38:39]
	s_nop 0
	v_pk_mul_f32 v[60:61], v[64:65], v[40:41]
	ds_read2_b64 v[38:41], v0 offset0:128 offset1:160
	s_waitcnt lgkmcnt(0)
	v_pk_mul_f32 v[54:55], v[60:61], v[38:39]
	s_nop 0
	v_pk_mul_f32 v[48:49], v[54:55], v[40:41]
	ds_read2_b64 v[38:41], v0 offset0:192 offset1:224
	v_add_u32_e32 v0, 0x800, v0
	ds_read2_b64 v[68:71], v0 offset0:128 offset1:160
	s_waitcnt lgkmcnt(1)
	v_pk_mul_f32 v[44:45], v[48:49], v[38:39]
	s_nop 0
	v_pk_mul_f32 v[38:39], v[44:45], v[40:41]
	ds_read2_b64 v[40:43], v0 offset1:32
	s_waitcnt lgkmcnt(0)
	v_pk_mul_f32 v[58:59], v[38:39], v[40:41]
	s_nop 0
	v_pk_mul_f32 v[50:51], v[58:59], v[42:43]
	ds_read2_b64 v[40:43], v0 offset0:64 offset1:96
	s_waitcnt lgkmcnt(0)
	v_pk_mul_f32 v[46:47], v[50:51], v[40:41]
	s_nop 0
	v_pk_mul_f32 v[42:43], v[46:47], v[42:43]
	v_rcp_f32_e32 v40, v38
	v_pk_mul_f32 v[62:63], v[42:43], v[68:69]
	v_rcp_f32_e32 v41, v39
	v_pk_mul_f32 v[56:57], v[62:63], v[70:71]
	ds_read2_b64 v[68:71], v0 offset0:192 offset1:224
	s_waitcnt lgkmcnt(0)
	v_pk_mul_f32 v[52:53], v[56:57], v[68:69]
	s_nop 0
	v_pk_mul_f32 v[0:1], v[52:53], v[70:71]
	s_and_saveexec_b64 s[26:27], s[4:5]
	s_cbranch_execz .LBB0_458
	v_lshl_add_u32 v252, v173, 1, v2
	ds_read2st64_b32 v[72:73], v252 offset0:96 offset1:112
	ds_read2st64_b32 v[68:69], v252 offset0:64 offset1:80
	v_lshl_add_u32 v74, v173, 1, v2
	s_nop 0
	ds_read_b32 v84, v74 offset:32768
	s_nop 0
	v_rcp_f32_e32 v70, v36
	v_rcp_f32_e32 v71, v37
	s_nop 0
	s_nop 0
	s_waitcnt lgkmcnt(2)
	v_cvt_f32_f16_e32 v78, v73
	v_cvt_f32_f16_sdwa v79, v73 dst_sel:DWORD dst_unused:UNUSED_PAD src0_sel:WORD_1
	s_nop 0
	v_lshl_add_u32 v252, v180, 1, v2
	ds_read2st64_b32 v[146:147], v252 offset0:64 offset1:80
	s_waitcnt lgkmcnt(2)
	v_cvt_f32_f16_e32 v74, v68
	v_cvt_f32_f16_sdwa v75, v68 dst_sel:DWORD dst_unused:UNUSED_PAD src0_sel:WORD_1
	v_cvt_f32_f16_e32 v76, v72
	ds_read2st64_b32 v[148:149], v252 offset0:96 offset1:112
	v_cvt_f32_f16_sdwa v77, v72 dst_sel:DWORD dst_unused:UNUSED_PAD src0_sel:WORD_1
	v_cvt_f32_f16_e32 v72, v69
	v_cvt_f32_f16_sdwa v73, v69 dst_sel:DWORD dst_unused:UNUSED_PAD src0_sel:WORD_1
	v_pk_mul_f32 v[78:79], v[36:37], v[78:79]
	v_pk_mul_f32 v[76:77], v[70:71], v[76:77]
	v_pk_mul_f32 v[70:71], v[70:71], v[74:75]
	v_pk_mul_f32 v[72:73], v[40:41], v[72:73]
	v_pk_mul_f32 v[74:75], v[40:41], v[78:79]
	v_cvt_pk_f16_f32 v68, v78, v79
	v_pk_mul_f32 v[80:81], v[38:39], v[76:77]
	v_pk_mul_f32 v[82:83], v[38:39], v[70:71]
	ds_write2st64_b32 v179, v69, v68 offset1:18
	v_cvt_pk_f16_f32 v68, v72, v73
	v_cvt_pk_f16_f32 v69, v74, v75
	v_pk_mul_f32 v[76:77], v[0:1], v[76:77]
	ds_write2st64_b32 v179, v68, v69 offset0:36 offset1:54
	v_cvt_pk_f16_f32 v68, v80, v81
	v_cvt_pk_f16_f32 v69, v82, v83
	ds_write2st64_b32 v179, v68, v69 offset0:72 offset1:90
	v_cvt_f16_f32_e32 v68, v76
	v_pk_mul_f32 v[70:71], v[0:1], v[70:71]
	v_cvt_f16_f32_e32 v69, v77
	v_cvt_f16_f32_e32 v70, v70
	v_cvt_f16_f32_e32 v71, v71
	ds_write_b16 v174, v68
	ds_write_b16 v174, v69 offset:40
	ds_write_b16 v174, v70 offset:5120
	ds_write_b16 v174, v71 offset:5160
	s_nop 0
	s_waitcnt lgkmcnt(9)
	ds_write_b16 v174, v84 offset:10240
	v_lshl_add_u32 v74, v180, 1, v2
	s_nop 0
	s_nop 0
	ds_read_b32 v82, v74 offset:32768
	v_rcp_f32_e32 v70, v66
	v_rcp_f32_e32 v71, v67
	s_nop 0
	s_waitcnt lgkmcnt(10)
	v_cvt_f32_f16_e32 v76, v147
	v_cvt_f32_f16_sdwa v77, v147 dst_sel:DWORD dst_unused:UNUSED_PAD src0_sel:WORD_1
	s_nop 0
	s_waitcnt lgkmcnt(9)
	v_cvt_f32_f16_e32 v80, v149
	v_cvt_f32_f16_sdwa v81, v149 dst_sel:DWORD dst_unused:UNUSED_PAD src0_sel:WORD_1
	v_lshl_add_u32 v252, v182, 1, v2
	ds_read2st64_b32 v[232:233], v252 offset0:64 offset1:80
	v_cvt_f32_f16_e32 v74, v146
	v_cvt_f32_f16_e32 v78, v148
	v_cvt_f32_f16_sdwa v79, v148 dst_sel:DWORD dst_unused:UNUSED_PAD src0_sel:WORD_1
	ds_read2st64_b32 v[148:149], v252 offset0:96 offset1:112
	v_cvt_f32_f16_sdwa v75, v146 dst_sel:DWORD dst_unused:UNUSED_PAD src0_sel:WORD_1
	v_pk_mul_f32 v[36:37], v[36:37], v[76:77]
	v_pk_mul_f32 v[68:69], v[66:67], v[80:81]
	v_pk_mul_f32 v[72:73], v[70:71], v[78:79]
	v_pk_mul_f32 v[70:71], v[70:71], v[74:75]
	v_pk_mul_f32 v[74:75], v[40:41], v[36:37]
	v_pk_mul_f32 v[76:77], v[40:41], v[68:69]
	v_cvt_pk_f16_f32 v36, v36, v37
	v_cvt_pk_f16_f32 v37, v68, v69
	v_pk_mul_f32 v[78:79], v[38:39], v[72:73]
	v_pk_mul_f32 v[80:81], v[38:39], v[70:71]
	ds_write2st64_b32 v181, v36, v37 offset1:18
	v_cvt_pk_f16_f32 v36, v74, v75
	v_cvt_pk_f16_f32 v37, v76, v77
	v_pk_mul_f32 v[72:73], v[0:1], v[72:73]
	ds_write2st64_b32 v181, v36, v37 offset0:36 offset1:54
	v_cvt_pk_f16_f32 v36, v78, v79
	v_cvt_pk_f16_f32 v37, v80, v81
	ds_write2st64_b32 v181, v36, v37 offset0:72 offset1:90
	v_cvt_f16_f32_e32 v36, v72
	v_pk_mul_f32 v[70:71], v[0:1], v[70:71]
	v_cvt_f16_f32_e32 v37, v73
	v_cvt_f16_f32_e32 v68, v70
	v_cvt_f16_f32_e32 v69, v71
	ds_write_b16 v174, v36 offset:2
	s_waitcnt lgkmcnt(14)
	ds_write_b16 v174, v37 offset:42
	s_waitcnt lgkmcnt(14)
	ds_write_b16 v174, v68 offset:5122
	s_waitcnt lgkmcnt(14)
	ds_write_b16 v174, v69 offset:5162
	s_nop 0
	s_waitcnt lgkmcnt(9)
	ds_write_b16 v174, v82 offset:10242
	v_lshl_add_u32 v72, v182, 1, v2
	s_nop 0
	s_nop 0
	ds_read_b32 v80, v72 offset:32768
	v_rcp_f32_e32 v68, v64
	v_rcp_f32_e32 v69, v65
	s_nop 0
	s_waitcnt lgkmcnt(10)
	v_cvt_f32_f16_e32 v74, v233
	v_cvt_f32_f16_sdwa v75, v233 dst_sel:DWORD dst_unused:UNUSED_PAD src0_sel:WORD_1
	s_nop 0
	s_waitcnt lgkmcnt(9)
	v_cvt_f32_f16_e32 v78, v149
	v_cvt_f32_f16_sdwa v79, v149 dst_sel:DWORD dst_unused:UNUSED_PAD src0_sel:WORD_1
	v_lshl_add_u32 v252, v184, 1, v2
	ds_read2st64_b32 v[146:147], v252 offset0:64 offset1:80
	v_cvt_f32_f16_e32 v72, v232
	v_cvt_f32_f16_e32 v76, v148
	v_cvt_f32_f16_sdwa v77, v148 dst_sel:DWORD dst_unused:UNUSED_PAD src0_sel:WORD_1
	ds_read2st64_b32 v[148:149], v252 offset0:96 offset1:112
	v_cvt_f32_f16_sdwa v73, v232 dst_sel:DWORD dst_unused:UNUSED_PAD src0_sel:WORD_1
	v_pk_mul_f32 v[36:37], v[66:67], v[74:75]
	v_pk_mul_f32 v[66:67], v[64:65], v[78:79]
	v_pk_mul_f32 v[70:71], v[68:69], v[76:77]
	v_pk_mul_f32 v[68:69], v[68:69], v[72:73]
	v_pk_mul_f32 v[72:73], v[40:41], v[36:37]
	v_pk_mul_f32 v[74:75], v[40:41], v[66:67]
	v_cvt_pk_f16_f32 v36, v36, v37
	v_cvt_pk_f16_f32 v37, v66, v67
	v_pk_mul_f32 v[76:77], v[38:39], v[70:71]
	v_pk_mul_f32 v[78:79], v[38:39], v[68:69]
	ds_write2st64_b32 v183, v36, v37 offset1:18
	v_cvt_pk_f16_f32 v36, v72, v73
	v_cvt_pk_f16_f32 v37, v74, v75
	v_pk_mul_f32 v[70:71], v[0:1], v[70:71]
	ds_write2st64_b32 v183, v36, v37 offset0:36 offset1:54
	v_cvt_pk_f16_f32 v36, v76, v77
	v_cvt_pk_f16_f32 v37, v78, v79
	ds_write2st64_b32 v183, v36, v37 offset0:72 offset1:90
	v_cvt_f16_f32_e32 v36, v70
	v_pk_mul_f32 v[68:69], v[0:1], v[68:69]
	v_cvt_f16_f32_e32 v37, v71
	v_cvt_f16_f32_e32 v66, v68
	v_cvt_f16_f32_e32 v67, v69
	ds_write_b16 v174, v36 offset:4
	s_waitcnt lgkmcnt(14)
	ds_write_b16 v174, v37 offset:44
	s_waitcnt lgkmcnt(14)
	ds_write_b16 v174, v66 offset:5124
	s_waitcnt lgkmcnt(14)
	ds_write_b16 v174, v67 offset:5164
	s_nop 0
	s_waitcnt lgkmcnt(9)
	ds_write_b16 v174, v80 offset:10244
	v_lshl_add_u32 v70, v184, 1, v2
	s_nop 0
	s_nop 0
	ds_read_b32 v78, v70 offset:32768
	v_rcp_f32_e32 v66, v60
	v_rcp_f32_e32 v67, v61
	s_nop 0
	s_waitcnt lgkmcnt(10)
	v_cvt_f32_f16_e32 v72, v147
	v_cvt_f32_f16_sdwa v73, v147 dst_sel:DWORD dst_unused:UNUSED_PAD src0_sel:WORD_1
	s_nop 0
	s_waitcnt lgkmcnt(9)
	v_cvt_f32_f16_e32 v76, v149
	v_cvt_f32_f16_sdwa v77, v149 dst_sel:DWORD dst_unused:UNUSED_PAD src0_sel:WORD_1
	v_cvt_f32_f16_e32 v70, v146
	v_cvt_f32_f16_e32 v74, v148
	v_cvt_f32_f16_sdwa v75, v148 dst_sel:DWORD dst_unused:UNUSED_PAD src0_sel:WORD_1
	v_cvt_f32_f16_sdwa v71, v146 dst_sel:DWORD dst_unused:UNUSED_PAD src0_sel:WORD_1
	v_pk_mul_f32 v[36:37], v[64:65], v[72:73]
	v_pk_mul_f32 v[64:65], v[60:61], v[76:77]
	v_pk_mul_f32 v[68:69], v[66:67], v[74:75]
	v_pk_mul_f32 v[66:67], v[66:67], v[70:71]
	v_pk_mul_f32 v[70:71], v[40:41], v[36:37]
	v_pk_mul_f32 v[72:73], v[40:41], v[64:65]
	v_cvt_pk_f16_f32 v36, v36, v37
	v_cvt_pk_f16_f32 v37, v64, v65
	v_pk_mul_f32 v[74:75], v[38:39], v[68:69]
	v_pk_mul_f32 v[76:77], v[38:39], v[66:67]
	ds_write2st64_b32 v185, v36, v37 offset1:18
	v_cvt_pk_f16_f32 v36, v70, v71
	v_cvt_pk_f16_f32 v37, v72, v73
	v_pk_mul_f32 v[68:69], v[0:1], v[68:69]
	ds_write2st64_b32 v185, v36, v37 offset0:36 offset1:54
	v_cvt_pk_f16_f32 v36, v74, v75
	v_cvt_pk_f16_f32 v37, v76, v77
	ds_write2st64_b32 v185, v36, v37 offset0:72 offset1:90
	v_cvt_f16_f32_e32 v36, v68
	v_pk_mul_f32 v[66:67], v[0:1], v[66:67]
	v_cvt_f16_f32_e32 v37, v69
	v_cvt_f16_f32_e32 v64, v66
	v_cvt_f16_f32_e32 v65, v67
	ds_write_b16 v174, v36 offset:6
	ds_write_b16 v174, v37 offset:46
	ds_write_b16 v174, v64 offset:5126
	s_waitcnt lgkmcnt(14)
	ds_write_b16 v174, v65 offset:5166
	s_nop 0
	s_waitcnt lgkmcnt(7)
	ds_write_b16 v174, v78 offset:10246
	v_perm_b32 v36, v82, v84, s82
	v_perm_b32 v37, v78, v80, s82
	ds_write_b64 v174, v[36:37] offset:10280

.LBB0_462:
	s_or_b64 exec, exec, s[26:27]
	s_waitcnt lgkmcnt(0)
	s_barrier
	ds_read_b128 v[40:43], v210 offset:9216
	ds_read_b128 v[48:51], v210 offset:18496
	ds_read_b128 v[56:59], v210 offset:9280
	ds_read_b128 v[60:63], v210 offset:23040
	ds_read_b128 v[36:39], v210 offset:18432
	s_nop 0
	s_nop 0
	s_nop 0
	ds_read_b128 v[64:67], v210 offset:13824
	s_waitcnt lgkmcnt(1)
	v_mfma_f32_16x16x32_f16 v[52:55], v[40:43], v[36:39], 0
	s_nop 0
	s_nop 0
	s_nop 0
	ds_read_b128 v[68:71], v210 offset:13888
	ds_read_b128 v[72:75], v210 offset:23104
	v_add_u32_e32 v80, 0x1000, v215
	s_nop 0
	v_mfma_f32_16x16x32_f16 v[52:55], v[56:59], v[48:51], v[52:55]
	v_mov_b32_e32 v82, v3
	v_mov_b32_e32 v83, v3
	v_mov_b32_e32 v86, v3
	v_mfma_f32_16x16x32_f16 v[44:47], v[36:39], v[40:43], 0
	s_nop 3
	v_cvt_f16_f32_e32 v0, v52
	v_cvt_f16_f32_e32 v1, v54
	v_cvt_f16_f32_e32 v2, v55
	v_mfma_f32_16x16x32_f16 v[44:47], v[48:51], v[56:59], v[44:47]
	v_cndmask_b32_e64 v79, 0, v0, s[12:13]
	v_cvt_f16_f32_e32 v0, v53
	v_cndmask_b32_e64 v54, 0, v1, s[18:19]
	s_nop 0
	v_mfma_f32_16x16x32_f16 v[40:43], v[60:63], v[40:43], 0
	v_cndmask_b32_e64 v55, 0, v2, s[22:23]
	s_nop 1
	v_cndmask_b32_e64 v76, 0, v44, s[10:11]
	v_cndmask_b32_e64 v77, 0, v45, s[14:15]
	s_nop 0
	s_waitcnt lgkmcnt(2)
	v_mfma_f32_16x16x32_f16 v[36:39], v[36:39], v[64:67], 0
	v_cndmask_b32_e64 v52, 0, v46, s[16:17]
	v_cndmask_b32_e64 v78, 0, v47, s[20:21]
	v_cndmask_b32_e64 v53, v0, 0, s[10:11]
	v_mfma_f32_16x16x32_f16 v[44:47], v[60:63], v[64:67], 0
	v_cvt_pk_f16_f32 v1, v52, v78
	v_cvt_pk_f16_f32 v0, v76, v77
	v_mov_b32_e32 v2, v3
	s_nop 0
	s_waitcnt lgkmcnt(0)
	v_mfma_f32_16x16x32_f16 v[60:63], v[72:75], v[56:59], v[40:43]
	v_add_f32_e32 v56, v211, v76
	v_add_f32_e32 v57, v212, v77
	v_add_f32_e32 v58, v213, v52
	v_mfma_f32_16x16x32_f16 v[40:43], v[48:51], v[68:71], v[36:39]
	v_add_f32_e32 v59, v214, v78
	v_cvt_pk_f16_f32 v67, v18, v19
	v_cvt_pk_f16_f32 v66, v16, v17
	v_pack_b32_f16 v37, v54, v55
	v_pack_b32_f16 v36, v79, v53
	v_mov_b32_e32 v38, v3
	v_mov_b32_e32 v39, v3
	v_mfma_f32_16x16x32_f16 v[52:55], v[72:75], v[68:71], v[44:47]
	ds_read2_b64 v[68:71], v215 offset0:8 offset1:12
	v_cvt_pk_f16_f32 v65, v14, v15
	v_cvt_pk_f16_f32 v64, v12, v13
	v_mfma_f32_16x16x32_f16 v[48:51], v[0:3], v[36:39], 0
	v_cvt_pk_f16_f32 v45, v58, v59
	v_cvt_pk_f16_f32 v44, v56, v57
	v_mov_b32_e32 v46, v3
	v_mfma_f32_16x16x32_f16 v[36:39], v[36:39], v[0:3], 0
	v_mov_b32_e32 v47, v3
	s_nop 2
	v_cvt_pk_f16_f32 v1, v50, v51
	v_cvt_pk_f16_f32 v0, v48, v49
	v_mov_b32_e32 v50, v3
	v_mov_b32_e32 v51, v3
	v_cvt_pk_f16_f32 v49, v38, v39
	v_cvt_pk_f16_f32 v48, v36, v37
	v_mfma_f32_16x16x32_f16 v[44:47], v[0:3], v[44:47], v[56:59]
	v_mov_b32_e32 v87, v3
	v_mov_b32_e32 v90, v3
	v_mov_b32_e32 v91, v3
	v_mfma_f32_16x16x32_f16 v[36:39], v[48:51], v[0:3], 0
	ds_read2_b64 v[126:129], v215 offset1:4
	v_cvt_pk_f16_f32 v59, v10, v11
	v_cvt_pk_f16_f32 v58, v8, v9
	v_cvt_pk_f16_f32 v57, v6, v7
	v_mfma_f32_16x16x32_f16 v[48:51], v[0:3], v[48:51], 0
	v_cvt_pk_f16_f32 v56, v4, v5
	s_nop 2
	v_cvt_pk_f16_f32 v1, v38, v39
	v_cvt_pk_f16_f32 v0, v36, v37
	v_cvt_pk_f16_f32 v37, v46, v47
	v_cvt_pk_f16_f32 v36, v44, v45
	v_mov_b32_e32 v38, v3
	v_mov_b32_e32 v39, v3
	v_cvt_f16_f32_e32 v52, v52
	s_add_i32 s28, s76, 1
	v_mfma_f32_16x16x32_f16 v[44:47], v[0:3], v[36:39], v[44:47]
	v_cvt_pk_f16_f32 v37, v50, v51
	v_cvt_pk_f16_f32 v36, v48, v49
	v_mov_b32_e32 v50, v3
	v_mov_b32_e32 v51, v3
	v_mfma_f32_16x16x32_f16 v[36:39], v[36:39], v[0:3], 0
	s_nop 2
	v_cvt_pk_f16_f32 v1, v46, v47
	v_cvt_pk_f16_f32 v0, v44, v45
	s_nop 2
	v_cvt_pk_f16_f32 v49, v38, v39
	v_cvt_pk_f16_f32 v48, v36, v37
	s_nop 0
	s_nop 0
	s_waitcnt lgkmcnt(0)
	v_mfma_f32_16x16x32_f16 v[36:39], v[126:129], v[56:59], 0
	v_mfma_f32_16x16x32_f16 v[44:47], v[48:51], v[0:3], v[44:47]
	v_cvt_f16_f32_e32 v0, v60
	v_cvt_f16_f32_e32 v1, v61
	v_cvt_f16_f32_e32 v2, v62
	v_cvt_f16_f32_e32 v48, v63
	v_mfma_f32_16x16x32_f16 v[76:79], v[68:71], v[64:67], v[36:39]
	ds_read2_b64 v[72:75], v80 offset0:64 offset1:68
	ds_read2st64_b64 v[130:133], v216 offset0:20 offset1:25
	ds_read2_b64 v[68:71], v80 offset0:72 offset1:76
	s_nop 0
	s_nop 0
	v_cndmask_b32_e64 v0, 0, v0, s[10:11]
	v_cndmask_b32_e64 v49, 0, v1, s[14:15]
	v_cndmask_b32_e64 v1, 0, v2, s[16:17]
	v_cndmask_b32_e64 v2, 0, v48, s[20:21]
	v_pack_b32_f16 v1, v1, v2
	v_pack_b32_f16 v0, v0, v49
	v_mov_b32_e32 v2, v3
	s_nop 0
	s_waitcnt lgkmcnt(1)
	v_mov_b32_e32 v60, v130
	v_mov_b32_e32 v61, v131
	ds_read2_b64 v[126:129], v231 offset1:80
	v_mov_b32_e32 v62, v3
	v_mov_b32_e32 v63, v3
	v_cvt_f16_f32_e32 v36, v40
	ds_read_b128 v[134:137], v176
	v_cvt_f16_f32_e32 v40, v42
	v_mfma_f32_16x16x32_f16 v[48:51], v[0:3], v[60:63], v[76:79]
	v_cvt_pk_f16_f32 v1, v46, v47
	v_cvt_pk_f16_f32 v0, v44, v45
	v_cvt_f16_f32_e32 v37, v41
	v_mov_b32_e32 v78, v3
	v_mov_b32_e32 v79, v3
	s_nop 2
	v_cvt_pk_f16_f32 v77, v50, v51
	v_cvt_pk_f16_f32 v76, v48, v49
	v_cndmask_b32_e64 v88, v40, 0, s[18:19]
	v_mfma_f32_16x16x32_f16 v[56:59], v[72:75], v[56:59], 0
	v_cndmask_b32_e64 v36, v36, 0, s[12:13]
	v_cndmask_b32_e64 v37, 0, v37, s[10:11]
	v_mov_b32_e32 v74, v3
	v_mfma_f32_16x16x32_f16 v[44:47], v[0:3], v[76:79], 0
	ds_read_b64 v[76:77], v217 offset:5120
	ds_read_b128 v[138:141], v176 offset:64
	v_mov_b32_e32 v75, v3
	s_waitcnt lgkmcnt(4)
	v_mfma_f32_16x16x32_f16 v[56:59], v[68:71], v[64:67], v[56:59]
	s_nop 5
	v_cvt_pk_f16_f32 v1, v46, v47
	v_cvt_pk_f16_f32 v0, v44, v45
	s_nop 0
	s_nop 0
	s_nop 0
	s_nop 0
	s_waitcnt lgkmcnt(3)
	v_mov_b32_e32 v80, v126
	v_mov_b32_e32 v81, v127
	ds_read_b64 v[44:45], v218 offset:5120
	ds_read2_b64 v[142:145], v231 offset0:160 offset1:240
	s_nop 0
	s_waitcnt lgkmcnt(4)
	v_pk_mul_f32 v[50:51], v[6:7], v[136:137]
	v_pk_mul_f32 v[48:49], v[4:5], v[134:135]
	ds_read_b128 v[134:137], v176 offset:128
	s_nop 1
	v_mfma_f32_16x16x32_f16 v[48:51], v[80:83], v[0:3], v[48:51]
	v_cvt_f16_f32_e32 v80, v43
	v_cndmask_b32_e64 v89, v80, 0, s[22:23]
	s_nop 0
	s_waitcnt lgkmcnt(4)
	v_mfma_f32_16x16x32_f16 v[40:43], v[76:79], v[60:63], v[48:51]
	s_nop 3
	s_nop 0
	s_nop 0
	ds_read_b64 v[80:81], v219 offset:5120
	v_mov_b32_e32 v76, v128
	v_mov_b32_e32 v77, v129
	v_mov_b32_e32 v46, v3
	s_nop 0
	s_waitcnt lgkmcnt(4)
	v_pk_mul_f32 v[50:51], v[10:11], v[140:141]
	v_pk_mul_f32 v[48:49], v[8:9], v[138:139]
	v_mov_b32_e32 v47, v3
	ds_read_b128 v[126:129], v176 offset:192
	s_nop 0
	v_mfma_f32_16x16x32_f16 v[48:51], v[76:79], v[0:3], v[48:51]
	s_nop 0
	s_nop 0
	s_waitcnt lgkmcnt(3)
	v_mov_b32_e32 v84, v142
	v_mfma_f32_16x16x32_f16 v[48:51], v[44:47], v[60:63], v[48:51]
	s_nop 0
	s_nop 0
	v_mov_b32_e32 v85, v143
	v_pack_b32_f16 v77, v88, v89
	v_mov_b32_e32 v88, v144
	s_nop 0
	s_waitcnt lgkmcnt(2)
	v_pk_mul_f32 v[46:47], v[14:15], v[136:137]
	v_pk_mul_f32 v[44:45], v[12:13], v[134:135]
	v_mov_b32_e32 v89, v145
	v_pack_b32_f16 v76, v36, v37
	v_mfma_f32_16x16x32_f16 v[44:47], v[84:87], v[0:3], v[44:47]
	ds_read_b64 v[84:85], v220 offset:5120
	v_cndmask_b32_e64 v36, v52, 0, s[12:13]
	v_cvt_f16_f32_e32 v37, v53
	v_cndmask_b32_e64 v37, 0, v37, s[10:11]
	s_nop 0
	s_waitcnt lgkmcnt(2)
	v_mfma_f32_16x16x32_f16 v[44:47], v[80:83], v[60:63], v[44:47]
	s_nop 0
	s_nop 0
	v_pack_b32_f16 v72, v36, v37
	ds_read_b128 v[68:71], v221 offset:9216
	ds_read_b128 v[94:97], v221 offset:9280
	s_nop 0
	s_waitcnt lgkmcnt(3)
	v_pk_mul_f32 v[82:83], v[18:19], v[128:129]
	ds_read_b128 v[64:67], v221 offset:18432
	v_pk_mul_f32 v[80:81], v[16:17], v[126:127]
	s_nop 0
	ds_read_b128 v[98:101], v221 offset:23104
	v_mfma_f32_16x16x32_f16 v[78:81], v[88:91], v[0:3], v[80:83]
	ds_read_b128 v[90:93], v221 offset:18496
	s_nop 1
	v_cvt_f16_f32_e32 v82, v54
	v_cvt_f16_f32_e32 v83, v55
	s_nop 0
	s_waitcnt lgkmcnt(5)
	v_mfma_f32_16x16x32_f16 v[52:55], v[84:87], v[60:63], v[78:81]
	ds_read_b128 v[86:89], v221 offset:13824
	s_nop 1
	v_cndmask_b32_e64 v78, v82, 0, s[18:19]
	v_cndmask_b32_e64 v79, v83, 0, s[22:23]
	v_pack_b32_f16 v73, v78, v79
	v_mov_b32_e32 v78, v3
	v_mov_b32_e32 v79, v3
	v_add_u32_e32 v80, s71, v153
	v_add_u32_e32 v81, s70, v230
	v_mfma_f32_16x16x32_f16 v[56:59], v[76:79], v[0:3], v[56:59]
	ds_read_b128 v[76:79], v221 offset:23040
	v_subrev_u32_e32 v102, 64, v80
	v_add_u32_e32 v0, 0x7ff, v81
	v_mfma_f32_16x16x32_f16 v[58:61], v[72:75], v[60:63], v[56:59]
	v_cndmask_b32_e64 v0, v0, v102, s[2:3]
	v_add_u32_e32 v0, v0, v151
	v_mad_i64_i32 v[0:1], s[26:27], v0, s91, v[122:123]
	s_nop 0
	s_waitcnt lgkmcnt(4)
	v_mfma_f32_16x16x32_f16 v[82:85], v[68:71], v[64:67], 0
	s_nop 2
	v_cvt_f16_f32_e32 v2, v58
	v_cvt_f16_f32_e32 v60, v60
	ds_read_b128 v[126:129], v221 offset:13888
	global_store_short v[0:1], v2, off
	v_subrev_u32_e32 v0, 63, v80
	v_xad_u32 v1, v102, -2, v170
	v_cvt_f16_f32_e32 v2, v59
	s_nop 0
	v_mfma_f32_16x16x32_f16 v[72:75], v[64:67], v[68:71], 0
	v_cndmask_b32_e64 v0, v1, v0, s[2:3]
	v_add_u32_e32 v0, v0, v151
	v_mad_i64_i32 v[0:1], s[26:27], v0, s91, v[122:123]
	s_nop 0
	s_waitcnt lgkmcnt(2)
	v_mfma_f32_16x16x32_f16 v[62:65], v[64:67], v[86:89], 0
	global_store_short v[0:1], v2, off
	v_subrev_u32_e32 v0, 62, v80
	v_xad_u32 v1, v102, -3, v170
	v_mfma_f32_16x16x32_f16 v[82:85], v[94:97], v[90:93], v[82:85]
	v_cndmask_b32_e64 v36, v1, v0, s[2:3]
	v_add_u32_e32 v36, v36, v151
	s_nop 0
	s_waitcnt lgkmcnt(1)
	v_mfma_f32_16x16x32_f16 v[68:71], v[76:79], v[68:71], 0
	v_mfma_f32_16x16x32_f16 v[86:89], v[76:79], v[86:89], 0
	s_nop 2
	v_cvt_f16_f32_e32 v1, v82
	v_cvt_f16_f32_e32 v2, v83
	v_cvt_f16_f32_e32 v66, v85
	v_mfma_f32_16x16x32_f16 v[72:75], v[90:93], v[94:97], v[72:75]
	v_mov_b32_e32 v85, v3
	v_cndmask_b32_e64 v66, 0, v66, s[22:23]
	s_nop 0
	s_waitcnt lgkmcnt(0)
	v_mfma_f32_16x16x32_f16 v[76:79], v[90:93], v[126:129], v[62:65]
	v_mov_b32_e32 v92, v3
	s_nop 2
	v_cndmask_b32_e64 v0, 0, v72, s[10:11]
	v_cndmask_b32_e64 v37, 0, v73, s[14:15]
	v_cvt_f16_f32_e32 v63, v84
	v_mfma_f32_16x16x32_f16 v[94:97], v[98:101], v[94:97], v[68:71]
	v_cndmask_b32_e64 v64, 0, v74, s[16:17]
	v_cndmask_b32_e64 v65, 0, v75, s[20:21]
	v_cndmask_b32_e64 v63, 0, v63, s[18:19]
	v_cndmask_b32_e64 v68, 0, v1, s[12:13]
	v_cndmask_b32_e64 v69, v2, 0, s[10:11]
	v_add_f32_e32 v62, v211, v0
	v_cvt_pk_f16_f32 v1, v64, v65
	v_cvt_pk_f16_f32 v0, v0, v37
	v_mov_b32_e32 v2, v3
	v_pack_b32_f16 v67, v63, v66
	v_pack_b32_f16 v66, v68, v69
	v_mov_b32_e32 v68, v3
	v_mov_b32_e32 v69, v3
	v_add_f32_e32 v63, v212, v37
	v_add_f32_e32 v64, v213, v64
	v_mfma_f32_16x16x32_f16 v[70:73], v[0:3], v[66:69], 0
	v_add_f32_e32 v65, v214, v65
	v_cvt_pk_f16_f32 v83, v64, v65
	v_cvt_pk_f16_f32 v82, v62, v63
	v_mfma_f32_16x16x32_f16 v[66:69], v[66:69], v[0:3], 0
	v_mov_b32_e32 v84, v3
	s_nop 2
	v_cvt_pk_f16_f32 v0, v70, v71
	v_mov_b32_e32 v70, v3
	v_mov_b32_e32 v71, v3
	v_cvt_pk_f16_f32 v1, v72, v73
	v_cvt_pk_f16_f32 v69, v68, v69
	v_cvt_pk_f16_f32 v68, v66, v67
	v_mfma_f32_16x16x32_f16 v[62:65], v[0:3], v[82:85], v[62:65]
	v_mad_i64_i32 v[36:37], s[26:27], v36, s91, v[122:123]
	global_store_short v[36:37], v60, off
	v_mfma_f32_16x16x32_f16 v[72:75], v[68:71], v[0:3], 0
	v_cvt_f16_f32_e32 v82, v61
	v_subrev_u32_e32 v36, 61, v80
	v_xad_u32 v37, v102, -4, v170
	v_mfma_f32_16x16x32_f16 v[66:69], v[0:3], v[68:71], 0
	s_nop 0
	v_cvt_pk_f16_f32 v71, v64, v65
	s_nop 1
	v_cvt_pk_f16_f32 v1, v74, v75
	v_cvt_pk_f16_f32 v0, v72, v73
	ds_read2_b64 v[134:137], v222 offset1:4
	v_mfma_f32_16x16x32_f16 v[56:59], v[98:101], v[126:129], v[86:89]
	v_cvt_pk_f16_f32 v70, v62, v63
	v_mov_b32_e32 v72, v3
	v_mov_b32_e32 v73, v3
	v_cvt_pk_f16_f32 v85, v68, v69
	ds_read2_b64 v[126:129], v222 offset0:8 offset1:12
	v_cvt_pk_f16_f32 v84, v66, v67
	v_mov_b32_e32 v86, v3
	v_mov_b32_e32 v87, v3
	v_mfma_f32_16x16x32_f16 v[88:91], v[0:3], v[70:73], v[62:65]
	s_nop 0
	s_nop 0
	v_cndmask_b32_e64 v36, v37, v36, s[2:3]
	v_mfma_f32_16x16x32_f16 v[60:63], v[84:87], v[0:3], 0
	v_add_u32_e32 v83, v36, v151
	s_nop 2
	v_cvt_pk_f16_f32 v1, v90, v91
	v_cvt_pk_f16_f32 v0, v88, v89
	v_cvt_pk_f16_f32 v67, v54, v55
	v_cvt_pk_f16_f32 v66, v52, v53
	v_cvt_pk_f16_f32 v85, v62, v63
	v_cvt_pk_f16_f32 v84, v60, v61
	v_cvt_pk_f16_f32 v63, v50, v51
	v_cvt_pk_f16_f32 v62, v48, v49
	v_cvt_pk_f16_f32 v61, v42, v43
	v_cvt_pk_f16_f32 v60, v40, v41
	v_cvt_pk_f16_f32 v65, v46, v47
	v_cvt_pk_f16_f32 v64, v44, v45
	s_nop 0
	s_waitcnt lgkmcnt(1)
	v_mfma_f32_16x16x32_f16 v[68:71], v[134:137], v[60:63], 0
	v_add_u32_e32 v36, 0x1000, v222
	v_mov_b32_e32 v93, v3
	v_cvt_f16_f32_e32 v76, v76
	s_nop 0
	s_waitcnt lgkmcnt(0)
	v_mfma_f32_16x16x32_f16 v[98:101], v[126:129], v[64:67], v[68:71]
	ds_read2_b64 v[72:75], v36 offset0:64 offset1:68
	s_nop 1
	ds_read2_b64 v[68:71], v36 offset0:72 offset1:76
	v_cvt_f16_f32_e32 v36, v97
	v_cvt_f16_f32_e32 v97, v77
	v_mfma_f32_16x16x32_f16 v[84:87], v[84:87], v[0:3], v[88:91]
	v_cvt_f16_f32_e32 v0, v94
	v_cvt_f16_f32_e32 v1, v95
	v_cvt_f16_f32_e32 v2, v96
	v_cndmask_b32_e64 v96, v76, 0, s[12:13]
	v_cndmask_b32_e64 v0, 0, v0, s[10:11]
	v_cndmask_b32_e64 v37, 0, v1, s[14:15]
	v_cndmask_b32_e64 v1, 0, v2, s[16:17]
	v_cndmask_b32_e64 v2, 0, v36, s[20:21]
	v_pack_b32_f16 v1, v1, v2
	v_pack_b32_f16 v0, v0, v37
	v_mov_b32_e32 v2, v3
	v_mov_b32_e32 v36, v132
	v_mov_b32_e32 v37, v133
	v_add_u32_e32 v253, 0x800, v231
	ds_read2_b64 v[126:129], v253 offset0:64 offset1:144
	v_mov_b32_e32 v38, v3
	v_mov_b32_e32 v39, v3
	v_mov_b32_e32 v94, v3
	ds_read_b128 v[130:133], v176 offset:256
	v_mov_b32_e32 v95, v3
	v_mfma_f32_16x16x32_f16 v[88:91], v[0:3], v[36:39], v[98:101]
	v_cvt_pk_f16_f32 v1, v86, v87
	v_cvt_pk_f16_f32 v0, v84, v85
	v_cvt_f16_f32_e32 v56, v56
	v_cvt_f16_f32_e32 v98, v78
	v_cvt_f16_f32_e32 v99, v79
	s_nop 2
	v_cvt_pk_f16_f32 v91, v90, v91
	v_cvt_pk_f16_f32 v90, v88, v89
	v_cndmask_b32_e64 v97, 0, v97, s[10:11]
	v_cndmask_b32_e64 v98, v98, 0, s[18:19]
	v_mfma_f32_16x16x32_f16 v[84:87], v[0:3], v[90:93], 0
	v_add_u32_e32 v2, 0x800, v231
	v_mov_b32_e32 v90, v3
	v_mov_b32_e32 v91, v3
	v_cndmask_b32_e64 v99, v99, 0, s[22:23]
	ds_read_b64 v[88:89], v223 offset:5120
	ds_read_b128 v[134:137], v176 offset:320
	s_nop 3
	v_cvt_pk_f16_f32 v1, v86, v87
	v_cvt_pk_f16_f32 v0, v84, v85
	s_nop 0
	s_nop 0
	s_nop 0
	v_mov_b32_e32 v2, v3
	s_nop 0
	s_waitcnt lgkmcnt(3)
	v_mov_b32_e32 v92, v126
	v_mov_b32_e32 v93, v127
	v_add_u32_e32 v253, 0xc00, v231
	ds_read_b64 v[84:85], v224 offset:5120
	ds_read2_b64 v[138:141], v253 offset0:96 offset1:176
	ds_read_b128 v[142:145], v176 offset:384
	s_nop 0
	s_waitcnt lgkmcnt(5)
	v_pk_mul_f32 v[42:43], v[42:43], v[132:133]
	v_pk_mul_f32 v[40:41], v[40:41], v[130:131]
	s_nop 0
	s_nop 0
	v_mfma_f32_16x16x32_f16 v[40:43], v[92:95], v[0:3], v[40:43]
	s_nop 0
	s_waitcnt lgkmcnt(3)
	v_pk_mul_f32 v[48:49], v[48:49], v[134:135]
	v_add_u32_e32 v76, 0xc00, v231
	v_mfma_f32_16x16x32_f16 v[40:43], v[88:91], v[36:39], v[40:43]
	v_mov_b32_e32 v88, v128
	v_mov_b32_e32 v89, v129
	v_pk_mul_f32 v[50:51], v[50:51], v[136:137]
	v_mov_b32_e32 v86, v3
	v_mov_b32_e32 v87, v3
	s_nop 0
	v_mfma_f32_16x16x32_f16 v[48:51], v[88:91], v[0:3], v[48:51]
	ds_read_b64 v[88:89], v225 offset:5120
	s_nop 0
	s_waitcnt lgkmcnt(2)
	v_mov_b32_e32 v92, v138
	v_mfma_f32_16x16x32_f16 v[48:51], v[84:87], v[36:39], v[48:51]
	s_nop 0
	s_nop 0
	v_mov_b32_e32 v93, v139
	v_pack_b32_f16 v76, v96, v97
	v_cndmask_b32_e64 v96, v56, 0, s[12:13]
	s_nop 0
	s_waitcnt lgkmcnt(1)
	v_pk_mul_f32 v[46:47], v[46:47], v[144:145]
	v_pk_mul_f32 v[44:45], v[44:45], v[142:143]
	ds_read_b128 v[84:87], v176 offset:448
	v_cvt_f16_f32_e32 v56, v57
	v_cvt_f16_f32_e32 v57, v58
	v_mfma_f32_16x16x32_f16 v[44:47], v[92:95], v[0:3], v[44:47]
	v_cvt_f16_f32_e32 v58, v59
	v_mov_b32_e32 v92, v140
	v_mov_b32_e32 v93, v141
	s_nop 0
	s_waitcnt lgkmcnt(1)
	v_mfma_f32_16x16x32_f16 v[44:47], v[88:91], v[36:39], v[44:47]
	ds_read_b64 v[88:89], v226 offset:5120
	s_nop 0
	s_nop 0
	v_cndmask_b32_e64 v78, v57, 0, s[18:19]
	v_cndmask_b32_e64 v79, v58, 0, s[22:23]
	v_pack_b32_f16 v77, v98, v99
	s_nop 0
	s_waitcnt lgkmcnt(1)
	v_pk_mul_f32 v[52:53], v[52:53], v[84:85]
	v_cndmask_b32_e64 v84, 0, v56, s[10:11]
	v_mfma_f32_16x16x32_f16 v[56:59], v[72:75], v[60:63], 0
	v_pack_b32_f16 v61, v78, v79
	v_mov_b32_e32 v78, v3
	v_mov_b32_e32 v79, v3
	v_mfma_f32_16x16x32_f16 v[56:59], v[68:71], v[64:67], v[56:59]
	v_mul_f32_e64 v54, v54, v86
	v_mul_f32_e64 v55, v55, v87
	v_pack_b32_f16 v60, v96, v84
	v_mov_b32_e32 v62, v3
	v_mov_b32_e32 v63, v3
	v_mfma_f32_16x16x32_f16 v[52:55], v[92:95], v[0:3], v[52:55]
	v_mfma_f32_16x16x32_f16 v[56:59], v[76:79], v[0:3], v[56:59]
	v_mad_i64_i32 v[0:1], s[26:27], v83, s91, v[122:123]
	global_store_short v[0:1], v82, off
	s_nop 0
	s_waitcnt lgkmcnt(0)
	v_mfma_f32_16x16x32_f16 v[52:55], v[88:91], v[36:39], v[52:55]
	v_subrev_u32_e32 v0, 48, v80
	v_add_u32_e32 v1, 0x7ef, v81
	v_cndmask_b32_e64 v0, v1, v0, s[2:3]
	v_mfma_f32_16x16x32_f16 v[36:39], v[60:63], v[36:39], v[56:59]
	v_add_u32_e32 v0, v0, v151
	v_mad_i64_i32 v[0:1], s[26:27], v0, s91, v[122:123]
	s_nop 5
	v_cvt_f16_f32_e32 v2, v36
	global_store_short v[0:1], v2, off
	v_subrev_u32_e32 v0, 47, v80
	v_add_u32_e32 v1, 0x7ee, v81
	v_cvt_f16_f32_e32 v2, v37
	v_cndmask_b32_e64 v0, v1, v0, s[2:3]
	v_add_u32_e32 v0, v0, v151
	v_mad_i64_i32 v[0:1], s[26:27], v0, s91, v[122:123]
	global_store_short v[0:1], v2, off
	v_subrev_u32_e32 v0, 46, v80
	v_add_u32_e32 v1, 0x7ed, v81
	v_cvt_f16_f32_e32 v2, v38
	v_cndmask_b32_e64 v0, v1, v0, s[2:3]
	v_add_u32_e32 v0, v0, v151
	v_mad_i64_i32 v[0:1], s[26:27], v0, s91, v[122:123]
	global_store_short v[0:1], v2, off
	v_subrev_u32_e32 v0, 45, v80
	v_add_u32_e32 v1, 0x7ec, v81
	v_cndmask_b32_e64 v0, v1, v0, s[2:3]
	v_cvt_f16_f32_e32 v2, v39
	v_add_u32_e32 v0, v0, v151
	v_mad_i64_i32 v[0:1], s[26:27], v0, s91, v[122:123]
	s_mov_b64 s[26:27], 0
	global_store_short v[0:1], v2, off

.LBB0_468:
	v_cmp_lt_i32_e32 vcc, 2, v172
	s_and_saveexec_b64 s[28:29], vcc
	s_xor_b64 s[28:29], exec, s[28:29]
	s_cbranch_execz .LBB0_470
	v_lshl_add_u32 v252, v202, 1, v2
	ds_read2st64_b32 v[36:37], v252 offset0:64 offset1:80
	ds_read2st64_b32 v[46:47], v252 offset0:96 offset1:112
	v_lshl_add_u32 v48, v202, 1, v2
	s_nop 0
	s_nop 0
	ds_read_b32 v60, v48 offset:32768
	v_rcp_f32_e32 v44, v62
	v_rcp_f32_e32 v45, v63
	s_nop 0
	s_waitcnt lgkmcnt(1)
	v_cvt_f32_f16_e32 v58, v47
	v_cvt_f32_f16_e32 v50, v37
	v_cvt_f32_f16_sdwa v51, v37 dst_sel:DWORD dst_unused:UNUSED_PAD src0_sel:WORD_1
	v_cvt_f32_f16_sdwa v59, v47 dst_sel:DWORD dst_unused:UNUSED_PAD src0_sel:WORD_1
	v_lshl_add_u32 v252, v204, 1, v2
	ds_read2st64_b32 v[146:147], v252 offset0:64 offset1:80
	v_cvt_f32_f16_e32 v48, v36
	v_cvt_f32_f16_e32 v54, v46
	v_cvt_f32_f16_sdwa v55, v46 dst_sel:DWORD dst_unused:UNUSED_PAD src0_sel:WORD_1
	ds_read2st64_b32 v[148:149], v252 offset0:96 offset1:112
	v_cvt_f32_f16_sdwa v49, v36 dst_sel:DWORD dst_unused:UNUSED_PAD src0_sel:WORD_1
	v_pk_mul_f32 v[36:37], v[42:43], v[50:51]
	v_pk_mul_f32 v[42:43], v[62:63], v[58:59]
	v_pk_mul_f32 v[46:47], v[44:45], v[54:55]
	v_pk_mul_f32 v[44:45], v[44:45], v[48:49]
	v_pk_mul_f32 v[48:49], v[40:41], v[36:37]
	v_pk_mul_f32 v[50:51], v[40:41], v[42:43]
	v_cvt_pk_f16_f32 v36, v36, v37
	v_cvt_pk_f16_f32 v37, v42, v43
	v_pk_mul_f32 v[54:55], v[38:39], v[46:47]
	v_pk_mul_f32 v[58:59], v[38:39], v[44:45]
	ds_write2st64_b32 v203, v36, v37 offset1:18
	v_cvt_pk_f16_f32 v36, v48, v49
	v_cvt_pk_f16_f32 v37, v50, v51
	v_pk_mul_f32 v[46:47], v[0:1], v[46:47]
	ds_write2st64_b32 v203, v36, v37 offset0:36 offset1:54
	v_cvt_pk_f16_f32 v36, v54, v55
	v_cvt_pk_f16_f32 v37, v58, v59
	ds_write2st64_b32 v203, v36, v37 offset0:72 offset1:90
	v_cvt_f16_f32_e32 v36, v46
	v_pk_mul_f32 v[44:45], v[0:1], v[44:45]
	v_cvt_f16_f32_e32 v37, v47
	v_cvt_f16_f32_e32 v42, v44
	v_cvt_f16_f32_e32 v43, v45
	ds_write_b16 v174, v36 offset:24
	ds_write_b16 v174, v37 offset:64
	ds_write_b16 v174, v42 offset:5144
	ds_write_b16 v174, v43 offset:5184
	s_nop 0
	s_waitcnt lgkmcnt(9)
	ds_write_b16 v174, v60 offset:10264
	v_lshl_add_u32 v46, v204, 1, v2
	s_nop 0
	s_nop 0
	ds_read_b32 v61, v46 offset:32768
	v_rcp_f32_e32 v42, v56
	v_rcp_f32_e32 v43, v57
	s_nop 0
	s_waitcnt lgkmcnt(10)
	v_cvt_f32_f16_e32 v48, v147
	v_cvt_f32_f16_sdwa v49, v147 dst_sel:DWORD dst_unused:UNUSED_PAD src0_sel:WORD_1
	s_nop 0
	s_waitcnt lgkmcnt(9)
	v_cvt_f32_f16_e32 v54, v149
	v_cvt_f32_f16_sdwa v55, v149 dst_sel:DWORD dst_unused:UNUSED_PAD src0_sel:WORD_1
	v_cvt_f32_f16_e32 v46, v146
	v_lshl_add_u32 v252, v206, 1, v2
	ds_read2st64_b32 v[232:233], v252 offset0:64 offset1:80
	v_cvt_f32_f16_e32 v50, v148
	v_cvt_f32_f16_sdwa v51, v148 dst_sel:DWORD dst_unused:UNUSED_PAD src0_sel:WORD_1
	v_cvt_f32_f16_sdwa v47, v146 dst_sel:DWORD dst_unused:UNUSED_PAD src0_sel:WORD_1
	ds_read2st64_b32 v[146:147], v252 offset0:96 offset1:112
	v_pk_mul_f32 v[36:37], v[62:63], v[48:49]
	v_pk_mul_f32 v[44:45], v[56:57], v[54:55]
	v_pk_mul_f32 v[48:49], v[42:43], v[50:51]
	v_pk_mul_f32 v[42:43], v[42:43], v[46:47]
	v_pk_mul_f32 v[46:47], v[40:41], v[36:37]
	v_pk_mul_f32 v[50:51], v[40:41], v[44:45]
	v_cvt_pk_f16_f32 v36, v36, v37
	v_cvt_pk_f16_f32 v37, v44, v45
	v_pk_mul_f32 v[54:55], v[38:39], v[48:49]
	v_pk_mul_f32 v[58:59], v[38:39], v[42:43]
	ds_write2st64_b32 v205, v36, v37 offset1:18
	v_cvt_pk_f16_f32 v36, v46, v47
	v_cvt_pk_f16_f32 v37, v50, v51
	v_pk_mul_f32 v[48:49], v[0:1], v[48:49]
	ds_write2st64_b32 v205, v36, v37 offset0:36 offset1:54
	v_cvt_pk_f16_f32 v36, v54, v55
	v_cvt_pk_f16_f32 v37, v58, v59
	ds_write2st64_b32 v205, v36, v37 offset0:72 offset1:90
	v_cvt_f16_f32_e32 v36, v48
	v_pk_mul_f32 v[42:43], v[0:1], v[42:43]
	v_cvt_f16_f32_e32 v37, v49
	v_cvt_f16_f32_e32 v42, v42
	v_cvt_f16_f32_e32 v43, v43
	ds_write_b16 v174, v36 offset:26
	s_waitcnt lgkmcnt(14)
	ds_write_b16 v174, v37 offset:66
	s_waitcnt lgkmcnt(14)
	ds_write_b16 v174, v42 offset:5146
	s_waitcnt lgkmcnt(14)
	ds_write_b16 v174, v43 offset:5186
	s_nop 0
	s_waitcnt lgkmcnt(9)
	ds_write_b16 v174, v61 offset:10266
	v_lshl_add_u32 v46, v206, 1, v2
	s_nop 0
	s_nop 0
	ds_read_b32 v58, v46 offset:32768
	v_rcp_f32_e32 v42, v52
	v_rcp_f32_e32 v43, v53
	v_lshl_add_u32 v2, v208, 1, v2
	s_nop 0
	s_waitcnt lgkmcnt(10)
	v_cvt_f32_f16_e32 v48, v233
	v_cvt_f32_f16_sdwa v49, v233 dst_sel:DWORD dst_unused:UNUSED_PAD src0_sel:WORD_1
	s_nop 0
	s_waitcnt lgkmcnt(9)
	v_cvt_f32_f16_e32 v54, v147
	ds_read2st64_b32 v[148:149], v2 offset0:64 offset1:80
	v_cvt_f32_f16_sdwa v55, v147 dst_sel:DWORD dst_unused:UNUSED_PAD src0_sel:WORD_1
	v_cvt_f32_f16_e32 v46, v232
	v_cvt_f32_f16_e32 v50, v146
	ds_read2st64_b32 v[234:235], v2 offset0:96 offset1:112
	v_cvt_f32_f16_sdwa v51, v146 dst_sel:DWORD dst_unused:UNUSED_PAD src0_sel:WORD_1
	v_cvt_f32_f16_sdwa v47, v232 dst_sel:DWORD dst_unused:UNUSED_PAD src0_sel:WORD_1
	v_pk_mul_f32 v[36:37], v[56:57], v[48:49]
	v_pk_mul_f32 v[44:45], v[52:53], v[54:55]
	v_pk_mul_f32 v[48:49], v[42:43], v[50:51]
	v_pk_mul_f32 v[42:43], v[42:43], v[46:47]
	v_pk_mul_f32 v[46:47], v[40:41], v[36:37]
	v_pk_mul_f32 v[50:51], v[40:41], v[44:45]
	v_cvt_pk_f16_f32 v36, v36, v37
	v_cvt_pk_f16_f32 v37, v44, v45
	v_pk_mul_f32 v[54:55], v[38:39], v[48:49]
	v_pk_mul_f32 v[56:57], v[38:39], v[42:43]
	ds_write2st64_b32 v207, v36, v37 offset1:18
	v_cvt_pk_f16_f32 v36, v46, v47
	v_cvt_pk_f16_f32 v37, v50, v51
	v_pk_mul_f32 v[48:49], v[0:1], v[48:49]
	ds_write2st64_b32 v207, v36, v37 offset0:36 offset1:54
	v_cvt_pk_f16_f32 v36, v54, v55
	v_cvt_pk_f16_f32 v37, v56, v57
	ds_write2st64_b32 v207, v36, v37 offset0:72 offset1:90
	v_cvt_f16_f32_e32 v36, v48
	v_pk_mul_f32 v[42:43], v[0:1], v[42:43]
	v_cvt_f16_f32_e32 v37, v49
	v_cvt_f16_f32_e32 v42, v42
	v_cvt_f16_f32_e32 v43, v43
	ds_write_b16 v174, v36 offset:28
	s_waitcnt lgkmcnt(14)
	ds_write_b16 v174, v37 offset:68
	s_waitcnt lgkmcnt(14)
	ds_write_b16 v174, v42 offset:5148
	s_waitcnt lgkmcnt(14)
	ds_write_b16 v174, v43 offset:5188
	s_nop 0
	s_waitcnt lgkmcnt(9)
	ds_write_b16 v174, v58 offset:10268
	s_nop 0
	s_nop 0
	ds_read_b32 v2, v2 offset:32768
	v_rcp_f32_e32 v42, v0
	v_rcp_f32_e32 v43, v1
	s_nop 0
	s_waitcnt lgkmcnt(10)
	v_cvt_f32_f16_e32 v48, v149
	v_cvt_f32_f16_sdwa v49, v149 dst_sel:DWORD dst_unused:UNUSED_PAD src0_sel:WORD_1
	s_nop 0
	s_waitcnt lgkmcnt(9)
	v_cvt_f32_f16_e32 v54, v235
	v_cvt_f32_f16_sdwa v55, v235 dst_sel:DWORD dst_unused:UNUSED_PAD src0_sel:WORD_1
	v_cvt_f32_f16_e32 v46, v148
	v_cvt_f32_f16_e32 v50, v234
	v_cvt_f32_f16_sdwa v51, v234 dst_sel:DWORD dst_unused:UNUSED_PAD src0_sel:WORD_1
	v_cvt_f32_f16_sdwa v47, v148 dst_sel:DWORD dst_unused:UNUSED_PAD src0_sel:WORD_1
	v_pk_mul_f32 v[36:37], v[52:53], v[48:49]
	v_pk_mul_f32 v[44:45], v[0:1], v[54:55]
	v_pk_mul_f32 v[48:49], v[42:43], v[50:51]
	v_pk_mul_f32 v[42:43], v[42:43], v[46:47]
	v_pk_mul_f32 v[46:47], v[40:41], v[36:37]
	v_pk_mul_f32 v[40:41], v[40:41], v[44:45]
	v_cvt_pk_f16_f32 v36, v36, v37
	v_cvt_pk_f16_f32 v37, v44, v45
	v_pk_mul_f32 v[50:51], v[38:39], v[48:49]
	v_pk_mul_f32 v[38:39], v[38:39], v[42:43]
	ds_write2st64_b32 v209, v36, v37 offset1:18
	v_cvt_pk_f16_f32 v36, v46, v47
	v_cvt_pk_f16_f32 v37, v40, v41
	v_pk_mul_f32 v[48:49], v[0:1], v[48:49]
	ds_write2st64_b32 v209, v36, v37 offset0:36 offset1:54
	v_cvt_pk_f16_f32 v36, v50, v51
	v_cvt_pk_f16_f32 v37, v38, v39
	ds_write2st64_b32 v209, v36, v37 offset0:72 offset1:90
	v_cvt_f16_f32_e32 v36, v48
	v_pk_mul_f32 v[42:43], v[0:1], v[42:43]
	v_cvt_f16_f32_e32 v37, v49
	v_cvt_f16_f32_e32 v38, v42
	v_cvt_f16_f32_e32 v39, v43
	ds_write_b16 v174, v36 offset:30
	ds_write_b16 v174, v37 offset:70
	ds_write_b16 v174, v38 offset:5150
	s_waitcnt lgkmcnt(14)
	ds_write_b16 v174, v39 offset:5190
	s_nop 0
	s_waitcnt lgkmcnt(7)
	ds_write_b16 v174, v2 offset:10270
	v_perm_b32 v36, v61, v60, s82
	v_perm_b32 v37, v2, v58, s82
	ds_write_b64 v174, v[36:37] offset:10304
.LBB0_470:
	s_andn2_saveexec_b64 s[28:29], s[28:29]
	s_cbranch_execz .LBB0_472
	v_lshl_add_u32 v252, v194, 1, v2
	ds_read2st64_b32 v[36:37], v252 offset0:64 offset1:80
	ds_read2st64_b32 v[48:49], v252 offset0:96 offset1:112
	v_lshl_add_u32 v52, v194, 1, v2
	s_nop 0
	s_nop 0
	ds_read_b32 v64, v52 offset:32768
	v_rcp_f32_e32 v44, v58
	v_rcp_f32_e32 v45, v59
	s_nop 0
	s_waitcnt lgkmcnt(1)
	v_cvt_f32_f16_e32 v60, v49
	v_cvt_f32_f16_e32 v54, v37
	v_cvt_f32_f16_sdwa v55, v37 dst_sel:DWORD dst_unused:UNUSED_PAD src0_sel:WORD_1
	v_cvt_f32_f16_sdwa v61, v49 dst_sel:DWORD dst_unused:UNUSED_PAD src0_sel:WORD_1
	v_lshl_add_u32 v252, v196, 1, v2
	ds_read2st64_b32 v[146:147], v252 offset0:64 offset1:80
	v_cvt_f32_f16_e32 v52, v36
	v_cvt_f32_f16_e32 v56, v48
	v_cvt_f32_f16_sdwa v57, v48 dst_sel:DWORD dst_unused:UNUSED_PAD src0_sel:WORD_1
	ds_read2st64_b32 v[148:149], v252 offset0:96 offset1:112
	v_cvt_f32_f16_sdwa v53, v36 dst_sel:DWORD dst_unused:UNUSED_PAD src0_sel:WORD_1
	v_pk_mul_f32 v[36:37], v[38:39], v[54:55]
	v_pk_mul_f32 v[48:49], v[58:59], v[60:61]
	v_pk_mul_f32 v[54:55], v[44:45], v[56:57]
	v_pk_mul_f32 v[44:45], v[44:45], v[52:53]
	v_pk_mul_f32 v[52:53], v[40:41], v[36:37]
	v_pk_mul_f32 v[56:57], v[40:41], v[48:49]
	v_cvt_pk_f16_f32 v36, v36, v37
	v_cvt_pk_f16_f32 v37, v48, v49
	v_pk_mul_f32 v[60:61], v[38:39], v[54:55]
	v_pk_mul_f32 v[62:63], v[38:39], v[44:45]
	ds_write2st64_b32 v195, v36, v37 offset1:18
	v_cvt_pk_f16_f32 v36, v52, v53
	v_cvt_pk_f16_f32 v37, v56, v57
	v_pk_mul_f32 v[54:55], v[0:1], v[54:55]
	ds_write2st64_b32 v195, v36, v37 offset0:36 offset1:54
	v_cvt_pk_f16_f32 v36, v60, v61
	v_cvt_pk_f16_f32 v37, v62, v63
	ds_write2st64_b32 v195, v36, v37 offset0:72 offset1:90
	v_cvt_f16_f32_e32 v36, v54
	v_pk_mul_f32 v[44:45], v[0:1], v[44:45]
	v_cvt_f16_f32_e32 v37, v55
	v_cvt_f16_f32_e32 v44, v44
	v_cvt_f16_f32_e32 v45, v45
	ds_write_b16 v174, v36 offset:16
	ds_write_b16 v174, v37 offset:56
	ds_write_b16 v174, v44 offset:5136
	ds_write_b16 v174, v45 offset:5176
	s_nop 0
	s_waitcnt lgkmcnt(9)
	ds_write_b16 v174, v64 offset:10256
	v_lshl_add_u32 v52, v196, 1, v2
	s_nop 0
	s_nop 0
	ds_read_b32 v62, v52 offset:32768
	v_rcp_f32_e32 v44, v50
	v_rcp_f32_e32 v45, v51
	s_nop 0
	s_waitcnt lgkmcnt(10)
	v_cvt_f32_f16_e32 v54, v147
	v_cvt_f32_f16_sdwa v55, v147 dst_sel:DWORD dst_unused:UNUSED_PAD src0_sel:WORD_1
	s_nop 0
	s_waitcnt lgkmcnt(9)
	v_cvt_f32_f16_e32 v60, v149
	v_cvt_f32_f16_sdwa v61, v149 dst_sel:DWORD dst_unused:UNUSED_PAD src0_sel:WORD_1
	v_cvt_f32_f16_e32 v52, v146
	v_lshl_add_u32 v252, v198, 1, v2
	ds_read2st64_b32 v[232:233], v252 offset0:64 offset1:80
	v_cvt_f32_f16_e32 v56, v148
	v_cvt_f32_f16_sdwa v57, v148 dst_sel:DWORD dst_unused:UNUSED_PAD src0_sel:WORD_1
	v_cvt_f32_f16_sdwa v53, v146 dst_sel:DWORD dst_unused:UNUSED_PAD src0_sel:WORD_1
	ds_read2st64_b32 v[146:147], v252 offset0:96 offset1:112
	v_pk_mul_f32 v[36:37], v[58:59], v[54:55]
	v_pk_mul_f32 v[48:49], v[50:51], v[60:61]
	v_pk_mul_f32 v[54:55], v[44:45], v[56:57]
	v_pk_mul_f32 v[44:45], v[44:45], v[52:53]
	v_pk_mul_f32 v[52:53], v[40:41], v[36:37]
	v_pk_mul_f32 v[56:57], v[40:41], v[48:49]
	v_cvt_pk_f16_f32 v36, v36, v37
	v_cvt_pk_f16_f32 v37, v48, v49
	v_pk_mul_f32 v[58:59], v[38:39], v[54:55]
	v_pk_mul_f32 v[60:61], v[38:39], v[44:45]
	ds_write2st64_b32 v197, v36, v37 offset1:18
	v_cvt_pk_f16_f32 v36, v52, v53
	v_cvt_pk_f16_f32 v37, v56, v57
	v_pk_mul_f32 v[54:55], v[0:1], v[54:55]
	ds_write2st64_b32 v197, v36, v37 offset0:36 offset1:54
	v_cvt_pk_f16_f32 v36, v58, v59
	v_cvt_pk_f16_f32 v37, v60, v61
	ds_write2st64_b32 v197, v36, v37 offset0:72 offset1:90
	v_cvt_f16_f32_e32 v36, v54
	v_pk_mul_f32 v[44:45], v[0:1], v[44:45]
	v_cvt_f16_f32_e32 v37, v55
	v_cvt_f16_f32_e32 v44, v44
	v_cvt_f16_f32_e32 v45, v45
	ds_write_b16 v174, v36 offset:18
	s_waitcnt lgkmcnt(14)
	ds_write_b16 v174, v37 offset:58
	s_waitcnt lgkmcnt(14)
	ds_write_b16 v174, v44 offset:5138
	s_waitcnt lgkmcnt(14)
	ds_write_b16 v174, v45 offset:5178
	s_nop 0
	s_waitcnt lgkmcnt(9)
	ds_write_b16 v174, v62 offset:10258
	v_lshl_add_u32 v52, v198, 1, v2
	s_nop 0
	s_nop 0
	ds_read_b32 v60, v52 offset:32768
	v_rcp_f32_e32 v44, v46
	v_rcp_f32_e32 v45, v47
	v_lshl_add_u32 v2, v200, 1, v2
	s_nop 0
	s_waitcnt lgkmcnt(10)
	v_cvt_f32_f16_e32 v54, v233
	v_cvt_f32_f16_sdwa v55, v233 dst_sel:DWORD dst_unused:UNUSED_PAD src0_sel:WORD_1
	s_nop 0
	s_waitcnt lgkmcnt(9)
	v_cvt_f32_f16_e32 v58, v147
	ds_read2st64_b32 v[148:149], v2 offset0:64 offset1:80
	v_cvt_f32_f16_sdwa v59, v147 dst_sel:DWORD dst_unused:UNUSED_PAD src0_sel:WORD_1
	v_cvt_f32_f16_e32 v52, v232
	v_cvt_f32_f16_e32 v56, v146
	ds_read2st64_b32 v[234:235], v2 offset0:96 offset1:112
	v_cvt_f32_f16_sdwa v57, v146 dst_sel:DWORD dst_unused:UNUSED_PAD src0_sel:WORD_1
	v_cvt_f32_f16_sdwa v53, v232 dst_sel:DWORD dst_unused:UNUSED_PAD src0_sel:WORD_1
	v_pk_mul_f32 v[36:37], v[50:51], v[54:55]
	v_pk_mul_f32 v[48:49], v[46:47], v[58:59]
	v_pk_mul_f32 v[50:51], v[44:45], v[56:57]
	v_pk_mul_f32 v[44:45], v[44:45], v[52:53]
	v_pk_mul_f32 v[52:53], v[40:41], v[36:37]
	v_pk_mul_f32 v[54:55], v[40:41], v[48:49]
	v_cvt_pk_f16_f32 v36, v36, v37
	v_cvt_pk_f16_f32 v37, v48, v49
	v_pk_mul_f32 v[56:57], v[38:39], v[50:51]
	v_pk_mul_f32 v[58:59], v[38:39], v[44:45]
	ds_write2st64_b32 v199, v36, v37 offset1:18
	v_cvt_pk_f16_f32 v36, v52, v53
	v_cvt_pk_f16_f32 v37, v54, v55
	v_pk_mul_f32 v[50:51], v[0:1], v[50:51]
	ds_write2st64_b32 v199, v36, v37 offset0:36 offset1:54
	v_cvt_pk_f16_f32 v36, v56, v57
	v_cvt_pk_f16_f32 v37, v58, v59
	ds_write2st64_b32 v199, v36, v37 offset0:72 offset1:90
	v_cvt_f16_f32_e32 v36, v50
	v_pk_mul_f32 v[44:45], v[0:1], v[44:45]
	v_cvt_f16_f32_e32 v37, v51
	v_cvt_f16_f32_e32 v44, v44
	v_cvt_f16_f32_e32 v45, v45
	ds_write_b16 v174, v36 offset:20
	s_waitcnt lgkmcnt(14)
	ds_write_b16 v174, v37 offset:60
	s_waitcnt lgkmcnt(14)
	ds_write_b16 v174, v44 offset:5140
	s_waitcnt lgkmcnt(14)
	ds_write_b16 v174, v45 offset:5180
	s_nop 0
	s_waitcnt lgkmcnt(9)
	ds_write_b16 v174, v60 offset:10260
	s_nop 0
	s_nop 0
	ds_read_b32 v2, v2 offset:32768
	v_rcp_f32_e32 v44, v42
	v_rcp_f32_e32 v45, v43
	s_nop 0
	s_waitcnt lgkmcnt(10)
	v_cvt_f32_f16_e32 v52, v149
	v_cvt_f32_f16_sdwa v53, v149 dst_sel:DWORD dst_unused:UNUSED_PAD src0_sel:WORD_1
	s_nop 0
	s_waitcnt lgkmcnt(9)
	v_cvt_f32_f16_e32 v56, v235
	v_cvt_f32_f16_sdwa v57, v235 dst_sel:DWORD dst_unused:UNUSED_PAD src0_sel:WORD_1
	v_cvt_f32_f16_e32 v50, v148
	v_cvt_f32_f16_e32 v54, v234
	v_cvt_f32_f16_sdwa v55, v234 dst_sel:DWORD dst_unused:UNUSED_PAD src0_sel:WORD_1
	v_cvt_f32_f16_sdwa v51, v148 dst_sel:DWORD dst_unused:UNUSED_PAD src0_sel:WORD_1
	v_pk_mul_f32 v[36:37], v[46:47], v[52:53]
	v_pk_mul_f32 v[42:43], v[42:43], v[56:57]
	v_pk_mul_f32 v[46:47], v[44:45], v[54:55]
	v_pk_mul_f32 v[44:45], v[44:45], v[50:51]
	v_pk_mul_f32 v[48:49], v[40:41], v[36:37]
	v_pk_mul_f32 v[40:41], v[40:41], v[42:43]
	v_cvt_pk_f16_f32 v36, v36, v37
	v_cvt_pk_f16_f32 v37, v42, v43
	v_pk_mul_f32 v[50:51], v[38:39], v[46:47]
	v_pk_mul_f32 v[38:39], v[38:39], v[44:45]
	ds_write2st64_b32 v201, v36, v37 offset1:18
	v_cvt_pk_f16_f32 v36, v48, v49
	v_cvt_pk_f16_f32 v37, v40, v41
	v_pk_mul_f32 v[46:47], v[0:1], v[46:47]
	ds_write2st64_b32 v201, v36, v37 offset0:36 offset1:54
	v_cvt_pk_f16_f32 v36, v50, v51
	v_cvt_pk_f16_f32 v37, v38, v39
	ds_write2st64_b32 v201, v36, v37 offset0:72 offset1:90
	v_cvt_f16_f32_e32 v36, v46
	v_pk_mul_f32 v[44:45], v[0:1], v[44:45]
	v_cvt_f16_f32_e32 v37, v47
	v_cvt_f16_f32_e32 v38, v44
	v_cvt_f16_f32_e32 v39, v45
	ds_write_b16 v174, v36 offset:22
	ds_write_b16 v174, v37 offset:62
	ds_write_b16 v174, v38 offset:5142
	s_waitcnt lgkmcnt(14)
	ds_write_b16 v174, v39 offset:5182
	s_nop 0
	s_waitcnt lgkmcnt(7)
	ds_write_b16 v174, v2 offset:10262
	v_perm_b32 v36, v62, v64, s82
	v_perm_b32 v37, v2, v60, s82
	ds_write_b64 v174, v[36:37] offset:10296

.LBB0_473:
	v_cmp_eq_u32_e32 vcc, 1, v172
	s_and_saveexec_b64 s[28:29], vcc
	s_cbranch_execz .LBB0_475
	v_lshl_add_u32 v252, v186, 1, v2
	ds_read2st64_b32 v[36:37], v252 offset0:64 offset1:80
	ds_read2st64_b32 v[46:47], v252 offset0:96 offset1:112
	v_lshl_add_u32 v50, v186, 1, v2
	s_nop 0
	s_nop 0
	ds_read_b32 v62, v50 offset:32768
	v_rcp_f32_e32 v42, v54
	v_rcp_f32_e32 v43, v55
	s_nop 0
	s_waitcnt lgkmcnt(1)
	v_cvt_f32_f16_e32 v58, v47
	v_cvt_f32_f16_e32 v52, v37
	v_cvt_f32_f16_sdwa v53, v37 dst_sel:DWORD dst_unused:UNUSED_PAD src0_sel:WORD_1
	v_cvt_f32_f16_sdwa v59, v47 dst_sel:DWORD dst_unused:UNUSED_PAD src0_sel:WORD_1
	v_lshl_add_u32 v252, v188, 1, v2
	ds_read2st64_b32 v[146:147], v252 offset0:64 offset1:80
	v_cvt_f32_f16_e32 v50, v36
	v_cvt_f32_f16_e32 v56, v46
	v_cvt_f32_f16_sdwa v57, v46 dst_sel:DWORD dst_unused:UNUSED_PAD src0_sel:WORD_1
	ds_read2st64_b32 v[148:149], v252 offset0:96 offset1:112
	v_cvt_f32_f16_sdwa v51, v36 dst_sel:DWORD dst_unused:UNUSED_PAD src0_sel:WORD_1
	v_pk_mul_f32 v[36:37], v[60:61], v[52:53]
	v_pk_mul_f32 v[46:47], v[54:55], v[58:59]
	v_pk_mul_f32 v[52:53], v[42:43], v[56:57]
	v_pk_mul_f32 v[42:43], v[42:43], v[50:51]
	v_pk_mul_f32 v[50:51], v[40:41], v[36:37]
	v_pk_mul_f32 v[56:57], v[40:41], v[46:47]
	v_cvt_pk_f16_f32 v36, v36, v37
	v_cvt_pk_f16_f32 v37, v46, v47
	v_pk_mul_f32 v[58:59], v[38:39], v[52:53]
	v_pk_mul_f32 v[60:61], v[38:39], v[42:43]
	ds_write2st64_b32 v187, v36, v37 offset1:18
	v_cvt_pk_f16_f32 v36, v50, v51
	v_cvt_pk_f16_f32 v37, v56, v57
	v_pk_mul_f32 v[52:53], v[0:1], v[52:53]
	ds_write2st64_b32 v187, v36, v37 offset0:36 offset1:54
	v_cvt_pk_f16_f32 v36, v58, v59
	v_cvt_pk_f16_f32 v37, v60, v61
	ds_write2st64_b32 v187, v36, v37 offset0:72 offset1:90
	v_cvt_f16_f32_e32 v36, v52
	v_pk_mul_f32 v[42:43], v[0:1], v[42:43]
	v_cvt_f16_f32_e32 v37, v53
	v_cvt_f16_f32_e32 v42, v42
	v_cvt_f16_f32_e32 v43, v43
	ds_write_b16 v174, v36 offset:8
	ds_write_b16 v174, v37 offset:48
	ds_write_b16 v174, v42 offset:5128
	ds_write_b16 v174, v43 offset:5168
	s_nop 0
	s_waitcnt lgkmcnt(9)
	ds_write_b16 v174, v62 offset:10248
	v_lshl_add_u32 v50, v188, 1, v2
	s_nop 0
	s_nop 0
	ds_read_b32 v60, v50 offset:32768
	v_rcp_f32_e32 v42, v48
	v_rcp_f32_e32 v43, v49
	s_nop 0
	s_waitcnt lgkmcnt(10)
	v_cvt_f32_f16_e32 v52, v147
	v_cvt_f32_f16_sdwa v53, v147 dst_sel:DWORD dst_unused:UNUSED_PAD src0_sel:WORD_1
	s_nop 0
	s_waitcnt lgkmcnt(9)
	v_cvt_f32_f16_e32 v58, v149
	v_cvt_f32_f16_sdwa v59, v149 dst_sel:DWORD dst_unused:UNUSED_PAD src0_sel:WORD_1
	v_cvt_f32_f16_e32 v50, v146
	v_lshl_add_u32 v252, v190, 1, v2
	ds_read2st64_b32 v[232:233], v252 offset0:64 offset1:80
	v_cvt_f32_f16_e32 v56, v148
	v_cvt_f32_f16_sdwa v57, v148 dst_sel:DWORD dst_unused:UNUSED_PAD src0_sel:WORD_1
	v_cvt_f32_f16_sdwa v51, v146 dst_sel:DWORD dst_unused:UNUSED_PAD src0_sel:WORD_1
	ds_read2st64_b32 v[146:147], v252 offset0:96 offset1:112
	v_pk_mul_f32 v[36:37], v[54:55], v[52:53]
	v_pk_mul_f32 v[46:47], v[48:49], v[58:59]
	v_pk_mul_f32 v[52:53], v[42:43], v[56:57]
	v_pk_mul_f32 v[42:43], v[42:43], v[50:51]
	v_pk_mul_f32 v[50:51], v[40:41], v[36:37]
	v_pk_mul_f32 v[54:55], v[40:41], v[46:47]
	v_cvt_pk_f16_f32 v36, v36, v37
	v_cvt_pk_f16_f32 v37, v46, v47
	v_pk_mul_f32 v[56:57], v[38:39], v[52:53]
	v_pk_mul_f32 v[58:59], v[38:39], v[42:43]
	ds_write2st64_b32 v189, v36, v37 offset1:18
	v_cvt_pk_f16_f32 v36, v50, v51
	v_cvt_pk_f16_f32 v37, v54, v55
	v_pk_mul_f32 v[52:53], v[0:1], v[52:53]
	ds_write2st64_b32 v189, v36, v37 offset0:36 offset1:54
	v_cvt_pk_f16_f32 v36, v56, v57
	v_cvt_pk_f16_f32 v37, v58, v59
	ds_write2st64_b32 v189, v36, v37 offset0:72 offset1:90
	v_cvt_f16_f32_e32 v36, v52
	v_pk_mul_f32 v[42:43], v[0:1], v[42:43]
	v_cvt_f16_f32_e32 v37, v53
	v_cvt_f16_f32_e32 v42, v42
	v_cvt_f16_f32_e32 v43, v43
	ds_write_b16 v174, v36 offset:10
	s_waitcnt lgkmcnt(14)
	ds_write_b16 v174, v37 offset:50
	s_waitcnt lgkmcnt(14)
	ds_write_b16 v174, v42 offset:5130
	s_waitcnt lgkmcnt(14)
	ds_write_b16 v174, v43 offset:5170
	s_nop 0
	s_waitcnt lgkmcnt(9)
	ds_write_b16 v174, v60 offset:10250
	v_lshl_add_u32 v50, v190, 1, v2
	s_nop 0
	s_nop 0
	ds_read_b32 v58, v50 offset:32768
	v_rcp_f32_e32 v42, v44
	v_rcp_f32_e32 v43, v45
	v_lshl_add_u32 v2, v192, 1, v2
	s_nop 0
	s_waitcnt lgkmcnt(10)
	v_cvt_f32_f16_e32 v52, v233
	v_cvt_f32_f16_sdwa v53, v233 dst_sel:DWORD dst_unused:UNUSED_PAD src0_sel:WORD_1
	ds_read2st64_b32 v[148:149], v2 offset0:64 offset1:80
	s_nop 0
	s_waitcnt lgkmcnt(10)
	v_cvt_f32_f16_e32 v56, v147
	v_cvt_f32_f16_sdwa v57, v147 dst_sel:DWORD dst_unused:UNUSED_PAD src0_sel:WORD_1
	ds_read2st64_b32 v[234:235], v2 offset0:96 offset1:112
	v_cvt_f32_f16_e32 v50, v232
	v_cvt_f32_f16_e32 v54, v146
	v_cvt_f32_f16_sdwa v55, v146 dst_sel:DWORD dst_unused:UNUSED_PAD src0_sel:WORD_1
	v_cvt_f32_f16_sdwa v51, v232 dst_sel:DWORD dst_unused:UNUSED_PAD src0_sel:WORD_1
	v_pk_mul_f32 v[36:37], v[48:49], v[52:53]
	v_pk_mul_f32 v[46:47], v[44:45], v[56:57]
	v_pk_mul_f32 v[48:49], v[42:43], v[54:55]
	v_pk_mul_f32 v[42:43], v[42:43], v[50:51]
	v_pk_mul_f32 v[50:51], v[40:41], v[36:37]
	v_pk_mul_f32 v[52:53], v[40:41], v[46:47]
	v_cvt_pk_f16_f32 v36, v36, v37
	v_cvt_pk_f16_f32 v37, v46, v47
	v_pk_mul_f32 v[54:55], v[38:39], v[48:49]
	v_pk_mul_f32 v[56:57], v[38:39], v[42:43]
	ds_write2st64_b32 v191, v36, v37 offset1:18
	v_cvt_pk_f16_f32 v36, v50, v51
	v_cvt_pk_f16_f32 v37, v52, v53
	v_pk_mul_f32 v[48:49], v[0:1], v[48:49]
	ds_write2st64_b32 v191, v36, v37 offset0:36 offset1:54
	v_cvt_pk_f16_f32 v36, v54, v55
	v_cvt_pk_f16_f32 v37, v56, v57
	ds_write2st64_b32 v191, v36, v37 offset0:72 offset1:90
	v_cvt_f16_f32_e32 v36, v48
	v_pk_mul_f32 v[42:43], v[0:1], v[42:43]
	v_cvt_f16_f32_e32 v37, v49
	v_cvt_f16_f32_e32 v42, v42
	v_cvt_f16_f32_e32 v43, v43
	ds_write_b16 v174, v36 offset:12
	s_waitcnt lgkmcnt(14)
	ds_write_b16 v174, v37 offset:52
	s_waitcnt lgkmcnt(14)
	ds_write_b16 v174, v42 offset:5132
	s_waitcnt lgkmcnt(14)
	ds_write_b16 v174, v43 offset:5172
	s_nop 0
	s_waitcnt lgkmcnt(9)
	ds_write_b16 v174, v58 offset:10252
	s_nop 0
	s_nop 0
	ds_read_b32 v2, v2 offset:32768
	s_nop 0
	s_waitcnt lgkmcnt(10)
	v_cvt_f32_f16_e32 v48, v149
	v_cvt_f32_f16_sdwa v49, v149 dst_sel:DWORD dst_unused:UNUSED_PAD src0_sel:WORD_1
	s_nop 0
	s_waitcnt lgkmcnt(9)
	v_cvt_f32_f16_e32 v52, v235
	v_cvt_f32_f16_sdwa v53, v235 dst_sel:DWORD dst_unused:UNUSED_PAD src0_sel:WORD_1
	v_cvt_f32_f16_e32 v46, v148
	v_cvt_f32_f16_e32 v50, v234
	v_cvt_f32_f16_sdwa v51, v234 dst_sel:DWORD dst_unused:UNUSED_PAD src0_sel:WORD_1
	v_cvt_f32_f16_sdwa v47, v148 dst_sel:DWORD dst_unused:UNUSED_PAD src0_sel:WORD_1
	v_pk_mul_f32 v[36:37], v[44:45], v[48:49]
	v_pk_mul_f32 v[42:43], v[38:39], v[52:53]
	v_pk_mul_f32 v[44:45], v[40:41], v[50:51]
	v_pk_mul_f32 v[46:47], v[40:41], v[46:47]
	v_pk_mul_f32 v[48:49], v[40:41], v[36:37]
	v_pk_mul_f32 v[40:41], v[40:41], v[42:43]
	v_cvt_pk_f16_f32 v36, v36, v37
	v_cvt_pk_f16_f32 v37, v42, v43
	v_pk_mul_f32 v[50:51], v[38:39], v[44:45]
	v_pk_mul_f32 v[38:39], v[38:39], v[46:47]
	ds_write2st64_b32 v193, v36, v37 offset1:18
	v_cvt_pk_f16_f32 v36, v48, v49
	v_cvt_pk_f16_f32 v37, v40, v41
	v_pk_mul_f32 v[44:45], v[0:1], v[44:45]
	ds_write2st64_b32 v193, v36, v37 offset0:36 offset1:54
	v_cvt_pk_f16_f32 v36, v50, v51
	v_cvt_pk_f16_f32 v37, v38, v39
	ds_write2st64_b32 v193, v36, v37 offset0:72 offset1:90
	v_cvt_f16_f32_e32 v36, v44
	v_pk_mul_f32 v[46:47], v[0:1], v[46:47]
	v_cvt_f16_f32_e32 v37, v45
	v_cvt_f16_f32_e32 v38, v46
	v_cvt_f16_f32_e32 v39, v47
	ds_write_b16 v174, v36 offset:14
	ds_write_b16 v174, v37 offset:54
	ds_write_b16 v174, v38 offset:5134
	s_waitcnt lgkmcnt(14)
	ds_write_b16 v174, v39 offset:5174
	s_nop 0
	s_waitcnt lgkmcnt(7)
	ds_write_b16 v174, v2 offset:10254
	v_perm_b32 v36, v60, v62, s82
	v_perm_b32 v37, v2, v58, s82
	ds_write_b64 v174, v[36:37] offset:10288

.LBB0_900:
	s_or_b64 exec, exec, s[0:1]
	s_nop 5
	v_cvt_f16_f32_e32 v2, v52
	v_cvt_f16_f32_e32 v52, v53
	v_cvt_f16_f32_e32 v53, v54
	v_cvt_f16_f32_e32 v54, v55
	v_cndmask_b32_e64 v2, v2, 0, s[18:19]
	v_cndmask_b32_e64 v52, 0, v52, s[20:21]
	v_cndmask_b32_e64 v53, v53, 0, s[22:23]
	v_cndmask_b32_e64 v54, v54, 0, s[24:25]
	v_pack_b32_f16 v53, v53, v54
	v_pack_b32_f16 v52, v2, v52
	ds_write_b64 v123, v[52:53]
	s_waitcnt lgkmcnt(0)
	s_barrier
	ds_read_b128 v[126:129], v124 offset:55360
	ds_read_b128 v[52:55], v125
	ds_read_b128 v[134:137], v125 offset:64
	ds_read_b128 v[138:141], v125 offset:2304
	ds_read_b128 v[142:145], v125 offset:2368
	ds_read_b128 v[146:149], v125 offset:4608
	ds_read_b128 v[162:165], v125 offset:4672
	ds_read_b128 v[68:71], v124 offset:55296
	s_nop 0
	s_nop 0
	ds_read_b128 v[178:181], v125 offset:6912
	s_nop 0
	s_waitcnt lgkmcnt(1)
	v_mfma_f32_16x16x32_f16 v[48:51], v[68:71], v[52:55], v[48:51]
	s_nop 0
	v_add_u32_e32 v2, 0x1e500, v96
	ds_read_b128 v[182:185], v125 offset:6976
	s_add_i32 s28, s28, 1
	s_nop 0
	v_mfma_f32_16x16x32_f16 v[52:55], v[126:129], v[134:137], v[48:51]
	ds_read_b128 v[134:137], v2
	s_nop 2
	s_nop 0
	s_nop 0
	v_mfma_f32_16x16x32_f16 v[48:51], v[68:71], v[138:141], v[56:59]
	s_nop 2
	s_nop 0
	ds_read_b128 v[138:141], v125 offset:46080
	v_cvt_pk_f16_f32 v55, v54, v55
	v_cvt_pk_f16_f32 v54, v52, v53
	s_nop 0
	v_mfma_f32_16x16x32_f16 v[56:59], v[126:129], v[142:145], v[48:51]
	ds_read_b128 v[142:145], v125 offset:46144
	s_nop 2
	s_nop 0
	s_nop 0
	ds_read_b128 v[186:189], v2 offset:64
	v_mfma_f32_16x16x32_f16 v[48:51], v[68:71], v[146:149], v[60:63]
	s_nop 2
	s_nop 0
	s_nop 0
	ds_read_b128 v[146:149], v125 offset:48384
	v_mfma_f32_16x16x32_f16 v[60:63], v[126:129], v[162:165], v[48:51]
	s_nop 2
	s_nop 0
	ds_read_b128 v[162:165], v125 offset:48448
	s_nop 0
	s_waitcnt lgkmcnt(7)
	v_mfma_f32_16x16x32_f16 v[48:51], v[68:71], v[178:181], v[64:67]
	s_nop 2
	ds_read_b128 v[178:181], v2 offset:128
	s_nop 0
	s_nop 0
	s_waitcnt lgkmcnt(7)
	v_mfma_f32_16x16x32_f16 v[48:51], v[126:129], v[182:185], v[48:51]
	s_nop 0
	ds_read_b128 v[182:185], v125 offset:50688
	s_nop 0
	s_waitcnt lgkmcnt(7)
	v_pk_mul_f32 v[44:45], v[44:45], v[134:135]
	v_pk_mul_f32 v[46:47], v[46:47], v[136:137]
	ds_read_b128 v[134:137], v125 offset:50752
	s_nop 0
	s_nop 2
	v_cvt_pk_f16_f32 v51, v50, v51
	s_nop 0
	s_waitcnt lgkmcnt(7)
	v_mfma_f32_16x16x32_f16 v[44:47], v[138:141], v[68:71], v[44:47]
	ds_read_b128 v[138:141], v2 offset:192
	s_nop 0
	v_cvt_pk_f16_f32 v50, v48, v49
	s_nop 0
	s_waitcnt lgkmcnt(7)
	v_mfma_f32_16x16x32_f16 v[44:47], v[142:145], v[126:129], v[44:47]
	ds_read_b128 v[142:145], v125 offset:52992
	s_nop 0
	s_nop 0
	s_waitcnt lgkmcnt(7)
	v_pk_mul_f32 v[32:33], v[32:33], v[186:187]
	v_pk_mul_f32 v[34:35], v[34:35], v[188:189]
	s_nop 0
	s_nop 0
	s_waitcnt lgkmcnt(6)
	v_mfma_f32_16x16x32_f16 v[32:35], v[146:149], v[68:71], v[32:35]
	s_nop 0
	s_nop 0
	s_waitcnt lgkmcnt(5)
	v_mfma_f32_16x16x32_f16 v[32:35], v[162:165], v[126:129], v[32:35]
	s_nop 0
	s_nop 0
	s_waitcnt lgkmcnt(4)
	v_pk_mul_f32 v[40:41], v[40:41], v[178:179]
	v_pk_mul_f32 v[42:43], v[42:43], v[180:181]
	s_nop 0
	s_nop 0
	s_waitcnt lgkmcnt(3)
	v_mfma_f32_16x16x32_f16 v[40:43], v[182:185], v[68:71], v[40:43]
	s_nop 0
	s_nop 0
	s_waitcnt lgkmcnt(2)
	v_mfma_f32_16x16x32_f16 v[40:43], v[134:137], v[126:129], v[40:43]
	s_nop 0
	v_add_u32_e32 v2, s26, v91
	s_add_i32 s26, s26, 64
	s_nop 0
	s_waitcnt lgkmcnt(1)
	v_pk_mul_f32 v[36:37], v[36:37], v[138:139]
	v_pk_mul_f32 v[38:39], v[38:39], v[140:141]
	s_nop 0
	s_nop 0
	s_waitcnt lgkmcnt(0)
	v_mfma_f32_16x16x32_f16 v[36:39], v[142:145], v[68:71], v[36:39]
	ds_read_b128 v[64:67], v125 offset:53056
	s_nop 0
	s_waitcnt lgkmcnt(0)
	v_mfma_f32_16x16x32_f16 v[36:39], v[64:67], v[126:129], v[36:39]
	v_add_u32_e32 v64, s27, v112
	v_add_u32_e32 v65, 0xff, v64
	v_cndmask_b32_e64 v65, v65, v2, s[2:3]
	v_add_u32_e32 v52, v65, v89
	v_mad_i64_i32 v[52:53], s[0:1], v52, s88, v[82:83]
	global_store_dwordx2 v[52:53], v[54:55], off
	v_add_u32_e32 v52, 16, v2
	v_add_u32_e32 v53, 0xef, v64
	v_cndmask_b32_e64 v54, v53, v52, s[2:3]
	v_add_u32_e32 v54, v54, v89
	v_cvt_pk_f16_f32 v53, v58, v59
	v_cvt_pk_f16_f32 v52, v56, v57
	v_mad_i64_i32 v[54:55], s[0:1], v54, s88, v[82:83]
	global_store_dwordx2 v[54:55], v[52:53], off
	v_add_u32_e32 v52, 32, v2
	v_add_u32_e32 v53, 0xdf, v64
	v_cndmask_b32_e64 v54, v53, v52, s[2:3]
	v_add_u32_e32 v54, v54, v89
	v_cvt_pk_f16_f32 v53, v62, v63
	v_cvt_pk_f16_f32 v52, v60, v61
	v_mad_i64_i32 v[54:55], s[0:1], v54, s88, v[82:83]
	global_store_dwordx2 v[54:55], v[52:53], off
	v_add_u32_e32 v2, 48, v2
	v_add_u32_e32 v52, 0xcf, v64
	v_cndmask_b32_e64 v2, v52, v2, s[2:3]
	v_add_u32_e32 v2, v2, v89
	s_sub_i32 s27, s27, 64
	v_mad_i64_i32 v[48:49], s[0:1], v2, s88, v[82:83]
	s_cmpk_lg_i32 s27, 0xff00
	global_store_dwordx2 v[48:49], v[50:51], off
	s_cbranch_scc0 .LBB0_1058

.LBB0_909:
	v_add_u32_e32 v251, v93, v106
	ds_read_b128 v[48:51], v251
	ds_read_b128 v[52:55], v251 offset:64
	v_add_u32_e32 v2, v93, v106
	s_nop 0
	s_nop 0
	s_nop 0
	s_waitcnt lgkmcnt(1)
	v_mfma_f32_16x16x32_f16 v[48:51], v[48:51], v[24:27], 0
	s_nop 0
	s_waitcnt lgkmcnt(0)
	v_mfma_f32_16x16x32_f16 v[48:51], v[52:55], v[28:31], v[48:51]
	s_nop 7
	ds_write_b128 v107, v[48:51]
	s_and_saveexec_b64 s[0:1], s[68:69]
	s_cbranch_execz .LBB0_911
	v_mul_f32_e32 v2, 0x3fb8aa3b, v48
	v_exp_f32_e32 v48, v2
	v_mul_f32_e32 v2, 0x3fb8aa3b, v49
	v_exp_f32_e32 v49, v2
	v_mul_f32_e32 v2, 0x3fb8aa3b, v50
	v_exp_f32_e32 v50, v2
	v_mul_f32_e32 v2, 0x3fb8aa3b, v51
	v_exp_f32_e32 v51, v2
	ds_write_b128 v110, v[48:51]
.LBB0_911:
	s_or_b64 exec, exec, s[0:1]
	v_add_u32_e32 v251, v93, v108
	ds_read_b128 v[48:51], v251
	ds_read_b128 v[52:55], v251 offset:64
	v_add_u32_e32 v2, v93, v108
	s_nop 0
	s_nop 0
	s_nop 0
	s_waitcnt lgkmcnt(1)
	v_mfma_f32_16x16x32_f16 v[48:51], v[48:51], v[24:27], 0
	s_nop 0
	s_waitcnt lgkmcnt(0)
	v_mfma_f32_16x16x32_f16 v[48:51], v[52:55], v[28:31], v[48:51]
	s_nop 7
	ds_write_b128 v109, v[48:51]
	s_and_saveexec_b64 s[0:1], s[68:69]
	s_cbranch_execz .LBB0_913
	v_mul_f32_e32 v2, 0x3fb8aa3b, v48
	v_exp_f32_e32 v48, v2
	v_mul_f32_e32 v2, 0x3fb8aa3b, v49
	v_exp_f32_e32 v49, v2
	v_mul_f32_e32 v2, 0x3fb8aa3b, v50
	v_exp_f32_e32 v50, v2
	v_mul_f32_e32 v2, 0x3fb8aa3b, v51
	v_exp_f32_e32 v51, v2
	ds_write_b128 v111, v[48:51]
.LBB0_913:
	s_or_b64 exec, exec, s[0:1]
	s_waitcnt lgkmcnt(0)
	s_barrier
	ds_read_b128 v[52:55], v92 offset:9216
	ds_read_b128 v[60:63], v94
	ds_read_b128 v[48:51], v92
	s_nop 0
	s_nop 0
	ds_read_b128 v[68:71], v101
	ds_read_b128 v[56:59], v94 offset:16
	s_nop 0
	v_add_u32_e32 v81, v95, v103
	s_nop 0
	s_waitcnt lgkmcnt(4)
	v_cvt_f32_f16_sdwa v67, v52 dst_sel:DWORD dst_unused:UNUSED_PAD src0_sel:WORD_1
	s_nop 0
	s_waitcnt lgkmcnt(3)
	v_mul_f32_e32 v2, 0x3fb8aa3b, v60
	v_exp_f32_e32 v60, v2
	v_mul_f32_e32 v2, 0x3fb8aa3b, v61
	v_exp_f32_e32 v61, v2
	v_cvt_f32_f16_e32 v66, v52
	v_rcp_f32_e32 v64, v60
	v_add_u32_e32 v52, v78, v97
	v_rcp_f32_e32 v65, v61
	v_cvt_f32_f16_sdwa v127, v54 dst_sel:DWORD dst_unused:UNUSED_PAD src0_sel:WORD_1
	v_cvt_f32_f16_e32 v126, v54
	v_pk_mul_f32 v[66:67], v[64:65], v[66:67]
	s_waitcnt lgkmcnt(2)
	v_cvt_f32_f16_sdwa v65, v48 dst_sel:DWORD dst_unused:UNUSED_PAD src0_sel:WORD_1
	v_cvt_f32_f16_e32 v64, v48
	s_nop 0
	s_waitcnt lgkmcnt(1)
	v_fma_mixlo_f16 v2, v68, v66, 0
	ds_write_b16 v52, v2 offset:46080
	v_fma_mixlo_f16 v2, v69, v67, 0
	v_pk_mul_f32 v[64:65], v[64:65], s[72:73] op_sel_hi:[1,0]
	ds_write_b16 v121, v2 offset:46080
	v_mul_f32_e32 v2, 0x3fb8aa3b, v62
	v_pk_mul_f32 v[64:65], v[64:65], v[60:61]
	v_exp_f32_e32 v60, v2
	v_mul_f32_e32 v2, 0x3fb8aa3b, v63
	v_exp_f32_e32 v61, v2
	v_cvt_f32_f16_sdwa v69, v53 dst_sel:DWORD dst_unused:UNUSED_PAD src0_sel:WORD_1
	v_rcp_f32_e32 v62, v60
	v_cvt_f32_f16_e32 v68, v53
	v_rcp_f32_e32 v63, v61
	v_cvt_f32_f16_sdwa v53, v49 dst_sel:DWORD dst_unused:UNUSED_PAD src0_sel:WORD_1
	v_cvt_f32_f16_e32 v52, v49
	v_cvt_pk_f16_f32 v48, v64, v65
	v_pk_mul_f32 v[68:69], v[62:63], v[68:69]
	v_pk_mul_f32 v[52:53], v[52:53], s[72:73] op_sel_hi:[1,0]
	v_fma_mixlo_f16 v2, v70, v68, 0
	ds_write_b16 v121, v2 offset:46224
	v_fma_mixlo_f16 v2, v71, v69, 0
	ds_write_b16 v121, v2 offset:46368
	s_waitcnt lgkmcnt(4)
	v_mul_f32_e32 v2, 0x3fb8aa3b, v56
	v_exp_f32_e32 v56, v2
	v_mul_f32_e32 v2, 0x3fb8aa3b, v57
	v_exp_f32_e32 v57, v2
	v_pk_mul_f32 v[52:53], v[52:53], v[60:61]
	ds_read_b128 v[60:63], v102
	v_rcp_f32_e32 v70, v56
	s_nop 0
	v_rcp_f32_e32 v71, v57
	v_cvt_pk_f16_f32 v49, v52, v53
	v_pk_mul_f32 v[70:71], v[70:71], v[126:127]
	s_nop 0
	s_waitcnt lgkmcnt(0)
	v_fma_mixlo_f16 v2, v60, v70, 0
	ds_write_b16 v121, v2 offset:46512
	v_fma_mixlo_f16 v2, v61, v71, 0
	ds_write_b16 v121, v2 offset:46656
	v_mul_f32_e32 v2, 0x3fb8aa3b, v58
	v_cvt_f32_f16_sdwa v127, v50 dst_sel:DWORD dst_unused:UNUSED_PAD src0_sel:WORD_1
	v_cvt_f32_f16_e32 v126, v50
	v_exp_f32_e32 v58, v2
	v_mul_f32_e32 v2, 0x3fb8aa3b, v59
	v_exp_f32_e32 v59, v2
	v_pk_mul_f32 v[126:127], v[126:127], s[72:73] op_sel_hi:[1,0]
	v_cvt_f32_f16_sdwa v61, v55 dst_sel:DWORD dst_unused:UNUSED_PAD src0_sel:WORD_1
	v_pk_mul_f32 v[126:127], v[126:127], v[56:57]
	v_rcp_f32_e32 v56, v58
	v_rcp_f32_e32 v57, v59
	v_cvt_f32_f16_e32 v60, v55
	v_bfe_u32 v55, v71, 16, 1
	v_add3_u32 v55, v71, v55, s34
	v_cvt_pk_f16_f32 v50, v126, v127
	v_pk_mul_f32 v[128:129], v[56:57], v[60:61]
	v_bfe_u32 v56, v70, 16, 1
	v_fma_mixlo_f16 v2, v62, v128, 0
	ds_write_b16 v121, v2 offset:46800
	v_bfe_u32 v2, v129, 16, 1
	v_bfe_u32 v54, v128, 16, 1
	v_bfe_u32 v57, v69, 16, 1
	v_bfe_u32 v60, v68, 16, 1
	v_bfe_u32 v61, v67, 16, 1
	v_bfe_u32 v62, v66, 16, 1
	v_add3_u32 v62, v66, v62, s34
	v_add3_u32 v61, v67, v61, s34
	v_add3_u32 v60, v68, v60, s34
	v_add3_u32 v66, v69, v57, s34
	v_add3_u32 v56, v70, v56, s34
	v_add3_u32 v54, v128, v54, s34
	v_add3_u32 v2, v129, v2, s34
	v_perm_b32 v57, v2, v54, s35
	v_perm_b32 v56, v55, v56, s35
	v_perm_b32 v55, v66, v60, s35
	v_perm_b32 v54, v61, v62, s35
	v_cvt_f32_f16_sdwa v61, v51 dst_sel:DWORD dst_unused:UNUSED_PAD src0_sel:WORD_1
	v_cvt_f32_f16_e32 v60, v51
	v_bfe_u32 v62, v126, 16, 1
	v_bfe_u32 v66, v53, 16, 1
	v_bfe_u32 v67, v52, 16, 1
	v_pk_mul_f32 v[60:61], v[60:61], s[72:73] op_sel_hi:[1,0]
	v_bfe_u32 v68, v65, 16, 1
	v_pk_mul_f32 v[58:59], v[60:61], v[58:59]
	v_bfe_u32 v61, v127, 16, 1
	v_bfe_u32 v2, v59, 16, 1
	v_bfe_u32 v60, v58, 16, 1
	v_cvt_pk_f16_f32 v51, v58, v59
	v_bfe_u32 v69, v64, 16, 1
	v_add3_u32 v58, v58, v60, s34
	v_add3_u32 v2, v59, v2, s34
	v_add3_u32 v64, v64, v69, s34
	v_add3_u32 v65, v65, v68, s34
	v_add3_u32 v52, v52, v67, s34
	v_add3_u32 v53, v53, v66, s34
	v_add3_u32 v62, v126, v62, s34
	v_add3_u32 v66, v127, v61, s34
	v_perm_b32 v61, v2, v58, s35
	v_fma_mixlo_f16 v2, v63, v129, 0
	v_perm_b32 v60, v66, v62, s35
	v_perm_b32 v59, v53, v52, s35
	v_perm_b32 v58, v65, v64, s35
	ds_write_b16 v121, v2 offset:46944
	ds_write_b128 v92, v[58:61] offset:18432
	ds_write_b128 v92, v[54:57] offset:27648
	ds_write_b128 v92, v[48:51] offset:36864
	v_add_u32_e32 v2, v79, v72
	s_nop 0
	s_barrier
	ds_read_b128 v[52:55], v81 offset:36864
	ds_read_b128 v[56:59], v81 offset:39168
	ds_read_b128 v[60:63], v81 offset:41472
	ds_read_b128 v[64:67], v81 offset:43776
	ds_read_b128 v[68:71], v2 offset:64
	ds_read_b128 v[134:137], v81 offset:36928
	ds_read_b128 v[138:141], v81 offset:39232
	ds_read_b128 v[142:145], v81 offset:41536
	ds_read_b128 v[48:51], v2
	s_nop 0
	s_nop 0
	s_nop 0
	s_nop 0
	s_nop 0
	s_waitcnt lgkmcnt(0)
	v_mfma_f32_16x16x32_f16 v[52:55], v[48:51], v[52:55], 0
	s_nop 0
	v_mfma_f32_16x16x32_f16 v[56:59], v[48:51], v[56:59], 0
	s_nop 0
	v_mfma_f32_16x16x32_f16 v[60:63], v[48:51], v[60:63], 0
	s_nop 0
	v_mfma_f32_16x16x32_f16 v[64:67], v[48:51], v[64:67], 0
	s_nop 0
	s_nop 0
	v_add_u32_e32 v2, v100, v72
	s_nop 0
	v_mfma_f32_16x16x32_f16 v[48:51], v[68:71], v[134:137], v[52:55]
	s_nop 2
	s_nop 0
	s_nop 0
	v_mfma_f32_16x16x32_f16 v[56:59], v[68:71], v[138:141], v[56:59]
	s_nop 0
	s_nop 0
	v_mfma_f32_16x16x32_f16 v[60:63], v[68:71], v[142:145], v[60:63]
	ds_read_b128 v[52:55], v81 offset:43840
	s_nop 0
	s_waitcnt lgkmcnt(0)
	v_mfma_f32_16x16x32_f16 v[64:67], v[68:71], v[52:55], v[64:67]
	v_mov_b32_e32 v52, 0
	v_mov_b32_e32 v68, 0
	v_mov_b32_e32 v69, 0
	v_mov_b32_e32 v70, 0
	v_mov_b32_e32 v71, 0
	s_and_saveexec_b64 s[0:1], s[6:7]
	s_cbranch_execz .LBB0_915
	v_add_u32_e32 v251, v95, v106
	ds_read_b128 v[68:71], v2 offset:18432
	ds_read_b128 v[126:129], v251 offset:27648
	v_add_u32_e32 v53, v95, v106
	s_nop 0
	s_nop 0
	s_nop 0
	s_waitcnt lgkmcnt(0)
	v_mfma_f32_16x16x32_bf16 v[68:71], v[126:129], v[68:71], 0
	ds_read_b128 v[130:133], v53 offset:27712
	ds_read_b128 v[126:129], v2 offset:18496
	s_nop 0
	s_nop 0
	s_waitcnt lgkmcnt(0)
	v_mfma_f32_16x16x32_bf16 v[68:71], v[130:133], v[126:129], v[68:71]
.LBB0_915:
	s_or_b64 exec, exec, s[0:1]
	s_nop 6
	v_cvt_f16_f32_e32 v53, v68
	v_cvt_f16_f32_e32 v54, v69
	v_cvt_f16_f32_e32 v55, v70
	v_cvt_f16_f32_e32 v68, v71
	v_cndmask_b32_e64 v53, v53, 0, s[10:11]
	v_cndmask_b32_e64 v54, 0, v54, s[12:13]
	v_cndmask_b32_e64 v55, v55, 0, s[14:15]
	v_cndmask_b32_e64 v68, v68, 0, s[16:17]
	v_pack_b32_f16 v55, v55, v68
	v_pack_b32_f16 v54, v53, v54
	ds_write_b64 v122, v[54:55]
	v_mov_b32_e32 v53, 0
	v_mov_b32_e32 v54, 0
	v_mov_b32_e32 v55, 0
	s_and_saveexec_b64 s[0:1], s[8:9]
	s_cbranch_execz .LBB0_900
	v_add_u32_e32 v251, v95, v108
	ds_read_b128 v[52:55], v2 offset:18432
	ds_read_b128 v[68:71], v251 offset:27648
	v_add_u32_e32 v81, v95, v108
	s_nop 0
	s_nop 0
	s_nop 0
	s_waitcnt lgkmcnt(0)
	v_mfma_f32_16x16x32_bf16 v[52:55], v[68:71], v[52:55], 0
	ds_read_b128 v[126:129], v81 offset:27712
	ds_read_b128 v[68:71], v2 offset:18496
	s_nop 0
	s_nop 0
	s_waitcnt lgkmcnt(0)
	v_mfma_f32_16x16x32_bf16 v[52:55], v[126:129], v[68:71], v[52:55]
	s_branch .LBB0_900

.LBB0_929:
	s_and_b32 s27, s26, 1
	v_lshl_add_u32 v0, s27, 13, v234
	ds_read2_b64 v[36:39], v0 offset1:32
	v_mad_u32_u24 v2, s27, v167, v235
	s_waitcnt lgkmcnt(0)
	v_pk_mul_f32 v[66:67], v[36:37], v[38:39]
	ds_read2_b64 v[38:41], v0 offset0:64 offset1:96
	s_waitcnt lgkmcnt(0)
	v_pk_mul_f32 v[64:65], v[66:67], v[38:39]
	s_nop 0
	v_pk_mul_f32 v[60:61], v[64:65], v[40:41]
	ds_read2_b64 v[38:41], v0 offset0:128 offset1:160
	s_waitcnt lgkmcnt(0)
	v_pk_mul_f32 v[54:55], v[60:61], v[38:39]
	s_nop 0
	v_pk_mul_f32 v[48:49], v[54:55], v[40:41]
	ds_read2_b64 v[38:41], v0 offset0:192 offset1:224
	v_add_u32_e32 v0, 0x800, v0
	ds_read2_b64 v[68:71], v0 offset0:128 offset1:160
	s_waitcnt lgkmcnt(1)
	v_pk_mul_f32 v[44:45], v[48:49], v[38:39]
	s_nop 0
	v_pk_mul_f32 v[38:39], v[44:45], v[40:41]
	ds_read2_b64 v[40:43], v0 offset1:32
	s_waitcnt lgkmcnt(0)
	v_pk_mul_f32 v[58:59], v[38:39], v[40:41]
	s_nop 0
	v_pk_mul_f32 v[50:51], v[58:59], v[42:43]
	ds_read2_b64 v[40:43], v0 offset0:64 offset1:96
	s_waitcnt lgkmcnt(0)
	v_pk_mul_f32 v[46:47], v[50:51], v[40:41]
	s_nop 0
	v_pk_mul_f32 v[42:43], v[46:47], v[42:43]
	v_rcp_f32_e32 v40, v38
	v_pk_mul_f32 v[62:63], v[42:43], v[68:69]
	v_rcp_f32_e32 v41, v39
	v_pk_mul_f32 v[56:57], v[62:63], v[70:71]
	ds_read2_b64 v[68:71], v0 offset0:192 offset1:224
	s_waitcnt lgkmcnt(0)
	v_pk_mul_f32 v[52:53], v[56:57], v[68:69]
	s_nop 0
	v_pk_mul_f32 v[0:1], v[52:53], v[70:71]
	s_and_saveexec_b64 s[28:29], s[4:5]
	s_cbranch_execz .LBB0_931
	v_lshl_add_u32 v250, v179, 1, v2
	ds_read2st64_b32 v[72:73], v250 offset0:96 offset1:112
	ds_read2st64_b32 v[68:69], v250 offset0:64 offset1:80
	v_lshl_add_u32 v74, v179, 1, v2
	s_nop 0
	ds_read_b32 v84, v74 offset:32768
	s_nop 0
	v_rcp_f32_e32 v70, v36
	v_rcp_f32_e32 v71, v37
	s_nop 0
	s_nop 0
	s_waitcnt lgkmcnt(2)
	v_cvt_f32_f16_e32 v78, v73
	v_cvt_f32_f16_sdwa v79, v73 dst_sel:DWORD dst_unused:UNUSED_PAD src0_sel:WORD_1
	s_nop 0
	v_lshl_add_u32 v250, v186, 1, v2
	ds_read2st64_b32 v[148:149], v250 offset0:64 offset1:80
	s_waitcnt lgkmcnt(2)
	v_cvt_f32_f16_e32 v74, v68
	v_cvt_f32_f16_sdwa v75, v68 dst_sel:DWORD dst_unused:UNUSED_PAD src0_sel:WORD_1
	v_cvt_f32_f16_e32 v76, v72
	ds_read2st64_b32 v[162:163], v250 offset0:96 offset1:112
	v_cvt_f32_f16_sdwa v77, v72 dst_sel:DWORD dst_unused:UNUSED_PAD src0_sel:WORD_1
	v_cvt_f32_f16_e32 v72, v69
	v_cvt_f32_f16_sdwa v73, v69 dst_sel:DWORD dst_unused:UNUSED_PAD src0_sel:WORD_1
	v_pk_mul_f32 v[78:79], v[36:37], v[78:79]
	v_pk_mul_f32 v[76:77], v[70:71], v[76:77]
	v_pk_mul_f32 v[70:71], v[70:71], v[74:75]
	v_pk_mul_f32 v[72:73], v[40:41], v[72:73]
	v_pk_mul_f32 v[74:75], v[40:41], v[78:79]
	v_cvt_pk_f16_f32 v68, v78, v79
	v_pk_mul_f32 v[80:81], v[38:39], v[76:77]
	v_pk_mul_f32 v[82:83], v[38:39], v[70:71]
	ds_write2st64_b32 v185, v69, v68 offset1:18
	v_cvt_pk_f16_f32 v68, v72, v73
	v_cvt_pk_f16_f32 v69, v74, v75
	v_pk_mul_f32 v[76:77], v[0:1], v[76:77]
	ds_write2st64_b32 v185, v68, v69 offset0:36 offset1:54
	v_cvt_pk_f16_f32 v68, v80, v81
	v_cvt_pk_f16_f32 v69, v82, v83
	ds_write2st64_b32 v185, v68, v69 offset0:72 offset1:90
	v_cvt_f16_f32_e32 v68, v76
	v_pk_mul_f32 v[70:71], v[0:1], v[70:71]
	v_cvt_f16_f32_e32 v69, v77
	v_cvt_f16_f32_e32 v70, v70
	v_cvt_f16_f32_e32 v71, v71
	ds_write_b16 v180, v68
	ds_write_b16 v180, v69 offset:40
	ds_write_b16 v180, v70 offset:5120
	ds_write_b16 v180, v71 offset:5160
	s_nop 0
	s_waitcnt lgkmcnt(9)
	ds_write_b16 v180, v84 offset:10240
	v_lshl_add_u32 v74, v186, 1, v2
	s_nop 0
	s_nop 0
	ds_read_b32 v82, v74 offset:32768
	v_rcp_f32_e32 v70, v66
	v_rcp_f32_e32 v71, v67
	s_nop 0
	s_waitcnt lgkmcnt(10)
	v_cvt_f32_f16_e32 v76, v149
	v_cvt_f32_f16_sdwa v77, v149 dst_sel:DWORD dst_unused:UNUSED_PAD src0_sel:WORD_1
	s_nop 0
	s_waitcnt lgkmcnt(9)
	v_cvt_f32_f16_e32 v80, v163
	v_cvt_f32_f16_sdwa v81, v163 dst_sel:DWORD dst_unused:UNUSED_PAD src0_sel:WORD_1
	v_lshl_add_u32 v250, v188, 1, v2
	ds_read2st64_b32 v[164:165], v250 offset0:64 offset1:80
	v_cvt_f32_f16_e32 v74, v148
	v_cvt_f32_f16_e32 v78, v162
	v_cvt_f32_f16_sdwa v79, v162 dst_sel:DWORD dst_unused:UNUSED_PAD src0_sel:WORD_1
	ds_read2st64_b32 v[162:163], v250 offset0:96 offset1:112
	v_cvt_f32_f16_sdwa v75, v148 dst_sel:DWORD dst_unused:UNUSED_PAD src0_sel:WORD_1
	v_pk_mul_f32 v[36:37], v[36:37], v[76:77]
	v_pk_mul_f32 v[68:69], v[66:67], v[80:81]
	v_pk_mul_f32 v[72:73], v[70:71], v[78:79]
	v_pk_mul_f32 v[70:71], v[70:71], v[74:75]
	v_pk_mul_f32 v[74:75], v[40:41], v[36:37]
	v_pk_mul_f32 v[76:77], v[40:41], v[68:69]
	v_cvt_pk_f16_f32 v36, v36, v37
	v_cvt_pk_f16_f32 v37, v68, v69
	v_pk_mul_f32 v[78:79], v[38:39], v[72:73]
	v_pk_mul_f32 v[80:81], v[38:39], v[70:71]
	ds_write2st64_b32 v187, v36, v37 offset1:18
	v_cvt_pk_f16_f32 v36, v74, v75
	v_cvt_pk_f16_f32 v37, v76, v77
	v_pk_mul_f32 v[72:73], v[0:1], v[72:73]
	ds_write2st64_b32 v187, v36, v37 offset0:36 offset1:54
	v_cvt_pk_f16_f32 v36, v78, v79
	v_cvt_pk_f16_f32 v37, v80, v81
	ds_write2st64_b32 v187, v36, v37 offset0:72 offset1:90
	v_cvt_f16_f32_e32 v36, v72
	v_pk_mul_f32 v[70:71], v[0:1], v[70:71]
	v_cvt_f16_f32_e32 v37, v73
	v_cvt_f16_f32_e32 v68, v70
	v_cvt_f16_f32_e32 v69, v71
	ds_write_b16 v180, v36 offset:2
	s_waitcnt lgkmcnt(14)
	ds_write_b16 v180, v37 offset:42
	s_waitcnt lgkmcnt(14)
	ds_write_b16 v180, v68 offset:5122
	s_waitcnt lgkmcnt(14)
	ds_write_b16 v180, v69 offset:5162
	s_nop 0
	s_waitcnt lgkmcnt(9)
	ds_write_b16 v180, v82 offset:10242
	v_lshl_add_u32 v72, v188, 1, v2
	s_nop 0
	s_nop 0
	ds_read_b32 v80, v72 offset:32768
	v_rcp_f32_e32 v68, v64
	v_rcp_f32_e32 v69, v65
	s_nop 0
	s_waitcnt lgkmcnt(10)
	v_cvt_f32_f16_e32 v74, v165
	v_cvt_f32_f16_sdwa v75, v165 dst_sel:DWORD dst_unused:UNUSED_PAD src0_sel:WORD_1
	s_nop 0
	s_waitcnt lgkmcnt(9)
	v_cvt_f32_f16_e32 v78, v163
	v_cvt_f32_f16_sdwa v79, v163 dst_sel:DWORD dst_unused:UNUSED_PAD src0_sel:WORD_1
	v_lshl_add_u32 v250, v190, 1, v2
	ds_read2st64_b32 v[148:149], v250 offset0:64 offset1:80
	v_cvt_f32_f16_e32 v72, v164
	v_cvt_f32_f16_e32 v76, v162
	v_cvt_f32_f16_sdwa v77, v162 dst_sel:DWORD dst_unused:UNUSED_PAD src0_sel:WORD_1
	ds_read2st64_b32 v[162:163], v250 offset0:96 offset1:112
	v_cvt_f32_f16_sdwa v73, v164 dst_sel:DWORD dst_unused:UNUSED_PAD src0_sel:WORD_1
	v_pk_mul_f32 v[36:37], v[66:67], v[74:75]
	v_pk_mul_f32 v[66:67], v[64:65], v[78:79]
	v_pk_mul_f32 v[70:71], v[68:69], v[76:77]
	v_pk_mul_f32 v[68:69], v[68:69], v[72:73]
	v_pk_mul_f32 v[72:73], v[40:41], v[36:37]
	v_pk_mul_f32 v[74:75], v[40:41], v[66:67]
	v_cvt_pk_f16_f32 v36, v36, v37
	v_cvt_pk_f16_f32 v37, v66, v67
	v_pk_mul_f32 v[76:77], v[38:39], v[70:71]
	v_pk_mul_f32 v[78:79], v[38:39], v[68:69]
	ds_write2st64_b32 v189, v36, v37 offset1:18
	v_cvt_pk_f16_f32 v36, v72, v73
	v_cvt_pk_f16_f32 v37, v74, v75
	v_pk_mul_f32 v[70:71], v[0:1], v[70:71]
	ds_write2st64_b32 v189, v36, v37 offset0:36 offset1:54
	v_cvt_pk_f16_f32 v36, v76, v77
	v_cvt_pk_f16_f32 v37, v78, v79
	ds_write2st64_b32 v189, v36, v37 offset0:72 offset1:90
	v_cvt_f16_f32_e32 v36, v70
	v_pk_mul_f32 v[68:69], v[0:1], v[68:69]
	v_cvt_f16_f32_e32 v37, v71
	v_cvt_f16_f32_e32 v66, v68
	v_cvt_f16_f32_e32 v67, v69
	ds_write_b16 v180, v36 offset:4
	s_waitcnt lgkmcnt(14)
	ds_write_b16 v180, v37 offset:44
	s_waitcnt lgkmcnt(14)
	ds_write_b16 v180, v66 offset:5124
	s_waitcnt lgkmcnt(14)
	ds_write_b16 v180, v67 offset:5164
	s_nop 0
	s_waitcnt lgkmcnt(9)
	ds_write_b16 v180, v80 offset:10244
	v_lshl_add_u32 v70, v190, 1, v2
	s_nop 0
	s_nop 0
	ds_read_b32 v78, v70 offset:32768
	v_rcp_f32_e32 v66, v60
	v_rcp_f32_e32 v67, v61
	s_nop 0
	s_waitcnt lgkmcnt(10)
	v_cvt_f32_f16_e32 v72, v149
	v_cvt_f32_f16_sdwa v73, v149 dst_sel:DWORD dst_unused:UNUSED_PAD src0_sel:WORD_1
	s_nop 0
	s_waitcnt lgkmcnt(9)
	v_cvt_f32_f16_e32 v76, v163
	v_cvt_f32_f16_sdwa v77, v163 dst_sel:DWORD dst_unused:UNUSED_PAD src0_sel:WORD_1
	v_cvt_f32_f16_e32 v70, v148
	v_cvt_f32_f16_e32 v74, v162
	v_cvt_f32_f16_sdwa v75, v162 dst_sel:DWORD dst_unused:UNUSED_PAD src0_sel:WORD_1
	v_cvt_f32_f16_sdwa v71, v148 dst_sel:DWORD dst_unused:UNUSED_PAD src0_sel:WORD_1
	v_pk_mul_f32 v[36:37], v[64:65], v[72:73]
	v_pk_mul_f32 v[64:65], v[60:61], v[76:77]
	v_pk_mul_f32 v[68:69], v[66:67], v[74:75]
	v_pk_mul_f32 v[66:67], v[66:67], v[70:71]
	v_pk_mul_f32 v[70:71], v[40:41], v[36:37]
	v_pk_mul_f32 v[72:73], v[40:41], v[64:65]
	v_cvt_pk_f16_f32 v36, v36, v37
	v_cvt_pk_f16_f32 v37, v64, v65
	v_pk_mul_f32 v[74:75], v[38:39], v[68:69]
	v_pk_mul_f32 v[76:77], v[38:39], v[66:67]
	ds_write2st64_b32 v191, v36, v37 offset1:18
	v_cvt_pk_f16_f32 v36, v70, v71
	v_cvt_pk_f16_f32 v37, v72, v73
	v_pk_mul_f32 v[68:69], v[0:1], v[68:69]
	ds_write2st64_b32 v191, v36, v37 offset0:36 offset1:54
	v_cvt_pk_f16_f32 v36, v74, v75
	v_cvt_pk_f16_f32 v37, v76, v77
	ds_write2st64_b32 v191, v36, v37 offset0:72 offset1:90
	v_cvt_f16_f32_e32 v36, v68
	v_pk_mul_f32 v[66:67], v[0:1], v[66:67]
	v_cvt_f16_f32_e32 v37, v69
	v_cvt_f16_f32_e32 v64, v66
	v_cvt_f16_f32_e32 v65, v67
	ds_write_b16 v180, v36 offset:6
	ds_write_b16 v180, v37 offset:46
	ds_write_b16 v180, v64 offset:5126
	s_waitcnt lgkmcnt(14)
	ds_write_b16 v180, v65 offset:5166
	s_nop 0
	s_waitcnt lgkmcnt(7)
	ds_write_b16 v180, v78 offset:10246
	v_perm_b32 v36, v82, v84, s35
	v_perm_b32 v37, v78, v80, s35
	ds_write_b64 v180, v[36:37] offset:10280

.LBB0_935:
	s_or_b64 exec, exec, s[28:29]
	s_waitcnt lgkmcnt(0)
	s_barrier
	ds_read_b128 v[40:43], v216 offset:9216
	ds_read_b128 v[48:51], v216 offset:18496
	ds_read_b128 v[56:59], v216 offset:9280
	ds_read_b128 v[60:63], v216 offset:23040
	ds_read_b128 v[36:39], v216 offset:18432
	s_nop 0
	s_nop 0
	s_nop 0
	ds_read_b128 v[64:67], v216 offset:13824
	s_waitcnt lgkmcnt(1)
	v_mfma_f32_16x16x32_f16 v[52:55], v[40:43], v[36:39], 0
	s_nop 0
	s_nop 0
	s_nop 0
	ds_read_b128 v[68:71], v216 offset:13888
	ds_read_b128 v[72:75], v216 offset:23104
	v_add_u32_e32 v80, 0x1000, v222
	s_nop 0
	v_mfma_f32_16x16x32_f16 v[52:55], v[56:59], v[48:51], v[52:55]
	v_mov_b32_e32 v82, v3
	v_mov_b32_e32 v83, v3
	v_mov_b32_e32 v86, v3
	v_mfma_f32_16x16x32_f16 v[44:47], v[36:39], v[40:43], 0
	s_nop 3
	v_cvt_f16_f32_e32 v0, v52
	v_cvt_f16_f32_e32 v1, v54
	v_cvt_f16_f32_e32 v2, v55
	v_mfma_f32_16x16x32_f16 v[44:47], v[48:51], v[56:59], v[44:47]
	v_cndmask_b32_e64 v79, 0, v0, s[12:13]
	v_cvt_f16_f32_e32 v0, v53
	v_cndmask_b32_e64 v54, 0, v1, s[18:19]
	s_nop 0
	v_mfma_f32_16x16x32_f16 v[40:43], v[60:63], v[40:43], 0
	v_cndmask_b32_e64 v55, 0, v2, s[22:23]
	s_nop 1
	v_cndmask_b32_e64 v76, 0, v44, s[10:11]
	v_cndmask_b32_e64 v77, 0, v45, s[14:15]
	s_nop 0
	s_waitcnt lgkmcnt(2)
	v_mfma_f32_16x16x32_f16 v[36:39], v[36:39], v[64:67], 0
	v_cndmask_b32_e64 v52, 0, v46, s[16:17]
	v_cndmask_b32_e64 v78, 0, v47, s[20:21]
	v_cndmask_b32_e64 v53, v0, 0, s[10:11]
	v_mfma_f32_16x16x32_f16 v[44:47], v[60:63], v[64:67], 0
	v_cvt_pk_f16_f32 v1, v52, v78
	v_cvt_pk_f16_f32 v0, v76, v77
	v_mov_b32_e32 v2, v3
	s_nop 0
	s_waitcnt lgkmcnt(0)
	v_mfma_f32_16x16x32_f16 v[60:63], v[72:75], v[56:59], v[40:43]
	v_add_f32_e32 v56, v217, v76
	v_add_f32_e32 v57, v219, v77
	v_add_f32_e32 v58, v220, v52
	v_mfma_f32_16x16x32_f16 v[40:43], v[48:51], v[68:71], v[36:39]
	v_add_f32_e32 v59, v221, v78
	v_cvt_pk_f16_f32 v67, v26, v27
	v_cvt_pk_f16_f32 v66, v24, v25
	v_pack_b32_f16 v37, v54, v55
	v_pack_b32_f16 v36, v79, v53
	v_mov_b32_e32 v38, v3
	v_mov_b32_e32 v39, v3
	v_mfma_f32_16x16x32_f16 v[52:55], v[72:75], v[68:71], v[44:47]
	ds_read2_b64 v[68:71], v222 offset0:8 offset1:12
	v_cvt_pk_f16_f32 v65, v30, v31
	v_cvt_pk_f16_f32 v64, v28, v29
	v_mfma_f32_16x16x32_f16 v[48:51], v[0:3], v[36:39], 0
	v_cvt_pk_f16_f32 v45, v58, v59
	v_cvt_pk_f16_f32 v44, v56, v57
	v_mov_b32_e32 v46, v3
	v_mfma_f32_16x16x32_f16 v[36:39], v[36:39], v[0:3], 0
	v_mov_b32_e32 v47, v3
	s_nop 2
	v_cvt_pk_f16_f32 v1, v50, v51
	v_cvt_pk_f16_f32 v0, v48, v49
	v_mov_b32_e32 v50, v3
	v_mov_b32_e32 v51, v3
	v_cvt_pk_f16_f32 v49, v38, v39
	v_cvt_pk_f16_f32 v48, v36, v37
	v_mfma_f32_16x16x32_f16 v[44:47], v[0:3], v[44:47], v[56:59]
	v_mov_b32_e32 v87, v3
	v_mov_b32_e32 v90, v3
	v_mov_b32_e32 v91, v3
	v_mfma_f32_16x16x32_f16 v[36:39], v[48:51], v[0:3], 0
	ds_read2_b64 v[128:131], v222 offset1:4
	v_cvt_pk_f16_f32 v59, v34, v35
	v_cvt_pk_f16_f32 v58, v32, v33
	v_cvt_pk_f16_f32 v57, v22, v23
	v_mfma_f32_16x16x32_f16 v[48:51], v[0:3], v[48:51], 0
	v_cvt_pk_f16_f32 v56, v20, v21
	s_nop 2
	v_cvt_pk_f16_f32 v1, v38, v39
	v_cvt_pk_f16_f32 v0, v36, v37
	v_cvt_pk_f16_f32 v37, v46, v47
	v_cvt_pk_f16_f32 v36, v44, v45
	v_mov_b32_e32 v38, v3
	v_mov_b32_e32 v39, v3
	v_cvt_f16_f32_e32 v52, v52
	s_add_i32 s27, s26, 1
	v_mfma_f32_16x16x32_f16 v[44:47], v[0:3], v[36:39], v[44:47]
	v_cvt_pk_f16_f32 v37, v50, v51
	v_cvt_pk_f16_f32 v36, v48, v49
	v_mov_b32_e32 v50, v3
	v_mov_b32_e32 v51, v3
	v_mfma_f32_16x16x32_f16 v[36:39], v[36:39], v[0:3], 0
	s_nop 2
	v_cvt_pk_f16_f32 v1, v46, v47
	v_cvt_pk_f16_f32 v0, v44, v45
	s_nop 2
	v_cvt_pk_f16_f32 v49, v38, v39
	v_cvt_pk_f16_f32 v48, v36, v37
	s_nop 0
	s_nop 0
	s_waitcnt lgkmcnt(0)
	v_mfma_f32_16x16x32_f16 v[36:39], v[128:131], v[56:59], 0
	v_mfma_f32_16x16x32_f16 v[44:47], v[48:51], v[0:3], v[44:47]
	v_cvt_f16_f32_e32 v0, v60
	v_cvt_f16_f32_e32 v1, v61
	v_cvt_f16_f32_e32 v2, v62
	v_cvt_f16_f32_e32 v48, v63
	v_mfma_f32_16x16x32_f16 v[76:79], v[68:71], v[64:67], v[36:39]
	ds_read2_b64 v[72:75], v80 offset0:64 offset1:68
	ds_read2st64_b64 v[132:135], v223 offset0:20 offset1:25
	ds_read2_b64 v[68:71], v80 offset0:72 offset1:76
	s_nop 0
	s_nop 0
	v_cndmask_b32_e64 v0, 0, v0, s[10:11]
	v_cndmask_b32_e64 v49, 0, v1, s[14:15]
	v_cndmask_b32_e64 v1, 0, v2, s[16:17]
	v_cndmask_b32_e64 v2, 0, v48, s[20:21]
	v_pack_b32_f16 v1, v1, v2
	v_pack_b32_f16 v0, v0, v49
	v_mov_b32_e32 v2, v3
	s_nop 0
	s_waitcnt lgkmcnt(1)
	v_mov_b32_e32 v60, v132
	v_mov_b32_e32 v61, v133
	ds_read2_b64 v[128:131], v240 offset1:80
	v_mov_b32_e32 v62, v3
	v_mov_b32_e32 v63, v3
	v_cvt_f16_f32_e32 v36, v40
	ds_read_b128 v[136:139], v182
	v_cvt_f16_f32_e32 v40, v42
	v_mfma_f32_16x16x32_f16 v[48:51], v[0:3], v[60:63], v[76:79]
	v_cvt_pk_f16_f32 v1, v46, v47
	v_cvt_pk_f16_f32 v0, v44, v45
	v_cvt_f16_f32_e32 v37, v41
	v_mov_b32_e32 v78, v3
	v_mov_b32_e32 v79, v3
	s_nop 2
	v_cvt_pk_f16_f32 v77, v50, v51
	v_cvt_pk_f16_f32 v76, v48, v49
	v_cndmask_b32_e64 v88, v40, 0, s[18:19]
	v_mfma_f32_16x16x32_f16 v[56:59], v[72:75], v[56:59], 0
	v_cndmask_b32_e64 v36, v36, 0, s[12:13]
	v_cndmask_b32_e64 v37, 0, v37, s[10:11]
	v_mov_b32_e32 v74, v3
	v_mfma_f32_16x16x32_f16 v[44:47], v[0:3], v[76:79], 0
	ds_read_b64 v[76:77], v224 offset:5120
	ds_read_b128 v[140:143], v182 offset:64
	v_mov_b32_e32 v75, v3
	s_waitcnt lgkmcnt(4)
	v_mfma_f32_16x16x32_f16 v[56:59], v[68:71], v[64:67], v[56:59]
	s_nop 5
	v_cvt_pk_f16_f32 v1, v46, v47
	v_cvt_pk_f16_f32 v0, v44, v45
	s_nop 0
	s_nop 0
	s_nop 0
	s_nop 0
	s_waitcnt lgkmcnt(3)
	v_mov_b32_e32 v80, v128
	v_mov_b32_e32 v81, v129
	ds_read_b64 v[44:45], v225 offset:5120
	ds_read2_b64 v[144:147], v240 offset0:160 offset1:240
	s_nop 0
	s_waitcnt lgkmcnt(4)
	v_pk_mul_f32 v[50:51], v[22:23], v[138:139]
	v_pk_mul_f32 v[48:49], v[20:21], v[136:137]
	ds_read_b128 v[136:139], v182 offset:128
	s_nop 1
	v_mfma_f32_16x16x32_f16 v[48:51], v[80:83], v[0:3], v[48:51]
	v_cvt_f16_f32_e32 v80, v43
	v_cndmask_b32_e64 v89, v80, 0, s[22:23]
	s_nop 0
	s_waitcnt lgkmcnt(4)
	v_mfma_f32_16x16x32_f16 v[40:43], v[76:79], v[60:63], v[48:51]
	s_nop 3
	s_nop 0
	s_nop 0
	ds_read_b64 v[80:81], v226 offset:5120
	v_mov_b32_e32 v76, v130
	v_mov_b32_e32 v77, v131
	v_mov_b32_e32 v46, v3
	s_nop 0
	s_waitcnt lgkmcnt(4)
	v_pk_mul_f32 v[50:51], v[34:35], v[142:143]
	v_pk_mul_f32 v[48:49], v[32:33], v[140:141]
	v_mov_b32_e32 v47, v3
	ds_read_b128 v[128:131], v182 offset:192
	s_nop 0
	v_mfma_f32_16x16x32_f16 v[48:51], v[76:79], v[0:3], v[48:51]
	s_nop 0
	s_nop 0
	s_waitcnt lgkmcnt(3)
	v_mov_b32_e32 v84, v144
	v_mfma_f32_16x16x32_f16 v[48:51], v[44:47], v[60:63], v[48:51]
	s_nop 0
	s_nop 0
	v_mov_b32_e32 v85, v145
	v_pack_b32_f16 v77, v88, v89
	v_mov_b32_e32 v88, v146
	s_nop 0
	s_waitcnt lgkmcnt(2)
	v_pk_mul_f32 v[46:47], v[30:31], v[138:139]
	v_pk_mul_f32 v[44:45], v[28:29], v[136:137]
	v_mov_b32_e32 v89, v147
	v_pack_b32_f16 v76, v36, v37
	v_mfma_f32_16x16x32_f16 v[44:47], v[84:87], v[0:3], v[44:47]
	ds_read_b64 v[84:85], v227 offset:5120
	v_cndmask_b32_e64 v36, v52, 0, s[12:13]
	v_cvt_f16_f32_e32 v37, v53
	v_cndmask_b32_e64 v37, 0, v37, s[10:11]
	s_nop 0
	s_waitcnt lgkmcnt(2)
	v_mfma_f32_16x16x32_f16 v[44:47], v[80:83], v[60:63], v[44:47]
	s_nop 0
	s_nop 0
	v_pack_b32_f16 v72, v36, v37
	ds_read_b128 v[68:71], v228 offset:9216
	ds_read_b128 v[94:97], v228 offset:9280
	s_nop 0
	s_waitcnt lgkmcnt(3)
	v_pk_mul_f32 v[82:83], v[26:27], v[130:131]
	ds_read_b128 v[64:67], v228 offset:18432
	v_pk_mul_f32 v[80:81], v[24:25], v[128:129]
	s_nop 0
	ds_read_b128 v[98:101], v228 offset:23104
	v_mfma_f32_16x16x32_f16 v[78:81], v[88:91], v[0:3], v[80:83]
	ds_read_b128 v[90:93], v228 offset:18496
	s_nop 1
	v_cvt_f16_f32_e32 v82, v54
	v_cvt_f16_f32_e32 v83, v55
	s_nop 0
	s_waitcnt lgkmcnt(5)
	v_mfma_f32_16x16x32_f16 v[52:55], v[84:87], v[60:63], v[78:81]
	ds_read_b128 v[86:89], v228 offset:13824
	s_nop 1
	v_cndmask_b32_e64 v78, v82, 0, s[18:19]
	v_cndmask_b32_e64 v79, v83, 0, s[22:23]
	v_pack_b32_f16 v73, v78, v79
	v_mov_b32_e32 v78, v3
	v_mov_b32_e32 v79, v3
	v_add_u32_e32 v80, s77, v122
	v_add_u32_e32 v81, s76, v237
	v_mfma_f32_16x16x32_f16 v[56:59], v[76:79], v[0:3], v[56:59]
	ds_read_b128 v[76:79], v228 offset:23040
	v_subrev_u32_e32 v102, 64, v80
	v_add_u32_e32 v0, 0xff, v81
	v_mfma_f32_16x16x32_f16 v[58:61], v[72:75], v[60:63], v[56:59]
	v_cndmask_b32_e64 v0, v0, v102, s[2:3]
	v_add_u32_e32 v0, v0, v175
	v_mad_i64_i32 v[0:1], s[28:29], v0, s88, v[126:127]
	s_nop 0
	s_waitcnt lgkmcnt(4)
	v_mfma_f32_16x16x32_f16 v[82:85], v[68:71], v[64:67], 0
	s_nop 2
	v_cvt_f16_f32_e32 v2, v58
	v_cvt_f16_f32_e32 v60, v60
	ds_read_b128 v[128:131], v228 offset:13888
	global_store_short v[0:1], v2, off
	v_subrev_u32_e32 v0, 63, v80
	v_xad_u32 v1, v102, -2, v168
	v_cvt_f16_f32_e32 v2, v59
	s_nop 0
	v_mfma_f32_16x16x32_f16 v[72:75], v[64:67], v[68:71], 0
	v_cndmask_b32_e64 v0, v1, v0, s[2:3]
	v_add_u32_e32 v0, v0, v175
	v_mad_i64_i32 v[0:1], s[28:29], v0, s88, v[126:127]
	s_nop 0
	s_waitcnt lgkmcnt(2)
	v_mfma_f32_16x16x32_f16 v[62:65], v[64:67], v[86:89], 0
	global_store_short v[0:1], v2, off
	v_subrev_u32_e32 v0, 62, v80
	v_xad_u32 v1, v102, -3, v168
	v_mfma_f32_16x16x32_f16 v[82:85], v[94:97], v[90:93], v[82:85]
	v_cndmask_b32_e64 v36, v1, v0, s[2:3]
	v_add_u32_e32 v36, v36, v175
	s_nop 0
	s_waitcnt lgkmcnt(1)
	v_mfma_f32_16x16x32_f16 v[68:71], v[76:79], v[68:71], 0
	v_mfma_f32_16x16x32_f16 v[86:89], v[76:79], v[86:89], 0
	s_nop 2
	v_cvt_f16_f32_e32 v1, v82
	v_cvt_f16_f32_e32 v2, v83
	v_cvt_f16_f32_e32 v66, v85
	v_mfma_f32_16x16x32_f16 v[72:75], v[90:93], v[94:97], v[72:75]
	v_mov_b32_e32 v85, v3
	v_cndmask_b32_e64 v66, 0, v66, s[22:23]
	s_nop 0
	s_waitcnt lgkmcnt(0)
	v_mfma_f32_16x16x32_f16 v[76:79], v[90:93], v[128:131], v[62:65]
	v_mov_b32_e32 v92, v3
	s_nop 2
	v_cndmask_b32_e64 v0, 0, v72, s[10:11]
	v_cndmask_b32_e64 v37, 0, v73, s[14:15]
	v_cvt_f16_f32_e32 v63, v84
	v_mfma_f32_16x16x32_f16 v[94:97], v[98:101], v[94:97], v[68:71]
	v_cndmask_b32_e64 v64, 0, v74, s[16:17]
	v_cndmask_b32_e64 v65, 0, v75, s[20:21]
	v_cndmask_b32_e64 v63, 0, v63, s[18:19]
	v_cndmask_b32_e64 v68, 0, v1, s[12:13]
	v_cndmask_b32_e64 v69, v2, 0, s[10:11]
	v_add_f32_e32 v62, v217, v0
	v_cvt_pk_f16_f32 v1, v64, v65
	v_cvt_pk_f16_f32 v0, v0, v37
	v_mov_b32_e32 v2, v3
	v_pack_b32_f16 v67, v63, v66
	v_pack_b32_f16 v66, v68, v69
	v_mov_b32_e32 v68, v3
	v_mov_b32_e32 v69, v3
	v_add_f32_e32 v63, v219, v37
	v_add_f32_e32 v64, v220, v64
	v_mfma_f32_16x16x32_f16 v[70:73], v[0:3], v[66:69], 0
	v_add_f32_e32 v65, v221, v65
	v_cvt_pk_f16_f32 v83, v64, v65
	v_cvt_pk_f16_f32 v82, v62, v63
	v_mfma_f32_16x16x32_f16 v[66:69], v[66:69], v[0:3], 0
	v_mov_b32_e32 v84, v3
	s_nop 2
	v_cvt_pk_f16_f32 v0, v70, v71
	v_mov_b32_e32 v70, v3
	v_mov_b32_e32 v71, v3
	v_cvt_pk_f16_f32 v1, v72, v73
	v_cvt_pk_f16_f32 v69, v68, v69
	v_cvt_pk_f16_f32 v68, v66, v67
	v_mfma_f32_16x16x32_f16 v[62:65], v[0:3], v[82:85], v[62:65]
	v_mad_i64_i32 v[36:37], s[28:29], v36, s88, v[126:127]
	global_store_short v[36:37], v60, off
	v_mfma_f32_16x16x32_f16 v[72:75], v[68:71], v[0:3], 0
	v_cvt_f16_f32_e32 v82, v61
	v_subrev_u32_e32 v36, 61, v80
	v_xad_u32 v37, v102, -4, v168
	v_mfma_f32_16x16x32_f16 v[66:69], v[0:3], v[68:71], 0
	s_nop 0
	v_cvt_pk_f16_f32 v71, v64, v65
	s_nop 1
	v_cvt_pk_f16_f32 v1, v74, v75
	v_cvt_pk_f16_f32 v0, v72, v73
	ds_read2_b64 v[136:139], v229 offset1:4
	v_mfma_f32_16x16x32_f16 v[56:59], v[98:101], v[128:131], v[86:89]
	v_cvt_pk_f16_f32 v70, v62, v63
	v_mov_b32_e32 v72, v3
	v_mov_b32_e32 v73, v3
	v_cvt_pk_f16_f32 v85, v68, v69
	ds_read2_b64 v[128:131], v229 offset0:8 offset1:12
	v_cvt_pk_f16_f32 v84, v66, v67
	v_mov_b32_e32 v86, v3
	v_mov_b32_e32 v87, v3
	v_mfma_f32_16x16x32_f16 v[88:91], v[0:3], v[70:73], v[62:65]
	s_nop 0
	s_nop 0
	v_cndmask_b32_e64 v36, v37, v36, s[2:3]
	v_mfma_f32_16x16x32_f16 v[60:63], v[84:87], v[0:3], 0
	v_add_u32_e32 v83, v36, v175
	s_nop 2
	v_cvt_pk_f16_f32 v1, v90, v91
	v_cvt_pk_f16_f32 v0, v88, v89
	v_cvt_pk_f16_f32 v67, v54, v55
	v_cvt_pk_f16_f32 v66, v52, v53
	v_cvt_pk_f16_f32 v85, v62, v63
	v_cvt_pk_f16_f32 v84, v60, v61
	v_cvt_pk_f16_f32 v63, v50, v51
	v_cvt_pk_f16_f32 v62, v48, v49
	v_cvt_pk_f16_f32 v61, v42, v43
	v_cvt_pk_f16_f32 v60, v40, v41
	v_cvt_pk_f16_f32 v65, v46, v47
	v_cvt_pk_f16_f32 v64, v44, v45
	s_nop 0
	s_waitcnt lgkmcnt(1)
	v_mfma_f32_16x16x32_f16 v[68:71], v[136:139], v[60:63], 0
	v_add_u32_e32 v36, 0x1000, v229
	v_mov_b32_e32 v93, v3
	v_cvt_f16_f32_e32 v76, v76
	s_nop 0
	s_waitcnt lgkmcnt(0)
	v_mfma_f32_16x16x32_f16 v[98:101], v[128:131], v[64:67], v[68:71]
	ds_read2_b64 v[72:75], v36 offset0:64 offset1:68
	s_nop 1
	ds_read2_b64 v[68:71], v36 offset0:72 offset1:76
	v_cvt_f16_f32_e32 v36, v97
	v_cvt_f16_f32_e32 v97, v77
	v_mfma_f32_16x16x32_f16 v[84:87], v[84:87], v[0:3], v[88:91]
	v_cvt_f16_f32_e32 v0, v94
	v_cvt_f16_f32_e32 v1, v95
	v_cvt_f16_f32_e32 v2, v96
	v_cndmask_b32_e64 v96, v76, 0, s[12:13]
	v_cndmask_b32_e64 v0, 0, v0, s[10:11]
	v_cndmask_b32_e64 v37, 0, v1, s[14:15]
	v_cndmask_b32_e64 v1, 0, v2, s[16:17]
	v_cndmask_b32_e64 v2, 0, v36, s[20:21]
	v_pack_b32_f16 v1, v1, v2
	v_pack_b32_f16 v0, v0, v37
	v_mov_b32_e32 v2, v3
	v_mov_b32_e32 v36, v134
	v_mov_b32_e32 v37, v135
	v_add_u32_e32 v251, 0x800, v240
	ds_read2_b64 v[128:131], v251 offset0:64 offset1:144
	v_mov_b32_e32 v38, v3
	v_mov_b32_e32 v39, v3
	v_mov_b32_e32 v94, v3
	ds_read_b128 v[132:135], v182 offset:256
	v_mov_b32_e32 v95, v3
	v_mfma_f32_16x16x32_f16 v[88:91], v[0:3], v[36:39], v[98:101]
	v_cvt_pk_f16_f32 v1, v86, v87
	v_cvt_pk_f16_f32 v0, v84, v85
	v_cvt_f16_f32_e32 v56, v56
	v_cvt_f16_f32_e32 v98, v78
	v_cvt_f16_f32_e32 v99, v79
	s_nop 2
	v_cvt_pk_f16_f32 v91, v90, v91
	v_cvt_pk_f16_f32 v90, v88, v89
	v_cndmask_b32_e64 v97, 0, v97, s[10:11]
	v_cndmask_b32_e64 v98, v98, 0, s[18:19]
	v_mfma_f32_16x16x32_f16 v[84:87], v[0:3], v[90:93], 0
	v_add_u32_e32 v2, 0x800, v240
	v_mov_b32_e32 v90, v3
	v_mov_b32_e32 v91, v3
	v_cndmask_b32_e64 v99, v99, 0, s[22:23]
	ds_read_b64 v[88:89], v230 offset:5120
	ds_read_b128 v[136:139], v182 offset:320
	s_nop 3
	v_cvt_pk_f16_f32 v1, v86, v87
	v_cvt_pk_f16_f32 v0, v84, v85
	s_nop 0
	s_nop 0
	s_nop 0
	v_mov_b32_e32 v2, v3
	s_nop 0
	s_waitcnt lgkmcnt(3)
	v_mov_b32_e32 v92, v128
	v_mov_b32_e32 v93, v129
	v_add_u32_e32 v251, 0xc00, v240
	ds_read_b64 v[84:85], v231 offset:5120
	ds_read2_b64 v[140:143], v251 offset0:96 offset1:176
	ds_read_b128 v[144:147], v182 offset:384
	s_nop 0
	s_waitcnt lgkmcnt(5)
	v_pk_mul_f32 v[42:43], v[42:43], v[134:135]
	v_pk_mul_f32 v[40:41], v[40:41], v[132:133]
	s_nop 0
	s_nop 0
	v_mfma_f32_16x16x32_f16 v[40:43], v[92:95], v[0:3], v[40:43]
	s_nop 0
	s_waitcnt lgkmcnt(3)
	v_pk_mul_f32 v[48:49], v[48:49], v[136:137]
	v_add_u32_e32 v76, 0xc00, v240
	v_mfma_f32_16x16x32_f16 v[40:43], v[88:91], v[36:39], v[40:43]
	v_mov_b32_e32 v88, v130
	v_mov_b32_e32 v89, v131
	v_pk_mul_f32 v[50:51], v[50:51], v[138:139]
	v_mov_b32_e32 v86, v3
	v_mov_b32_e32 v87, v3
	s_nop 0
	v_mfma_f32_16x16x32_f16 v[48:51], v[88:91], v[0:3], v[48:51]
	ds_read_b64 v[88:89], v232 offset:5120
	s_nop 0
	s_waitcnt lgkmcnt(2)
	v_mov_b32_e32 v92, v140
	v_mfma_f32_16x16x32_f16 v[48:51], v[84:87], v[36:39], v[48:51]
	s_nop 0
	s_nop 0
	v_mov_b32_e32 v93, v141
	v_pack_b32_f16 v76, v96, v97
	v_cndmask_b32_e64 v96, v56, 0, s[12:13]
	s_nop 0
	s_waitcnt lgkmcnt(1)
	v_pk_mul_f32 v[46:47], v[46:47], v[146:147]
	v_pk_mul_f32 v[44:45], v[44:45], v[144:145]
	ds_read_b128 v[84:87], v182 offset:448
	v_cvt_f16_f32_e32 v56, v57
	v_cvt_f16_f32_e32 v57, v58
	v_mfma_f32_16x16x32_f16 v[44:47], v[92:95], v[0:3], v[44:47]
	v_cvt_f16_f32_e32 v58, v59
	v_mov_b32_e32 v92, v142
	v_mov_b32_e32 v93, v143
	s_nop 0
	s_waitcnt lgkmcnt(1)
	v_mfma_f32_16x16x32_f16 v[44:47], v[88:91], v[36:39], v[44:47]
	ds_read_b64 v[88:89], v233 offset:5120
	s_nop 0
	s_nop 0
	v_cndmask_b32_e64 v78, v57, 0, s[18:19]
	v_cndmask_b32_e64 v79, v58, 0, s[22:23]
	v_pack_b32_f16 v77, v98, v99
	s_nop 0
	s_waitcnt lgkmcnt(1)
	v_pk_mul_f32 v[52:53], v[52:53], v[84:85]
	v_cndmask_b32_e64 v84, 0, v56, s[10:11]
	v_mfma_f32_16x16x32_f16 v[56:59], v[72:75], v[60:63], 0
	v_pack_b32_f16 v61, v78, v79
	v_mov_b32_e32 v78, v3
	v_mov_b32_e32 v79, v3
	v_mfma_f32_16x16x32_f16 v[56:59], v[68:71], v[64:67], v[56:59]
	v_mul_f32_e64 v54, v54, v86
	v_mul_f32_e64 v55, v55, v87
	v_pack_b32_f16 v60, v96, v84
	v_mov_b32_e32 v62, v3
	v_mov_b32_e32 v63, v3
	v_mfma_f32_16x16x32_f16 v[52:55], v[92:95], v[0:3], v[52:55]
	v_mfma_f32_16x16x32_f16 v[56:59], v[76:79], v[0:3], v[56:59]
	v_mad_i64_i32 v[0:1], s[28:29], v83, s88, v[126:127]
	global_store_short v[0:1], v82, off
	s_nop 0
	s_waitcnt lgkmcnt(0)
	v_mfma_f32_16x16x32_f16 v[52:55], v[88:91], v[36:39], v[52:55]
	v_subrev_u32_e32 v0, 48, v80
	v_add_u32_e32 v1, 0xef, v81
	v_cndmask_b32_e64 v0, v1, v0, s[2:3]
	v_mfma_f32_16x16x32_f16 v[36:39], v[60:63], v[36:39], v[56:59]
	v_add_u32_e32 v0, v0, v175
	v_mad_i64_i32 v[0:1], s[28:29], v0, s88, v[126:127]
	s_nop 5
	v_cvt_f16_f32_e32 v2, v36
	global_store_short v[0:1], v2, off
	v_subrev_u32_e32 v0, 47, v80
	v_add_u32_e32 v1, 0xee, v81
	v_cvt_f16_f32_e32 v2, v37
	v_cndmask_b32_e64 v0, v1, v0, s[2:3]
	v_add_u32_e32 v0, v0, v175
	v_mad_i64_i32 v[0:1], s[28:29], v0, s88, v[126:127]
	global_store_short v[0:1], v2, off
	v_subrev_u32_e32 v0, 46, v80
	v_add_u32_e32 v1, 0xed, v81
	v_cvt_f16_f32_e32 v2, v38
	v_cndmask_b32_e64 v0, v1, v0, s[2:3]
	v_add_u32_e32 v0, v0, v175
	v_mad_i64_i32 v[0:1], s[28:29], v0, s88, v[126:127]
	global_store_short v[0:1], v2, off
	v_subrev_u32_e32 v0, 45, v80
	v_add_u32_e32 v1, 0xec, v81
	v_cndmask_b32_e64 v0, v1, v0, s[2:3]
	v_cvt_f16_f32_e32 v2, v39
	v_add_u32_e32 v0, v0, v175
	v_mad_i64_i32 v[0:1], s[28:29], v0, s88, v[126:127]
	s_mov_b64 s[28:29], 0
	global_store_short v[0:1], v2, off

.LBB0_942:
	v_cmp_lt_i32_e32 vcc, 2, v178
	s_and_saveexec_b64 s[30:31], vcc
	s_xor_b64 s[68:69], exec, s[30:31]
	s_cbranch_execz .LBB0_944
	v_lshl_add_u32 v250, v208, 1, v2
	ds_read2st64_b32 v[36:37], v250 offset0:64 offset1:80
	ds_read2st64_b32 v[46:47], v250 offset0:96 offset1:112
	v_lshl_add_u32 v48, v208, 1, v2
	s_nop 0
	s_nop 0
	ds_read_b32 v60, v48 offset:32768
	v_rcp_f32_e32 v44, v62
	v_rcp_f32_e32 v45, v63
	s_nop 0
	s_waitcnt lgkmcnt(1)
	v_cvt_f32_f16_e32 v58, v47
	v_cvt_f32_f16_e32 v50, v37
	v_cvt_f32_f16_sdwa v51, v37 dst_sel:DWORD dst_unused:UNUSED_PAD src0_sel:WORD_1
	v_cvt_f32_f16_sdwa v59, v47 dst_sel:DWORD dst_unused:UNUSED_PAD src0_sel:WORD_1
	v_lshl_add_u32 v250, v210, 1, v2
	ds_read2st64_b32 v[148:149], v250 offset0:64 offset1:80
	v_cvt_f32_f16_e32 v48, v36
	v_cvt_f32_f16_e32 v54, v46
	v_cvt_f32_f16_sdwa v55, v46 dst_sel:DWORD dst_unused:UNUSED_PAD src0_sel:WORD_1
	ds_read2st64_b32 v[162:163], v250 offset0:96 offset1:112
	v_cvt_f32_f16_sdwa v49, v36 dst_sel:DWORD dst_unused:UNUSED_PAD src0_sel:WORD_1
	v_pk_mul_f32 v[36:37], v[42:43], v[50:51]
	v_pk_mul_f32 v[42:43], v[62:63], v[58:59]
	v_pk_mul_f32 v[46:47], v[44:45], v[54:55]
	v_pk_mul_f32 v[44:45], v[44:45], v[48:49]
	v_pk_mul_f32 v[48:49], v[40:41], v[36:37]
	v_pk_mul_f32 v[50:51], v[40:41], v[42:43]
	v_cvt_pk_f16_f32 v36, v36, v37
	v_cvt_pk_f16_f32 v37, v42, v43
	v_pk_mul_f32 v[54:55], v[38:39], v[46:47]
	v_pk_mul_f32 v[58:59], v[38:39], v[44:45]
	ds_write2st64_b32 v209, v36, v37 offset1:18
	v_cvt_pk_f16_f32 v36, v48, v49
	v_cvt_pk_f16_f32 v37, v50, v51
	v_pk_mul_f32 v[46:47], v[0:1], v[46:47]
	ds_write2st64_b32 v209, v36, v37 offset0:36 offset1:54
	v_cvt_pk_f16_f32 v36, v54, v55
	v_cvt_pk_f16_f32 v37, v58, v59
	ds_write2st64_b32 v209, v36, v37 offset0:72 offset1:90
	v_cvt_f16_f32_e32 v36, v46
	v_pk_mul_f32 v[44:45], v[0:1], v[44:45]
	v_cvt_f16_f32_e32 v37, v47
	v_cvt_f16_f32_e32 v42, v44
	v_cvt_f16_f32_e32 v43, v45
	ds_write_b16 v180, v36 offset:24
	ds_write_b16 v180, v37 offset:64
	ds_write_b16 v180, v42 offset:5144
	ds_write_b16 v180, v43 offset:5184
	s_nop 0
	s_waitcnt lgkmcnt(9)
	ds_write_b16 v180, v60 offset:10264
	v_lshl_add_u32 v46, v210, 1, v2
	s_nop 0
	s_nop 0
	ds_read_b32 v61, v46 offset:32768
	v_rcp_f32_e32 v42, v56
	v_rcp_f32_e32 v43, v57
	s_nop 0
	s_waitcnt lgkmcnt(10)
	v_cvt_f32_f16_e32 v48, v149
	v_cvt_f32_f16_sdwa v49, v149 dst_sel:DWORD dst_unused:UNUSED_PAD src0_sel:WORD_1
	s_nop 0
	s_waitcnt lgkmcnt(9)
	v_cvt_f32_f16_e32 v54, v163
	v_cvt_f32_f16_sdwa v55, v163 dst_sel:DWORD dst_unused:UNUSED_PAD src0_sel:WORD_1
	v_cvt_f32_f16_e32 v46, v148
	v_lshl_add_u32 v250, v212, 1, v2
	ds_read2st64_b32 v[164:165], v250 offset0:64 offset1:80
	v_cvt_f32_f16_e32 v50, v162
	v_cvt_f32_f16_sdwa v51, v162 dst_sel:DWORD dst_unused:UNUSED_PAD src0_sel:WORD_1
	v_cvt_f32_f16_sdwa v47, v148 dst_sel:DWORD dst_unused:UNUSED_PAD src0_sel:WORD_1
	ds_read2st64_b32 v[148:149], v250 offset0:96 offset1:112
	v_pk_mul_f32 v[36:37], v[62:63], v[48:49]
	v_pk_mul_f32 v[44:45], v[56:57], v[54:55]
	v_pk_mul_f32 v[48:49], v[42:43], v[50:51]
	v_pk_mul_f32 v[42:43], v[42:43], v[46:47]
	v_pk_mul_f32 v[46:47], v[40:41], v[36:37]
	v_pk_mul_f32 v[50:51], v[40:41], v[44:45]
	v_cvt_pk_f16_f32 v36, v36, v37
	v_cvt_pk_f16_f32 v37, v44, v45
	v_pk_mul_f32 v[54:55], v[38:39], v[48:49]
	v_pk_mul_f32 v[58:59], v[38:39], v[42:43]
	ds_write2st64_b32 v211, v36, v37 offset1:18
	v_cvt_pk_f16_f32 v36, v46, v47
	v_cvt_pk_f16_f32 v37, v50, v51
	v_pk_mul_f32 v[48:49], v[0:1], v[48:49]
	ds_write2st64_b32 v211, v36, v37 offset0:36 offset1:54
	v_cvt_pk_f16_f32 v36, v54, v55
	v_cvt_pk_f16_f32 v37, v58, v59
	ds_write2st64_b32 v211, v36, v37 offset0:72 offset1:90
	v_cvt_f16_f32_e32 v36, v48
	v_pk_mul_f32 v[42:43], v[0:1], v[42:43]
	v_cvt_f16_f32_e32 v37, v49
	v_cvt_f16_f32_e32 v42, v42
	v_cvt_f16_f32_e32 v43, v43
	ds_write_b16 v180, v36 offset:26
	s_waitcnt lgkmcnt(14)
	ds_write_b16 v180, v37 offset:66
	s_waitcnt lgkmcnt(14)
	ds_write_b16 v180, v42 offset:5146
	s_waitcnt lgkmcnt(14)
	ds_write_b16 v180, v43 offset:5186
	s_nop 0
	s_waitcnt lgkmcnt(9)
	ds_write_b16 v180, v61 offset:10266
	v_lshl_add_u32 v46, v212, 1, v2
	s_nop 0
	s_nop 0
	ds_read_b32 v58, v46 offset:32768
	v_rcp_f32_e32 v42, v52
	v_rcp_f32_e32 v43, v53
	v_lshl_add_u32 v2, v214, 1, v2
	s_nop 0
	s_waitcnt lgkmcnt(10)
	v_cvt_f32_f16_e32 v48, v165
	v_cvt_f32_f16_sdwa v49, v165 dst_sel:DWORD dst_unused:UNUSED_PAD src0_sel:WORD_1
	s_nop 0
	s_waitcnt lgkmcnt(9)
	v_cvt_f32_f16_e32 v54, v149
	ds_read2st64_b32 v[162:163], v2 offset0:64 offset1:80
	v_cvt_f32_f16_sdwa v55, v149 dst_sel:DWORD dst_unused:UNUSED_PAD src0_sel:WORD_1
	v_cvt_f32_f16_e32 v46, v164
	v_cvt_f32_f16_e32 v50, v148
	ds_read2st64_b32 v[242:243], v2 offset0:96 offset1:112
	v_cvt_f32_f16_sdwa v51, v148 dst_sel:DWORD dst_unused:UNUSED_PAD src0_sel:WORD_1
	v_cvt_f32_f16_sdwa v47, v164 dst_sel:DWORD dst_unused:UNUSED_PAD src0_sel:WORD_1
	v_pk_mul_f32 v[36:37], v[56:57], v[48:49]
	v_pk_mul_f32 v[44:45], v[52:53], v[54:55]
	v_pk_mul_f32 v[48:49], v[42:43], v[50:51]
	v_pk_mul_f32 v[42:43], v[42:43], v[46:47]
	v_pk_mul_f32 v[46:47], v[40:41], v[36:37]
	v_pk_mul_f32 v[50:51], v[40:41], v[44:45]
	v_cvt_pk_f16_f32 v36, v36, v37
	v_cvt_pk_f16_f32 v37, v44, v45
	v_pk_mul_f32 v[54:55], v[38:39], v[48:49]
	v_pk_mul_f32 v[56:57], v[38:39], v[42:43]
	ds_write2st64_b32 v213, v36, v37 offset1:18
	v_cvt_pk_f16_f32 v36, v46, v47
	v_cvt_pk_f16_f32 v37, v50, v51
	v_pk_mul_f32 v[48:49], v[0:1], v[48:49]
	ds_write2st64_b32 v213, v36, v37 offset0:36 offset1:54
	v_cvt_pk_f16_f32 v36, v54, v55
	v_cvt_pk_f16_f32 v37, v56, v57
	ds_write2st64_b32 v213, v36, v37 offset0:72 offset1:90
	v_cvt_f16_f32_e32 v36, v48
	v_pk_mul_f32 v[42:43], v[0:1], v[42:43]
	v_cvt_f16_f32_e32 v37, v49
	v_cvt_f16_f32_e32 v42, v42
	v_cvt_f16_f32_e32 v43, v43
	ds_write_b16 v180, v36 offset:28
	s_waitcnt lgkmcnt(14)
	ds_write_b16 v180, v37 offset:68
	s_waitcnt lgkmcnt(14)
	ds_write_b16 v180, v42 offset:5148
	s_waitcnt lgkmcnt(14)
	ds_write_b16 v180, v43 offset:5188
	s_nop 0
	s_waitcnt lgkmcnt(9)
	ds_write_b16 v180, v58 offset:10268
	s_nop 0
	s_nop 0
	ds_read_b32 v2, v2 offset:32768
	v_rcp_f32_e32 v42, v0
	v_rcp_f32_e32 v43, v1
	s_nop 0
	s_waitcnt lgkmcnt(10)
	v_cvt_f32_f16_e32 v48, v163
	v_cvt_f32_f16_sdwa v49, v163 dst_sel:DWORD dst_unused:UNUSED_PAD src0_sel:WORD_1
	s_nop 0
	s_waitcnt lgkmcnt(9)
	v_cvt_f32_f16_e32 v54, v243
	v_cvt_f32_f16_sdwa v55, v243 dst_sel:DWORD dst_unused:UNUSED_PAD src0_sel:WORD_1
	v_cvt_f32_f16_e32 v46, v162
	v_cvt_f32_f16_e32 v50, v242
	v_cvt_f32_f16_sdwa v51, v242 dst_sel:DWORD dst_unused:UNUSED_PAD src0_sel:WORD_1
	v_cvt_f32_f16_sdwa v47, v162 dst_sel:DWORD dst_unused:UNUSED_PAD src0_sel:WORD_1
	v_pk_mul_f32 v[36:37], v[52:53], v[48:49]
	v_pk_mul_f32 v[44:45], v[0:1], v[54:55]
	v_pk_mul_f32 v[48:49], v[42:43], v[50:51]
	v_pk_mul_f32 v[42:43], v[42:43], v[46:47]
	v_pk_mul_f32 v[46:47], v[40:41], v[36:37]
	v_pk_mul_f32 v[40:41], v[40:41], v[44:45]
	v_cvt_pk_f16_f32 v36, v36, v37
	v_cvt_pk_f16_f32 v37, v44, v45
	v_pk_mul_f32 v[50:51], v[38:39], v[48:49]
	v_pk_mul_f32 v[38:39], v[38:39], v[42:43]
	ds_write2st64_b32 v215, v36, v37 offset1:18
	v_cvt_pk_f16_f32 v36, v46, v47
	v_cvt_pk_f16_f32 v37, v40, v41
	v_pk_mul_f32 v[48:49], v[0:1], v[48:49]
	ds_write2st64_b32 v215, v36, v37 offset0:36 offset1:54
	v_cvt_pk_f16_f32 v36, v50, v51
	v_cvt_pk_f16_f32 v37, v38, v39
	ds_write2st64_b32 v215, v36, v37 offset0:72 offset1:90
	v_cvt_f16_f32_e32 v36, v48
	v_pk_mul_f32 v[42:43], v[0:1], v[42:43]
	v_cvt_f16_f32_e32 v37, v49
	v_cvt_f16_f32_e32 v38, v42
	v_cvt_f16_f32_e32 v39, v43
	ds_write_b16 v180, v36 offset:30
	ds_write_b16 v180, v37 offset:70
	ds_write_b16 v180, v38 offset:5150
	s_waitcnt lgkmcnt(14)
	ds_write_b16 v180, v39 offset:5190
	s_nop 0
	s_waitcnt lgkmcnt(7)
	ds_write_b16 v180, v2 offset:10270
	v_perm_b32 v36, v61, v60, s35
	v_perm_b32 v37, v2, v58, s35
	ds_write_b64 v180, v[36:37] offset:10304
.LBB0_944:
	s_andn2_saveexec_b64 s[68:69], s[68:69]
	s_cbranch_execz .LBB0_946
	v_lshl_add_u32 v250, v200, 1, v2
	ds_read2st64_b32 v[36:37], v250 offset0:64 offset1:80
	ds_read2st64_b32 v[48:49], v250 offset0:96 offset1:112
	v_lshl_add_u32 v52, v200, 1, v2
	s_nop 0
	s_nop 0
	ds_read_b32 v64, v52 offset:32768
	v_rcp_f32_e32 v44, v58
	v_rcp_f32_e32 v45, v59
	s_nop 0
	s_waitcnt lgkmcnt(1)
	v_cvt_f32_f16_e32 v60, v49
	v_cvt_f32_f16_e32 v54, v37
	v_cvt_f32_f16_sdwa v55, v37 dst_sel:DWORD dst_unused:UNUSED_PAD src0_sel:WORD_1
	v_cvt_f32_f16_sdwa v61, v49 dst_sel:DWORD dst_unused:UNUSED_PAD src0_sel:WORD_1
	v_lshl_add_u32 v250, v202, 1, v2
	ds_read2st64_b32 v[148:149], v250 offset0:64 offset1:80
	v_cvt_f32_f16_e32 v52, v36
	v_cvt_f32_f16_e32 v56, v48
	v_cvt_f32_f16_sdwa v57, v48 dst_sel:DWORD dst_unused:UNUSED_PAD src0_sel:WORD_1
	ds_read2st64_b32 v[162:163], v250 offset0:96 offset1:112
	v_cvt_f32_f16_sdwa v53, v36 dst_sel:DWORD dst_unused:UNUSED_PAD src0_sel:WORD_1
	v_pk_mul_f32 v[36:37], v[38:39], v[54:55]
	v_pk_mul_f32 v[48:49], v[58:59], v[60:61]
	v_pk_mul_f32 v[54:55], v[44:45], v[56:57]
	v_pk_mul_f32 v[44:45], v[44:45], v[52:53]
	v_pk_mul_f32 v[52:53], v[40:41], v[36:37]
	v_pk_mul_f32 v[56:57], v[40:41], v[48:49]
	v_cvt_pk_f16_f32 v36, v36, v37
	v_cvt_pk_f16_f32 v37, v48, v49
	v_pk_mul_f32 v[60:61], v[38:39], v[54:55]
	v_pk_mul_f32 v[62:63], v[38:39], v[44:45]
	ds_write2st64_b32 v201, v36, v37 offset1:18
	v_cvt_pk_f16_f32 v36, v52, v53
	v_cvt_pk_f16_f32 v37, v56, v57
	v_pk_mul_f32 v[54:55], v[0:1], v[54:55]
	ds_write2st64_b32 v201, v36, v37 offset0:36 offset1:54
	v_cvt_pk_f16_f32 v36, v60, v61
	v_cvt_pk_f16_f32 v37, v62, v63
	ds_write2st64_b32 v201, v36, v37 offset0:72 offset1:90
	v_cvt_f16_f32_e32 v36, v54
	v_pk_mul_f32 v[44:45], v[0:1], v[44:45]
	v_cvt_f16_f32_e32 v37, v55
	v_cvt_f16_f32_e32 v44, v44
	v_cvt_f16_f32_e32 v45, v45
	ds_write_b16 v180, v36 offset:16
	ds_write_b16 v180, v37 offset:56
	ds_write_b16 v180, v44 offset:5136
	ds_write_b16 v180, v45 offset:5176
	s_nop 0
	s_waitcnt lgkmcnt(9)
	ds_write_b16 v180, v64 offset:10256
	v_lshl_add_u32 v52, v202, 1, v2
	s_nop 0
	s_nop 0
	ds_read_b32 v62, v52 offset:32768
	v_rcp_f32_e32 v44, v50
	v_rcp_f32_e32 v45, v51
	s_nop 0
	s_waitcnt lgkmcnt(10)
	v_cvt_f32_f16_e32 v54, v149
	v_cvt_f32_f16_sdwa v55, v149 dst_sel:DWORD dst_unused:UNUSED_PAD src0_sel:WORD_1
	s_nop 0
	s_waitcnt lgkmcnt(9)
	v_cvt_f32_f16_e32 v60, v163
	v_cvt_f32_f16_sdwa v61, v163 dst_sel:DWORD dst_unused:UNUSED_PAD src0_sel:WORD_1
	v_cvt_f32_f16_e32 v52, v148
	v_lshl_add_u32 v250, v204, 1, v2
	ds_read2st64_b32 v[164:165], v250 offset0:64 offset1:80
	v_cvt_f32_f16_e32 v56, v162
	v_cvt_f32_f16_sdwa v57, v162 dst_sel:DWORD dst_unused:UNUSED_PAD src0_sel:WORD_1
	v_cvt_f32_f16_sdwa v53, v148 dst_sel:DWORD dst_unused:UNUSED_PAD src0_sel:WORD_1
	ds_read2st64_b32 v[148:149], v250 offset0:96 offset1:112
	v_pk_mul_f32 v[36:37], v[58:59], v[54:55]
	v_pk_mul_f32 v[48:49], v[50:51], v[60:61]
	v_pk_mul_f32 v[54:55], v[44:45], v[56:57]
	v_pk_mul_f32 v[44:45], v[44:45], v[52:53]
	v_pk_mul_f32 v[52:53], v[40:41], v[36:37]
	v_pk_mul_f32 v[56:57], v[40:41], v[48:49]
	v_cvt_pk_f16_f32 v36, v36, v37
	v_cvt_pk_f16_f32 v37, v48, v49
	v_pk_mul_f32 v[58:59], v[38:39], v[54:55]
	v_pk_mul_f32 v[60:61], v[38:39], v[44:45]
	ds_write2st64_b32 v203, v36, v37 offset1:18
	v_cvt_pk_f16_f32 v36, v52, v53
	v_cvt_pk_f16_f32 v37, v56, v57
	v_pk_mul_f32 v[54:55], v[0:1], v[54:55]
	ds_write2st64_b32 v203, v36, v37 offset0:36 offset1:54
	v_cvt_pk_f16_f32 v36, v58, v59
	v_cvt_pk_f16_f32 v37, v60, v61
	ds_write2st64_b32 v203, v36, v37 offset0:72 offset1:90
	v_cvt_f16_f32_e32 v36, v54
	v_pk_mul_f32 v[44:45], v[0:1], v[44:45]
	v_cvt_f16_f32_e32 v37, v55
	v_cvt_f16_f32_e32 v44, v44
	v_cvt_f16_f32_e32 v45, v45
	ds_write_b16 v180, v36 offset:18
	s_waitcnt lgkmcnt(14)
	ds_write_b16 v180, v37 offset:58
	s_waitcnt lgkmcnt(14)
	ds_write_b16 v180, v44 offset:5138
	s_waitcnt lgkmcnt(14)
	ds_write_b16 v180, v45 offset:5178
	s_nop 0
	s_waitcnt lgkmcnt(9)
	ds_write_b16 v180, v62 offset:10258
	v_lshl_add_u32 v52, v204, 1, v2
	s_nop 0
	s_nop 0
	ds_read_b32 v60, v52 offset:32768
	v_rcp_f32_e32 v44, v46
	v_rcp_f32_e32 v45, v47
	v_lshl_add_u32 v2, v206, 1, v2
	s_nop 0
	s_waitcnt lgkmcnt(10)
	v_cvt_f32_f16_e32 v54, v165
	v_cvt_f32_f16_sdwa v55, v165 dst_sel:DWORD dst_unused:UNUSED_PAD src0_sel:WORD_1
	s_nop 0
	s_waitcnt lgkmcnt(9)
	v_cvt_f32_f16_e32 v58, v149
	ds_read2st64_b32 v[162:163], v2 offset0:64 offset1:80
	v_cvt_f32_f16_sdwa v59, v149 dst_sel:DWORD dst_unused:UNUSED_PAD src0_sel:WORD_1
	v_cvt_f32_f16_e32 v52, v164
	v_cvt_f32_f16_e32 v56, v148
	ds_read2st64_b32 v[242:243], v2 offset0:96 offset1:112
	v_cvt_f32_f16_sdwa v57, v148 dst_sel:DWORD dst_unused:UNUSED_PAD src0_sel:WORD_1
	v_cvt_f32_f16_sdwa v53, v164 dst_sel:DWORD dst_unused:UNUSED_PAD src0_sel:WORD_1
	v_pk_mul_f32 v[36:37], v[50:51], v[54:55]
	v_pk_mul_f32 v[48:49], v[46:47], v[58:59]
	v_pk_mul_f32 v[50:51], v[44:45], v[56:57]
	v_pk_mul_f32 v[44:45], v[44:45], v[52:53]
	v_pk_mul_f32 v[52:53], v[40:41], v[36:37]
	v_pk_mul_f32 v[54:55], v[40:41], v[48:49]
	v_cvt_pk_f16_f32 v36, v36, v37
	v_cvt_pk_f16_f32 v37, v48, v49
	v_pk_mul_f32 v[56:57], v[38:39], v[50:51]
	v_pk_mul_f32 v[58:59], v[38:39], v[44:45]
	ds_write2st64_b32 v205, v36, v37 offset1:18
	v_cvt_pk_f16_f32 v36, v52, v53
	v_cvt_pk_f16_f32 v37, v54, v55
	v_pk_mul_f32 v[50:51], v[0:1], v[50:51]
	ds_write2st64_b32 v205, v36, v37 offset0:36 offset1:54
	v_cvt_pk_f16_f32 v36, v56, v57
	v_cvt_pk_f16_f32 v37, v58, v59
	ds_write2st64_b32 v205, v36, v37 offset0:72 offset1:90
	v_cvt_f16_f32_e32 v36, v50
	v_pk_mul_f32 v[44:45], v[0:1], v[44:45]
	v_cvt_f16_f32_e32 v37, v51
	v_cvt_f16_f32_e32 v44, v44
	v_cvt_f16_f32_e32 v45, v45
	ds_write_b16 v180, v36 offset:20
	s_waitcnt lgkmcnt(14)
	ds_write_b16 v180, v37 offset:60
	s_waitcnt lgkmcnt(14)
	ds_write_b16 v180, v44 offset:5140
	s_waitcnt lgkmcnt(14)
	ds_write_b16 v180, v45 offset:5180
	s_nop 0
	s_waitcnt lgkmcnt(9)
	ds_write_b16 v180, v60 offset:10260
	s_nop 0
	s_nop 0
	ds_read_b32 v2, v2 offset:32768
	v_rcp_f32_e32 v44, v42
	v_rcp_f32_e32 v45, v43
	s_nop 0
	s_waitcnt lgkmcnt(10)
	v_cvt_f32_f16_e32 v52, v163
	v_cvt_f32_f16_sdwa v53, v163 dst_sel:DWORD dst_unused:UNUSED_PAD src0_sel:WORD_1
	s_nop 0
	s_waitcnt lgkmcnt(9)
	v_cvt_f32_f16_e32 v56, v243
	v_cvt_f32_f16_sdwa v57, v243 dst_sel:DWORD dst_unused:UNUSED_PAD src0_sel:WORD_1
	v_cvt_f32_f16_e32 v50, v162
	v_cvt_f32_f16_e32 v54, v242
	v_cvt_f32_f16_sdwa v55, v242 dst_sel:DWORD dst_unused:UNUSED_PAD src0_sel:WORD_1
	v_cvt_f32_f16_sdwa v51, v162 dst_sel:DWORD dst_unused:UNUSED_PAD src0_sel:WORD_1
	v_pk_mul_f32 v[36:37], v[46:47], v[52:53]
	v_pk_mul_f32 v[42:43], v[42:43], v[56:57]
	v_pk_mul_f32 v[46:47], v[44:45], v[54:55]
	v_pk_mul_f32 v[44:45], v[44:45], v[50:51]
	v_pk_mul_f32 v[48:49], v[40:41], v[36:37]
	v_pk_mul_f32 v[40:41], v[40:41], v[42:43]
	v_cvt_pk_f16_f32 v36, v36, v37
	v_cvt_pk_f16_f32 v37, v42, v43
	v_pk_mul_f32 v[50:51], v[38:39], v[46:47]
	v_pk_mul_f32 v[38:39], v[38:39], v[44:45]
	ds_write2st64_b32 v207, v36, v37 offset1:18
	v_cvt_pk_f16_f32 v36, v48, v49
	v_cvt_pk_f16_f32 v37, v40, v41
	v_pk_mul_f32 v[46:47], v[0:1], v[46:47]
	ds_write2st64_b32 v207, v36, v37 offset0:36 offset1:54
	v_cvt_pk_f16_f32 v36, v50, v51
	v_cvt_pk_f16_f32 v37, v38, v39
	ds_write2st64_b32 v207, v36, v37 offset0:72 offset1:90
	v_cvt_f16_f32_e32 v36, v46
	v_pk_mul_f32 v[44:45], v[0:1], v[44:45]
	v_cvt_f16_f32_e32 v37, v47
	v_cvt_f16_f32_e32 v38, v44
	v_cvt_f16_f32_e32 v39, v45
	ds_write_b16 v180, v36 offset:22
	ds_write_b16 v180, v37 offset:62
	ds_write_b16 v180, v38 offset:5142
	s_waitcnt lgkmcnt(14)
	ds_write_b16 v180, v39 offset:5182
	s_nop 0
	s_waitcnt lgkmcnt(7)
	ds_write_b16 v180, v2 offset:10262
	v_perm_b32 v36, v62, v64, s35
	v_perm_b32 v37, v2, v60, s35
	ds_write_b64 v180, v[36:37] offset:10296

.LBB0_947:
	v_cmp_eq_u32_e32 vcc, 1, v178
	s_and_saveexec_b64 s[68:69], vcc
	s_cbranch_execz .LBB0_949
	v_lshl_add_u32 v250, v192, 1, v2
	ds_read2st64_b32 v[36:37], v250 offset0:64 offset1:80
	ds_read2st64_b32 v[46:47], v250 offset0:96 offset1:112
	v_lshl_add_u32 v50, v192, 1, v2
	s_nop 0
	s_nop 0
	ds_read_b32 v62, v50 offset:32768
	v_rcp_f32_e32 v42, v54
	v_rcp_f32_e32 v43, v55
	s_nop 0
	s_waitcnt lgkmcnt(1)
	v_cvt_f32_f16_e32 v58, v47
	v_cvt_f32_f16_e32 v52, v37
	v_cvt_f32_f16_sdwa v53, v37 dst_sel:DWORD dst_unused:UNUSED_PAD src0_sel:WORD_1
	v_cvt_f32_f16_sdwa v59, v47 dst_sel:DWORD dst_unused:UNUSED_PAD src0_sel:WORD_1
	v_lshl_add_u32 v250, v194, 1, v2
	ds_read2st64_b32 v[148:149], v250 offset0:64 offset1:80
	v_cvt_f32_f16_e32 v50, v36
	v_cvt_f32_f16_e32 v56, v46
	v_cvt_f32_f16_sdwa v57, v46 dst_sel:DWORD dst_unused:UNUSED_PAD src0_sel:WORD_1
	ds_read2st64_b32 v[162:163], v250 offset0:96 offset1:112
	v_cvt_f32_f16_sdwa v51, v36 dst_sel:DWORD dst_unused:UNUSED_PAD src0_sel:WORD_1
	v_pk_mul_f32 v[36:37], v[60:61], v[52:53]
	v_pk_mul_f32 v[46:47], v[54:55], v[58:59]
	v_pk_mul_f32 v[52:53], v[42:43], v[56:57]
	v_pk_mul_f32 v[42:43], v[42:43], v[50:51]
	v_pk_mul_f32 v[50:51], v[40:41], v[36:37]
	v_pk_mul_f32 v[56:57], v[40:41], v[46:47]
	v_cvt_pk_f16_f32 v36, v36, v37
	v_cvt_pk_f16_f32 v37, v46, v47
	v_pk_mul_f32 v[58:59], v[38:39], v[52:53]
	v_pk_mul_f32 v[60:61], v[38:39], v[42:43]
	ds_write2st64_b32 v193, v36, v37 offset1:18
	v_cvt_pk_f16_f32 v36, v50, v51
	v_cvt_pk_f16_f32 v37, v56, v57
	v_pk_mul_f32 v[52:53], v[0:1], v[52:53]
	ds_write2st64_b32 v193, v36, v37 offset0:36 offset1:54
	v_cvt_pk_f16_f32 v36, v58, v59
	v_cvt_pk_f16_f32 v37, v60, v61
	ds_write2st64_b32 v193, v36, v37 offset0:72 offset1:90
	v_cvt_f16_f32_e32 v36, v52
	v_pk_mul_f32 v[42:43], v[0:1], v[42:43]
	v_cvt_f16_f32_e32 v37, v53
	v_cvt_f16_f32_e32 v42, v42
	v_cvt_f16_f32_e32 v43, v43
	ds_write_b16 v180, v36 offset:8
	ds_write_b16 v180, v37 offset:48
	ds_write_b16 v180, v42 offset:5128
	ds_write_b16 v180, v43 offset:5168
	s_nop 0
	s_waitcnt lgkmcnt(9)
	ds_write_b16 v180, v62 offset:10248
	v_lshl_add_u32 v50, v194, 1, v2
	s_nop 0
	s_nop 0
	ds_read_b32 v60, v50 offset:32768
	v_rcp_f32_e32 v42, v48
	v_rcp_f32_e32 v43, v49
	s_nop 0
	s_waitcnt lgkmcnt(10)
	v_cvt_f32_f16_e32 v52, v149
	v_cvt_f32_f16_sdwa v53, v149 dst_sel:DWORD dst_unused:UNUSED_PAD src0_sel:WORD_1
	s_nop 0
	s_waitcnt lgkmcnt(9)
	v_cvt_f32_f16_e32 v58, v163
	v_cvt_f32_f16_sdwa v59, v163 dst_sel:DWORD dst_unused:UNUSED_PAD src0_sel:WORD_1
	v_cvt_f32_f16_e32 v50, v148
	v_lshl_add_u32 v250, v196, 1, v2
	ds_read2st64_b32 v[164:165], v250 offset0:64 offset1:80
	v_cvt_f32_f16_e32 v56, v162
	v_cvt_f32_f16_sdwa v57, v162 dst_sel:DWORD dst_unused:UNUSED_PAD src0_sel:WORD_1
	v_cvt_f32_f16_sdwa v51, v148 dst_sel:DWORD dst_unused:UNUSED_PAD src0_sel:WORD_1
	ds_read2st64_b32 v[148:149], v250 offset0:96 offset1:112
	v_pk_mul_f32 v[36:37], v[54:55], v[52:53]
	v_pk_mul_f32 v[46:47], v[48:49], v[58:59]
	v_pk_mul_f32 v[52:53], v[42:43], v[56:57]
	v_pk_mul_f32 v[42:43], v[42:43], v[50:51]
	v_pk_mul_f32 v[50:51], v[40:41], v[36:37]
	v_pk_mul_f32 v[54:55], v[40:41], v[46:47]
	v_cvt_pk_f16_f32 v36, v36, v37
	v_cvt_pk_f16_f32 v37, v46, v47
	v_pk_mul_f32 v[56:57], v[38:39], v[52:53]
	v_pk_mul_f32 v[58:59], v[38:39], v[42:43]
	ds_write2st64_b32 v195, v36, v37 offset1:18
	v_cvt_pk_f16_f32 v36, v50, v51
	v_cvt_pk_f16_f32 v37, v54, v55
	v_pk_mul_f32 v[52:53], v[0:1], v[52:53]
	ds_write2st64_b32 v195, v36, v37 offset0:36 offset1:54
	v_cvt_pk_f16_f32 v36, v56, v57
	v_cvt_pk_f16_f32 v37, v58, v59
	ds_write2st64_b32 v195, v36, v37 offset0:72 offset1:90
	v_cvt_f16_f32_e32 v36, v52
	v_pk_mul_f32 v[42:43], v[0:1], v[42:43]
	v_cvt_f16_f32_e32 v37, v53
	v_cvt_f16_f32_e32 v42, v42
	v_cvt_f16_f32_e32 v43, v43
	ds_write_b16 v180, v36 offset:10
	s_waitcnt lgkmcnt(14)
	ds_write_b16 v180, v37 offset:50
	s_waitcnt lgkmcnt(14)
	ds_write_b16 v180, v42 offset:5130
	s_waitcnt lgkmcnt(14)
	ds_write_b16 v180, v43 offset:5170
	s_nop 0
	s_waitcnt lgkmcnt(9)
	ds_write_b16 v180, v60 offset:10250
	v_lshl_add_u32 v50, v196, 1, v2
	s_nop 0
	s_nop 0
	ds_read_b32 v58, v50 offset:32768
	v_rcp_f32_e32 v42, v44
	v_rcp_f32_e32 v43, v45
	v_lshl_add_u32 v2, v198, 1, v2
	s_nop 0
	s_waitcnt lgkmcnt(10)
	v_cvt_f32_f16_e32 v52, v165
	v_cvt_f32_f16_sdwa v53, v165 dst_sel:DWORD dst_unused:UNUSED_PAD src0_sel:WORD_1
	ds_read2st64_b32 v[162:163], v2 offset0:64 offset1:80
	s_nop 0
	s_waitcnt lgkmcnt(10)
	v_cvt_f32_f16_e32 v56, v149
	v_cvt_f32_f16_sdwa v57, v149 dst_sel:DWORD dst_unused:UNUSED_PAD src0_sel:WORD_1
	ds_read2st64_b32 v[242:243], v2 offset0:96 offset1:112
	v_cvt_f32_f16_e32 v50, v164
	v_cvt_f32_f16_e32 v54, v148
	v_cvt_f32_f16_sdwa v55, v148 dst_sel:DWORD dst_unused:UNUSED_PAD src0_sel:WORD_1
	v_cvt_f32_f16_sdwa v51, v164 dst_sel:DWORD dst_unused:UNUSED_PAD src0_sel:WORD_1
	v_pk_mul_f32 v[36:37], v[48:49], v[52:53]
	v_pk_mul_f32 v[46:47], v[44:45], v[56:57]
	v_pk_mul_f32 v[48:49], v[42:43], v[54:55]
	v_pk_mul_f32 v[42:43], v[42:43], v[50:51]
	v_pk_mul_f32 v[50:51], v[40:41], v[36:37]
	v_pk_mul_f32 v[52:53], v[40:41], v[46:47]
	v_cvt_pk_f16_f32 v36, v36, v37
	v_cvt_pk_f16_f32 v37, v46, v47
	v_pk_mul_f32 v[54:55], v[38:39], v[48:49]
	v_pk_mul_f32 v[56:57], v[38:39], v[42:43]
	ds_write2st64_b32 v197, v36, v37 offset1:18
	v_cvt_pk_f16_f32 v36, v50, v51
	v_cvt_pk_f16_f32 v37, v52, v53
	v_pk_mul_f32 v[48:49], v[0:1], v[48:49]
	ds_write2st64_b32 v197, v36, v37 offset0:36 offset1:54
	v_cvt_pk_f16_f32 v36, v54, v55
	v_cvt_pk_f16_f32 v37, v56, v57
	ds_write2st64_b32 v197, v36, v37 offset0:72 offset1:90
	v_cvt_f16_f32_e32 v36, v48
	v_pk_mul_f32 v[42:43], v[0:1], v[42:43]
	v_cvt_f16_f32_e32 v37, v49
	v_cvt_f16_f32_e32 v42, v42
	v_cvt_f16_f32_e32 v43, v43
	ds_write_b16 v180, v36 offset:12
	s_waitcnt lgkmcnt(14)
	ds_write_b16 v180, v37 offset:52
	s_waitcnt lgkmcnt(14)
	ds_write_b16 v180, v42 offset:5132
	s_waitcnt lgkmcnt(14)
	ds_write_b16 v180, v43 offset:5172
	s_nop 0
	s_waitcnt lgkmcnt(9)
	ds_write_b16 v180, v58 offset:10252
	s_nop 0
	s_nop 0
	ds_read_b32 v2, v2 offset:32768
	s_nop 0
	s_waitcnt lgkmcnt(10)
	v_cvt_f32_f16_e32 v48, v163
	v_cvt_f32_f16_sdwa v49, v163 dst_sel:DWORD dst_unused:UNUSED_PAD src0_sel:WORD_1
	s_nop 0
	s_waitcnt lgkmcnt(9)
	v_cvt_f32_f16_e32 v52, v243
	v_cvt_f32_f16_sdwa v53, v243 dst_sel:DWORD dst_unused:UNUSED_PAD src0_sel:WORD_1
	v_cvt_f32_f16_e32 v46, v162
	v_cvt_f32_f16_e32 v50, v242
	v_cvt_f32_f16_sdwa v51, v242 dst_sel:DWORD dst_unused:UNUSED_PAD src0_sel:WORD_1
	v_cvt_f32_f16_sdwa v47, v162 dst_sel:DWORD dst_unused:UNUSED_PAD src0_sel:WORD_1
	v_pk_mul_f32 v[36:37], v[44:45], v[48:49]
	v_pk_mul_f32 v[42:43], v[38:39], v[52:53]
	v_pk_mul_f32 v[44:45], v[40:41], v[50:51]
	v_pk_mul_f32 v[46:47], v[40:41], v[46:47]
	v_pk_mul_f32 v[48:49], v[40:41], v[36:37]
	v_pk_mul_f32 v[40:41], v[40:41], v[42:43]
	v_cvt_pk_f16_f32 v36, v36, v37
	v_cvt_pk_f16_f32 v37, v42, v43
	v_pk_mul_f32 v[50:51], v[38:39], v[44:45]
	v_pk_mul_f32 v[38:39], v[38:39], v[46:47]
	ds_write2st64_b32 v199, v36, v37 offset1:18
	v_cvt_pk_f16_f32 v36, v48, v49
	v_cvt_pk_f16_f32 v37, v40, v41
	v_pk_mul_f32 v[44:45], v[0:1], v[44:45]
	ds_write2st64_b32 v199, v36, v37 offset0:36 offset1:54
	v_cvt_pk_f16_f32 v36, v50, v51
	v_cvt_pk_f16_f32 v37, v38, v39
	ds_write2st64_b32 v199, v36, v37 offset0:72 offset1:90
	v_cvt_f16_f32_e32 v36, v44
	v_pk_mul_f32 v[46:47], v[0:1], v[46:47]
	v_cvt_f16_f32_e32 v37, v45
	v_cvt_f16_f32_e32 v38, v46
	v_cvt_f16_f32_e32 v39, v47
	ds_write_b16 v180, v36 offset:14
	ds_write_b16 v180, v37 offset:54
	ds_write_b16 v180, v38 offset:5134
	s_waitcnt lgkmcnt(14)
	ds_write_b16 v180, v39 offset:5174
	s_nop 0
	s_waitcnt lgkmcnt(7)
	ds_write_b16 v180, v2 offset:10254
	v_perm_b32 v36, v60, v62, s35
	v_perm_b32 v37, v2, v58, s35
	ds_write_b64 v180, v[36:37] offset:10288

.LBB0_994:
	s_or_b64 exec, exec, s[0:1]
	s_nop 5
	v_cvt_f16_f32_e32 v65, v65
	v_cvt_f16_f32_e32 v64, v64
	s_add_i32 s30, s30, 1
	v_cndmask_b32_e64 v68, 0, v65, s[24:25]
	v_cvt_f16_f32_e32 v65, v66
	v_cvt_f16_f32_e32 v66, v67
	v_cndmask_b32_e64 v64, v64, 0, s[22:23]
	v_pack_b32_f16 v64, v64, v68
	v_cndmask_b32_e64 v65, v65, 0, s[26:27]
	v_cndmask_b32_e64 v66, v66, 0, s[28:29]
	v_pack_b32_f16 v65, v65, v66
	ds_write_b64 v115, v[64:65]
	s_waitcnt lgkmcnt(0)
	s_barrier
	ds_read_b128 v[118:121], v116 offset:55360
	ds_read_b128 v[122:125], v117
	ds_read_b128 v[142:145], v117 offset:64
	ds_read_b128 v[146:149], v117 offset:2304
	ds_read_b128 v[162:165], v117 offset:2368
	ds_read_b128 v[178:181], v117 offset:4608
	ds_read_b128 v[182:185], v117 offset:4672
	ds_read_b128 v[186:189], v117 offset:6912
	ds_read_b128 v[64:67], v116 offset:55296
	ds_read_b128 v[190:193], v117 offset:6976
	s_nop 0
	s_nop 0
	s_nop 0
	v_add_u32_e32 v251, 0x1e500, v87
	s_waitcnt lgkmcnt(1)
	v_mfma_f32_16x16x32_f16 v[52:55], v[64:67], v[122:125], v[52:55]
	ds_read_b128 v[194:197], v251
	s_nop 0
	v_add_u32_e32 v68, 0x1e500, v87
	s_nop 0
	v_mfma_f32_16x16x32_f16 v[52:55], v[118:121], v[142:145], v[52:55]
	s_nop 0
	ds_read_b128 v[142:145], v117 offset:46080
	s_nop 0
	v_mfma_f32_16x16x32_f16 v[56:59], v[64:67], v[146:149], v[56:59]
	s_nop 0
	s_nop 3
	ds_read_b128 v[146:149], v117 offset:46144
	v_cvt_pk_f16_f32 v55, v54, v55
	v_cvt_pk_f16_f32 v54, v52, v53
	s_nop 0
	ds_read_b128 v[198:201], v68 offset:64
	v_mfma_f32_16x16x32_f16 v[56:59], v[118:121], v[162:165], v[56:59]
	s_nop 0
	s_nop 0
	v_mfma_f32_16x16x32_f16 v[60:63], v[64:67], v[178:181], v[60:63]
	ds_read_b128 v[162:165], v117 offset:48384
	s_nop 0
	s_nop 0
	v_mfma_f32_16x16x32_f16 v[60:63], v[118:121], v[182:185], v[60:63]
	ds_read_b128 v[178:181], v117 offset:48448
	s_nop 0
	s_nop 0
	v_mfma_f32_16x16x32_f16 v[48:51], v[64:67], v[186:189], v[48:51]
	ds_read_b128 v[182:185], v68 offset:128
	s_nop 0
	s_nop 0
	s_waitcnt lgkmcnt(7)
	v_mfma_f32_16x16x32_f16 v[48:51], v[118:121], v[190:193], v[48:51]
	s_nop 0
	ds_read_b128 v[186:189], v117 offset:50688
	s_nop 0
	s_waitcnt lgkmcnt(7)
	v_pk_mul_f32 v[8:9], v[8:9], v[194:195]
	v_pk_mul_f32 v[10:11], v[10:11], v[196:197]
	ds_read_b128 v[190:193], v117 offset:50752
	s_nop 0
	s_nop 2
	v_cvt_pk_f16_f32 v51, v50, v51
	ds_read_b128 v[194:197], v68 offset:192
	s_nop 0
	s_waitcnt lgkmcnt(8)
	v_mfma_f32_16x16x32_f16 v[8:11], v[142:145], v[64:67], v[8:11]
	s_nop 0
	v_cvt_pk_f16_f32 v50, v48, v49
	s_nop 0
	s_waitcnt lgkmcnt(7)
	v_mfma_f32_16x16x32_f16 v[8:11], v[146:149], v[118:121], v[8:11]
	s_nop 0
	s_nop 0
	s_waitcnt lgkmcnt(6)
	v_pk_mul_f32 v[4:5], v[4:5], v[198:199]
	v_pk_mul_f32 v[6:7], v[6:7], v[200:201]
	s_nop 0
	s_nop 0
	s_waitcnt lgkmcnt(5)
	v_mfma_f32_16x16x32_f16 v[4:7], v[162:165], v[64:67], v[4:7]
	s_nop 0
	s_nop 0
	s_waitcnt lgkmcnt(4)
	v_mfma_f32_16x16x32_f16 v[4:7], v[178:181], v[118:121], v[4:7]
	s_nop 0
	s_nop 0
	s_waitcnt lgkmcnt(3)
	v_pk_mul_f32 v[16:17], v[16:17], v[182:183]
	v_pk_mul_f32 v[18:19], v[18:19], v[184:185]
	s_nop 0
	s_nop 0
	s_waitcnt lgkmcnt(2)
	v_mfma_f32_16x16x32_f16 v[16:19], v[186:189], v[64:67], v[16:19]
	s_nop 0
	s_nop 0
	s_waitcnt lgkmcnt(1)
	v_mfma_f32_16x16x32_f16 v[16:19], v[190:193], v[118:121], v[16:19]
	s_nop 0
	s_nop 0
	s_waitcnt lgkmcnt(0)
	v_pk_mul_f32 v[12:13], v[12:13], v[194:195]
	v_pk_mul_f32 v[14:15], v[14:15], v[196:197]
	ds_read_b128 v[122:125], v117 offset:52992
	s_nop 0
	s_waitcnt lgkmcnt(0)
	v_mfma_f32_16x16x32_f16 v[12:15], v[122:125], v[64:67], v[12:15]
	ds_read_b128 v[64:67], v117 offset:53056
	s_nop 0
	s_waitcnt lgkmcnt(0)
	v_mfma_f32_16x16x32_f16 v[12:15], v[64:67], v[118:121], v[12:15]
	v_add_u32_e32 v65, s96, v104
	v_add_u32_e32 v64, s80, v80
	v_add_u32_e32 v66, 0x7ff, v65
	v_cndmask_b32_e64 v66, v66, v64, s[2:3]
	v_add_u32_e32 v52, v66, v81
	v_mad_i64_i32 v[52:53], s[0:1], v52, s88, v[76:77]
	global_store_dwordx2 v[52:53], v[54:55], off
	v_add_u32_e32 v52, 16, v64
	v_add_u32_e32 v53, 0x7ef, v65
	v_cndmask_b32_e64 v54, v53, v52, s[2:3]
	v_add_u32_e32 v54, v54, v81
	v_cvt_pk_f16_f32 v53, v58, v59
	v_cvt_pk_f16_f32 v52, v56, v57
	v_mad_i64_i32 v[54:55], s[0:1], v54, s88, v[76:77]
	global_store_dwordx2 v[54:55], v[52:53], off
	v_add_u32_e32 v52, 32, v64
	v_add_u32_e32 v53, 0x7df, v65
	v_cndmask_b32_e64 v54, v53, v52, s[2:3]
	v_add_u32_e32 v54, v54, v81
	v_cvt_pk_f16_f32 v53, v62, v63
	v_cvt_pk_f16_f32 v52, v60, v61
	v_mad_i64_i32 v[54:55], s[0:1], v54, s88, v[76:77]
	global_store_dwordx2 v[54:55], v[52:53], off
	v_add_u32_e32 v52, 48, v64
	v_add_u32_e32 v53, 0x7cf, v65
	v_cndmask_b32_e64 v52, v53, v52, s[2:3]
	v_add_u32_e32 v48, v52, v81
	s_sub_i32 s96, s96, 64
	s_add_i32 s80, s80, 64
	v_mad_i64_i32 v[48:49], s[0:1], v48, s88, v[76:77]
	s_cmpk_lg_i32 s96, 0xf800
	global_store_dwordx2 v[48:49], v[50:51], off
	s_cbranch_scc0 .LBB0_1011

.LBB0_1003:
	v_add_u32_e32 v251, v84, v98
	ds_read_b128 v[48:51], v251
	v_add_u32_e32 v52, v84, v98
	s_nop 0
	ds_read_b128 v[52:55], v251 offset:64
	s_nop 0
	s_waitcnt lgkmcnt(1)
	v_mfma_f32_16x16x32_f16 v[48:51], v[48:51], v[40:43], 0
	s_nop 0
	s_waitcnt lgkmcnt(0)
	v_mfma_f32_16x16x32_f16 v[48:51], v[52:55], v[44:47], v[48:51]
	s_nop 7
	ds_write_b128 v99, v[48:51]
	s_and_saveexec_b64 s[0:1], s[68:69]
	s_cbranch_execz .LBB0_1005
	v_mul_f32_e32 v48, 0x3fb8aa3b, v48
	v_mul_f32_e32 v49, 0x3fb8aa3b, v49
	v_mul_f32_e32 v50, 0x3fb8aa3b, v50
	v_mul_f32_e32 v51, 0x3fb8aa3b, v51
	v_exp_f32_e32 v48, v48
	v_exp_f32_e32 v49, v49
	v_exp_f32_e32 v50, v50
	v_exp_f32_e32 v51, v51
	ds_write_b128 v102, v[48:51]
.LBB0_1005:
	s_or_b64 exec, exec, s[0:1]
	v_add_u32_e32 v251, v84, v100
	ds_read_b128 v[48:51], v251
	v_add_u32_e32 v52, v84, v100
	s_nop 0
	ds_read_b128 v[52:55], v251 offset:64
	s_nop 0
	s_waitcnt lgkmcnt(1)
	v_mfma_f32_16x16x32_f16 v[48:51], v[48:51], v[40:43], 0
	s_nop 0
	s_waitcnt lgkmcnt(0)
	v_mfma_f32_16x16x32_f16 v[48:51], v[52:55], v[44:47], v[48:51]
	s_nop 7
	ds_write_b128 v101, v[48:51]
	s_and_saveexec_b64 s[0:1], s[68:69]
	s_cbranch_execz .LBB0_1007
	v_mul_f32_e32 v48, 0x3fb8aa3b, v48
	v_mul_f32_e32 v49, 0x3fb8aa3b, v49
	v_mul_f32_e32 v50, 0x3fb8aa3b, v50
	v_mul_f32_e32 v51, 0x3fb8aa3b, v51
	v_exp_f32_e32 v48, v48
	v_exp_f32_e32 v49, v49
	v_exp_f32_e32 v50, v50
	v_exp_f32_e32 v51, v51
	ds_write_b128 v103, v[48:51]
.LBB0_1007:
	s_or_b64 exec, exec, s[0:1]
	v_add_u32_e32 v57, s80, v82
	v_add_u32_e32 v56, 0x7ff, v56
	v_cndmask_b32_e64 v56, v56, v57, s[2:3]
	s_waitcnt lgkmcnt(0)
	s_barrier
	ds_read_b128 v[58:61], v83
	ds_read_b128 v[62:65], v88
	ds_read_b128 v[48:51], v83 offset:9216
	s_nop 0
	ds_read_b128 v[66:69], v85
	ds_read_b128 v[52:55], v88 offset:9216
	v_lshrrev_b32_e32 v57, 6, v56
	v_and_b32_e32 v56, 63, v56
	v_cndmask_b32_e64 v56, v56, v57, s[6:7]
	v_lshl_or_b32 v57, v56, 6, v112
	s_nop 0
	v_add_u32_e32 v251, s81, v57
	ds_read_b128 v[122:125], v251
	ds_read_b128 v[118:121], v85 offset:16
	v_add_u32_e32 v75, s81, v57
	s_add_i32 s0, 0, 0x1f600
	v_add_u32_e32 v250, s0, v57
	ds_read_b128 v[126:129], v250
	v_add_u32_e32 v79, s0, v57
	s_nop 0
	s_nop 0
	s_nop 0
	s_waitcnt lgkmcnt(6)
	v_cvt_f32_f16_sdwa v137, v62 dst_sel:DWORD dst_unused:UNUSED_PAD src0_sel:WORD_1
	v_cvt_f32_f16_e32 v136, v62
	v_or_b32_e32 v57, 16, v57
	v_cvt_f32_f16_sdwa v135, v58 dst_sel:DWORD dst_unused:UNUSED_PAD src0_sel:WORD_1
	v_cvt_f32_f16_e32 v134, v58
	s_nop 0
	s_waitcnt lgkmcnt(4)
	v_mul_f32_e32 v56, 0x3fb8aa3b, v66
	v_add_u32_e32 v140, s81, v57
	ds_read_b128 v[130:133], v93
	v_add_u32_e32 v141, s0, v57
	v_mul_f32_e32 v57, 0x3fb8aa3b, v67
	v_exp_f32_e32 v56, v56
	v_exp_f32_e32 v57, v57
	v_pk_mul_f32 v[136:137], v[136:137], s[72:73] op_sel_hi:[1,0]
	v_pk_mul_f32 v[134:135], v[134:135], s[72:73] op_sel_hi:[1,0]
	s_nop 0
	s_waitcnt lgkmcnt(1)
	v_pk_mul_f32 v[136:137], v[136:137], v[126:127]
	v_rcp_f32_e32 v66, v56
	v_cndmask_b32_e64 v137, v137, -v137, s[8:9]
	v_cndmask_b32_e64 v136, v136, -v136, s[8:9]
	v_pk_fma_f32 v[134:135], v[134:135], v[122:123], v[136:137]
	v_cvt_f32_f16_sdwa v137, v48 dst_sel:DWORD dst_unused:UNUSED_PAD src0_sel:WORD_1
	v_pk_mul_f32 v[138:139], v[134:135], v[56:57]
	v_cvt_f32_f16_sdwa v135, v52 dst_sel:DWORD dst_unused:UNUSED_PAD src0_sel:WORD_1
	v_cvt_f32_f16_e32 v134, v52
	v_cvt_f32_f16_e32 v136, v48
	s_nop 0
	v_rcp_f32_e32 v67, v57
	v_pk_mul_f32 v[126:127], v[126:127], v[134:135]
	v_add_u32_e32 v52, v72, v89
	v_cndmask_b32_e64 v127, v127, -v127, s[8:9]
	v_cndmask_b32_e64 v126, v126, -v126, s[8:9]
	v_pk_fma_f32 v[122:123], v[122:123], v[136:137], v[126:127]
	ds_read_b128 v[134:137], v94
	v_pk_mul_f32 v[126:127], v[122:123], v[66:67]
	v_cvt_f32_f16_e32 v58, v63
	s_nop 0
	s_waitcnt lgkmcnt(1)
	v_fma_mixlo_f16 v48, v130, v126, 0
	ds_write_b16 v52, v48 offset:46080
	v_fma_mixlo_f16 v48, v131, v127, 0
	ds_write_b16 v113, v48 offset:46080
	v_mul_f32_e32 v48, 0x3fb8aa3b, v68
	v_exp_f32_e32 v66, v48
	v_mul_f32_e32 v48, 0x3fb8aa3b, v69
	v_cvt_f32_f16_sdwa v69, v59 dst_sel:DWORD dst_unused:UNUSED_PAD src0_sel:WORD_1
	v_cvt_f32_f16_e32 v68, v59
	v_cvt_f32_f16_sdwa v59, v63 dst_sel:DWORD dst_unused:UNUSED_PAD src0_sel:WORD_1
	v_exp_f32_e32 v67, v48
	v_cvt_f32_f16_e32 v52, v49
	v_pk_mul_f32 v[68:69], v[68:69], s[72:73] op_sel_hi:[1,0]
	v_pk_mul_f32 v[58:59], v[58:59], s[72:73] op_sel_hi:[1,0]
	v_rcp_f32_e32 v62, v66
	v_pk_mul_f32 v[58:59], v[58:59], v[128:129]
	v_rcp_f32_e32 v63, v67
	v_cndmask_b32_e64 v59, v59, -v59, s[8:9]
	v_cndmask_b32_e64 v58, v58, -v58, s[8:9]
	v_pk_fma_f32 v[58:59], v[68:69], v[124:125], v[58:59]
	v_cvt_pk_f16_f32 v56, v138, v139
	v_pk_mul_f32 v[130:131], v[58:59], v[66:67]
	v_cvt_f32_f16_sdwa v59, v53 dst_sel:DWORD dst_unused:UNUSED_PAD src0_sel:WORD_1
	v_cvt_f32_f16_e32 v58, v53
	v_cvt_f32_f16_sdwa v53, v49 dst_sel:DWORD dst_unused:UNUSED_PAD src0_sel:WORD_1
	v_cvt_pk_f16_f32 v57, v130, v131
	v_pk_mul_f32 v[48:49], v[128:129], v[58:59]
	s_nop 0
	v_cndmask_b32_e64 v49, v49, -v49, s[8:9]
	v_cndmask_b32_e64 v48, v48, -v48, s[8:9]
	v_pk_fma_f32 v[48:49], v[124:125], v[52:53], v[48:49]
	v_cvt_f32_f16_sdwa v59, v60 dst_sel:DWORD dst_unused:UNUSED_PAD src0_sel:WORD_1
	v_pk_mul_f32 v[48:49], v[48:49], v[62:63]
	v_cvt_f32_f16_sdwa v63, v64 dst_sel:DWORD dst_unused:UNUSED_PAD src0_sel:WORD_1
	v_fma_mixlo_f16 v52, v132, v48, 0
	ds_write_b16 v113, v52 offset:46224
	v_fma_mixlo_f16 v52, v133, v49, 0
	ds_write_b16 v113, v52 offset:46368
	ds_read_b128 v[122:125], v141
	ds_read_b128 v[66:69], v140
	s_nop 0
	v_cvt_f32_f16_e32 v62, v64
	v_cvt_f32_f16_e32 v58, v60
	v_mul_f32_e32 v52, 0x3fb8aa3b, v118
	v_mul_f32_e32 v53, 0x3fb8aa3b, v119
	v_pk_mul_f32 v[62:63], v[62:63], s[72:73] op_sel_hi:[1,0]
	v_exp_f32_e32 v52, v52
	s_nop 0
	s_waitcnt lgkmcnt(1)
	v_pk_mul_f32 v[62:63], v[62:63], v[122:123]
	v_exp_f32_e32 v53, v53
	v_pk_mul_f32 v[58:59], v[58:59], s[72:73] op_sel_hi:[1,0]
	v_cndmask_b32_e64 v63, v63, -v63, s[8:9]
	v_cndmask_b32_e64 v62, v62, -v62, s[8:9]
	s_waitcnt lgkmcnt(0)
	v_pk_fma_f32 v[58:59], v[58:59], v[66:67], v[62:63]
	v_cvt_f32_f16_sdwa v63, v54 dst_sel:DWORD dst_unused:UNUSED_PAD src0_sel:WORD_1
	v_cvt_f32_f16_e32 v62, v54
	v_cvt_f32_f16_sdwa v129, v50 dst_sel:DWORD dst_unused:UNUSED_PAD src0_sel:WORD_1
	v_cvt_f32_f16_e32 v128, v50
	v_rcp_f32_e32 v118, v52
	v_rcp_f32_e32 v119, v53
	v_pk_mul_f32 v[62:63], v[122:123], v[62:63]
	v_cvt_f32_f16_e32 v60, v65
	v_cndmask_b32_e64 v63, v63, -v63, s[8:9]
	v_cndmask_b32_e64 v62, v62, -v62, s[8:9]
	v_pk_fma_f32 v[62:63], v[66:67], v[128:129], v[62:63]
	v_pk_mul_f32 v[52:53], v[58:59], v[52:53]
	v_pk_mul_f32 v[66:67], v[62:63], v[118:119]
	v_cvt_f32_f16_sdwa v119, v61 dst_sel:DWORD dst_unused:UNUSED_PAD src0_sel:WORD_1
	v_fma_mixlo_f16 v50, v134, v66, 0
	v_cvt_f32_f16_e32 v118, v61
	v_cvt_f32_f16_sdwa v61, v65 dst_sel:DWORD dst_unused:UNUSED_PAD src0_sel:WORD_1
	ds_write_b16 v113, v50 offset:46512
	v_fma_mixlo_f16 v50, v135, v67, 0
	ds_write_b16 v113, v50 offset:46656
	v_mul_f32_e32 v50, 0x3fb8aa3b, v120
	v_exp_f32_e32 v62, v50
	v_mul_f32_e32 v50, 0x3fb8aa3b, v121
	v_exp_f32_e32 v63, v50
	v_pk_mul_f32 v[60:61], v[60:61], s[72:73] op_sel_hi:[1,0]
	v_pk_mul_f32 v[118:119], v[118:119], s[72:73] op_sel_hi:[1,0]
	v_pk_mul_f32 v[60:61], v[60:61], v[124:125]
	v_rcp_f32_e32 v64, v62
	v_cndmask_b32_e64 v61, v61, -v61, s[8:9]
	v_cndmask_b32_e64 v60, v60, -v60, s[8:9]
	v_pk_fma_f32 v[60:61], v[118:119], v[68:69], v[60:61]
	v_rcp_f32_e32 v65, v63
	v_pk_mul_f32 v[60:61], v[60:61], v[62:63]
	v_bfe_u32 v62, v131, 16, 1
	v_bfe_u32 v63, v130, 16, 1
	v_bfe_u32 v75, v53, 16, 1
	v_bfe_u32 v79, v52, 16, 1
	v_cvt_pk_f16_f32 v58, v52, v53
	v_bfe_u32 v50, v61, 16, 1
	v_add3_u32 v120, v130, v63, s34
	v_add3_u32 v62, v131, v62, s34
	v_add3_u32 v52, v52, v79, s34
	v_add3_u32 v53, v53, v75, s34
	v_cvt_pk_f16_f32 v59, v60, v61
	v_bfe_u32 v54, v60, 16, 1
	v_add3_u32 v50, v61, v50, s34
	v_perm_b32 v61, v62, v120, s35
	v_perm_b32 v62, v53, v52, s35
	v_cvt_f32_f16_sdwa v53, v55 dst_sel:DWORD dst_unused:UNUSED_PAD src0_sel:WORD_1
	v_cvt_f32_f16_e32 v52, v55
	v_add3_u32 v54, v60, v54, s34
	v_perm_b32 v63, v50, v54, s35
	v_cvt_f32_f16_sdwa v55, v51 dst_sel:DWORD dst_unused:UNUSED_PAD src0_sel:WORD_1
	v_cvt_f32_f16_e32 v54, v51
	v_pk_mul_f32 v[50:51], v[124:125], v[52:53]
	v_bfe_u32 v118, v139, 16, 1
	v_cndmask_b32_e64 v51, v51, -v51, s[8:9]
	v_cndmask_b32_e64 v50, v50, -v50, s[8:9]
	v_pk_fma_f32 v[50:51], v[68:69], v[54:55], v[50:51]
	v_bfe_u32 v119, v138, 16, 1
	v_pk_mul_f32 v[52:53], v[50:51], v[64:65]
	v_bfe_u32 v51, v48, 16, 1
	v_fma_mixlo_f16 v50, v136, v52, 0
	v_bfe_u32 v54, v53, 16, 1
	v_bfe_u32 v55, v52, 16, 1
	ds_write_b16 v113, v50 offset:46800
	v_bfe_u32 v50, v49, 16, 1
	v_bfe_u32 v64, v67, 16, 1
	v_bfe_u32 v65, v66, 16, 1
	v_bfe_u32 v68, v127, 16, 1
	v_bfe_u32 v69, v126, 16, 1
	v_add3_u32 v52, v52, v55, s34
	v_add3_u32 v54, v53, v54, s34
	v_add3_u32 v60, v138, v119, s34
	v_add3_u32 v118, v139, v118, s34
	v_add3_u32 v48, v48, v51, s34
	v_add3_u32 v49, v49, v50, s34
	v_add3_u32 v55, v126, v69, s34
	v_add3_u32 v68, v127, v68, s34
	v_add3_u32 v50, v66, v65, s34
	v_add3_u32 v64, v67, v64, s34
	v_perm_b32 v51, v54, v52, s35
	v_fma_mixlo_f16 v52, v137, v53, 0
	v_perm_b32 v60, v118, v60, s35
	v_perm_b32 v49, v49, v48, s35
	v_perm_b32 v50, v64, v50, s35
	v_perm_b32 v48, v68, v55, s35
	ds_write_b16 v113, v52 offset:46944
	ds_write_b128 v83, v[60:63] offset:18432
	ds_write_b128 v83, v[48:51] offset:27648
	ds_write_b128 v83, v[56:59] offset:36864
	v_add_u32_e32 v56, v73, v0
	s_nop 0
	s_barrier
	v_add_u32_e32 v251, v86, v95
	ds_read_b128 v[52:55], v251 offset:36864
	ds_read_b128 v[64:67], v56 offset:64
	ds_read_b128 v[142:145], v251 offset:36928
	ds_read_b128 v[60:63], v251 offset:39168
	ds_read_b128 v[118:121], v251 offset:39232
	ds_read_b128 v[122:125], v251 offset:41472
	ds_read_b128 v[126:129], v251 offset:41536
	ds_read_b128 v[130:133], v251 offset:43776
	ds_read_b128 v[134:137], v251 offset:43840
	ds_read_b128 v[48:51], v56
	v_add_u32_e32 v68, v86, v95
	s_nop 0
	s_nop 0
	s_nop 0
	s_nop 0
	s_nop 0
	s_nop 0
	s_nop 0
	s_nop 0
	s_nop 0
	s_nop 0
	s_waitcnt lgkmcnt(0)
	v_mfma_f32_16x16x32_f16 v[52:55], v[48:51], v[52:55], 0
	v_add_u32_e32 v75, v92, v0
	v_mov_b32_e32 v68, 0
	v_mov_b32_e32 v69, 0
	s_nop 0
	v_mfma_f32_16x16x32_f16 v[60:63], v[48:51], v[60:63], 0
	s_nop 0
	v_mfma_f32_16x16x32_f16 v[122:125], v[48:51], v[122:125], 0
	s_nop 0
	v_mfma_f32_16x16x32_f16 v[48:51], v[48:51], v[130:133], 0
	v_mfma_f32_16x16x32_f16 v[52:55], v[64:67], v[142:145], v[52:55]
	v_mfma_f32_16x16x32_f16 v[56:59], v[64:67], v[118:121], v[60:63]
	v_mfma_f32_16x16x32_f16 v[60:63], v[64:67], v[126:129], v[122:125]
	s_nop 0
	v_mfma_f32_16x16x32_f16 v[48:51], v[64:67], v[134:137], v[48:51]
	v_mov_b32_e32 v64, 0
	v_mov_b32_e32 v66, 0
	v_mov_b32_e32 v67, 0
	s_and_saveexec_b64 s[0:1], s[10:11]
	s_cbranch_execz .LBB0_1009
	v_add_u32_e32 v251, v86, v98
	ds_read_b128 v[66:69], v75 offset:18432
	ds_read_b128 v[118:121], v251 offset:27648
	v_add_u32_e32 v65, v86, v98
	s_nop 0
	s_nop 0
	s_nop 0
	s_waitcnt lgkmcnt(0)
	v_mfma_f32_16x16x32_bf16 v[66:69], v[118:121], v[66:69], 0
	ds_read_b128 v[122:125], v65 offset:27712
	ds_read_b128 v[118:121], v75 offset:18496
	s_nop 0
	s_nop 0
	s_waitcnt lgkmcnt(0)
	v_mfma_f32_16x16x32_bf16 v[66:69], v[122:125], v[118:121], v[66:69]
.LBB0_1009:
	s_or_b64 exec, exec, s[0:1]
	s_nop 6
	v_cvt_f16_f32_e32 v65, v66
	v_cvt_f16_f32_e32 v66, v67
	v_cvt_f16_f32_e32 v67, v68
	v_cvt_f16_f32_e32 v68, v69
	v_cndmask_b32_e64 v65, v65, 0, s[14:15]
	v_cndmask_b32_e64 v66, 0, v66, s[16:17]
	v_cndmask_b32_e64 v67, v67, 0, s[18:19]
	v_cndmask_b32_e64 v68, v68, 0, s[20:21]
	v_pack_b32_f16 v67, v67, v68
	v_pack_b32_f16 v66, v65, v66
	ds_write_b64 v114, v[66:67]
	v_mov_b32_e32 v65, 0
	v_mov_b32_e32 v66, 0
	v_mov_b32_e32 v67, 0
	s_and_saveexec_b64 s[0:1], s[12:13]
	s_cbranch_execz .LBB0_994
	v_add_u32_e32 v251, v86, v100
	ds_read_b128 v[64:67], v75 offset:18432
	ds_read_b128 v[118:121], v251 offset:27648
	v_add_u32_e32 v68, v86, v100
	s_nop 0
	s_nop 0
	s_nop 0
	s_waitcnt lgkmcnt(0)
	v_mfma_f32_16x16x32_bf16 v[64:67], v[118:121], v[64:67], 0
	ds_read_b128 v[122:125], v68 offset:27712
	ds_read_b128 v[118:121], v75 offset:18496
	s_nop 0
	s_nop 0
	s_waitcnt lgkmcnt(0)
	v_mfma_f32_16x16x32_bf16 v[64:67], v[122:125], v[118:121], v[64:67]
	s_branch .LBB0_994

.LBB0_1028:
	s_andn2_b64 vcc, exec, s[24:25]
	s_mov_b64 s[26:27], -1
	s_cbranch_vccnz .LBB0_1036
	s_and_b32 s26, s76, 1
	v_lshl_add_u32 v0, s26, 13, v229
	ds_read2_b64 v[36:39], v0 offset1:32
	v_mad_u32_u24 v2, s26, v167, v230
	s_waitcnt lgkmcnt(0)
	v_pk_mul_f32 v[66:67], v[36:37], v[38:39]
	ds_read2_b64 v[38:41], v0 offset0:64 offset1:96
	s_waitcnt lgkmcnt(0)
	v_pk_mul_f32 v[64:65], v[66:67], v[38:39]
	s_nop 0
	v_pk_mul_f32 v[60:61], v[64:65], v[40:41]
	ds_read2_b64 v[38:41], v0 offset0:128 offset1:160
	s_waitcnt lgkmcnt(0)
	v_pk_mul_f32 v[54:55], v[60:61], v[38:39]
	s_nop 0
	v_pk_mul_f32 v[48:49], v[54:55], v[40:41]
	ds_read2_b64 v[38:41], v0 offset0:192 offset1:224
	v_add_u32_e32 v0, 0x800, v0
	ds_read2_b64 v[68:71], v0 offset0:128 offset1:160
	s_waitcnt lgkmcnt(1)
	v_pk_mul_f32 v[44:45], v[48:49], v[38:39]
	s_nop 0
	v_pk_mul_f32 v[38:39], v[44:45], v[40:41]
	ds_read2_b64 v[40:43], v0 offset1:32
	s_waitcnt lgkmcnt(0)
	v_pk_mul_f32 v[58:59], v[38:39], v[40:41]
	s_nop 0
	v_pk_mul_f32 v[50:51], v[58:59], v[42:43]
	ds_read2_b64 v[40:43], v0 offset0:64 offset1:96
	s_waitcnt lgkmcnt(0)
	v_pk_mul_f32 v[46:47], v[50:51], v[40:41]
	s_nop 0
	v_pk_mul_f32 v[42:43], v[46:47], v[42:43]
	v_rcp_f32_e32 v40, v38
	v_pk_mul_f32 v[62:63], v[42:43], v[68:69]
	v_rcp_f32_e32 v41, v39
	v_pk_mul_f32 v[56:57], v[62:63], v[70:71]
	ds_read2_b64 v[68:71], v0 offset0:192 offset1:224
	s_waitcnt lgkmcnt(0)
	v_pk_mul_f32 v[52:53], v[56:57], v[68:69]
	s_nop 0
	v_pk_mul_f32 v[0:1], v[52:53], v[70:71]
	s_and_saveexec_b64 s[26:27], s[4:5]
	s_cbranch_execz .LBB0_1031
	v_lshl_add_u32 v250, v175, 1, v2
	ds_read2st64_b32 v[72:73], v250 offset0:96 offset1:112
	ds_read2st64_b32 v[68:69], v250 offset0:64 offset1:80
	v_lshl_add_u32 v74, v175, 1, v2
	s_nop 0
	ds_read_b32 v84, v74 offset:32768
	s_nop 0
	v_rcp_f32_e32 v70, v36
	v_rcp_f32_e32 v71, v37
	s_nop 0
	s_nop 0
	s_waitcnt lgkmcnt(2)
	v_cvt_f32_f16_e32 v78, v73
	v_cvt_f32_f16_sdwa v79, v73 dst_sel:DWORD dst_unused:UNUSED_PAD src0_sel:WORD_1
	s_nop 0
	v_lshl_add_u32 v250, v182, 1, v2
	ds_read2st64_b32 v[146:147], v250 offset0:64 offset1:80
	s_waitcnt lgkmcnt(2)
	v_cvt_f32_f16_e32 v74, v68
	v_cvt_f32_f16_sdwa v75, v68 dst_sel:DWORD dst_unused:UNUSED_PAD src0_sel:WORD_1
	v_cvt_f32_f16_e32 v76, v72
	ds_read2st64_b32 v[148:149], v250 offset0:96 offset1:112
	v_cvt_f32_f16_sdwa v77, v72 dst_sel:DWORD dst_unused:UNUSED_PAD src0_sel:WORD_1
	v_cvt_f32_f16_e32 v72, v69
	v_cvt_f32_f16_sdwa v73, v69 dst_sel:DWORD dst_unused:UNUSED_PAD src0_sel:WORD_1
	v_pk_mul_f32 v[78:79], v[36:37], v[78:79]
	v_pk_mul_f32 v[76:77], v[70:71], v[76:77]
	v_pk_mul_f32 v[70:71], v[70:71], v[74:75]
	v_pk_mul_f32 v[72:73], v[40:41], v[72:73]
	v_pk_mul_f32 v[74:75], v[40:41], v[78:79]
	v_cvt_pk_f16_f32 v68, v78, v79
	v_pk_mul_f32 v[80:81], v[38:39], v[76:77]
	v_pk_mul_f32 v[82:83], v[38:39], v[70:71]
	ds_write2st64_b32 v181, v69, v68 offset1:18
	v_cvt_pk_f16_f32 v68, v72, v73
	v_cvt_pk_f16_f32 v69, v74, v75
	v_pk_mul_f32 v[76:77], v[0:1], v[76:77]
	ds_write2st64_b32 v181, v68, v69 offset0:36 offset1:54
	v_cvt_pk_f16_f32 v68, v80, v81
	v_cvt_pk_f16_f32 v69, v82, v83
	ds_write2st64_b32 v181, v68, v69 offset0:72 offset1:90
	v_cvt_f16_f32_e32 v68, v76
	v_pk_mul_f32 v[70:71], v[0:1], v[70:71]
	v_cvt_f16_f32_e32 v69, v77
	v_cvt_f16_f32_e32 v70, v70
	v_cvt_f16_f32_e32 v71, v71
	ds_write_b16 v176, v68
	ds_write_b16 v176, v69 offset:40
	ds_write_b16 v176, v70 offset:5120
	ds_write_b16 v176, v71 offset:5160
	s_nop 0
	s_waitcnt lgkmcnt(9)
	ds_write_b16 v176, v84 offset:10240
	v_lshl_add_u32 v74, v182, 1, v2
	s_nop 0
	s_nop 0
	ds_read_b32 v82, v74 offset:32768
	v_rcp_f32_e32 v70, v66
	v_rcp_f32_e32 v71, v67
	s_nop 0
	s_waitcnt lgkmcnt(10)
	v_cvt_f32_f16_e32 v76, v147
	v_cvt_f32_f16_sdwa v77, v147 dst_sel:DWORD dst_unused:UNUSED_PAD src0_sel:WORD_1
	s_nop 0
	s_waitcnt lgkmcnt(9)
	v_cvt_f32_f16_e32 v80, v149
	v_cvt_f32_f16_sdwa v81, v149 dst_sel:DWORD dst_unused:UNUSED_PAD src0_sel:WORD_1
	v_lshl_add_u32 v250, v184, 1, v2
	ds_read2st64_b32 v[162:163], v250 offset0:64 offset1:80
	v_cvt_f32_f16_e32 v74, v146
	v_cvt_f32_f16_e32 v78, v148
	v_cvt_f32_f16_sdwa v79, v148 dst_sel:DWORD dst_unused:UNUSED_PAD src0_sel:WORD_1
	ds_read2st64_b32 v[148:149], v250 offset0:96 offset1:112
	v_cvt_f32_f16_sdwa v75, v146 dst_sel:DWORD dst_unused:UNUSED_PAD src0_sel:WORD_1
	v_pk_mul_f32 v[36:37], v[36:37], v[76:77]
	v_pk_mul_f32 v[68:69], v[66:67], v[80:81]
	v_pk_mul_f32 v[72:73], v[70:71], v[78:79]
	v_pk_mul_f32 v[70:71], v[70:71], v[74:75]
	v_pk_mul_f32 v[74:75], v[40:41], v[36:37]
	v_pk_mul_f32 v[76:77], v[40:41], v[68:69]
	v_cvt_pk_f16_f32 v36, v36, v37
	v_cvt_pk_f16_f32 v37, v68, v69
	v_pk_mul_f32 v[78:79], v[38:39], v[72:73]
	v_pk_mul_f32 v[80:81], v[38:39], v[70:71]
	ds_write2st64_b32 v183, v36, v37 offset1:18
	v_cvt_pk_f16_f32 v36, v74, v75
	v_cvt_pk_f16_f32 v37, v76, v77
	v_pk_mul_f32 v[72:73], v[0:1], v[72:73]
	ds_write2st64_b32 v183, v36, v37 offset0:36 offset1:54
	v_cvt_pk_f16_f32 v36, v78, v79
	v_cvt_pk_f16_f32 v37, v80, v81
	ds_write2st64_b32 v183, v36, v37 offset0:72 offset1:90
	v_cvt_f16_f32_e32 v36, v72
	v_pk_mul_f32 v[70:71], v[0:1], v[70:71]
	v_cvt_f16_f32_e32 v37, v73
	v_cvt_f16_f32_e32 v68, v70
	v_cvt_f16_f32_e32 v69, v71
	ds_write_b16 v176, v36 offset:2
	s_waitcnt lgkmcnt(14)
	ds_write_b16 v176, v37 offset:42
	s_waitcnt lgkmcnt(14)
	ds_write_b16 v176, v68 offset:5122
	s_waitcnt lgkmcnt(14)
	ds_write_b16 v176, v69 offset:5162
	s_nop 0
	s_waitcnt lgkmcnt(9)
	ds_write_b16 v176, v82 offset:10242
	v_lshl_add_u32 v72, v184, 1, v2
	s_nop 0
	s_nop 0
	ds_read_b32 v80, v72 offset:32768
	v_rcp_f32_e32 v68, v64
	v_rcp_f32_e32 v69, v65
	s_nop 0
	s_waitcnt lgkmcnt(10)
	v_cvt_f32_f16_e32 v74, v163
	v_cvt_f32_f16_sdwa v75, v163 dst_sel:DWORD dst_unused:UNUSED_PAD src0_sel:WORD_1
	s_nop 0
	s_waitcnt lgkmcnt(9)
	v_cvt_f32_f16_e32 v78, v149
	v_cvt_f32_f16_sdwa v79, v149 dst_sel:DWORD dst_unused:UNUSED_PAD src0_sel:WORD_1
	v_lshl_add_u32 v250, v186, 1, v2
	ds_read2st64_b32 v[146:147], v250 offset0:64 offset1:80
	v_cvt_f32_f16_e32 v72, v162
	v_cvt_f32_f16_e32 v76, v148
	v_cvt_f32_f16_sdwa v77, v148 dst_sel:DWORD dst_unused:UNUSED_PAD src0_sel:WORD_1
	ds_read2st64_b32 v[148:149], v250 offset0:96 offset1:112
	v_cvt_f32_f16_sdwa v73, v162 dst_sel:DWORD dst_unused:UNUSED_PAD src0_sel:WORD_1
	v_pk_mul_f32 v[36:37], v[66:67], v[74:75]
	v_pk_mul_f32 v[66:67], v[64:65], v[78:79]
	v_pk_mul_f32 v[70:71], v[68:69], v[76:77]
	v_pk_mul_f32 v[68:69], v[68:69], v[72:73]
	v_pk_mul_f32 v[72:73], v[40:41], v[36:37]
	v_pk_mul_f32 v[74:75], v[40:41], v[66:67]
	v_cvt_pk_f16_f32 v36, v36, v37
	v_cvt_pk_f16_f32 v37, v66, v67
	v_pk_mul_f32 v[76:77], v[38:39], v[70:71]
	v_pk_mul_f32 v[78:79], v[38:39], v[68:69]
	ds_write2st64_b32 v185, v36, v37 offset1:18
	v_cvt_pk_f16_f32 v36, v72, v73
	v_cvt_pk_f16_f32 v37, v74, v75
	v_pk_mul_f32 v[70:71], v[0:1], v[70:71]
	ds_write2st64_b32 v185, v36, v37 offset0:36 offset1:54
	v_cvt_pk_f16_f32 v36, v76, v77
	v_cvt_pk_f16_f32 v37, v78, v79
	ds_write2st64_b32 v185, v36, v37 offset0:72 offset1:90
	v_cvt_f16_f32_e32 v36, v70
	v_pk_mul_f32 v[68:69], v[0:1], v[68:69]
	v_cvt_f16_f32_e32 v37, v71
	v_cvt_f16_f32_e32 v66, v68
	v_cvt_f16_f32_e32 v67, v69
	ds_write_b16 v176, v36 offset:4
	s_waitcnt lgkmcnt(14)
	ds_write_b16 v176, v37 offset:44
	s_waitcnt lgkmcnt(14)
	ds_write_b16 v176, v66 offset:5124
	s_waitcnt lgkmcnt(14)
	ds_write_b16 v176, v67 offset:5164
	s_nop 0
	s_waitcnt lgkmcnt(9)
	ds_write_b16 v176, v80 offset:10244
	v_lshl_add_u32 v70, v186, 1, v2
	s_nop 0
	s_nop 0
	ds_read_b32 v78, v70 offset:32768
	v_rcp_f32_e32 v66, v60
	v_rcp_f32_e32 v67, v61
	s_nop 0
	s_waitcnt lgkmcnt(10)
	v_cvt_f32_f16_e32 v72, v147
	v_cvt_f32_f16_sdwa v73, v147 dst_sel:DWORD dst_unused:UNUSED_PAD src0_sel:WORD_1
	s_nop 0
	s_waitcnt lgkmcnt(9)
	v_cvt_f32_f16_e32 v76, v149
	v_cvt_f32_f16_sdwa v77, v149 dst_sel:DWORD dst_unused:UNUSED_PAD src0_sel:WORD_1
	v_cvt_f32_f16_e32 v70, v146
	v_cvt_f32_f16_e32 v74, v148
	v_cvt_f32_f16_sdwa v75, v148 dst_sel:DWORD dst_unused:UNUSED_PAD src0_sel:WORD_1
	v_cvt_f32_f16_sdwa v71, v146 dst_sel:DWORD dst_unused:UNUSED_PAD src0_sel:WORD_1
	v_pk_mul_f32 v[36:37], v[64:65], v[72:73]
	v_pk_mul_f32 v[64:65], v[60:61], v[76:77]
	v_pk_mul_f32 v[68:69], v[66:67], v[74:75]
	v_pk_mul_f32 v[66:67], v[66:67], v[70:71]
	v_pk_mul_f32 v[70:71], v[40:41], v[36:37]
	v_pk_mul_f32 v[72:73], v[40:41], v[64:65]
	v_cvt_pk_f16_f32 v36, v36, v37
	v_cvt_pk_f16_f32 v37, v64, v65
	v_pk_mul_f32 v[74:75], v[38:39], v[68:69]
	v_pk_mul_f32 v[76:77], v[38:39], v[66:67]
	ds_write2st64_b32 v187, v36, v37 offset1:18
	v_cvt_pk_f16_f32 v36, v70, v71
	v_cvt_pk_f16_f32 v37, v72, v73
	v_pk_mul_f32 v[68:69], v[0:1], v[68:69]
	ds_write2st64_b32 v187, v36, v37 offset0:36 offset1:54
	v_cvt_pk_f16_f32 v36, v74, v75
	v_cvt_pk_f16_f32 v37, v76, v77
	ds_write2st64_b32 v187, v36, v37 offset0:72 offset1:90
	v_cvt_f16_f32_e32 v36, v68
	v_pk_mul_f32 v[66:67], v[0:1], v[66:67]
	v_cvt_f16_f32_e32 v37, v69
	v_cvt_f16_f32_e32 v64, v66
	v_cvt_f16_f32_e32 v65, v67
	ds_write_b16 v176, v36 offset:6
	ds_write_b16 v176, v37 offset:46
	ds_write_b16 v176, v64 offset:5126
	s_waitcnt lgkmcnt(14)
	ds_write_b16 v176, v65 offset:5166
	s_nop 0
	s_waitcnt lgkmcnt(7)
	ds_write_b16 v176, v78 offset:10246
	v_perm_b32 v36, v82, v84, s35
	v_perm_b32 v37, v78, v80, s35
	ds_write_b64 v176, v[36:37] offset:10280

.LBB0_1035:
	s_or_b64 exec, exec, s[26:27]
	s_waitcnt lgkmcnt(0)
	s_barrier
	ds_read_b128 v[40:43], v212 offset:9216
	ds_read_b128 v[48:51], v212 offset:18496
	ds_read_b128 v[56:59], v212 offset:9280
	ds_read_b128 v[60:63], v212 offset:23040
	ds_read_b128 v[36:39], v212 offset:18432
	s_nop 0
	s_nop 0
	s_nop 0
	ds_read_b128 v[64:67], v212 offset:13824
	s_waitcnt lgkmcnt(1)
	v_mfma_f32_16x16x32_f16 v[52:55], v[40:43], v[36:39], 0
	s_nop 0
	s_nop 0
	s_nop 0
	ds_read_b128 v[68:71], v212 offset:13888
	ds_read_b128 v[72:75], v212 offset:23104
	v_add_u32_e32 v80, 0x1000, v217
	s_nop 0
	v_mfma_f32_16x16x32_f16 v[52:55], v[56:59], v[48:51], v[52:55]
	v_mov_b32_e32 v82, v3
	v_mov_b32_e32 v83, v3
	v_mov_b32_e32 v86, v3
	v_mfma_f32_16x16x32_f16 v[44:47], v[36:39], v[40:43], 0
	s_nop 3
	v_cvt_f16_f32_e32 v0, v52
	v_cvt_f16_f32_e32 v1, v54
	v_cvt_f16_f32_e32 v2, v55
	v_mfma_f32_16x16x32_f16 v[44:47], v[48:51], v[56:59], v[44:47]
	v_cndmask_b32_e64 v79, 0, v0, s[12:13]
	v_cvt_f16_f32_e32 v0, v53
	v_cndmask_b32_e64 v54, 0, v1, s[18:19]
	s_nop 0
	v_mfma_f32_16x16x32_f16 v[40:43], v[60:63], v[40:43], 0
	v_cndmask_b32_e64 v55, 0, v2, s[22:23]
	s_nop 1
	v_cndmask_b32_e64 v76, 0, v44, s[10:11]
	v_cndmask_b32_e64 v77, 0, v45, s[14:15]
	s_nop 0
	s_waitcnt lgkmcnt(2)
	v_mfma_f32_16x16x32_f16 v[36:39], v[36:39], v[64:67], 0
	v_cndmask_b32_e64 v52, 0, v46, s[16:17]
	v_cndmask_b32_e64 v78, 0, v47, s[20:21]
	v_cndmask_b32_e64 v53, v0, 0, s[10:11]
	v_mfma_f32_16x16x32_f16 v[44:47], v[60:63], v[64:67], 0
	v_cvt_pk_f16_f32 v1, v52, v78
	v_cvt_pk_f16_f32 v0, v76, v77
	v_mov_b32_e32 v2, v3
	s_nop 0
	s_waitcnt lgkmcnt(0)
	v_mfma_f32_16x16x32_f16 v[60:63], v[72:75], v[56:59], v[40:43]
	v_add_f32_e32 v56, v213, v76
	v_add_f32_e32 v57, v214, v77
	v_add_f32_e32 v58, v215, v52
	v_mfma_f32_16x16x32_f16 v[40:43], v[48:51], v[68:71], v[36:39]
	v_add_f32_e32 v59, v216, v78
	v_cvt_pk_f16_f32 v67, v18, v19
	v_cvt_pk_f16_f32 v66, v16, v17
	v_pack_b32_f16 v37, v54, v55
	v_pack_b32_f16 v36, v79, v53
	v_mov_b32_e32 v38, v3
	v_mov_b32_e32 v39, v3
	v_mfma_f32_16x16x32_f16 v[52:55], v[72:75], v[68:71], v[44:47]
	ds_read2_b64 v[68:71], v217 offset0:8 offset1:12
	v_cvt_pk_f16_f32 v65, v14, v15
	v_cvt_pk_f16_f32 v64, v12, v13
	v_mfma_f32_16x16x32_f16 v[48:51], v[0:3], v[36:39], 0
	v_cvt_pk_f16_f32 v45, v58, v59
	v_cvt_pk_f16_f32 v44, v56, v57
	v_mov_b32_e32 v46, v3
	v_mfma_f32_16x16x32_f16 v[36:39], v[36:39], v[0:3], 0
	v_mov_b32_e32 v47, v3
	s_nop 2
	v_cvt_pk_f16_f32 v1, v50, v51
	v_cvt_pk_f16_f32 v0, v48, v49
	v_mov_b32_e32 v50, v3
	v_mov_b32_e32 v51, v3
	v_cvt_pk_f16_f32 v49, v38, v39
	v_cvt_pk_f16_f32 v48, v36, v37
	v_mfma_f32_16x16x32_f16 v[44:47], v[0:3], v[44:47], v[56:59]
	v_mov_b32_e32 v87, v3
	v_mov_b32_e32 v90, v3
	v_mov_b32_e32 v91, v3
	v_mfma_f32_16x16x32_f16 v[36:39], v[48:51], v[0:3], 0
	ds_read2_b64 v[126:129], v217 offset1:4
	v_cvt_pk_f16_f32 v59, v10, v11
	v_cvt_pk_f16_f32 v58, v8, v9
	v_cvt_pk_f16_f32 v57, v6, v7
	v_mfma_f32_16x16x32_f16 v[48:51], v[0:3], v[48:51], 0
	v_cvt_pk_f16_f32 v56, v4, v5
	s_nop 2
	v_cvt_pk_f16_f32 v1, v38, v39
	v_cvt_pk_f16_f32 v0, v36, v37
	v_cvt_pk_f16_f32 v37, v46, v47
	v_cvt_pk_f16_f32 v36, v44, v45
	v_mov_b32_e32 v38, v3
	v_mov_b32_e32 v39, v3
	v_cvt_f16_f32_e32 v52, v52
	s_add_i32 s28, s76, 1
	v_mfma_f32_16x16x32_f16 v[44:47], v[0:3], v[36:39], v[44:47]
	v_cvt_pk_f16_f32 v37, v50, v51
	v_cvt_pk_f16_f32 v36, v48, v49
	v_mov_b32_e32 v50, v3
	v_mov_b32_e32 v51, v3
	v_mfma_f32_16x16x32_f16 v[36:39], v[36:39], v[0:3], 0
	s_nop 2
	v_cvt_pk_f16_f32 v1, v46, v47
	v_cvt_pk_f16_f32 v0, v44, v45
	s_nop 2
	v_cvt_pk_f16_f32 v49, v38, v39
	v_cvt_pk_f16_f32 v48, v36, v37
	s_nop 0
	s_nop 0
	s_waitcnt lgkmcnt(0)
	v_mfma_f32_16x16x32_f16 v[36:39], v[126:129], v[56:59], 0
	v_mfma_f32_16x16x32_f16 v[44:47], v[48:51], v[0:3], v[44:47]
	v_cvt_f16_f32_e32 v0, v60
	v_cvt_f16_f32_e32 v1, v61
	v_cvt_f16_f32_e32 v2, v62
	v_cvt_f16_f32_e32 v48, v63
	v_mfma_f32_16x16x32_f16 v[76:79], v[68:71], v[64:67], v[36:39]
	ds_read2_b64 v[72:75], v80 offset0:64 offset1:68
	ds_read2st64_b64 v[130:133], v218 offset0:20 offset1:25
	ds_read2_b64 v[68:71], v80 offset0:72 offset1:76
	s_nop 0
	s_nop 0
	v_cndmask_b32_e64 v0, 0, v0, s[10:11]
	v_cndmask_b32_e64 v49, 0, v1, s[14:15]
	v_cndmask_b32_e64 v1, 0, v2, s[16:17]
	v_cndmask_b32_e64 v2, 0, v48, s[20:21]
	v_pack_b32_f16 v1, v1, v2
	v_pack_b32_f16 v0, v0, v49
	v_mov_b32_e32 v2, v3
	s_nop 0
	s_waitcnt lgkmcnt(1)
	v_mov_b32_e32 v60, v130
	v_mov_b32_e32 v61, v131
	ds_read2_b64 v[126:129], v233 offset1:80
	v_mov_b32_e32 v62, v3
	v_mov_b32_e32 v63, v3
	v_cvt_f16_f32_e32 v36, v40
	ds_read_b128 v[134:137], v178
	v_cvt_f16_f32_e32 v40, v42
	v_mfma_f32_16x16x32_f16 v[48:51], v[0:3], v[60:63], v[76:79]
	v_cvt_pk_f16_f32 v1, v46, v47
	v_cvt_pk_f16_f32 v0, v44, v45
	v_cvt_f16_f32_e32 v37, v41
	v_mov_b32_e32 v78, v3
	v_mov_b32_e32 v79, v3
	s_nop 2
	v_cvt_pk_f16_f32 v77, v50, v51
	v_cvt_pk_f16_f32 v76, v48, v49
	v_cndmask_b32_e64 v88, v40, 0, s[18:19]
	v_mfma_f32_16x16x32_f16 v[56:59], v[72:75], v[56:59], 0
	v_cndmask_b32_e64 v36, v36, 0, s[12:13]
	v_cndmask_b32_e64 v37, 0, v37, s[10:11]
	v_mov_b32_e32 v74, v3
	v_mfma_f32_16x16x32_f16 v[44:47], v[0:3], v[76:79], 0
	ds_read_b64 v[76:77], v219 offset:5120
	ds_read_b128 v[138:141], v178 offset:64
	v_mov_b32_e32 v75, v3
	s_waitcnt lgkmcnt(4)
	v_mfma_f32_16x16x32_f16 v[56:59], v[68:71], v[64:67], v[56:59]
	s_nop 5
	v_cvt_pk_f16_f32 v1, v46, v47
	v_cvt_pk_f16_f32 v0, v44, v45
	s_nop 0
	s_nop 0
	s_nop 0
	s_nop 0
	s_waitcnt lgkmcnt(3)
	v_mov_b32_e32 v80, v126
	v_mov_b32_e32 v81, v127
	ds_read_b64 v[44:45], v220 offset:5120
	ds_read2_b64 v[142:145], v233 offset0:160 offset1:240
	s_nop 0
	s_waitcnt lgkmcnt(4)
	v_pk_mul_f32 v[50:51], v[6:7], v[136:137]
	v_pk_mul_f32 v[48:49], v[4:5], v[134:135]
	ds_read_b128 v[134:137], v178 offset:128
	s_nop 1
	v_mfma_f32_16x16x32_f16 v[48:51], v[80:83], v[0:3], v[48:51]
	v_cvt_f16_f32_e32 v80, v43
	v_cndmask_b32_e64 v89, v80, 0, s[22:23]
	s_nop 0
	s_waitcnt lgkmcnt(4)
	v_mfma_f32_16x16x32_f16 v[40:43], v[76:79], v[60:63], v[48:51]
	s_nop 3
	s_nop 0
	s_nop 0
	ds_read_b64 v[80:81], v221 offset:5120
	v_mov_b32_e32 v76, v128
	v_mov_b32_e32 v77, v129
	v_mov_b32_e32 v46, v3
	s_nop 0
	s_waitcnt lgkmcnt(4)
	v_pk_mul_f32 v[50:51], v[10:11], v[140:141]
	v_pk_mul_f32 v[48:49], v[8:9], v[138:139]
	v_mov_b32_e32 v47, v3
	ds_read_b128 v[126:129], v178 offset:192
	s_nop 0
	v_mfma_f32_16x16x32_f16 v[48:51], v[76:79], v[0:3], v[48:51]
	s_nop 0
	s_nop 0
	s_waitcnt lgkmcnt(3)
	v_mov_b32_e32 v84, v142
	v_mfma_f32_16x16x32_f16 v[48:51], v[44:47], v[60:63], v[48:51]
	s_nop 0
	s_nop 0
	v_mov_b32_e32 v85, v143
	v_pack_b32_f16 v77, v88, v89
	v_mov_b32_e32 v88, v144
	s_nop 0
	s_waitcnt lgkmcnt(2)
	v_pk_mul_f32 v[46:47], v[14:15], v[136:137]
	v_pk_mul_f32 v[44:45], v[12:13], v[134:135]
	v_mov_b32_e32 v89, v145
	v_pack_b32_f16 v76, v36, v37
	v_mfma_f32_16x16x32_f16 v[44:47], v[84:87], v[0:3], v[44:47]
	ds_read_b64 v[84:85], v222 offset:5120
	v_cndmask_b32_e64 v36, v52, 0, s[12:13]
	v_cvt_f16_f32_e32 v37, v53
	v_cndmask_b32_e64 v37, 0, v37, s[10:11]
	s_nop 0
	s_waitcnt lgkmcnt(2)
	v_mfma_f32_16x16x32_f16 v[44:47], v[80:83], v[60:63], v[44:47]
	s_nop 0
	s_nop 0
	v_pack_b32_f16 v72, v36, v37
	ds_read_b128 v[68:71], v223 offset:9216
	ds_read_b128 v[94:97], v223 offset:9280
	s_nop 0
	s_waitcnt lgkmcnt(3)
	v_pk_mul_f32 v[82:83], v[18:19], v[128:129]
	ds_read_b128 v[64:67], v223 offset:18432
	v_pk_mul_f32 v[80:81], v[16:17], v[126:127]
	s_nop 0
	ds_read_b128 v[98:101], v223 offset:23104
	v_mfma_f32_16x16x32_f16 v[78:81], v[88:91], v[0:3], v[80:83]
	ds_read_b128 v[90:93], v223 offset:18496
	s_nop 1
	v_cvt_f16_f32_e32 v82, v54
	v_cvt_f16_f32_e32 v83, v55
	s_nop 0
	s_waitcnt lgkmcnt(5)
	v_mfma_f32_16x16x32_f16 v[52:55], v[84:87], v[60:63], v[78:81]
	ds_read_b128 v[86:89], v223 offset:13824
	s_nop 1
	v_cndmask_b32_e64 v78, v82, 0, s[18:19]
	v_cndmask_b32_e64 v79, v83, 0, s[22:23]
	v_pack_b32_f16 v73, v78, v79
	v_mov_b32_e32 v78, v3
	v_mov_b32_e32 v79, v3
	v_add_u32_e32 v80, s69, v153
	v_add_u32_e32 v81, s68, v232
	v_mfma_f32_16x16x32_f16 v[56:59], v[76:79], v[0:3], v[56:59]
	ds_read_b128 v[76:79], v223 offset:23040
	v_subrev_u32_e32 v102, 64, v80
	v_add_u32_e32 v0, 0x7ff, v81
	v_mfma_f32_16x16x32_f16 v[58:61], v[72:75], v[60:63], v[56:59]
	v_cndmask_b32_e64 v0, v0, v102, s[2:3]
	v_add_u32_e32 v0, v0, v151
	v_mad_i64_i32 v[0:1], s[26:27], v0, s88, v[122:123]
	s_nop 0
	s_waitcnt lgkmcnt(4)
	v_mfma_f32_16x16x32_f16 v[82:85], v[68:71], v[64:67], 0
	s_nop 2
	v_cvt_f16_f32_e32 v2, v58
	v_cvt_f16_f32_e32 v60, v60
	ds_read_b128 v[126:129], v223 offset:13888
	global_store_short v[0:1], v2, off
	v_subrev_u32_e32 v0, 63, v80
	v_xad_u32 v1, v102, -2, v172
	v_cvt_f16_f32_e32 v2, v59
	s_nop 0
	v_mfma_f32_16x16x32_f16 v[72:75], v[64:67], v[68:71], 0
	v_cndmask_b32_e64 v0, v1, v0, s[2:3]
	v_add_u32_e32 v0, v0, v151
	v_mad_i64_i32 v[0:1], s[26:27], v0, s88, v[122:123]
	s_nop 0
	s_waitcnt lgkmcnt(2)
	v_mfma_f32_16x16x32_f16 v[62:65], v[64:67], v[86:89], 0
	global_store_short v[0:1], v2, off
	v_subrev_u32_e32 v0, 62, v80
	v_xad_u32 v1, v102, -3, v172
	v_mfma_f32_16x16x32_f16 v[82:85], v[94:97], v[90:93], v[82:85]
	v_cndmask_b32_e64 v36, v1, v0, s[2:3]
	v_add_u32_e32 v36, v36, v151
	s_nop 0
	s_waitcnt lgkmcnt(1)
	v_mfma_f32_16x16x32_f16 v[68:71], v[76:79], v[68:71], 0
	v_mfma_f32_16x16x32_f16 v[86:89], v[76:79], v[86:89], 0
	s_nop 2
	v_cvt_f16_f32_e32 v1, v82
	v_cvt_f16_f32_e32 v2, v83
	v_cvt_f16_f32_e32 v66, v85
	v_mfma_f32_16x16x32_f16 v[72:75], v[90:93], v[94:97], v[72:75]
	v_mov_b32_e32 v85, v3
	v_cndmask_b32_e64 v66, 0, v66, s[22:23]
	s_nop 0
	s_waitcnt lgkmcnt(0)
	v_mfma_f32_16x16x32_f16 v[76:79], v[90:93], v[126:129], v[62:65]
	v_mov_b32_e32 v92, v3
	s_nop 2
	v_cndmask_b32_e64 v0, 0, v72, s[10:11]
	v_cndmask_b32_e64 v37, 0, v73, s[14:15]
	v_cvt_f16_f32_e32 v63, v84
	v_mfma_f32_16x16x32_f16 v[94:97], v[98:101], v[94:97], v[68:71]
	v_cndmask_b32_e64 v64, 0, v74, s[16:17]
	v_cndmask_b32_e64 v65, 0, v75, s[20:21]
	v_cndmask_b32_e64 v63, 0, v63, s[18:19]
	v_cndmask_b32_e64 v68, 0, v1, s[12:13]
	v_cndmask_b32_e64 v69, v2, 0, s[10:11]
	v_add_f32_e32 v62, v213, v0
	v_cvt_pk_f16_f32 v1, v64, v65
	v_cvt_pk_f16_f32 v0, v0, v37
	v_mov_b32_e32 v2, v3
	v_pack_b32_f16 v67, v63, v66
	v_pack_b32_f16 v66, v68, v69
	v_mov_b32_e32 v68, v3
	v_mov_b32_e32 v69, v3
	v_add_f32_e32 v63, v214, v37
	v_add_f32_e32 v64, v215, v64
	v_mfma_f32_16x16x32_f16 v[70:73], v[0:3], v[66:69], 0
	v_add_f32_e32 v65, v216, v65
	v_cvt_pk_f16_f32 v83, v64, v65
	v_cvt_pk_f16_f32 v82, v62, v63
	v_mfma_f32_16x16x32_f16 v[66:69], v[66:69], v[0:3], 0
	v_mov_b32_e32 v84, v3
	s_nop 2
	v_cvt_pk_f16_f32 v0, v70, v71
	v_mov_b32_e32 v70, v3
	v_mov_b32_e32 v71, v3
	v_cvt_pk_f16_f32 v1, v72, v73
	v_cvt_pk_f16_f32 v69, v68, v69
	v_cvt_pk_f16_f32 v68, v66, v67
	v_mfma_f32_16x16x32_f16 v[62:65], v[0:3], v[82:85], v[62:65]
	v_mad_i64_i32 v[36:37], s[26:27], v36, s88, v[122:123]
	global_store_short v[36:37], v60, off
	v_mfma_f32_16x16x32_f16 v[72:75], v[68:71], v[0:3], 0
	v_cvt_f16_f32_e32 v82, v61
	v_subrev_u32_e32 v36, 61, v80
	v_xad_u32 v37, v102, -4, v172
	v_mfma_f32_16x16x32_f16 v[66:69], v[0:3], v[68:71], 0
	s_nop 0
	v_cvt_pk_f16_f32 v71, v64, v65
	s_nop 1
	v_cvt_pk_f16_f32 v1, v74, v75
	v_cvt_pk_f16_f32 v0, v72, v73
	ds_read2_b64 v[134:137], v224 offset1:4
	v_mfma_f32_16x16x32_f16 v[56:59], v[98:101], v[126:129], v[86:89]
	v_cvt_pk_f16_f32 v70, v62, v63
	v_mov_b32_e32 v72, v3
	v_mov_b32_e32 v73, v3
	v_cvt_pk_f16_f32 v85, v68, v69
	ds_read2_b64 v[126:129], v224 offset0:8 offset1:12
	v_cvt_pk_f16_f32 v84, v66, v67
	v_mov_b32_e32 v86, v3
	v_mov_b32_e32 v87, v3
	v_mfma_f32_16x16x32_f16 v[88:91], v[0:3], v[70:73], v[62:65]
	s_nop 0
	s_nop 0
	v_cndmask_b32_e64 v36, v37, v36, s[2:3]
	v_mfma_f32_16x16x32_f16 v[60:63], v[84:87], v[0:3], 0
	v_add_u32_e32 v83, v36, v151
	s_nop 2
	v_cvt_pk_f16_f32 v1, v90, v91
	v_cvt_pk_f16_f32 v0, v88, v89
	v_cvt_pk_f16_f32 v67, v54, v55
	v_cvt_pk_f16_f32 v66, v52, v53
	v_cvt_pk_f16_f32 v85, v62, v63
	v_cvt_pk_f16_f32 v84, v60, v61
	v_cvt_pk_f16_f32 v63, v50, v51
	v_cvt_pk_f16_f32 v62, v48, v49
	v_cvt_pk_f16_f32 v61, v42, v43
	v_cvt_pk_f16_f32 v60, v40, v41
	v_cvt_pk_f16_f32 v65, v46, v47
	v_cvt_pk_f16_f32 v64, v44, v45
	s_nop 0
	s_waitcnt lgkmcnt(1)
	v_mfma_f32_16x16x32_f16 v[68:71], v[134:137], v[60:63], 0
	v_add_u32_e32 v36, 0x1000, v224
	v_mov_b32_e32 v93, v3
	v_cvt_f16_f32_e32 v76, v76
	s_nop 0
	s_waitcnt lgkmcnt(0)
	v_mfma_f32_16x16x32_f16 v[98:101], v[126:129], v[64:67], v[68:71]
	ds_read2_b64 v[72:75], v36 offset0:64 offset1:68
	s_nop 1
	ds_read2_b64 v[68:71], v36 offset0:72 offset1:76
	v_cvt_f16_f32_e32 v36, v97
	v_cvt_f16_f32_e32 v97, v77
	v_mfma_f32_16x16x32_f16 v[84:87], v[84:87], v[0:3], v[88:91]
	v_cvt_f16_f32_e32 v0, v94
	v_cvt_f16_f32_e32 v1, v95
	v_cvt_f16_f32_e32 v2, v96
	v_cndmask_b32_e64 v96, v76, 0, s[12:13]
	v_cndmask_b32_e64 v0, 0, v0, s[10:11]
	v_cndmask_b32_e64 v37, 0, v1, s[14:15]
	v_cndmask_b32_e64 v1, 0, v2, s[16:17]
	v_cndmask_b32_e64 v2, 0, v36, s[20:21]
	v_pack_b32_f16 v1, v1, v2
	v_pack_b32_f16 v0, v0, v37
	v_mov_b32_e32 v2, v3
	v_mov_b32_e32 v36, v132
	v_mov_b32_e32 v37, v133
	v_add_u32_e32 v251, 0x800, v233
	ds_read2_b64 v[126:129], v251 offset0:64 offset1:144
	v_mov_b32_e32 v38, v3
	v_mov_b32_e32 v39, v3
	v_mov_b32_e32 v94, v3
	ds_read_b128 v[130:133], v178 offset:256
	v_mov_b32_e32 v95, v3
	v_mfma_f32_16x16x32_f16 v[88:91], v[0:3], v[36:39], v[98:101]
	v_cvt_pk_f16_f32 v1, v86, v87
	v_cvt_pk_f16_f32 v0, v84, v85
	v_cvt_f16_f32_e32 v56, v56
	v_cvt_f16_f32_e32 v98, v78
	v_cvt_f16_f32_e32 v99, v79
	s_nop 2
	v_cvt_pk_f16_f32 v91, v90, v91
	v_cvt_pk_f16_f32 v90, v88, v89
	v_cndmask_b32_e64 v97, 0, v97, s[10:11]
	v_cndmask_b32_e64 v98, v98, 0, s[18:19]
	v_mfma_f32_16x16x32_f16 v[84:87], v[0:3], v[90:93], 0
	v_add_u32_e32 v2, 0x800, v233
	v_mov_b32_e32 v90, v3
	v_mov_b32_e32 v91, v3
	v_cndmask_b32_e64 v99, v99, 0, s[22:23]
	ds_read_b64 v[88:89], v225 offset:5120
	ds_read_b128 v[134:137], v178 offset:320
	s_nop 3
	v_cvt_pk_f16_f32 v1, v86, v87
	v_cvt_pk_f16_f32 v0, v84, v85
	s_nop 0
	s_nop 0
	s_nop 0
	v_mov_b32_e32 v2, v3
	s_nop 0
	s_waitcnt lgkmcnt(3)
	v_mov_b32_e32 v92, v126
	v_mov_b32_e32 v93, v127
	v_add_u32_e32 v251, 0xc00, v233
	ds_read_b64 v[84:85], v226 offset:5120
	ds_read2_b64 v[138:141], v251 offset0:96 offset1:176
	ds_read_b128 v[142:145], v178 offset:384
	s_nop 0
	s_waitcnt lgkmcnt(5)
	v_pk_mul_f32 v[42:43], v[42:43], v[132:133]
	v_pk_mul_f32 v[40:41], v[40:41], v[130:131]
	s_nop 0
	s_nop 0
	v_mfma_f32_16x16x32_f16 v[40:43], v[92:95], v[0:3], v[40:43]
	s_nop 0
	s_waitcnt lgkmcnt(3)
	v_pk_mul_f32 v[48:49], v[48:49], v[134:135]
	v_add_u32_e32 v76, 0xc00, v233
	v_mfma_f32_16x16x32_f16 v[40:43], v[88:91], v[36:39], v[40:43]
	v_mov_b32_e32 v88, v128
	v_mov_b32_e32 v89, v129
	v_pk_mul_f32 v[50:51], v[50:51], v[136:137]
	v_mov_b32_e32 v86, v3
	v_mov_b32_e32 v87, v3
	s_nop 0
	v_mfma_f32_16x16x32_f16 v[48:51], v[88:91], v[0:3], v[48:51]
	ds_read_b64 v[88:89], v227 offset:5120
	s_nop 0
	s_waitcnt lgkmcnt(2)
	v_mov_b32_e32 v92, v138
	v_mfma_f32_16x16x32_f16 v[48:51], v[84:87], v[36:39], v[48:51]
	s_nop 0
	s_nop 0
	v_mov_b32_e32 v93, v139
	v_pack_b32_f16 v76, v96, v97
	v_cndmask_b32_e64 v96, v56, 0, s[12:13]
	s_nop 0
	s_waitcnt lgkmcnt(1)
	v_pk_mul_f32 v[46:47], v[46:47], v[144:145]
	v_pk_mul_f32 v[44:45], v[44:45], v[142:143]
	ds_read_b128 v[84:87], v178 offset:448
	v_cvt_f16_f32_e32 v56, v57
	v_cvt_f16_f32_e32 v57, v58
	v_mfma_f32_16x16x32_f16 v[44:47], v[92:95], v[0:3], v[44:47]
	v_cvt_f16_f32_e32 v58, v59
	v_mov_b32_e32 v92, v140
	v_mov_b32_e32 v93, v141
	s_nop 0
	s_waitcnt lgkmcnt(1)
	v_mfma_f32_16x16x32_f16 v[44:47], v[88:91], v[36:39], v[44:47]
	ds_read_b64 v[88:89], v228 offset:5120
	s_nop 0
	s_nop 0
	v_cndmask_b32_e64 v78, v57, 0, s[18:19]
	v_cndmask_b32_e64 v79, v58, 0, s[22:23]
	v_pack_b32_f16 v77, v98, v99
	s_nop 0
	s_waitcnt lgkmcnt(1)
	v_pk_mul_f32 v[52:53], v[52:53], v[84:85]
	v_cndmask_b32_e64 v84, 0, v56, s[10:11]
	v_mfma_f32_16x16x32_f16 v[56:59], v[72:75], v[60:63], 0
	v_pack_b32_f16 v61, v78, v79
	v_mov_b32_e32 v78, v3
	v_mov_b32_e32 v79, v3
	v_mfma_f32_16x16x32_f16 v[56:59], v[68:71], v[64:67], v[56:59]
	v_mul_f32_e64 v54, v54, v86
	v_mul_f32_e64 v55, v55, v87
	v_pack_b32_f16 v60, v96, v84
	v_mov_b32_e32 v62, v3
	v_mov_b32_e32 v63, v3
	v_mfma_f32_16x16x32_f16 v[52:55], v[92:95], v[0:3], v[52:55]
	v_mfma_f32_16x16x32_f16 v[56:59], v[76:79], v[0:3], v[56:59]
	v_mad_i64_i32 v[0:1], s[26:27], v83, s88, v[122:123]
	global_store_short v[0:1], v82, off
	s_nop 0
	s_waitcnt lgkmcnt(0)
	v_mfma_f32_16x16x32_f16 v[52:55], v[88:91], v[36:39], v[52:55]
	v_subrev_u32_e32 v0, 48, v80
	v_add_u32_e32 v1, 0x7ef, v81
	v_cndmask_b32_e64 v0, v1, v0, s[2:3]
	v_mfma_f32_16x16x32_f16 v[36:39], v[60:63], v[36:39], v[56:59]
	v_add_u32_e32 v0, v0, v151
	v_mad_i64_i32 v[0:1], s[26:27], v0, s88, v[122:123]
	s_nop 5
	v_cvt_f16_f32_e32 v2, v36
	global_store_short v[0:1], v2, off
	v_subrev_u32_e32 v0, 47, v80
	v_add_u32_e32 v1, 0x7ee, v81
	v_cvt_f16_f32_e32 v2, v37
	v_cndmask_b32_e64 v0, v1, v0, s[2:3]
	v_add_u32_e32 v0, v0, v151
	v_mad_i64_i32 v[0:1], s[26:27], v0, s88, v[122:123]
	global_store_short v[0:1], v2, off
	v_subrev_u32_e32 v0, 46, v80
	v_add_u32_e32 v1, 0x7ed, v81
	v_cvt_f16_f32_e32 v2, v38
	v_cndmask_b32_e64 v0, v1, v0, s[2:3]
	v_add_u32_e32 v0, v0, v151
	v_mad_i64_i32 v[0:1], s[26:27], v0, s88, v[122:123]
	global_store_short v[0:1], v2, off
	v_subrev_u32_e32 v0, 45, v80
	v_add_u32_e32 v1, 0x7ec, v81
	v_cndmask_b32_e64 v0, v1, v0, s[2:3]
	v_cvt_f16_f32_e32 v2, v39
	v_add_u32_e32 v0, v0, v151
	v_mad_i64_i32 v[0:1], s[26:27], v0, s88, v[122:123]
	s_mov_b64 s[26:27], 0
	global_store_short v[0:1], v2, off

.LBB0_1041:
	v_cmp_lt_i32_e32 vcc, 2, v174
	s_and_saveexec_b64 s[28:29], vcc
	s_xor_b64 s[28:29], exec, s[28:29]
	s_cbranch_execz .LBB0_1043
	v_lshl_add_u32 v250, v204, 1, v2
	ds_read2st64_b32 v[36:37], v250 offset0:64 offset1:80
	ds_read2st64_b32 v[46:47], v250 offset0:96 offset1:112
	v_lshl_add_u32 v48, v204, 1, v2
	s_nop 0
	s_nop 0
	ds_read_b32 v60, v48 offset:32768
	v_rcp_f32_e32 v44, v62
	v_rcp_f32_e32 v45, v63
	s_nop 0
	s_waitcnt lgkmcnt(1)
	v_cvt_f32_f16_e32 v58, v47
	v_cvt_f32_f16_e32 v50, v37
	v_cvt_f32_f16_sdwa v51, v37 dst_sel:DWORD dst_unused:UNUSED_PAD src0_sel:WORD_1
	v_cvt_f32_f16_sdwa v59, v47 dst_sel:DWORD dst_unused:UNUSED_PAD src0_sel:WORD_1
	v_lshl_add_u32 v250, v206, 1, v2
	ds_read2st64_b32 v[146:147], v250 offset0:64 offset1:80
	v_cvt_f32_f16_e32 v48, v36
	v_cvt_f32_f16_e32 v54, v46
	v_cvt_f32_f16_sdwa v55, v46 dst_sel:DWORD dst_unused:UNUSED_PAD src0_sel:WORD_1
	ds_read2st64_b32 v[148:149], v250 offset0:96 offset1:112
	v_cvt_f32_f16_sdwa v49, v36 dst_sel:DWORD dst_unused:UNUSED_PAD src0_sel:WORD_1
	v_pk_mul_f32 v[36:37], v[42:43], v[50:51]
	v_pk_mul_f32 v[42:43], v[62:63], v[58:59]
	v_pk_mul_f32 v[46:47], v[44:45], v[54:55]
	v_pk_mul_f32 v[44:45], v[44:45], v[48:49]
	v_pk_mul_f32 v[48:49], v[40:41], v[36:37]
	v_pk_mul_f32 v[50:51], v[40:41], v[42:43]
	v_cvt_pk_f16_f32 v36, v36, v37
	v_cvt_pk_f16_f32 v37, v42, v43
	v_pk_mul_f32 v[54:55], v[38:39], v[46:47]
	v_pk_mul_f32 v[58:59], v[38:39], v[44:45]
	ds_write2st64_b32 v205, v36, v37 offset1:18
	v_cvt_pk_f16_f32 v36, v48, v49
	v_cvt_pk_f16_f32 v37, v50, v51
	v_pk_mul_f32 v[46:47], v[0:1], v[46:47]
	ds_write2st64_b32 v205, v36, v37 offset0:36 offset1:54
	v_cvt_pk_f16_f32 v36, v54, v55
	v_cvt_pk_f16_f32 v37, v58, v59
	ds_write2st64_b32 v205, v36, v37 offset0:72 offset1:90
	v_cvt_f16_f32_e32 v36, v46
	v_pk_mul_f32 v[44:45], v[0:1], v[44:45]
	v_cvt_f16_f32_e32 v37, v47
	v_cvt_f16_f32_e32 v42, v44
	v_cvt_f16_f32_e32 v43, v45
	ds_write_b16 v176, v36 offset:24
	ds_write_b16 v176, v37 offset:64
	ds_write_b16 v176, v42 offset:5144
	ds_write_b16 v176, v43 offset:5184
	s_nop 0
	s_waitcnt lgkmcnt(9)
	ds_write_b16 v176, v60 offset:10264
	v_lshl_add_u32 v46, v206, 1, v2
	s_nop 0
	s_nop 0
	ds_read_b32 v61, v46 offset:32768
	v_rcp_f32_e32 v42, v56
	v_rcp_f32_e32 v43, v57
	s_nop 0
	s_waitcnt lgkmcnt(10)
	v_cvt_f32_f16_e32 v48, v147
	v_cvt_f32_f16_sdwa v49, v147 dst_sel:DWORD dst_unused:UNUSED_PAD src0_sel:WORD_1
	s_nop 0
	s_waitcnt lgkmcnt(9)
	v_cvt_f32_f16_e32 v54, v149
	v_cvt_f32_f16_sdwa v55, v149 dst_sel:DWORD dst_unused:UNUSED_PAD src0_sel:WORD_1
	v_cvt_f32_f16_e32 v46, v146
	v_lshl_add_u32 v250, v208, 1, v2
	ds_read2st64_b32 v[162:163], v250 offset0:64 offset1:80
	v_cvt_f32_f16_e32 v50, v148
	v_cvt_f32_f16_sdwa v51, v148 dst_sel:DWORD dst_unused:UNUSED_PAD src0_sel:WORD_1
	v_cvt_f32_f16_sdwa v47, v146 dst_sel:DWORD dst_unused:UNUSED_PAD src0_sel:WORD_1
	ds_read2st64_b32 v[146:147], v250 offset0:96 offset1:112
	v_pk_mul_f32 v[36:37], v[62:63], v[48:49]
	v_pk_mul_f32 v[44:45], v[56:57], v[54:55]
	v_pk_mul_f32 v[48:49], v[42:43], v[50:51]
	v_pk_mul_f32 v[42:43], v[42:43], v[46:47]
	v_pk_mul_f32 v[46:47], v[40:41], v[36:37]
	v_pk_mul_f32 v[50:51], v[40:41], v[44:45]
	v_cvt_pk_f16_f32 v36, v36, v37
	v_cvt_pk_f16_f32 v37, v44, v45
	v_pk_mul_f32 v[54:55], v[38:39], v[48:49]
	v_pk_mul_f32 v[58:59], v[38:39], v[42:43]
	ds_write2st64_b32 v207, v36, v37 offset1:18
	v_cvt_pk_f16_f32 v36, v46, v47
	v_cvt_pk_f16_f32 v37, v50, v51
	v_pk_mul_f32 v[48:49], v[0:1], v[48:49]
	ds_write2st64_b32 v207, v36, v37 offset0:36 offset1:54
	v_cvt_pk_f16_f32 v36, v54, v55
	v_cvt_pk_f16_f32 v37, v58, v59
	ds_write2st64_b32 v207, v36, v37 offset0:72 offset1:90
	v_cvt_f16_f32_e32 v36, v48
	v_pk_mul_f32 v[42:43], v[0:1], v[42:43]
	v_cvt_f16_f32_e32 v37, v49
	v_cvt_f16_f32_e32 v42, v42
	v_cvt_f16_f32_e32 v43, v43
	ds_write_b16 v176, v36 offset:26
	s_waitcnt lgkmcnt(14)
	ds_write_b16 v176, v37 offset:66
	s_waitcnt lgkmcnt(14)
	ds_write_b16 v176, v42 offset:5146
	s_waitcnt lgkmcnt(14)
	ds_write_b16 v176, v43 offset:5186
	s_nop 0
	s_waitcnt lgkmcnt(9)
	ds_write_b16 v176, v61 offset:10266
	v_lshl_add_u32 v46, v208, 1, v2
	s_nop 0
	s_nop 0
	ds_read_b32 v58, v46 offset:32768
	v_rcp_f32_e32 v42, v52
	v_rcp_f32_e32 v43, v53
	v_lshl_add_u32 v2, v210, 1, v2
	s_nop 0
	s_waitcnt lgkmcnt(10)
	v_cvt_f32_f16_e32 v48, v163
	v_cvt_f32_f16_sdwa v49, v163 dst_sel:DWORD dst_unused:UNUSED_PAD src0_sel:WORD_1
	s_nop 0
	s_waitcnt lgkmcnt(9)
	v_cvt_f32_f16_e32 v54, v147
	ds_read2st64_b32 v[148:149], v2 offset0:64 offset1:80
	v_cvt_f32_f16_sdwa v55, v147 dst_sel:DWORD dst_unused:UNUSED_PAD src0_sel:WORD_1
	v_cvt_f32_f16_e32 v46, v162
	v_cvt_f32_f16_e32 v50, v146
	ds_read2st64_b32 v[164:165], v2 offset0:96 offset1:112
	v_cvt_f32_f16_sdwa v51, v146 dst_sel:DWORD dst_unused:UNUSED_PAD src0_sel:WORD_1
	v_cvt_f32_f16_sdwa v47, v162 dst_sel:DWORD dst_unused:UNUSED_PAD src0_sel:WORD_1
	v_pk_mul_f32 v[36:37], v[56:57], v[48:49]
	v_pk_mul_f32 v[44:45], v[52:53], v[54:55]
	v_pk_mul_f32 v[48:49], v[42:43], v[50:51]
	v_pk_mul_f32 v[42:43], v[42:43], v[46:47]
	v_pk_mul_f32 v[46:47], v[40:41], v[36:37]
	v_pk_mul_f32 v[50:51], v[40:41], v[44:45]
	v_cvt_pk_f16_f32 v36, v36, v37
	v_cvt_pk_f16_f32 v37, v44, v45
	v_pk_mul_f32 v[54:55], v[38:39], v[48:49]
	v_pk_mul_f32 v[56:57], v[38:39], v[42:43]
	ds_write2st64_b32 v209, v36, v37 offset1:18
	v_cvt_pk_f16_f32 v36, v46, v47
	v_cvt_pk_f16_f32 v37, v50, v51
	v_pk_mul_f32 v[48:49], v[0:1], v[48:49]
	ds_write2st64_b32 v209, v36, v37 offset0:36 offset1:54
	v_cvt_pk_f16_f32 v36, v54, v55
	v_cvt_pk_f16_f32 v37, v56, v57
	ds_write2st64_b32 v209, v36, v37 offset0:72 offset1:90
	v_cvt_f16_f32_e32 v36, v48
	v_pk_mul_f32 v[42:43], v[0:1], v[42:43]
	v_cvt_f16_f32_e32 v37, v49
	v_cvt_f16_f32_e32 v42, v42
	v_cvt_f16_f32_e32 v43, v43
	ds_write_b16 v176, v36 offset:28
	s_waitcnt lgkmcnt(14)
	ds_write_b16 v176, v37 offset:68
	s_waitcnt lgkmcnt(14)
	ds_write_b16 v176, v42 offset:5148
	s_waitcnt lgkmcnt(14)
	ds_write_b16 v176, v43 offset:5188
	s_nop 0
	s_waitcnt lgkmcnt(9)
	ds_write_b16 v176, v58 offset:10268
	s_nop 0
	s_nop 0
	ds_read_b32 v2, v2 offset:32768
	v_rcp_f32_e32 v42, v0
	v_rcp_f32_e32 v43, v1
	s_nop 0
	s_waitcnt lgkmcnt(10)
	v_cvt_f32_f16_e32 v48, v149
	v_cvt_f32_f16_sdwa v49, v149 dst_sel:DWORD dst_unused:UNUSED_PAD src0_sel:WORD_1
	s_nop 0
	s_waitcnt lgkmcnt(9)
	v_cvt_f32_f16_e32 v54, v165
	v_cvt_f32_f16_sdwa v55, v165 dst_sel:DWORD dst_unused:UNUSED_PAD src0_sel:WORD_1
	v_cvt_f32_f16_e32 v46, v148
	v_cvt_f32_f16_e32 v50, v164
	v_cvt_f32_f16_sdwa v51, v164 dst_sel:DWORD dst_unused:UNUSED_PAD src0_sel:WORD_1
	v_cvt_f32_f16_sdwa v47, v148 dst_sel:DWORD dst_unused:UNUSED_PAD src0_sel:WORD_1
	v_pk_mul_f32 v[36:37], v[52:53], v[48:49]
	v_pk_mul_f32 v[44:45], v[0:1], v[54:55]
	v_pk_mul_f32 v[48:49], v[42:43], v[50:51]
	v_pk_mul_f32 v[42:43], v[42:43], v[46:47]
	v_pk_mul_f32 v[46:47], v[40:41], v[36:37]
	v_pk_mul_f32 v[40:41], v[40:41], v[44:45]
	v_cvt_pk_f16_f32 v36, v36, v37
	v_cvt_pk_f16_f32 v37, v44, v45
	v_pk_mul_f32 v[50:51], v[38:39], v[48:49]
	v_pk_mul_f32 v[38:39], v[38:39], v[42:43]
	ds_write2st64_b32 v211, v36, v37 offset1:18
	v_cvt_pk_f16_f32 v36, v46, v47
	v_cvt_pk_f16_f32 v37, v40, v41
	v_pk_mul_f32 v[48:49], v[0:1], v[48:49]
	ds_write2st64_b32 v211, v36, v37 offset0:36 offset1:54
	v_cvt_pk_f16_f32 v36, v50, v51
	v_cvt_pk_f16_f32 v37, v38, v39
	ds_write2st64_b32 v211, v36, v37 offset0:72 offset1:90
	v_cvt_f16_f32_e32 v36, v48
	v_pk_mul_f32 v[42:43], v[0:1], v[42:43]
	v_cvt_f16_f32_e32 v37, v49
	v_cvt_f16_f32_e32 v38, v42
	v_cvt_f16_f32_e32 v39, v43
	ds_write_b16 v176, v36 offset:30
	ds_write_b16 v176, v37 offset:70
	ds_write_b16 v176, v38 offset:5150
	s_waitcnt lgkmcnt(14)
	ds_write_b16 v176, v39 offset:5190
	s_nop 0
	s_waitcnt lgkmcnt(7)
	ds_write_b16 v176, v2 offset:10270
	v_perm_b32 v36, v61, v60, s35
	v_perm_b32 v37, v2, v58, s35
	ds_write_b64 v176, v[36:37] offset:10304
.LBB0_1043:
	s_andn2_saveexec_b64 s[28:29], s[28:29]
	s_cbranch_execz .LBB0_1045
	v_lshl_add_u32 v250, v196, 1, v2
	ds_read2st64_b32 v[36:37], v250 offset0:64 offset1:80
	ds_read2st64_b32 v[48:49], v250 offset0:96 offset1:112
	v_lshl_add_u32 v52, v196, 1, v2
	s_nop 0
	s_nop 0
	ds_read_b32 v64, v52 offset:32768
	v_rcp_f32_e32 v44, v58
	v_rcp_f32_e32 v45, v59
	s_nop 0
	s_waitcnt lgkmcnt(1)
	v_cvt_f32_f16_e32 v60, v49
	v_cvt_f32_f16_e32 v54, v37
	v_cvt_f32_f16_sdwa v55, v37 dst_sel:DWORD dst_unused:UNUSED_PAD src0_sel:WORD_1
	v_cvt_f32_f16_sdwa v61, v49 dst_sel:DWORD dst_unused:UNUSED_PAD src0_sel:WORD_1
	v_lshl_add_u32 v250, v198, 1, v2
	ds_read2st64_b32 v[146:147], v250 offset0:64 offset1:80
	v_cvt_f32_f16_e32 v52, v36
	v_cvt_f32_f16_e32 v56, v48
	v_cvt_f32_f16_sdwa v57, v48 dst_sel:DWORD dst_unused:UNUSED_PAD src0_sel:WORD_1
	ds_read2st64_b32 v[148:149], v250 offset0:96 offset1:112
	v_cvt_f32_f16_sdwa v53, v36 dst_sel:DWORD dst_unused:UNUSED_PAD src0_sel:WORD_1
	v_pk_mul_f32 v[36:37], v[38:39], v[54:55]
	v_pk_mul_f32 v[48:49], v[58:59], v[60:61]
	v_pk_mul_f32 v[54:55], v[44:45], v[56:57]
	v_pk_mul_f32 v[44:45], v[44:45], v[52:53]
	v_pk_mul_f32 v[52:53], v[40:41], v[36:37]
	v_pk_mul_f32 v[56:57], v[40:41], v[48:49]
	v_cvt_pk_f16_f32 v36, v36, v37
	v_cvt_pk_f16_f32 v37, v48, v49
	v_pk_mul_f32 v[60:61], v[38:39], v[54:55]
	v_pk_mul_f32 v[62:63], v[38:39], v[44:45]
	ds_write2st64_b32 v197, v36, v37 offset1:18
	v_cvt_pk_f16_f32 v36, v52, v53
	v_cvt_pk_f16_f32 v37, v56, v57
	v_pk_mul_f32 v[54:55], v[0:1], v[54:55]
	ds_write2st64_b32 v197, v36, v37 offset0:36 offset1:54
	v_cvt_pk_f16_f32 v36, v60, v61
	v_cvt_pk_f16_f32 v37, v62, v63
	ds_write2st64_b32 v197, v36, v37 offset0:72 offset1:90
	v_cvt_f16_f32_e32 v36, v54
	v_pk_mul_f32 v[44:45], v[0:1], v[44:45]
	v_cvt_f16_f32_e32 v37, v55
	v_cvt_f16_f32_e32 v44, v44
	v_cvt_f16_f32_e32 v45, v45
	ds_write_b16 v176, v36 offset:16
	ds_write_b16 v176, v37 offset:56
	ds_write_b16 v176, v44 offset:5136
	ds_write_b16 v176, v45 offset:5176
	s_nop 0
	s_waitcnt lgkmcnt(9)
	ds_write_b16 v176, v64 offset:10256
	v_lshl_add_u32 v52, v198, 1, v2
	s_nop 0
	s_nop 0
	ds_read_b32 v62, v52 offset:32768
	v_rcp_f32_e32 v44, v50
	v_rcp_f32_e32 v45, v51
	s_nop 0
	s_waitcnt lgkmcnt(10)
	v_cvt_f32_f16_e32 v54, v147
	v_cvt_f32_f16_sdwa v55, v147 dst_sel:DWORD dst_unused:UNUSED_PAD src0_sel:WORD_1
	s_nop 0
	s_waitcnt lgkmcnt(9)
	v_cvt_f32_f16_e32 v60, v149
	v_cvt_f32_f16_sdwa v61, v149 dst_sel:DWORD dst_unused:UNUSED_PAD src0_sel:WORD_1
	v_cvt_f32_f16_e32 v52, v146
	v_lshl_add_u32 v250, v200, 1, v2
	ds_read2st64_b32 v[162:163], v250 offset0:64 offset1:80
	v_cvt_f32_f16_e32 v56, v148
	v_cvt_f32_f16_sdwa v57, v148 dst_sel:DWORD dst_unused:UNUSED_PAD src0_sel:WORD_1
	v_cvt_f32_f16_sdwa v53, v146 dst_sel:DWORD dst_unused:UNUSED_PAD src0_sel:WORD_1
	ds_read2st64_b32 v[146:147], v250 offset0:96 offset1:112
	v_pk_mul_f32 v[36:37], v[58:59], v[54:55]
	v_pk_mul_f32 v[48:49], v[50:51], v[60:61]
	v_pk_mul_f32 v[54:55], v[44:45], v[56:57]
	v_pk_mul_f32 v[44:45], v[44:45], v[52:53]
	v_pk_mul_f32 v[52:53], v[40:41], v[36:37]
	v_pk_mul_f32 v[56:57], v[40:41], v[48:49]
	v_cvt_pk_f16_f32 v36, v36, v37
	v_cvt_pk_f16_f32 v37, v48, v49
	v_pk_mul_f32 v[58:59], v[38:39], v[54:55]
	v_pk_mul_f32 v[60:61], v[38:39], v[44:45]
	ds_write2st64_b32 v199, v36, v37 offset1:18
	v_cvt_pk_f16_f32 v36, v52, v53
	v_cvt_pk_f16_f32 v37, v56, v57
	v_pk_mul_f32 v[54:55], v[0:1], v[54:55]
	ds_write2st64_b32 v199, v36, v37 offset0:36 offset1:54
	v_cvt_pk_f16_f32 v36, v58, v59
	v_cvt_pk_f16_f32 v37, v60, v61
	ds_write2st64_b32 v199, v36, v37 offset0:72 offset1:90
	v_cvt_f16_f32_e32 v36, v54
	v_pk_mul_f32 v[44:45], v[0:1], v[44:45]
	v_cvt_f16_f32_e32 v37, v55
	v_cvt_f16_f32_e32 v44, v44
	v_cvt_f16_f32_e32 v45, v45
	ds_write_b16 v176, v36 offset:18
	s_waitcnt lgkmcnt(14)
	ds_write_b16 v176, v37 offset:58
	s_waitcnt lgkmcnt(14)
	ds_write_b16 v176, v44 offset:5138
	s_waitcnt lgkmcnt(14)
	ds_write_b16 v176, v45 offset:5178
	s_nop 0
	s_waitcnt lgkmcnt(9)
	ds_write_b16 v176, v62 offset:10258
	v_lshl_add_u32 v52, v200, 1, v2
	s_nop 0
	s_nop 0
	ds_read_b32 v60, v52 offset:32768
	v_rcp_f32_e32 v44, v46
	v_rcp_f32_e32 v45, v47
	v_lshl_add_u32 v2, v202, 1, v2
	s_nop 0
	s_waitcnt lgkmcnt(10)
	v_cvt_f32_f16_e32 v54, v163
	v_cvt_f32_f16_sdwa v55, v163 dst_sel:DWORD dst_unused:UNUSED_PAD src0_sel:WORD_1
	s_nop 0
	s_waitcnt lgkmcnt(9)
	v_cvt_f32_f16_e32 v58, v147
	ds_read2st64_b32 v[148:149], v2 offset0:64 offset1:80
	v_cvt_f32_f16_sdwa v59, v147 dst_sel:DWORD dst_unused:UNUSED_PAD src0_sel:WORD_1
	v_cvt_f32_f16_e32 v52, v162
	v_cvt_f32_f16_e32 v56, v146
	ds_read2st64_b32 v[164:165], v2 offset0:96 offset1:112
	v_cvt_f32_f16_sdwa v57, v146 dst_sel:DWORD dst_unused:UNUSED_PAD src0_sel:WORD_1
	v_cvt_f32_f16_sdwa v53, v162 dst_sel:DWORD dst_unused:UNUSED_PAD src0_sel:WORD_1
	v_pk_mul_f32 v[36:37], v[50:51], v[54:55]
	v_pk_mul_f32 v[48:49], v[46:47], v[58:59]
	v_pk_mul_f32 v[50:51], v[44:45], v[56:57]
	v_pk_mul_f32 v[44:45], v[44:45], v[52:53]
	v_pk_mul_f32 v[52:53], v[40:41], v[36:37]
	v_pk_mul_f32 v[54:55], v[40:41], v[48:49]
	v_cvt_pk_f16_f32 v36, v36, v37
	v_cvt_pk_f16_f32 v37, v48, v49
	v_pk_mul_f32 v[56:57], v[38:39], v[50:51]
	v_pk_mul_f32 v[58:59], v[38:39], v[44:45]
	ds_write2st64_b32 v201, v36, v37 offset1:18
	v_cvt_pk_f16_f32 v36, v52, v53
	v_cvt_pk_f16_f32 v37, v54, v55
	v_pk_mul_f32 v[50:51], v[0:1], v[50:51]
	ds_write2st64_b32 v201, v36, v37 offset0:36 offset1:54
	v_cvt_pk_f16_f32 v36, v56, v57
	v_cvt_pk_f16_f32 v37, v58, v59
	ds_write2st64_b32 v201, v36, v37 offset0:72 offset1:90
	v_cvt_f16_f32_e32 v36, v50
	v_pk_mul_f32 v[44:45], v[0:1], v[44:45]
	v_cvt_f16_f32_e32 v37, v51
	v_cvt_f16_f32_e32 v44, v44
	v_cvt_f16_f32_e32 v45, v45
	ds_write_b16 v176, v36 offset:20
	s_waitcnt lgkmcnt(14)
	ds_write_b16 v176, v37 offset:60
	s_waitcnt lgkmcnt(14)
	ds_write_b16 v176, v44 offset:5140
	s_waitcnt lgkmcnt(14)
	ds_write_b16 v176, v45 offset:5180
	s_nop 0
	s_waitcnt lgkmcnt(9)
	ds_write_b16 v176, v60 offset:10260
	s_nop 0
	s_nop 0
	ds_read_b32 v2, v2 offset:32768
	v_rcp_f32_e32 v44, v42
	v_rcp_f32_e32 v45, v43
	s_nop 0
	s_waitcnt lgkmcnt(10)
	v_cvt_f32_f16_e32 v52, v149
	v_cvt_f32_f16_sdwa v53, v149 dst_sel:DWORD dst_unused:UNUSED_PAD src0_sel:WORD_1
	s_nop 0
	s_waitcnt lgkmcnt(9)
	v_cvt_f32_f16_e32 v56, v165
	v_cvt_f32_f16_sdwa v57, v165 dst_sel:DWORD dst_unused:UNUSED_PAD src0_sel:WORD_1
	v_cvt_f32_f16_e32 v50, v148
	v_cvt_f32_f16_e32 v54, v164
	v_cvt_f32_f16_sdwa v55, v164 dst_sel:DWORD dst_unused:UNUSED_PAD src0_sel:WORD_1
	v_cvt_f32_f16_sdwa v51, v148 dst_sel:DWORD dst_unused:UNUSED_PAD src0_sel:WORD_1
	v_pk_mul_f32 v[36:37], v[46:47], v[52:53]
	v_pk_mul_f32 v[42:43], v[42:43], v[56:57]
	v_pk_mul_f32 v[46:47], v[44:45], v[54:55]
	v_pk_mul_f32 v[44:45], v[44:45], v[50:51]
	v_pk_mul_f32 v[48:49], v[40:41], v[36:37]
	v_pk_mul_f32 v[40:41], v[40:41], v[42:43]
	v_cvt_pk_f16_f32 v36, v36, v37
	v_cvt_pk_f16_f32 v37, v42, v43
	v_pk_mul_f32 v[50:51], v[38:39], v[46:47]
	v_pk_mul_f32 v[38:39], v[38:39], v[44:45]
	ds_write2st64_b32 v203, v36, v37 offset1:18
	v_cvt_pk_f16_f32 v36, v48, v49
	v_cvt_pk_f16_f32 v37, v40, v41
	v_pk_mul_f32 v[46:47], v[0:1], v[46:47]
	ds_write2st64_b32 v203, v36, v37 offset0:36 offset1:54
	v_cvt_pk_f16_f32 v36, v50, v51
	v_cvt_pk_f16_f32 v37, v38, v39
	ds_write2st64_b32 v203, v36, v37 offset0:72 offset1:90
	v_cvt_f16_f32_e32 v36, v46
	v_pk_mul_f32 v[44:45], v[0:1], v[44:45]
	v_cvt_f16_f32_e32 v37, v47
	v_cvt_f16_f32_e32 v38, v44
	v_cvt_f16_f32_e32 v39, v45
	ds_write_b16 v176, v36 offset:22
	ds_write_b16 v176, v37 offset:62
	ds_write_b16 v176, v38 offset:5142
	s_waitcnt lgkmcnt(14)
	ds_write_b16 v176, v39 offset:5182
	s_nop 0
	s_waitcnt lgkmcnt(7)
	ds_write_b16 v176, v2 offset:10262
	v_perm_b32 v36, v62, v64, s35
	v_perm_b32 v37, v2, v60, s35
	ds_write_b64 v176, v[36:37] offset:10296

.LBB0_1046:
	v_cmp_eq_u32_e32 vcc, 1, v174
	s_and_saveexec_b64 s[28:29], vcc
	s_cbranch_execz .LBB0_1048
	v_lshl_add_u32 v250, v188, 1, v2
	ds_read2st64_b32 v[36:37], v250 offset0:64 offset1:80
	ds_read2st64_b32 v[46:47], v250 offset0:96 offset1:112
	v_lshl_add_u32 v50, v188, 1, v2
	s_nop 0
	s_nop 0
	ds_read_b32 v62, v50 offset:32768
	v_rcp_f32_e32 v42, v54
	v_rcp_f32_e32 v43, v55
	s_nop 0
	s_waitcnt lgkmcnt(1)
	v_cvt_f32_f16_e32 v58, v47
	v_cvt_f32_f16_e32 v52, v37
	v_cvt_f32_f16_sdwa v53, v37 dst_sel:DWORD dst_unused:UNUSED_PAD src0_sel:WORD_1
	v_cvt_f32_f16_sdwa v59, v47 dst_sel:DWORD dst_unused:UNUSED_PAD src0_sel:WORD_1
	v_lshl_add_u32 v250, v190, 1, v2
	ds_read2st64_b32 v[146:147], v250 offset0:64 offset1:80
	v_cvt_f32_f16_e32 v50, v36
	v_cvt_f32_f16_e32 v56, v46
	v_cvt_f32_f16_sdwa v57, v46 dst_sel:DWORD dst_unused:UNUSED_PAD src0_sel:WORD_1
	ds_read2st64_b32 v[148:149], v250 offset0:96 offset1:112
	v_cvt_f32_f16_sdwa v51, v36 dst_sel:DWORD dst_unused:UNUSED_PAD src0_sel:WORD_1
	v_pk_mul_f32 v[36:37], v[60:61], v[52:53]
	v_pk_mul_f32 v[46:47], v[54:55], v[58:59]
	v_pk_mul_f32 v[52:53], v[42:43], v[56:57]
	v_pk_mul_f32 v[42:43], v[42:43], v[50:51]
	v_pk_mul_f32 v[50:51], v[40:41], v[36:37]
	v_pk_mul_f32 v[56:57], v[40:41], v[46:47]
	v_cvt_pk_f16_f32 v36, v36, v37
	v_cvt_pk_f16_f32 v37, v46, v47
	v_pk_mul_f32 v[58:59], v[38:39], v[52:53]
	v_pk_mul_f32 v[60:61], v[38:39], v[42:43]
	ds_write2st64_b32 v189, v36, v37 offset1:18
	v_cvt_pk_f16_f32 v36, v50, v51
	v_cvt_pk_f16_f32 v37, v56, v57
	v_pk_mul_f32 v[52:53], v[0:1], v[52:53]
	ds_write2st64_b32 v189, v36, v37 offset0:36 offset1:54
	v_cvt_pk_f16_f32 v36, v58, v59
	v_cvt_pk_f16_f32 v37, v60, v61
	ds_write2st64_b32 v189, v36, v37 offset0:72 offset1:90
	v_cvt_f16_f32_e32 v36, v52
	v_pk_mul_f32 v[42:43], v[0:1], v[42:43]
	v_cvt_f16_f32_e32 v37, v53
	v_cvt_f16_f32_e32 v42, v42
	v_cvt_f16_f32_e32 v43, v43
	ds_write_b16 v176, v36 offset:8
	ds_write_b16 v176, v37 offset:48
	ds_write_b16 v176, v42 offset:5128
	ds_write_b16 v176, v43 offset:5168
	s_nop 0
	s_waitcnt lgkmcnt(9)
	ds_write_b16 v176, v62 offset:10248
	v_lshl_add_u32 v50, v190, 1, v2
	s_nop 0
	s_nop 0
	ds_read_b32 v60, v50 offset:32768
	v_rcp_f32_e32 v42, v48
	v_rcp_f32_e32 v43, v49
	s_nop 0
	s_waitcnt lgkmcnt(10)
	v_cvt_f32_f16_e32 v52, v147
	v_cvt_f32_f16_sdwa v53, v147 dst_sel:DWORD dst_unused:UNUSED_PAD src0_sel:WORD_1
	s_nop 0
	s_waitcnt lgkmcnt(9)
	v_cvt_f32_f16_e32 v58, v149
	v_cvt_f32_f16_sdwa v59, v149 dst_sel:DWORD dst_unused:UNUSED_PAD src0_sel:WORD_1
	v_cvt_f32_f16_e32 v50, v146
	v_lshl_add_u32 v250, v192, 1, v2
	ds_read2st64_b32 v[162:163], v250 offset0:64 offset1:80
	v_cvt_f32_f16_e32 v56, v148
	v_cvt_f32_f16_sdwa v57, v148 dst_sel:DWORD dst_unused:UNUSED_PAD src0_sel:WORD_1
	v_cvt_f32_f16_sdwa v51, v146 dst_sel:DWORD dst_unused:UNUSED_PAD src0_sel:WORD_1
	ds_read2st64_b32 v[146:147], v250 offset0:96 offset1:112
	v_pk_mul_f32 v[36:37], v[54:55], v[52:53]
	v_pk_mul_f32 v[46:47], v[48:49], v[58:59]
	v_pk_mul_f32 v[52:53], v[42:43], v[56:57]
	v_pk_mul_f32 v[42:43], v[42:43], v[50:51]
	v_pk_mul_f32 v[50:51], v[40:41], v[36:37]
	v_pk_mul_f32 v[54:55], v[40:41], v[46:47]
	v_cvt_pk_f16_f32 v36, v36, v37
	v_cvt_pk_f16_f32 v37, v46, v47
	v_pk_mul_f32 v[56:57], v[38:39], v[52:53]
	v_pk_mul_f32 v[58:59], v[38:39], v[42:43]
	ds_write2st64_b32 v191, v36, v37 offset1:18
	v_cvt_pk_f16_f32 v36, v50, v51
	v_cvt_pk_f16_f32 v37, v54, v55
	v_pk_mul_f32 v[52:53], v[0:1], v[52:53]
	ds_write2st64_b32 v191, v36, v37 offset0:36 offset1:54
	v_cvt_pk_f16_f32 v36, v56, v57
	v_cvt_pk_f16_f32 v37, v58, v59
	ds_write2st64_b32 v191, v36, v37 offset0:72 offset1:90
	v_cvt_f16_f32_e32 v36, v52
	v_pk_mul_f32 v[42:43], v[0:1], v[42:43]
	v_cvt_f16_f32_e32 v37, v53
	v_cvt_f16_f32_e32 v42, v42
	v_cvt_f16_f32_e32 v43, v43
	ds_write_b16 v176, v36 offset:10
	s_waitcnt lgkmcnt(14)
	ds_write_b16 v176, v37 offset:50
	s_waitcnt lgkmcnt(14)
	ds_write_b16 v176, v42 offset:5130
	s_waitcnt lgkmcnt(14)
	ds_write_b16 v176, v43 offset:5170
	s_nop 0
	s_waitcnt lgkmcnt(9)
	ds_write_b16 v176, v60 offset:10250
	v_lshl_add_u32 v50, v192, 1, v2
	s_nop 0
	s_nop 0
	ds_read_b32 v58, v50 offset:32768
	v_rcp_f32_e32 v42, v44
	v_rcp_f32_e32 v43, v45
	v_lshl_add_u32 v2, v194, 1, v2
	s_nop 0
	s_waitcnt lgkmcnt(10)
	v_cvt_f32_f16_e32 v52, v163
	v_cvt_f32_f16_sdwa v53, v163 dst_sel:DWORD dst_unused:UNUSED_PAD src0_sel:WORD_1
	ds_read2st64_b32 v[148:149], v2 offset0:64 offset1:80
	s_nop 0
	s_waitcnt lgkmcnt(10)
	v_cvt_f32_f16_e32 v56, v147
	v_cvt_f32_f16_sdwa v57, v147 dst_sel:DWORD dst_unused:UNUSED_PAD src0_sel:WORD_1
	ds_read2st64_b32 v[164:165], v2 offset0:96 offset1:112
	v_cvt_f32_f16_e32 v50, v162
	v_cvt_f32_f16_e32 v54, v146
	v_cvt_f32_f16_sdwa v55, v146 dst_sel:DWORD dst_unused:UNUSED_PAD src0_sel:WORD_1
	v_cvt_f32_f16_sdwa v51, v162 dst_sel:DWORD dst_unused:UNUSED_PAD src0_sel:WORD_1
	v_pk_mul_f32 v[36:37], v[48:49], v[52:53]
	v_pk_mul_f32 v[46:47], v[44:45], v[56:57]
	v_pk_mul_f32 v[48:49], v[42:43], v[54:55]
	v_pk_mul_f32 v[42:43], v[42:43], v[50:51]
	v_pk_mul_f32 v[50:51], v[40:41], v[36:37]
	v_pk_mul_f32 v[52:53], v[40:41], v[46:47]
	v_cvt_pk_f16_f32 v36, v36, v37
	v_cvt_pk_f16_f32 v37, v46, v47
	v_pk_mul_f32 v[54:55], v[38:39], v[48:49]
	v_pk_mul_f32 v[56:57], v[38:39], v[42:43]
	ds_write2st64_b32 v193, v36, v37 offset1:18
	v_cvt_pk_f16_f32 v36, v50, v51
	v_cvt_pk_f16_f32 v37, v52, v53
	v_pk_mul_f32 v[48:49], v[0:1], v[48:49]
	ds_write2st64_b32 v193, v36, v37 offset0:36 offset1:54
	v_cvt_pk_f16_f32 v36, v54, v55
	v_cvt_pk_f16_f32 v37, v56, v57
	ds_write2st64_b32 v193, v36, v37 offset0:72 offset1:90
	v_cvt_f16_f32_e32 v36, v48
	v_pk_mul_f32 v[42:43], v[0:1], v[42:43]
	v_cvt_f16_f32_e32 v37, v49
	v_cvt_f16_f32_e32 v42, v42
	v_cvt_f16_f32_e32 v43, v43
	ds_write_b16 v176, v36 offset:12
	s_waitcnt lgkmcnt(14)
	ds_write_b16 v176, v37 offset:52
	s_waitcnt lgkmcnt(14)
	ds_write_b16 v176, v42 offset:5132
	s_waitcnt lgkmcnt(14)
	ds_write_b16 v176, v43 offset:5172
	s_nop 0
	s_waitcnt lgkmcnt(9)
	ds_write_b16 v176, v58 offset:10252
	s_nop 0
	s_nop 0
	ds_read_b32 v2, v2 offset:32768
	s_nop 0
	s_waitcnt lgkmcnt(10)
	v_cvt_f32_f16_e32 v48, v149
	v_cvt_f32_f16_sdwa v49, v149 dst_sel:DWORD dst_unused:UNUSED_PAD src0_sel:WORD_1
	s_nop 0
	s_waitcnt lgkmcnt(9)
	v_cvt_f32_f16_e32 v52, v165
	v_cvt_f32_f16_sdwa v53, v165 dst_sel:DWORD dst_unused:UNUSED_PAD src0_sel:WORD_1
	v_cvt_f32_f16_e32 v46, v148
	v_cvt_f32_f16_e32 v50, v164
	v_cvt_f32_f16_sdwa v51, v164 dst_sel:DWORD dst_unused:UNUSED_PAD src0_sel:WORD_1
	v_cvt_f32_f16_sdwa v47, v148 dst_sel:DWORD dst_unused:UNUSED_PAD src0_sel:WORD_1
	v_pk_mul_f32 v[36:37], v[44:45], v[48:49]
	v_pk_mul_f32 v[42:43], v[38:39], v[52:53]
	v_pk_mul_f32 v[44:45], v[40:41], v[50:51]
	v_pk_mul_f32 v[46:47], v[40:41], v[46:47]
	v_pk_mul_f32 v[48:49], v[40:41], v[36:37]
	v_pk_mul_f32 v[40:41], v[40:41], v[42:43]
	v_cvt_pk_f16_f32 v36, v36, v37
	v_cvt_pk_f16_f32 v37, v42, v43
	v_pk_mul_f32 v[50:51], v[38:39], v[44:45]
	v_pk_mul_f32 v[38:39], v[38:39], v[46:47]
	ds_write2st64_b32 v195, v36, v37 offset1:18
	v_cvt_pk_f16_f32 v36, v48, v49
	v_cvt_pk_f16_f32 v37, v40, v41
	v_pk_mul_f32 v[44:45], v[0:1], v[44:45]
	ds_write2st64_b32 v195, v36, v37 offset0:36 offset1:54
	v_cvt_pk_f16_f32 v36, v50, v51
	v_cvt_pk_f16_f32 v37, v38, v39
	ds_write2st64_b32 v195, v36, v37 offset0:72 offset1:90
	v_cvt_f16_f32_e32 v36, v44
	v_pk_mul_f32 v[46:47], v[0:1], v[46:47]
	v_cvt_f16_f32_e32 v37, v45
	v_cvt_f16_f32_e32 v38, v46
	v_cvt_f16_f32_e32 v39, v47
	ds_write_b16 v176, v36 offset:14
	ds_write_b16 v176, v37 offset:54
	ds_write_b16 v176, v38 offset:5134
	s_waitcnt lgkmcnt(14)
	ds_write_b16 v176, v39 offset:5174
	s_nop 0
	s_waitcnt lgkmcnt(7)
	ds_write_b16 v176, v2 offset:10254
	v_perm_b32 v36, v60, v62, s35
	v_perm_b32 v37, v2, v58, s35
	ds_write_b64 v176, v[36:37] offset:10288
